# attention v7: a tile is a pair of adjacent query rows sharing the staged K / V^T chunks (5 local + 2 ctx rounds per two rows instead of 12), row B one bias-table row lower with window-edge rows masked
# speedup vs baseline: 1.0068x; 1.0066x over previous
; __device__ __forceinline__ void attn_phase(const Params& P, char* smem_raw) {
;   u16* sm_k = reinterpret_cast<u16*>(smem_raw);
;   u16* sm_vt = sm_k + 128 * LDSS;
;   u16* sm_p = sm_vt + 64 * 136;
;   float* sm_rpb = reinterpret_cast<float*>(sm_p + 4 * 16 * 136);
;   const int tid = VTID, lane = tid & 63, wid = tid >> 6;
;   const u16* QKV = P.zq;
;   const u16* VTX = P.zf;
;   const u16* VTC = reinterpret_cast<const u16*>(P.summ);
;   uint4 kreg[4], vreg[4];
;   bf16x8 qn[2];
;     ...
;   int dco[4][4];
; #pragma unroll
;   for (int reg = 0; reg < 4; ++reg) {
;     const int c = wid * 16 + (lane >> 4) * 4 + reg;
;     const int cs = min(max(c - 8, 0), 48);
; #pragma unroll
;     for (int q4 = 0; q4 < 4; ++q4) {
;       const int kc = q4 * 16 + (lane & 15);
;       dco[reg][q4] = (kc >= cs && kc < cs + 16) ? (kc - c + 15) : 465;
;     }
;   }
;   int t = VBID;
;   __syncthreads();
;   if (t < 8192) {
;     const int h0 = t & 15;
;     for (int idx = tid; idx < 930; idx += VTHR) sm_rpb[idx] = (idx < 465) ? P.rpb[h0 * 465 + idx] * 1.4426950408889634f : -1e30f;
;     ATT_ISSUE(t, 0)
;     ATT_QLOAD(t)
;   }
.LBB0_1489:
	s_cmp_gt_i32 s34, 12
	s_cselect_b64 s[0:1], -1, 0
	s_cmp_lt_i32 s35, 13
	s_cselect_b64 s[4:5], -1, 0
	s_or_b64 s[0:1], s[0:1], s[4:5]
	s_and_b64 vcc, exec, s[0:1]
	s_cbranch_vccnz .LBB0_1555
	s_waitcnt vmcnt(5)
	v_lshl_add_u32 v109, s2, 1, v153
	s_movk_i32 s0, 0x2000
	v_mov_b32_e32 v0, v153
	v_cmp_gt_i32_e32 vcc, s0, v109
	s_barrier
	s_and_saveexec_b64 s[42:43], vcc
	s_cbranch_execz .LBB0_1501
	v_readlane_b32 s0, v252, 0
	v_readlane_b32 s1, v252, 1
	v_readfirstlane_b32 s3, v153
	s_nop 3
	s_sub_u32 s0, s0, 0x170
	s_subb_u32 s1, s1, 0
	s_load_dwordx2 s[12:13], s[0:1], 0xb8
	s_load_dwordx2 s[8:9], s[0:1], 0x130
	s_load_dwordx4 s[4:7], s[0:1], 0x148
	s_load_dwordx2 s[10:11], s[0:1], 0x158
	s_lshl_b32 s100, s2, 1
	s_add_u32 s3, s100, s3
	s_and_b32 s101, s3, 15
	s_lshl_b32 s3, s3, 8
	s_waitcnt lgkmcnt(0)
	s_lshl_b32 s100, s101, 7
	s_add_u32 s4, s4, s100
	s_addc_u32 s5, s5, 0
	s_add_u32 s10, s10, s100
	s_addc_u32 s11, s11, 0
	s_lshl_b32 s100, s101, 20
	s_add_u32 s6, s6, s100
	s_addc_u32 s7, s7, 0
	s_lshl_b32 s100, s101, 15
	s_add_u32 s8, s8, s100
	s_addc_u32 s9, s9, 0
	s_mul_i32 s100, s101, 0x744
	s_add_u32 s12, s12, s100
	s_addc_u32 s13, s13, 0
	v_and_b32_e32 v112, 0xff, v152
	v_and_b32_e32 v113, 63, v152
	v_bfe_u32 v114, v152, 6, 2
	v_lshrrev_b32_e32 v115, 4, v113
	v_and_b32_e32 v116, 15, v113
	v_mul_u32_u24_e32 v117, 0x12000, v153
	v_add_u32_e32 v117, 16, v117
	v_and_b32_e32 v118, 7, v116
	v_lshrrev_b32_e32 v119, 1, v114
	v_add_u32_e32 v119, v119, v114
	v_lshlrev_b32_e32 v119, 3, v119
	v_xor_b32_e32 v121, v115, v118
	v_lshl_add_u32 v122, v116, 7, v117
	v_lshl_add_u32 v149, v121, 4, v122
	v_xor_b32_e32 v121, 4, v121
	v_lshl_add_u32 v224, v121, 4, v122
	v_lshl_add_u32 v144, v119, 7, v149
	v_lshl_add_u32 v145, v119, 7, v224
	v_lshl_add_u32 v124, v116, 8, v117
	v_add_u32_e32 v124, 0x4000, v124
	v_lshrrev_b32_e32 v123, 2, v119
	v_add_u32_e32 v125, 0, v115
	v_xor_b32_e32 v125, v125, v116
	v_lshl_add_u32 v225, v125, 4, v124
	v_add_u32_e32 v125, 4, v115
	v_xor_b32_e32 v125, v125, v116
	v_lshl_add_u32 v226, v125, 4, v124
	v_add_u32_e32 v125, 8, v115
	v_xor_b32_e32 v125, v125, v116
	v_lshl_add_u32 v227, v125, 4, v124
	v_add_u32_e32 v125, 12, v115
	v_xor_b32_e32 v125, v125, v116
	v_lshl_add_u32 v228, v125, 4, v124
	v_add3_u32 v125, v123, 0, v115
	v_xor_b32_e32 v125, v125, v116
	v_lshl_add_u32 v146, v125, 4, v124
	v_add3_u32 v125, v123, 4, v115
	v_xor_b32_e32 v125, v125, v116
	v_lshl_add_u32 v147, v125, 4, v124
	v_lshrrev_b32_e32 v126, 3, v112
	v_and_b32_e32 v127, 7, v112
	v_and_b32_e32 v128, 7, v126
	v_xor_b32_e32 v128, v127, v128
	v_lshl_add_u32 v125, v126, 7, v117
	v_lshl_add_u32 v150, v128, 4, v125
	v_lshrrev_b32_e32 v129, 4, v112
	v_and_b32_e32 v130, 15, v112
	v_and_b32_e32 v125, 7, v130
	v_lshlrev_b32_e32 v125, 1, v125
	v_xor_b32_e32 v125, v125, v129
	v_lshl_add_u32 v128, v129, 8, v117
	v_lshl_add_u32 v151, v125, 4, v128
	v_xor_b32_e32 v125, 1, v125
	v_lshl_add_u32 v229, v125, 4, v128
	v_lshrrev_b32_e32 v125, 3, v130
	v_lshl_add_u32 v151, v125, 3, v151
	v_lshl_add_u32 v229, v125, 3, v229
	v_add_u32_e32 v151, 0x4000, v151
	v_add_u32_e32 v229, 0x4000, v229
	v_mul_u32_u24_e32 v125, 0x1800, v126
	v_lshl_add_u32 v154, v127, 4, v125
	v_add_u32_e32 v155, 0x30000, v154
	v_add_u32_e32 v156, 0x60000, v154
	v_add_u32_e32 v157, 0x90000, v154
	v_lshlrev_b32_e32 v125, 14, v129
	v_lshl_add_u32 v158, v130, 4, v125
	v_add_u32_e32 v159, 0x40000, v158
	v_add_u32_e32 v160, 0x80000, v158
	v_add_u32_e32 v161, 0xc0000, v158
	v_lshlrev_b32_e32 v125, 9, v129
	v_lshl_add_u32 v162, v130, 4, v125
	v_add_u32_e32 v163, 0x2000, v162
	v_add_u32_e32 v164, 0x4000, v162
	v_add_u32_e32 v165, 0x6000, v162
	v_lshl_add_u32 v131, v114, 4, v116
	v_mul_u32_u24_e32 v125, 0x1800, v131
	v_lshl_add_u32 v166, v115, 4, v125
	v_lshlrev_b32_e32 v125, 11, v131
	v_lshl_add_u32 v167, v115, 3, v125
	v_sub_u32_e64 v132, v131, 8 clamp
	v_min_u32_e32 v132, 48, v132
	v_mov_b32_e32 v210, 0x7c
	v_lshl_add_u32 v133, v115, 2, v119
	v_add_u32_e32 v134, 0, v133
	v_sub_u32_e32 v135, v134, v132
	v_cmp_gt_u32_e32 vcc, 16, v135
	v_sub_u32_e32 v136, v134, v131
	v_lshlrev_b32_e32 v136, 2, v136
	v_add_u32_e32 v136, 60, v136
	v_cndmask_b32_e32 v168, v210, v136, vcc
	v_add_u32_e32 v134, 1, v133
	v_sub_u32_e32 v135, v134, v132
	v_cmp_gt_u32_e32 vcc, 16, v135
	v_sub_u32_e32 v136, v134, v131
	v_lshlrev_b32_e32 v136, 2, v136
	v_add_u32_e32 v136, 60, v136
	v_cndmask_b32_e32 v169, v210, v136, vcc
	v_add_u32_e32 v134, 2, v133
	v_sub_u32_e32 v135, v134, v132
	v_cmp_gt_u32_e32 vcc, 16, v135
	v_sub_u32_e32 v136, v134, v131
	v_lshlrev_b32_e32 v136, 2, v136
	v_add_u32_e32 v136, 60, v136
	v_cndmask_b32_e32 v170, v210, v136, vcc
	v_add_u32_e32 v134, 3, v133
	v_sub_u32_e32 v135, v134, v132
	v_cmp_gt_u32_e32 vcc, 16, v135
	v_sub_u32_e32 v136, v134, v131
	v_lshlrev_b32_e32 v136, 2, v136
	v_add_u32_e32 v136, 60, v136
	v_cndmask_b32_e32 v171, v210, v136, vcc
	v_add_u32_e32 v134, 16, v133
	v_sub_u32_e32 v135, v134, v132
	v_cmp_gt_u32_e32 vcc, 16, v135
	v_sub_u32_e32 v136, v134, v131
	v_lshlrev_b32_e32 v136, 2, v136
	v_add_u32_e32 v136, 60, v136
	v_cndmask_b32_e32 v172, v210, v136, vcc
	v_add_u32_e32 v134, 17, v133
	v_sub_u32_e32 v135, v134, v132
	v_cmp_gt_u32_e32 vcc, 16, v135
	v_sub_u32_e32 v136, v134, v131
	v_lshlrev_b32_e32 v136, 2, v136
	v_add_u32_e32 v136, 60, v136
	v_cndmask_b32_e32 v173, v210, v136, vcc
	v_add_u32_e32 v134, 18, v133
	v_sub_u32_e32 v135, v134, v132
	v_cmp_gt_u32_e32 vcc, 16, v135
	v_sub_u32_e32 v136, v134, v131
	v_lshlrev_b32_e32 v136, 2, v136
	v_add_u32_e32 v136, 60, v136
	v_cndmask_b32_e32 v174, v210, v136, vcc
	v_add_u32_e32 v134, 19, v133
	v_sub_u32_e32 v135, v134, v132
	v_cmp_gt_u32_e32 vcc, 16, v135
	v_sub_u32_e32 v136, v134, v131
	v_lshlrev_b32_e32 v136, 2, v136
	v_add_u32_e32 v136, 60, v136
	v_cndmask_b32_e32 v175, v210, v136, vcc
	v_mov_b32_e32 v143, 0xf149f2ca
	v_mov_b32_e32 v137, v112
	v_lshrrev_b32_e32 v138, 5, v137
	v_and_b32_e32 v139, 31, v137
	v_mul_u32_u24_e32 v140, 31, v138
	v_add_u32_e32 v140, v140, v139
	v_min_u32_e32 v140, 0x1d0, v140
	v_lshlrev_b32_e32 v140, 2, v140
	global_load_dword v141, v140, s[12:13]
	v_lshl_add_u32 v142, v137, 2, v117
	v_add_u32_e32 v142, 0x10000, v142
	v_cmp_eq_u32_e32 vcc, 31, v139
	s_waitcnt vmcnt(0)
; __device__ __forceinline__ void attn_phase(const Params& P, char* smem_raw) {
;     ...
;   int dco[4][4];
; #pragma unroll
;   for (int reg = 0; reg < 4; ++reg) {
;     const int c = wid * 16 + (lane >> 4) * 4 + reg;
;     const int cs = min(max(c - 8, 0), 48);
; #pragma unroll
;     for (int q4 = 0; q4 < 4; ++q4) {
;       const int kc = q4 * 16 + (lane & 15);
;       dco[reg][q4] = (kc >= cs && kc < cs + 16) ? (kc - c + 15) : 465;
;     }
;   }
;   int t = VBID;
;   __syncthreads();
;   if (t < 8192) {
;     const int h0 = t & 15;
;     for (int idx = tid; idx < 930; idx += VTHR) sm_rpb[idx] = (idx < 465) ? P.rpb[h0 * 465 + idx] * 1.4426950408889634f : -1e30f;
;     ATT_ISSUE(t, 0)
;     ATT_QLOAD(t)
;   }
;   for (; t < 8192; t += VGRID) {
;     const int h = t & 15, r = (t >> 4) & 127, b = t >> 11;
;     const int rs = min(max(r - 4, 0), 120);
;     bf16x8 qf[2];
;     qf[0] = qn[0]; qf[1] = qn[1];
;     f32x4 o[4];
; #pragma unroll
;     for (int td = 0; td < 4; ++td) o[td] = f32x4{0.f, 0.f, 0.f, 0.f};
;     float mrow[4], lrow[4];
; #pragma unroll
;     for (int reg = 0; reg < 4; ++reg) { mrow[reg] = -1e30f; lrow[reg] = 0.f; }
	v_mul_f32_e32 v141, 0x3fb8aa3b, v141
	v_cndmask_b32_e32 v141, v141, v143, vcc
	ds_write_b32 v142, v141
	v_add_u32_e32 v137, 0x100, v112
	v_lshrrev_b32_e32 v138, 5, v137
	v_and_b32_e32 v139, 31, v137
	v_mul_u32_u24_e32 v140, 31, v138
	v_add_u32_e32 v140, v140, v139
	v_min_u32_e32 v140, 0x1d0, v140
	v_lshlrev_b32_e32 v140, 2, v140
	global_load_dword v141, v140, s[12:13]
	v_lshl_add_u32 v142, v137, 2, v117
	v_add_u32_e32 v142, 0x10000, v142
	v_cmp_eq_u32_e32 vcc, 31, v139
	s_waitcnt vmcnt(0)
	v_mul_f32_e32 v141, 0x3fb8aa3b, v141
	v_cndmask_b32_e32 v141, v141, v143, vcc
	ds_write_b32 v142, v141
	s_and_b32 s0, s3, 0xff
	s_lshr_b32 s1, s0, 1
	s_and_b32 s0, s0, 1
	s_lshl_b32 s0, s0, 5
	s_lshr_b32 vcc_lo, s3, 12
	s_add_u32 s0, s0, vcc_lo
	s_lshl_b32 s0, s0, 1
	s_sub_i32 vcc_lo, s0, 4
	s_max_i32 vcc_lo, vcc_lo, 0
	s_min_i32 vcc_lo, vcc_lo, 0x78
	s_lshl_b32 vcc_hi, s1, 13
	s_add_u32 s20, vcc_lo, 8
	s_min_u32 s20, s20, 0x7e
	s_sub_u32 s20, s20, vcc_lo
	s_lshl_b32 s21, s20, 7
	s_mul_i32 s20, s20, 0x60000
	s_lshl_b32 m0, vcc_lo, 6
	s_add_u32 m0, m0, vcc_hi
	s_mul_i32 m0, m0, 0x1800
	s_add_u32 s12, s4, m0
	s_addc_u32 s13, s5, 0
	s_lshl_b32 m0, s1, 24
	s_lshl_b32 s100, vcc_lo, 7
	s_add_u32 m0, m0, s100
	s_add_u32 s14, s6, m0
	s_addc_u32 s15, s7, 0
	s_lshl_b32 m0, s0, 6
	s_add_u32 m0, m0, vcc_hi
	s_mul_i32 m0, m0, 0x1800
	s_add_u32 s100, s4, m0
	s_addc_u32 s101, s5, 0
	global_load_dwordx4 v[64:67], v166, s[100:101]
	global_load_dwordx4 v[68:71], v166, s[100:101] offset:64
	s_add_u32 s100, s100, 0x60000
	s_addc_u32 s101, s101, 0
	global_load_dwordx4 v[230:233], v166, s[100:101]
	global_load_dwordx4 v[234:237], v166, s[100:101] offset:64
	s_and_b32 s0, s3, 0xff
	s_lshr_b32 s1, s0, 1
	s_and_b32 s0, s0, 1
	s_lshl_b32 s0, s0, 5
	s_lshr_b32 vcc_lo, s3, 12
	s_add_u32 s0, s0, vcc_lo
	s_lshl_b32 s0, s0, 1
	s_sub_i32 vcc_lo, s0, 4
	s_max_i32 vcc_lo, vcc_lo, 0
	s_min_i32 vcc_lo, vcc_lo, 0x78
	s_lshl_b32 vcc_hi, s1, 13
	s_sub_i32 vcc_lo, vcc_lo, s0
	s_add_i32 vcc_lo, vcc_lo, 4
	s_lshl_b32 vcc_lo, vcc_lo, 7
	s_bfe_u32 m0, s3, 0x10008
	s_mul_i32 m0, m0, 0x12000
	s_add_i32 vcc_lo, vcc_lo, m0
	s_add_i32 vcc_lo, vcc_lo, 0x10010
	v_add_u32_e32 v184, vcc_lo, v168
	v_add_u32_e32 v185, vcc_lo, v169
	v_add_u32_e32 v186, vcc_lo, v170
	v_add_u32_e32 v187, vcc_lo, v171
	v_add_u32_e32 v188, vcc_lo, v172
	v_add_u32_e32 v189, vcc_lo, v173
	v_add_u32_e32 v190, vcc_lo, v174
	v_add_u32_e32 v191, vcc_lo, v175
	s_add_u32 s100, s12, 0x0
	s_addc_u32 s101, s13, 0
	s_add_u32 s0, s14, 0x0
	s_addc_u32 s1, s15, 0
	global_load_dwordx4 v[80:83], v154, s[100:101] offset:2048
	global_load_dwordx4 v[96:99], v158, s[0:1]
	global_load_dwordx4 v[84:87], v155, s[100:101] offset:2048
	global_load_dwordx4 v[100:103], v159, s[0:1]
	global_load_dwordx4 v[88:91], v156, s[100:101] offset:2048
	global_load_dwordx4 v[104:107], v160, s[0:1]
	global_load_dwordx4 v[92:95], v157, s[100:101] offset:2048
	global_load_dwordx4 v[108:111], v161, s[0:1]
	v_mov_b32_e32 v200, 0xf149f2ca
	v_mov_b32_e32 v201, 0
	v_mov_b32_e32 v32, 0
	v_mov_b32_e32 v33, 0
	v_mov_b32_e32 v34, 0
	v_mov_b32_e32 v35, 0
	v_mov_b32_e32 v36, 0
	v_mov_b32_e32 v37, 0
	v_mov_b32_e32 v38, 0
	v_mov_b32_e32 v39, 0
	v_mov_b32_e32 v40, 0
	v_mov_b32_e32 v41, 0
	v_mov_b32_e32 v42, 0
	v_mov_b32_e32 v43, 0
	v_mov_b32_e32 v44, 0
	v_mov_b32_e32 v45, 0
	v_mov_b32_e32 v46, 0
	v_mov_b32_e32 v47, 0
	v_mov_b32_e32 v246, 0xf149f2ca
	v_mov_b32_e32 v247, 0
	v_mov_b32_e32 v176, 0
	v_mov_b32_e32 v177, 0
	v_mov_b32_e32 v178, 0
	v_mov_b32_e32 v179, 0
	v_mov_b32_e32 v180, 0
	v_mov_b32_e32 v181, 0
	v_mov_b32_e32 v182, 0
	v_mov_b32_e32 v183, 0
	v_mov_b32_e32 v192, 0
	v_mov_b32_e32 v193, 0
	v_mov_b32_e32 v194, 0
	v_mov_b32_e32 v195, 0
	v_mov_b32_e32 v196, 0
	v_mov_b32_e32 v197, 0
	v_mov_b32_e32 v198, 0
	v_mov_b32_e32 v199, 0
	s_waitcnt vmcnt(0)
	ds_write_b128 v150, v[80:83] offset:0
	ds_write_b128 v150, v[84:87] offset:4096
	ds_write_b128 v150, v[88:91] offset:8192
	ds_write_b128 v150, v[92:95] offset:12288
	ds_write_b64 v151, v[96:97] offset:0
	ds_write_b64 v229, v[98:99] offset:0
	ds_write_b64 v151, v[100:101] offset:4096
	ds_write_b64 v229, v[102:103] offset:4096
	ds_write_b64 v151, v[104:105] offset:8192
	ds_write_b64 v229, v[106:107] offset:8192
	ds_write_b64 v151, v[108:109] offset:12288
	ds_write_b64 v229, v[110:111] offset:12288
	s_add_u32 s100, s12, 0xc0000
	s_addc_u32 s101, s13, 0
	s_add_u32 s0, s14, 0x100
	s_addc_u32 s1, s15, 0
	global_load_dwordx4 v[80:83], v154, s[100:101] offset:2048
	global_load_dwordx4 v[96:99], v158, s[0:1]
	global_load_dwordx4 v[84:87], v155, s[100:101] offset:2048
	global_load_dwordx4 v[100:103], v159, s[0:1]
	global_load_dwordx4 v[88:91], v156, s[100:101] offset:2048
	global_load_dwordx4 v[104:107], v160, s[0:1]
	global_load_dwordx4 v[92:95], v157, s[100:101] offset:2048
	global_load_dwordx4 v[108:111], v161, s[0:1]
	s_waitcnt lgkmcnt(0)
	s_barrier
	ds_read_b32 v0, v184 offset:384
	ds_read_b32 v1, v185 offset:384
	ds_read_b32 v2, v186 offset:384
	ds_read_b32 v3, v187 offset:384
	ds_read_b32 v4, v184 offset:512
	ds_read_b32 v5, v185 offset:512
	ds_read_b32 v6, v186 offset:512
	ds_read_b32 v7, v187 offset:512
	ds_read_b32 v8, v188 offset:384
	ds_read_b32 v9, v189 offset:384
	ds_read_b32 v10, v190 offset:384
	ds_read_b32 v11, v191 offset:384
	ds_read_b32 v12, v188 offset:512
	ds_read_b32 v13, v189 offset:512
	ds_read_b32 v14, v190 offset:512
	ds_read_b32 v15, v191 offset:512
	s_waitcnt lgkmcnt(0)
	s_waitcnt vmcnt(0)
; __device__ __forceinline__ void attn_phase(const Params& P, char* smem_raw) {
;     ...
;       __syncthreads();
;       f32x4 sacc[8];
; #pragma unroll
;       for (int t8 = 0; t8 < 8; ++t8) sacc[t8] = f32x4{0.f, 0.f, 0.f, 0.f};
; #pragma unroll
;       for (int s = 0; s < 2; ++s)
; #pragma unroll
;         for (int t8 = 0; t8 < 8; ++t8) {
;           const bf16x8 kf = *reinterpret_cast<const bf16x8*>(&sm_k[(t8 * 16 + (lane_c & 15)) * LDSS + s * 32 + (lane_c >> 4) * 8]);
;           sacc[t8] = __builtin_amdgcn_mfma_f32_16x16x32_bf16(qf[s], kf, sacc[t8], 0, 0, 0);
;         }
;       if (ck < 5) {
;         ATT_ISSUE(t, ck + 1)
;       } else if (t + VGRID < 8192) {
;         ATT_ISSUE(t + VGRID, 0)
;         ATT_QLOAD(t + VGRID)
;       }
;       if (ck < 4) {
;         const float* rb0 = sm_rpb + (rs + ck * 2 - r + 7) * 31;
; #pragma unroll
;         for (int t8 = 0; t8 < 8; ++t8)
; #pragma unroll
;           for (int reg = 0; reg < 4; ++reg)
;             sacc[t8][reg] += rb0[(t8 >> 2) * 31 + dco[reg][t8 & 3]];
;       }
; #pragma unroll
;       for (int reg = 0; reg < 4; ++reg) {
;         float mx = sacc[0][reg];
; #pragma unroll
;         for (int t8 = 1; t8 < 8; ++t8) mx = fmaxf(mx, sacc[t8][reg]);
;         mx = row16_max(mx);
;         const float mnew = fmaxf(mrow[reg], mx);
;         const float alpha = __builtin_amdgcn_exp2f(mrow[reg] - mnew);
;         mrow[reg] = mnew;
;         float rsum = 0.f;
; #pragma unroll
;         for (int t8 = 0; t8 < 8; ++t8) {
;           const float p = __builtin_amdgcn_exp2f(sacc[t8][reg] - mnew);
;           rsum += p;
;           sm_p[(wid * 16 + (lane_c >> 4) * 4 + reg) * 136 + t8 * 16 + (lane_c & 15)] = f2bf(p);
;         }
;         rsum = row16_sum(rsum);
;         lrow[reg] = lrow[reg] * alpha + rsum;
; #pragma unroll
;         for (int td = 0; td < 4; ++td) o[td][reg] *= alpha;
;       }
;       asm volatile("s_waitcnt lgkmcnt(0)" ::: "memory");
; #pragma unroll
;       for (int s4 = 0; s4 < 4; ++s4) {
;         const bf16x8 pf = *reinterpret_cast<const bf16x8*>(&sm_p[(wid * 16 + (lane_c & 15)) * 136 + s4 * 32 + (lane_c >> 4) * 8]);
; #pragma unroll
;         for (int td = 0; td < 4; ++td) {
;           const bf16x8 vf = *reinterpret_cast<const bf16x8*>(&sm_vt[(td * 16 + (lane_c & 15)) * 136 + s4 * 32 + (lane_c >> 4) * 8]);
;           o[td] = __builtin_amdgcn_mfma_f32_16x16x32_bf16(pf, vf, o[td], 0, 0, 0);
.Lmy_att_tile:
	s_barrier
	ds_read_b128 v[112:115], v144 offset:0
	ds_read_b128 v[116:119], v145 offset:0
	ds_read_b128 v[120:123], v144 offset:8192
	ds_read_b128 v[124:127], v145 offset:8192
	ds_read_b128 v[128:131], v144 offset:2048
	ds_read_b128 v[132:135], v145 offset:2048
	ds_read_b128 v[136:139], v144 offset:10240
	ds_read_b128 v[140:143], v145 offset:10240
	s_waitcnt lgkmcnt(7)
	v_mfma_f32_16x16x32_bf16 v[0:3], v[112:115], v[64:67], v[0:3]
	s_waitcnt lgkmcnt(6)
	v_mfma_f32_16x16x32_bf16 v[0:3], v[116:119], v[68:71], v[0:3]
	s_waitcnt lgkmcnt(5)
	v_mfma_f32_16x16x32_bf16 v[4:7], v[120:123], v[64:67], v[4:7]
	s_waitcnt lgkmcnt(4)
	v_mfma_f32_16x16x32_bf16 v[4:7], v[124:127], v[68:71], v[4:7]
	s_waitcnt lgkmcnt(3)
	v_mfma_f32_16x16x32_bf16 v[8:11], v[128:131], v[64:67], v[8:11]
	s_waitcnt lgkmcnt(2)
	v_mfma_f32_16x16x32_bf16 v[8:11], v[132:135], v[68:71], v[8:11]
	s_waitcnt lgkmcnt(1)
	v_mfma_f32_16x16x32_bf16 v[12:15], v[136:139], v[64:67], v[12:15]
	s_waitcnt lgkmcnt(0)
	v_mfma_f32_16x16x32_bf16 v[12:15], v[140:143], v[68:71], v[12:15]
	s_nop 7
	v_max3_f32 v203, v0, v1, v2
	v_max3_f32 v203, v203, v3, v4
	v_max3_f32 v203, v203, v5, v6
	v_max3_f32 v203, v203, v7, v8
	v_max3_f32 v203, v203, v9, v10
	v_max3_f32 v203, v203, v11, v12
	v_max3_f32 v203, v203, v13, v14
	v_max_f32_e32 v203, v203, v15
	v_mov_b32_e32 v205, v203
	s_nop 1
	v_permlane16_swap_b32_e32 v203, v205
	v_max_f32_e32 v203, v203, v205
	v_mov_b32_e32 v205, v203
	s_nop 1
	v_permlane32_swap_b32_e32 v203, v205
	v_max_f32_e32 v203, v203, v205
	v_max_f32_e32 v218, v200, v203
	v_sub_f32_e32 v220, v200, v218
	v_mov_b32_e32 v219, v218
	v_exp_f32_e32 v220, v220
	v_mov_b32_e32 v200, v218
	v_pk_add_f32 v[0:1], v[0:1], v[218:219] neg_lo:[0,1] neg_hi:[0,1]
	v_pk_add_f32 v[2:3], v[2:3], v[218:219] neg_lo:[0,1] neg_hi:[0,1]
	v_pk_add_f32 v[4:5], v[4:5], v[218:219] neg_lo:[0,1] neg_hi:[0,1]
	v_pk_add_f32 v[6:7], v[6:7], v[218:219] neg_lo:[0,1] neg_hi:[0,1]
	v_pk_add_f32 v[8:9], v[8:9], v[218:219] neg_lo:[0,1] neg_hi:[0,1]
	v_pk_add_f32 v[10:11], v[10:11], v[218:219] neg_lo:[0,1] neg_hi:[0,1]
	v_pk_add_f32 v[12:13], v[12:13], v[218:219] neg_lo:[0,1] neg_hi:[0,1]
	v_pk_add_f32 v[14:15], v[14:15], v[218:219] neg_lo:[0,1] neg_hi:[0,1]
	v_exp_f32_e32 v0, v0
	s_waitcnt vmcnt(8)
	v_exp_f32_e32 v1, v1
	ds_write_b128 v150, v[80:83] offset:32768
	v_exp_f32_e32 v2, v2
	ds_write_b128 v150, v[84:87] offset:36864
	v_exp_f32_e32 v3, v3
	ds_write_b128 v150, v[88:91] offset:40960
	v_exp_f32_e32 v4, v4
	ds_write_b128 v150, v[92:95] offset:45056
	v_exp_f32_e32 v5, v5
	ds_write_b64 v151, v[96:97] offset:32768
	v_exp_f32_e32 v6, v6
	ds_write_b64 v229, v[98:99] offset:32768
	v_exp_f32_e32 v7, v7
	ds_write_b64 v151, v[100:101] offset:36864
	v_exp_f32_e32 v8, v8
	ds_write_b64 v229, v[102:103] offset:36864
	v_exp_f32_e32 v9, v9
	ds_write_b64 v151, v[104:105] offset:40960
	v_exp_f32_e32 v10, v10
	ds_write_b64 v229, v[106:107] offset:40960
	v_exp_f32_e32 v11, v11
	ds_write_b64 v151, v[108:109] offset:45056
	v_exp_f32_e32 v12, v12
	ds_write_b64 v229, v[110:111] offset:45056
	v_exp_f32_e32 v13, v13
	s_add_u32 s100, s12, 0x180000
	v_exp_f32_e32 v14, v14
	s_addc_u32 s101, s13, 0
	v_exp_f32_e32 v15, v15
	s_add_u32 s0, s14, 0x200
	s_addc_u32 s1, s15, 0
	global_load_dwordx4 v[80:83], v154, s[100:101] offset:2048
	global_load_dwordx4 v[96:99], v158, s[0:1]
	global_load_dwordx4 v[84:87], v155, s[100:101] offset:2048
	global_load_dwordx4 v[100:103], v159, s[0:1]
	global_load_dwordx4 v[88:91], v156, s[100:101] offset:2048
	global_load_dwordx4 v[104:107], v160, s[0:1]
	global_load_dwordx4 v[92:95], v157, s[100:101] offset:2048
	global_load_dwordx4 v[108:111], v161, s[0:1]
	s_and_b32 s0, s3, 0xff
	s_lshr_b32 s1, s0, 1
	s_and_b32 s0, s0, 1
	s_lshl_b32 s0, s0, 5
	s_lshr_b32 vcc_lo, s3, 12
	s_add_u32 s0, s0, vcc_lo
	s_lshl_b32 s0, s0, 1
	s_sub_i32 vcc_lo, s0, 4
	s_max_i32 vcc_lo, vcc_lo, 0
	s_min_i32 vcc_lo, vcc_lo, 0x78
	s_lshl_b32 vcc_hi, s1, 13
	s_sub_i32 s19, s0, 3
	s_max_i32 s19, s19, 0
	s_min_i32 s19, s19, 0x78
	s_sub_i32 s19, vcc_lo, s19
	s_lshl_b32 m0, s1, 8
	s_add_u32 m0, m0, 0x8000
	s_mul_i32 m0, m0, 0x1800
	s_add_u32 s16, s4, m0
	s_addc_u32 s17, s5, 0
	s_lshl_b32 m0, s1, 19
	s_add_u32 s36, s8, m0
	s_addc_u32 s37, s9, 0
	s_lshl_b32 m0, s0, 6
	s_add_u32 m0, m0, vcc_hi
	s_lshl_b32 m0, m0, 11
	s_add_u32 s98, s10, m0
	s_addc_u32 s99, s11, 0
	ds_read_b128 v[112:115], v146 offset:0
	ds_read_b128 v[116:119], v146 offset:4096
	ds_read_b128 v[120:123], v146 offset:8192
	ds_read_b128 v[124:127], v146 offset:12288
	ds_read_b128 v[128:131], v147 offset:0
	ds_read_b128 v[132:135], v147 offset:4096
	ds_read_b128 v[136:139], v147 offset:8192
	ds_read_b128 v[140:143], v147 offset:12288
	v_mov_b32_e32 v221, v220
	v_pk_add_f32 v[222:223], v[0:1], v[2:3]
	v_pk_add_f32 v[222:223], v[222:223], v[4:5]
	v_pk_add_f32 v[222:223], v[222:223], v[6:7]
	v_pk_add_f32 v[222:223], v[222:223], v[8:9]
	v_pk_add_f32 v[222:223], v[222:223], v[10:11]
	v_pk_add_f32 v[222:223], v[222:223], v[12:13]
	v_pk_add_f32 v[222:223], v[222:223], v[14:15]
	v_pk_mul_f32 v[32:33], v[32:33], v[220:221]
	v_pk_mul_f32 v[34:35], v[34:35], v[220:221]
	v_pk_mul_f32 v[36:37], v[36:37], v[220:221]
	v_pk_mul_f32 v[38:39], v[38:39], v[220:221]
	v_pk_mul_f32 v[40:41], v[40:41], v[220:221]
	v_pk_mul_f32 v[42:43], v[42:43], v[220:221]
	v_pk_mul_f32 v[44:45], v[44:45], v[220:221]
	v_pk_mul_f32 v[46:47], v[46:47], v[220:221]
	v_add_f32_e32 v203, v222, v223
	v_fma_f32 v201, v201, v220, v203
	v_cvt_pk_bf16_f32 v48, v0, v1
	v_cvt_pk_bf16_f32 v49, v2, v3
	v_cvt_pk_bf16_f32 v50, v4, v5
	v_cvt_pk_bf16_f32 v51, v6, v7
	v_cvt_pk_bf16_f32 v52, v8, v9
	v_cvt_pk_bf16_f32 v53, v10, v11
	v_cvt_pk_bf16_f32 v54, v12, v13
	v_cvt_pk_bf16_f32 v55, v14, v15
	s_waitcnt lgkmcnt(7)
	v_mfma_f32_16x16x32_bf16 v[32:35], v[112:115], v[48:51], v[32:35]
	s_waitcnt lgkmcnt(6)
	v_mfma_f32_16x16x32_bf16 v[36:39], v[116:119], v[48:51], v[36:39]
	s_waitcnt lgkmcnt(5)
	v_mfma_f32_16x16x32_bf16 v[40:43], v[120:123], v[48:51], v[40:43]
	s_waitcnt lgkmcnt(4)
	v_mfma_f32_16x16x32_bf16 v[44:47], v[124:127], v[48:51], v[44:47]
	s_waitcnt lgkmcnt(3)
	v_mfma_f32_16x16x32_bf16 v[32:35], v[128:131], v[52:55], v[32:35]
	s_waitcnt lgkmcnt(2)
	v_mfma_f32_16x16x32_bf16 v[36:39], v[132:135], v[52:55], v[36:39]
	s_waitcnt lgkmcnt(1)
	v_mfma_f32_16x16x32_bf16 v[40:43], v[136:139], v[52:55], v[40:43]
	s_waitcnt lgkmcnt(0)
	v_mfma_f32_16x16x32_bf16 v[44:47], v[140:143], v[52:55], v[44:47]
	s_cmp_eq_u32 s19, 0
	s_cbranch_scc1 .Lmy_att_b0_0
	v_mov_b32_e32 v0, 0xf149f2ca
	v_mov_b32_e32 v1, 0xf149f2ca
	v_mov_b32_e32 v2, 0xf149f2ca
	v_mov_b32_e32 v3, 0xf149f2ca
	v_mov_b32_e32 v8, 0xf149f2ca
	v_mov_b32_e32 v9, 0xf149f2ca
	v_mov_b32_e32 v10, 0xf149f2ca
	v_mov_b32_e32 v11, 0xf149f2ca
	s_branch .Lmy_att_b1_0
; __device__ __forceinline__ void attn_phase(const Params& P, char* smem_raw) {
;     ...
;       f32x4 sacc[8];
; #pragma unroll
;       for (int t8 = 0; t8 < 8; ++t8) sacc[t8] = f32x4{0.f, 0.f, 0.f, 0.f};
; #pragma unroll
;       for (int s = 0; s < 2; ++s)
; #pragma unroll
;         for (int t8 = 0; t8 < 8; ++t8) {
;           const bf16x8 kf = *reinterpret_cast<const bf16x8*>(&sm_k[(t8 * 16 + (lane_c & 15)) * LDSS + s * 32 + (lane_c >> 4) * 8]);
;           sacc[t8] = __builtin_amdgcn_mfma_f32_16x16x32_bf16(qf[s], kf, sacc[t8], 0, 0, 0);
;         }
;       if (ck < 5) {
;         ATT_ISSUE(t, ck + 1)
;       } else if (t + VGRID < 8192) {
;         ATT_ISSUE(t + VGRID, 0)
;         ATT_QLOAD(t + VGRID)
;       }
;       if (ck < 4) {
;         const float* rb0 = sm_rpb + (rs + ck * 2 - r + 7) * 31;
; #pragma unroll
;         for (int t8 = 0; t8 < 8; ++t8)
; #pragma unroll
;           for (int reg = 0; reg < 4; ++reg)
;             sacc[t8][reg] += rb0[(t8 >> 2) * 31 + dco[reg][t8 & 3]];
;       }
; #pragma unroll
;       for (int reg = 0; reg < 4; ++reg) {
;         float mx = sacc[0][reg];
; #pragma unroll
;         for (int t8 = 1; t8 < 8; ++t8) mx = fmaxf(mx, sacc[t8][reg]);
;         mx = row16_max(mx);
;         const float mnew = fmaxf(mrow[reg], mx);
;         const float alpha = __builtin_amdgcn_exp2f(mrow[reg] - mnew);
;         mrow[reg] = mnew;
;         float rsum = 0.f;
; #pragma unroll
;         for (int t8 = 0; t8 < 8; ++t8) {
;           const float p = __builtin_amdgcn_exp2f(sacc[t8][reg] - mnew);
;           rsum += p;
;           sm_p[(wid * 16 + (lane_c >> 4) * 4 + reg) * 136 + t8 * 16 + (lane_c & 15)] = f2bf(p);
;         }
;         rsum = row16_sum(rsum);
;         lrow[reg] = lrow[reg] * alpha + rsum;
; #pragma unroll
;         for (int td = 0; td < 4; ++td) o[td][reg] *= alpha;
;       }
;       asm volatile("s_waitcnt lgkmcnt(0)" ::: "memory");
; #pragma unroll
;       for (int s4 = 0; s4 < 4; ++s4) {
;         const bf16x8 pf = *reinterpret_cast<const bf16x8*>(&sm_p[(wid * 16 + (lane_c & 15)) * 136 + s4 * 32 + (lane_c >> 4) * 8]);
; #pragma unroll
;         for (int td = 0; td < 4; ++td) {
;           const bf16x8 vf = *reinterpret_cast<const bf16x8*>(&sm_vt[(td * 16 + (lane_c & 15)) * 136 + s4 * 32 + (lane_c >> 4) * 8]);
;           o[td] = __builtin_amdgcn_mfma_f32_16x16x32_bf16(pf, vf, o[td], 0, 0, 0);
;         }
;       }
.Lmy_att_b0_0:
	ds_read_b32 v0, v184 offset:256
	ds_read_b32 v1, v185 offset:256
	ds_read_b32 v2, v186 offset:256
	ds_read_b32 v3, v187 offset:256
	ds_read_b32 v8, v188 offset:256
	ds_read_b32 v9, v189 offset:256
	ds_read_b32 v10, v190 offset:256
	ds_read_b32 v11, v191 offset:256
.Lmy_att_b1_0:
	ds_read_b32 v4, v184 offset:384
	ds_read_b32 v5, v185 offset:384
	ds_read_b32 v6, v186 offset:384
	ds_read_b32 v7, v187 offset:384
	ds_read_b32 v12, v188 offset:384
	ds_read_b32 v13, v189 offset:384
	ds_read_b32 v14, v190 offset:384
	ds_read_b32 v15, v191 offset:384
	ds_read_b128 v[112:115], v144 offset:0
	ds_read_b128 v[116:119], v145 offset:0
	ds_read_b128 v[120:123], v144 offset:8192
	ds_read_b128 v[124:127], v145 offset:8192
	ds_read_b128 v[128:131], v144 offset:2048
	ds_read_b128 v[132:135], v145 offset:2048
	ds_read_b128 v[136:139], v144 offset:10240
	ds_read_b128 v[140:143], v145 offset:10240
	s_waitcnt lgkmcnt(7)
	v_mfma_f32_16x16x32_bf16 v[0:3], v[112:115], v[230:233], v[0:3]
	s_waitcnt lgkmcnt(6)
	v_mfma_f32_16x16x32_bf16 v[0:3], v[116:119], v[234:237], v[0:3]
	s_waitcnt lgkmcnt(5)
	v_mfma_f32_16x16x32_bf16 v[4:7], v[120:123], v[230:233], v[4:7]
	s_waitcnt lgkmcnt(4)
	v_mfma_f32_16x16x32_bf16 v[4:7], v[124:127], v[234:237], v[4:7]
	s_waitcnt lgkmcnt(3)
	v_mfma_f32_16x16x32_bf16 v[8:11], v[128:131], v[230:233], v[8:11]
	s_waitcnt lgkmcnt(2)
	v_mfma_f32_16x16x32_bf16 v[8:11], v[132:135], v[234:237], v[8:11]
	s_waitcnt lgkmcnt(1)
	v_mfma_f32_16x16x32_bf16 v[12:15], v[136:139], v[230:233], v[12:15]
	s_waitcnt lgkmcnt(0)
	v_mfma_f32_16x16x32_bf16 v[12:15], v[140:143], v[234:237], v[12:15]
	s_nop 7
	v_max3_f32 v203, v0, v1, v2
	v_max3_f32 v203, v203, v3, v4
	v_max3_f32 v203, v203, v5, v6
	v_max3_f32 v203, v203, v7, v8
	v_max3_f32 v203, v203, v9, v10
	v_max3_f32 v203, v203, v11, v12
	v_max3_f32 v203, v203, v13, v14
	v_max_f32_e32 v203, v203, v15
	v_mov_b32_e32 v205, v203
	s_nop 1
	v_permlane16_swap_b32_e32 v203, v205
	v_max_f32_e32 v203, v203, v205
	v_mov_b32_e32 v205, v203
	s_nop 1
	v_permlane32_swap_b32_e32 v203, v205
	v_max_f32_e32 v203, v203, v205
	v_max_f32_e32 v218, v246, v203
	v_sub_f32_e32 v220, v246, v218
	v_mov_b32_e32 v219, v218
	v_exp_f32_e32 v220, v220
	v_mov_b32_e32 v246, v218
	v_pk_add_f32 v[0:1], v[0:1], v[218:219] neg_lo:[0,1] neg_hi:[0,1]
	v_pk_add_f32 v[2:3], v[2:3], v[218:219] neg_lo:[0,1] neg_hi:[0,1]
	v_pk_add_f32 v[4:5], v[4:5], v[218:219] neg_lo:[0,1] neg_hi:[0,1]
	v_pk_add_f32 v[6:7], v[6:7], v[218:219] neg_lo:[0,1] neg_hi:[0,1]
	v_pk_add_f32 v[8:9], v[8:9], v[218:219] neg_lo:[0,1] neg_hi:[0,1]
	v_pk_add_f32 v[10:11], v[10:11], v[218:219] neg_lo:[0,1] neg_hi:[0,1]
	v_pk_add_f32 v[12:13], v[12:13], v[218:219] neg_lo:[0,1] neg_hi:[0,1]
	v_pk_add_f32 v[14:15], v[14:15], v[218:219] neg_lo:[0,1] neg_hi:[0,1]
	v_exp_f32_e32 v0, v0
	v_exp_f32_e32 v1, v1
	v_exp_f32_e32 v2, v2
	v_exp_f32_e32 v3, v3
	v_exp_f32_e32 v4, v4
	v_exp_f32_e32 v5, v5
	v_exp_f32_e32 v6, v6
	v_exp_f32_e32 v7, v7
	v_exp_f32_e32 v8, v8
	v_exp_f32_e32 v9, v9
	v_exp_f32_e32 v10, v10
	v_exp_f32_e32 v11, v11
	v_exp_f32_e32 v12, v12
	v_exp_f32_e32 v13, v13
	v_exp_f32_e32 v14, v14
	v_exp_f32_e32 v15, v15
	ds_read_b128 v[112:115], v146 offset:0
	ds_read_b128 v[116:119], v146 offset:4096
	ds_read_b128 v[120:123], v146 offset:8192
	ds_read_b128 v[124:127], v146 offset:12288
	ds_read_b128 v[128:131], v147 offset:0
	ds_read_b128 v[132:135], v147 offset:4096
	ds_read_b128 v[136:139], v147 offset:8192
	ds_read_b128 v[140:143], v147 offset:12288
	v_mov_b32_e32 v221, v220
	v_pk_add_f32 v[222:223], v[0:1], v[2:3]
	v_pk_add_f32 v[222:223], v[222:223], v[4:5]
	v_pk_add_f32 v[222:223], v[222:223], v[6:7]
	v_pk_add_f32 v[222:223], v[222:223], v[8:9]
	v_pk_add_f32 v[222:223], v[222:223], v[10:11]
	v_pk_add_f32 v[222:223], v[222:223], v[12:13]
	v_pk_add_f32 v[222:223], v[222:223], v[14:15]
	v_pk_mul_f32 v[176:177], v[176:177], v[220:221]
	v_pk_mul_f32 v[178:179], v[178:179], v[220:221]
	v_pk_mul_f32 v[180:181], v[180:181], v[220:221]
	v_pk_mul_f32 v[182:183], v[182:183], v[220:221]
	v_pk_mul_f32 v[192:193], v[192:193], v[220:221]
	v_pk_mul_f32 v[194:195], v[194:195], v[220:221]
	v_pk_mul_f32 v[196:197], v[196:197], v[220:221]
	v_pk_mul_f32 v[198:199], v[198:199], v[220:221]
	v_add_f32_e32 v203, v222, v223
	v_fma_f32 v247, v247, v220, v203
	v_cvt_pk_bf16_f32 v48, v0, v1
	v_cvt_pk_bf16_f32 v49, v2, v3
	v_cvt_pk_bf16_f32 v50, v4, v5
	v_cvt_pk_bf16_f32 v51, v6, v7
	v_cvt_pk_bf16_f32 v52, v8, v9
	v_cvt_pk_bf16_f32 v53, v10, v11
	v_cvt_pk_bf16_f32 v54, v12, v13
	v_cvt_pk_bf16_f32 v55, v14, v15
	s_waitcnt lgkmcnt(7)
	v_mfma_f32_16x16x32_bf16 v[176:179], v[112:115], v[48:51], v[176:179]
	s_waitcnt lgkmcnt(6)
	v_mfma_f32_16x16x32_bf16 v[180:183], v[116:119], v[48:51], v[180:183]
	s_waitcnt lgkmcnt(5)
	v_mfma_f32_16x16x32_bf16 v[192:195], v[120:123], v[48:51], v[192:195]
	s_waitcnt lgkmcnt(4)
	v_mfma_f32_16x16x32_bf16 v[196:199], v[124:127], v[48:51], v[196:199]
	s_waitcnt lgkmcnt(3)
	v_mfma_f32_16x16x32_bf16 v[176:179], v[128:131], v[52:55], v[176:179]
	s_waitcnt lgkmcnt(2)
	v_mfma_f32_16x16x32_bf16 v[180:183], v[132:135], v[52:55], v[180:183]
	s_waitcnt lgkmcnt(1)
	v_mfma_f32_16x16x32_bf16 v[192:195], v[136:139], v[52:55], v[192:195]
	s_waitcnt lgkmcnt(0)
	v_mfma_f32_16x16x32_bf16 v[196:199], v[140:143], v[52:55], v[196:199]
	ds_read_b32 v0, v184 offset:640
	ds_read_b32 v1, v185 offset:640
	ds_read_b32 v2, v186 offset:640
	ds_read_b32 v3, v187 offset:640
	ds_read_b32 v4, v184 offset:768
	ds_read_b32 v5, v185 offset:768
	ds_read_b32 v6, v186 offset:768
	ds_read_b32 v7, v187 offset:768
	ds_read_b32 v8, v188 offset:640
	ds_read_b32 v9, v189 offset:640
	ds_read_b32 v10, v190 offset:640
	ds_read_b32 v11, v191 offset:640
	ds_read_b32 v12, v188 offset:768
	ds_read_b32 v13, v189 offset:768
	ds_read_b32 v14, v190 offset:768
	ds_read_b32 v15, v191 offset:768
	s_waitcnt lgkmcnt(0)
	s_barrier
; __device__ __forceinline__ void attn_phase(const Params& P, char* smem_raw) {
;     ...
;       __syncthreads();
;       f32x4 sacc[8];
; #pragma unroll
;       for (int t8 = 0; t8 < 8; ++t8) sacc[t8] = f32x4{0.f, 0.f, 0.f, 0.f};
; #pragma unroll
;       for (int s = 0; s < 2; ++s)
; #pragma unroll
;         for (int t8 = 0; t8 < 8; ++t8) {
;           const bf16x8 kf = *reinterpret_cast<const bf16x8*>(&sm_k[(t8 * 16 + (lane_c & 15)) * LDSS + s * 32 + (lane_c >> 4) * 8]);
;           sacc[t8] = __builtin_amdgcn_mfma_f32_16x16x32_bf16(qf[s], kf, sacc[t8], 0, 0, 0);
;         }
;       if (ck < 5) {
;         ATT_ISSUE(t, ck + 1)
;       } else if (t + VGRID < 8192) {
;         ATT_ISSUE(t + VGRID, 0)
;         ATT_QLOAD(t + VGRID)
;       }
;       if (ck < 4) {
;         const float* rb0 = sm_rpb + (rs + ck * 2 - r + 7) * 31;
; #pragma unroll
;         for (int t8 = 0; t8 < 8; ++t8)
; #pragma unroll
;           for (int reg = 0; reg < 4; ++reg)
;             sacc[t8][reg] += rb0[(t8 >> 2) * 31 + dco[reg][t8 & 3]];
;       }
; #pragma unroll
;       for (int reg = 0; reg < 4; ++reg) {
;         float mx = sacc[0][reg];
; #pragma unroll
;         for (int t8 = 1; t8 < 8; ++t8) mx = fmaxf(mx, sacc[t8][reg]);
;         mx = row16_max(mx);
;         const float mnew = fmaxf(mrow[reg], mx);
;         const float alpha = __builtin_amdgcn_exp2f(mrow[reg] - mnew);
;         mrow[reg] = mnew;
;         float rsum = 0.f;
; #pragma unroll
;         for (int t8 = 0; t8 < 8; ++t8) {
;           const float p = __builtin_amdgcn_exp2f(sacc[t8][reg] - mnew);
;           rsum += p;
;           sm_p[(wid * 16 + (lane_c >> 4) * 4 + reg) * 136 + t8 * 16 + (lane_c & 15)] = f2bf(p);
;         }
;         rsum = row16_sum(rsum);
;         lrow[reg] = lrow[reg] * alpha + rsum;
; #pragma unroll
;         for (int td = 0; td < 4; ++td) o[td][reg] *= alpha;
;       }
;       asm volatile("s_waitcnt lgkmcnt(0)" ::: "memory");
; #pragma unroll
;       for (int s4 = 0; s4 < 4; ++s4) {
;         const bf16x8 pf = *reinterpret_cast<const bf16x8*>(&sm_p[(wid * 16 + (lane_c & 15)) * 136 + s4 * 32 + (lane_c >> 4) * 8]);
; #pragma unroll
;         for (int td = 0; td < 4; ++td) {
;           const bf16x8 vf = *reinterpret_cast<const bf16x8*>(&sm_vt[(td * 16 + (lane_c & 15)) * 136 + s4 * 32 + (lane_c >> 4) * 8]);
;           o[td] = __builtin_amdgcn_mfma_f32_16x16x32_bf16(pf, vf, o[td], 0, 0, 0);
	ds_read_b128 v[112:115], v144 offset:32768
	ds_read_b128 v[116:119], v145 offset:32768
	ds_read_b128 v[120:123], v144 offset:40960
	ds_read_b128 v[124:127], v145 offset:40960
	ds_read_b128 v[128:131], v144 offset:34816
	ds_read_b128 v[132:135], v145 offset:34816
	ds_read_b128 v[136:139], v144 offset:43008
	ds_read_b128 v[140:143], v145 offset:43008
	s_waitcnt lgkmcnt(7)
	v_mfma_f32_16x16x32_bf16 v[0:3], v[112:115], v[64:67], v[0:3]
	s_waitcnt lgkmcnt(6)
	v_mfma_f32_16x16x32_bf16 v[0:3], v[116:119], v[68:71], v[0:3]
	s_waitcnt lgkmcnt(5)
	v_mfma_f32_16x16x32_bf16 v[4:7], v[120:123], v[64:67], v[4:7]
	s_waitcnt lgkmcnt(4)
	v_mfma_f32_16x16x32_bf16 v[4:7], v[124:127], v[68:71], v[4:7]
	s_waitcnt lgkmcnt(3)
	v_mfma_f32_16x16x32_bf16 v[8:11], v[128:131], v[64:67], v[8:11]
	s_waitcnt lgkmcnt(2)
	v_mfma_f32_16x16x32_bf16 v[8:11], v[132:135], v[68:71], v[8:11]
	s_waitcnt lgkmcnt(1)
	v_mfma_f32_16x16x32_bf16 v[12:15], v[136:139], v[64:67], v[12:15]
	s_waitcnt lgkmcnt(0)
	v_mfma_f32_16x16x32_bf16 v[12:15], v[140:143], v[68:71], v[12:15]
	s_nop 7
	v_max3_f32 v203, v0, v1, v2
	v_max3_f32 v203, v203, v3, v4
	v_max3_f32 v203, v203, v5, v6
	v_max3_f32 v203, v203, v7, v8
	v_max3_f32 v203, v203, v9, v10
	v_max3_f32 v203, v203, v11, v12
	v_max3_f32 v203, v203, v13, v14
	v_max_f32_e32 v203, v203, v15
	v_mov_b32_e32 v205, v203
	s_nop 1
	v_permlane16_swap_b32_e32 v203, v205
	v_max_f32_e32 v203, v203, v205
	v_mov_b32_e32 v205, v203
	s_nop 1
	v_permlane32_swap_b32_e32 v203, v205
	v_max_f32_e32 v203, v203, v205
	v_max_f32_e32 v218, v200, v203
	v_sub_f32_e32 v220, v200, v218
	v_mov_b32_e32 v219, v218
	v_exp_f32_e32 v220, v220
	v_mov_b32_e32 v200, v218
	v_pk_add_f32 v[0:1], v[0:1], v[218:219] neg_lo:[0,1] neg_hi:[0,1]
	v_pk_add_f32 v[2:3], v[2:3], v[218:219] neg_lo:[0,1] neg_hi:[0,1]
	v_pk_add_f32 v[4:5], v[4:5], v[218:219] neg_lo:[0,1] neg_hi:[0,1]
	v_pk_add_f32 v[6:7], v[6:7], v[218:219] neg_lo:[0,1] neg_hi:[0,1]
	v_pk_add_f32 v[8:9], v[8:9], v[218:219] neg_lo:[0,1] neg_hi:[0,1]
	v_pk_add_f32 v[10:11], v[10:11], v[218:219] neg_lo:[0,1] neg_hi:[0,1]
	v_pk_add_f32 v[12:13], v[12:13], v[218:219] neg_lo:[0,1] neg_hi:[0,1]
	v_pk_add_f32 v[14:15], v[14:15], v[218:219] neg_lo:[0,1] neg_hi:[0,1]
	v_exp_f32_e32 v0, v0
	s_waitcnt vmcnt(0)
	v_exp_f32_e32 v1, v1
	ds_write_b128 v150, v[80:83] offset:0
	v_exp_f32_e32 v2, v2
	ds_write_b128 v150, v[84:87] offset:4096
	v_exp_f32_e32 v3, v3
	ds_write_b128 v150, v[88:91] offset:8192
	v_exp_f32_e32 v4, v4
	ds_write_b128 v150, v[92:95] offset:12288
	v_exp_f32_e32 v5, v5
	ds_write_b64 v151, v[96:97] offset:0
	v_exp_f32_e32 v6, v6
	ds_write_b64 v229, v[98:99] offset:0
	v_exp_f32_e32 v7, v7
	ds_write_b64 v151, v[100:101] offset:4096
	v_exp_f32_e32 v8, v8
	ds_write_b64 v229, v[102:103] offset:4096
	v_exp_f32_e32 v9, v9
	ds_write_b64 v151, v[104:105] offset:8192
	v_exp_f32_e32 v10, v10
	ds_write_b64 v229, v[106:107] offset:8192
	v_exp_f32_e32 v11, v11
	ds_write_b64 v151, v[108:109] offset:12288
	v_exp_f32_e32 v12, v12
	ds_write_b64 v229, v[110:111] offset:12288
	v_exp_f32_e32 v13, v13
	s_add_u32 s100, s12, 0x240000
	v_exp_f32_e32 v14, v14
	s_addc_u32 s101, s13, 0
	v_exp_f32_e32 v15, v15
	s_add_u32 s0, s14, 0x300
	s_addc_u32 s1, s15, 0
	global_load_dwordx4 v[80:83], v154, s[100:101] offset:2048
	global_load_dwordx4 v[96:99], v158, s[0:1]
	global_load_dwordx4 v[84:87], v155, s[100:101] offset:2048
	global_load_dwordx4 v[100:103], v159, s[0:1]
	global_load_dwordx4 v[88:91], v156, s[100:101] offset:2048
	global_load_dwordx4 v[104:107], v160, s[0:1]
	global_load_dwordx4 v[92:95], v157, s[100:101] offset:2048
	global_load_dwordx4 v[108:111], v161, s[0:1]
	ds_read_b128 v[112:115], v146 offset:32768
	ds_read_b128 v[116:119], v146 offset:36864
	ds_read_b128 v[120:123], v146 offset:40960
	ds_read_b128 v[124:127], v146 offset:45056
	ds_read_b128 v[128:131], v147 offset:32768
	ds_read_b128 v[132:135], v147 offset:36864
	ds_read_b128 v[136:139], v147 offset:40960
	ds_read_b128 v[140:143], v147 offset:45056
	v_mov_b32_e32 v221, v220
	v_pk_add_f32 v[222:223], v[0:1], v[2:3]
	v_pk_add_f32 v[222:223], v[222:223], v[4:5]
	v_pk_add_f32 v[222:223], v[222:223], v[6:7]
	v_pk_add_f32 v[222:223], v[222:223], v[8:9]
	v_pk_add_f32 v[222:223], v[222:223], v[10:11]
	v_pk_add_f32 v[222:223], v[222:223], v[12:13]
	v_pk_add_f32 v[222:223], v[222:223], v[14:15]
	v_pk_mul_f32 v[32:33], v[32:33], v[220:221]
	v_pk_mul_f32 v[34:35], v[34:35], v[220:221]
	v_pk_mul_f32 v[36:37], v[36:37], v[220:221]
	v_pk_mul_f32 v[38:39], v[38:39], v[220:221]
	v_pk_mul_f32 v[40:41], v[40:41], v[220:221]
	v_pk_mul_f32 v[42:43], v[42:43], v[220:221]
	v_pk_mul_f32 v[44:45], v[44:45], v[220:221]
	v_pk_mul_f32 v[46:47], v[46:47], v[220:221]
	v_add_f32_e32 v203, v222, v223
	v_fma_f32 v201, v201, v220, v203
	v_cvt_pk_bf16_f32 v48, v0, v1
	v_cvt_pk_bf16_f32 v49, v2, v3
	v_cvt_pk_bf16_f32 v50, v4, v5
	v_cvt_pk_bf16_f32 v51, v6, v7
	v_cvt_pk_bf16_f32 v52, v8, v9
	v_cvt_pk_bf16_f32 v53, v10, v11
	v_cvt_pk_bf16_f32 v54, v12, v13
	v_cvt_pk_bf16_f32 v55, v14, v15
	s_waitcnt lgkmcnt(7)
	v_mfma_f32_16x16x32_bf16 v[32:35], v[112:115], v[48:51], v[32:35]
	s_waitcnt lgkmcnt(6)
	v_mfma_f32_16x16x32_bf16 v[36:39], v[116:119], v[48:51], v[36:39]
	s_waitcnt lgkmcnt(5)
	v_mfma_f32_16x16x32_bf16 v[40:43], v[120:123], v[48:51], v[40:43]
	s_waitcnt lgkmcnt(4)
	v_mfma_f32_16x16x32_bf16 v[44:47], v[124:127], v[48:51], v[44:47]
	s_waitcnt lgkmcnt(3)
	v_mfma_f32_16x16x32_bf16 v[32:35], v[128:131], v[52:55], v[32:35]
	s_waitcnt lgkmcnt(2)
	v_mfma_f32_16x16x32_bf16 v[36:39], v[132:135], v[52:55], v[36:39]
	s_waitcnt lgkmcnt(1)
	v_mfma_f32_16x16x32_bf16 v[40:43], v[136:139], v[52:55], v[40:43]
	s_waitcnt lgkmcnt(0)
; __device__ __forceinline__ void attn_phase(const Params& P, char* smem_raw) {
;     ...
;       f32x4 sacc[8];
; #pragma unroll
;       for (int t8 = 0; t8 < 8; ++t8) sacc[t8] = f32x4{0.f, 0.f, 0.f, 0.f};
; #pragma unroll
;       for (int s = 0; s < 2; ++s)
; #pragma unroll
;         for (int t8 = 0; t8 < 8; ++t8) {
;           const bf16x8 kf = *reinterpret_cast<const bf16x8*>(&sm_k[(t8 * 16 + (lane_c & 15)) * LDSS + s * 32 + (lane_c >> 4) * 8]);
;           sacc[t8] = __builtin_amdgcn_mfma_f32_16x16x32_bf16(qf[s], kf, sacc[t8], 0, 0, 0);
;         }
;       if (ck < 5) {
;         ATT_ISSUE(t, ck + 1)
;       } else if (t + VGRID < 8192) {
;         ATT_ISSUE(t + VGRID, 0)
;         ATT_QLOAD(t + VGRID)
;       }
;       if (ck < 4) {
;         const float* rb0 = sm_rpb + (rs + ck * 2 - r + 7) * 31;
; #pragma unroll
;         for (int t8 = 0; t8 < 8; ++t8)
; #pragma unroll
;           for (int reg = 0; reg < 4; ++reg)
;             sacc[t8][reg] += rb0[(t8 >> 2) * 31 + dco[reg][t8 & 3]];
;       }
; #pragma unroll
;       for (int reg = 0; reg < 4; ++reg) {
;         float mx = sacc[0][reg];
; #pragma unroll
;         for (int t8 = 1; t8 < 8; ++t8) mx = fmaxf(mx, sacc[t8][reg]);
;         mx = row16_max(mx);
;         const float mnew = fmaxf(mrow[reg], mx);
;         const float alpha = __builtin_amdgcn_exp2f(mrow[reg] - mnew);
;         mrow[reg] = mnew;
;         float rsum = 0.f;
; #pragma unroll
;         for (int t8 = 0; t8 < 8; ++t8) {
;           const float p = __builtin_amdgcn_exp2f(sacc[t8][reg] - mnew);
;           rsum += p;
;           sm_p[(wid * 16 + (lane_c >> 4) * 4 + reg) * 136 + t8 * 16 + (lane_c & 15)] = f2bf(p);
;         }
;         rsum = row16_sum(rsum);
;         lrow[reg] = lrow[reg] * alpha + rsum;
; #pragma unroll
;         for (int td = 0; td < 4; ++td) o[td][reg] *= alpha;
;       }
;       asm volatile("s_waitcnt lgkmcnt(0)" ::: "memory");
; #pragma unroll
;       for (int s4 = 0; s4 < 4; ++s4) {
;         const bf16x8 pf = *reinterpret_cast<const bf16x8*>(&sm_p[(wid * 16 + (lane_c & 15)) * 136 + s4 * 32 + (lane_c >> 4) * 8]);
; #pragma unroll
;         for (int td = 0; td < 4; ++td) {
;           const bf16x8 vf = *reinterpret_cast<const bf16x8*>(&sm_vt[(td * 16 + (lane_c & 15)) * 136 + s4 * 32 + (lane_c >> 4) * 8]);
;           o[td] = __builtin_amdgcn_mfma_f32_16x16x32_bf16(pf, vf, o[td], 0, 0, 0);
;         }
;       }
	v_mfma_f32_16x16x32_bf16 v[44:47], v[140:143], v[52:55], v[44:47]
	ds_read_b32 v0, v184 offset:512
	ds_read_b32 v1, v185 offset:512
	ds_read_b32 v2, v186 offset:512
	ds_read_b32 v3, v187 offset:512
	ds_read_b32 v4, v184 offset:640
	ds_read_b32 v5, v185 offset:640
	ds_read_b32 v6, v186 offset:640
	ds_read_b32 v7, v187 offset:640
	ds_read_b32 v8, v188 offset:512
	ds_read_b32 v9, v189 offset:512
	ds_read_b32 v10, v190 offset:512
	ds_read_b32 v11, v191 offset:512
	ds_read_b32 v12, v188 offset:640
	ds_read_b32 v13, v189 offset:640
	ds_read_b32 v14, v190 offset:640
	ds_read_b32 v15, v191 offset:640
	ds_read_b128 v[112:115], v144 offset:32768
	ds_read_b128 v[116:119], v145 offset:32768
	ds_read_b128 v[120:123], v144 offset:40960
	ds_read_b128 v[124:127], v145 offset:40960
	ds_read_b128 v[128:131], v144 offset:34816
	ds_read_b128 v[132:135], v145 offset:34816
	ds_read_b128 v[136:139], v144 offset:43008
	ds_read_b128 v[140:143], v145 offset:43008
	s_waitcnt lgkmcnt(7)
	v_mfma_f32_16x16x32_bf16 v[0:3], v[112:115], v[230:233], v[0:3]
	s_waitcnt lgkmcnt(6)
	v_mfma_f32_16x16x32_bf16 v[0:3], v[116:119], v[234:237], v[0:3]
	s_waitcnt lgkmcnt(5)
	v_mfma_f32_16x16x32_bf16 v[4:7], v[120:123], v[230:233], v[4:7]
	s_waitcnt lgkmcnt(4)
	v_mfma_f32_16x16x32_bf16 v[4:7], v[124:127], v[234:237], v[4:7]
	s_waitcnt lgkmcnt(3)
	v_mfma_f32_16x16x32_bf16 v[8:11], v[128:131], v[230:233], v[8:11]
	s_waitcnt lgkmcnt(2)
	v_mfma_f32_16x16x32_bf16 v[8:11], v[132:135], v[234:237], v[8:11]
	s_waitcnt lgkmcnt(1)
	v_mfma_f32_16x16x32_bf16 v[12:15], v[136:139], v[230:233], v[12:15]
	s_waitcnt lgkmcnt(0)
	v_mfma_f32_16x16x32_bf16 v[12:15], v[140:143], v[234:237], v[12:15]
	s_nop 7
	v_max3_f32 v203, v0, v1, v2
	v_max3_f32 v203, v203, v3, v4
	v_max3_f32 v203, v203, v5, v6
	v_max3_f32 v203, v203, v7, v8
	v_max3_f32 v203, v203, v9, v10
	v_max3_f32 v203, v203, v11, v12
	v_max3_f32 v203, v203, v13, v14
	v_max_f32_e32 v203, v203, v15
	v_mov_b32_e32 v205, v203
	s_nop 1
	v_permlane16_swap_b32_e32 v203, v205
	v_max_f32_e32 v203, v203, v205
	v_mov_b32_e32 v205, v203
	s_nop 1
	v_permlane32_swap_b32_e32 v203, v205
	v_max_f32_e32 v203, v203, v205
	v_max_f32_e32 v218, v246, v203
	v_sub_f32_e32 v220, v246, v218
	v_mov_b32_e32 v219, v218
	v_exp_f32_e32 v220, v220
	v_mov_b32_e32 v246, v218
	v_pk_add_f32 v[0:1], v[0:1], v[218:219] neg_lo:[0,1] neg_hi:[0,1]
	v_pk_add_f32 v[2:3], v[2:3], v[218:219] neg_lo:[0,1] neg_hi:[0,1]
	v_pk_add_f32 v[4:5], v[4:5], v[218:219] neg_lo:[0,1] neg_hi:[0,1]
	v_pk_add_f32 v[6:7], v[6:7], v[218:219] neg_lo:[0,1] neg_hi:[0,1]
	v_pk_add_f32 v[8:9], v[8:9], v[218:219] neg_lo:[0,1] neg_hi:[0,1]
	v_pk_add_f32 v[10:11], v[10:11], v[218:219] neg_lo:[0,1] neg_hi:[0,1]
	v_pk_add_f32 v[12:13], v[12:13], v[218:219] neg_lo:[0,1] neg_hi:[0,1]
	v_pk_add_f32 v[14:15], v[14:15], v[218:219] neg_lo:[0,1] neg_hi:[0,1]
	v_exp_f32_e32 v0, v0
	v_exp_f32_e32 v1, v1
	v_exp_f32_e32 v2, v2
	v_exp_f32_e32 v3, v3
	v_exp_f32_e32 v4, v4
	v_exp_f32_e32 v5, v5
	v_exp_f32_e32 v6, v6
	v_exp_f32_e32 v7, v7
	v_exp_f32_e32 v8, v8
	v_exp_f32_e32 v9, v9
	v_exp_f32_e32 v10, v10
	v_exp_f32_e32 v11, v11
	v_exp_f32_e32 v12, v12
	v_exp_f32_e32 v13, v13
	v_exp_f32_e32 v14, v14
	v_exp_f32_e32 v15, v15
	ds_read_b128 v[112:115], v146 offset:32768
	ds_read_b128 v[116:119], v146 offset:36864
	ds_read_b128 v[120:123], v146 offset:40960
	ds_read_b128 v[124:127], v146 offset:45056
	ds_read_b128 v[128:131], v147 offset:32768
	ds_read_b128 v[132:135], v147 offset:36864
	ds_read_b128 v[136:139], v147 offset:40960
	ds_read_b128 v[140:143], v147 offset:45056
	v_mov_b32_e32 v221, v220
	v_pk_add_f32 v[222:223], v[0:1], v[2:3]
	v_pk_add_f32 v[222:223], v[222:223], v[4:5]
	v_pk_add_f32 v[222:223], v[222:223], v[6:7]
	v_pk_add_f32 v[222:223], v[222:223], v[8:9]
	v_pk_add_f32 v[222:223], v[222:223], v[10:11]
	v_pk_add_f32 v[222:223], v[222:223], v[12:13]
	v_pk_add_f32 v[222:223], v[222:223], v[14:15]
	v_pk_mul_f32 v[176:177], v[176:177], v[220:221]
	v_pk_mul_f32 v[178:179], v[178:179], v[220:221]
	v_pk_mul_f32 v[180:181], v[180:181], v[220:221]
	v_pk_mul_f32 v[182:183], v[182:183], v[220:221]
	v_pk_mul_f32 v[192:193], v[192:193], v[220:221]
	v_pk_mul_f32 v[194:195], v[194:195], v[220:221]
	v_pk_mul_f32 v[196:197], v[196:197], v[220:221]
	v_pk_mul_f32 v[198:199], v[198:199], v[220:221]
	v_add_f32_e32 v203, v222, v223
	v_fma_f32 v247, v247, v220, v203
	v_cvt_pk_bf16_f32 v48, v0, v1
	v_cvt_pk_bf16_f32 v49, v2, v3
	v_cvt_pk_bf16_f32 v50, v4, v5
	v_cvt_pk_bf16_f32 v51, v6, v7
	v_cvt_pk_bf16_f32 v52, v8, v9
	v_cvt_pk_bf16_f32 v53, v10, v11
	v_cvt_pk_bf16_f32 v54, v12, v13
	v_cvt_pk_bf16_f32 v55, v14, v15
	s_waitcnt lgkmcnt(7)
	v_mfma_f32_16x16x32_bf16 v[176:179], v[112:115], v[48:51], v[176:179]
	s_waitcnt lgkmcnt(6)
	v_mfma_f32_16x16x32_bf16 v[180:183], v[116:119], v[48:51], v[180:183]
	s_waitcnt lgkmcnt(5)
	v_mfma_f32_16x16x32_bf16 v[192:195], v[120:123], v[48:51], v[192:195]
	s_waitcnt lgkmcnt(4)
	v_mfma_f32_16x16x32_bf16 v[196:199], v[124:127], v[48:51], v[196:199]
	s_waitcnt lgkmcnt(3)
	v_mfma_f32_16x16x32_bf16 v[176:179], v[128:131], v[52:55], v[176:179]
	s_waitcnt lgkmcnt(2)
	v_mfma_f32_16x16x32_bf16 v[180:183], v[132:135], v[52:55], v[180:183]
	s_waitcnt lgkmcnt(1)
	v_mfma_f32_16x16x32_bf16 v[192:195], v[136:139], v[52:55], v[192:195]
	s_waitcnt lgkmcnt(0)
	v_mfma_f32_16x16x32_bf16 v[196:199], v[140:143], v[52:55], v[196:199]
	ds_read_b32 v0, v184 offset:896
	ds_read_b32 v1, v185 offset:896
	ds_read_b32 v2, v186 offset:896
	ds_read_b32 v3, v187 offset:896
	ds_read_b32 v4, v184 offset:1024
	ds_read_b32 v5, v185 offset:1024
	ds_read_b32 v6, v186 offset:1024
	ds_read_b32 v7, v187 offset:1024
	ds_read_b32 v8, v188 offset:896
	ds_read_b32 v9, v189 offset:896
	ds_read_b32 v10, v190 offset:896
	ds_read_b32 v11, v191 offset:896
	ds_read_b32 v12, v188 offset:1024
	ds_read_b32 v13, v189 offset:1024
	ds_read_b32 v14, v190 offset:1024
	ds_read_b32 v15, v191 offset:1024
	s_waitcnt lgkmcnt(0)
	s_barrier
; __device__ __forceinline__ void attn_phase(const Params& P, char* smem_raw) {
;     ...
;       __syncthreads();
;       f32x4 sacc[8];
; #pragma unroll
;       for (int t8 = 0; t8 < 8; ++t8) sacc[t8] = f32x4{0.f, 0.f, 0.f, 0.f};
; #pragma unroll
;       for (int s = 0; s < 2; ++s)
; #pragma unroll
;         for (int t8 = 0; t8 < 8; ++t8) {
;           const bf16x8 kf = *reinterpret_cast<const bf16x8*>(&sm_k[(t8 * 16 + (lane_c & 15)) * LDSS + s * 32 + (lane_c >> 4) * 8]);
;           sacc[t8] = __builtin_amdgcn_mfma_f32_16x16x32_bf16(qf[s], kf, sacc[t8], 0, 0, 0);
;         }
;       if (ck < 5) {
;         ATT_ISSUE(t, ck + 1)
;       } else if (t + VGRID < 8192) {
;         ATT_ISSUE(t + VGRID, 0)
;         ATT_QLOAD(t + VGRID)
;       }
;       if (ck < 4) {
;         const float* rb0 = sm_rpb + (rs + ck * 2 - r + 7) * 31;
; #pragma unroll
;         for (int t8 = 0; t8 < 8; ++t8)
; #pragma unroll
;           for (int reg = 0; reg < 4; ++reg)
;             sacc[t8][reg] += rb0[(t8 >> 2) * 31 + dco[reg][t8 & 3]];
;       }
; #pragma unroll
;       for (int reg = 0; reg < 4; ++reg) {
;         float mx = sacc[0][reg];
; #pragma unroll
;         for (int t8 = 1; t8 < 8; ++t8) mx = fmaxf(mx, sacc[t8][reg]);
;         mx = row16_max(mx);
;         const float mnew = fmaxf(mrow[reg], mx);
;         const float alpha = __builtin_amdgcn_exp2f(mrow[reg] - mnew);
;         mrow[reg] = mnew;
;         float rsum = 0.f;
; #pragma unroll
;         for (int t8 = 0; t8 < 8; ++t8) {
;           const float p = __builtin_amdgcn_exp2f(sacc[t8][reg] - mnew);
;           rsum += p;
;           sm_p[(wid * 16 + (lane_c >> 4) * 4 + reg) * 136 + t8 * 16 + (lane_c & 15)] = f2bf(p);
;         }
;         rsum = row16_sum(rsum);
;         lrow[reg] = lrow[reg] * alpha + rsum;
; #pragma unroll
;         for (int td = 0; td < 4; ++td) o[td][reg] *= alpha;
;       }
;       asm volatile("s_waitcnt lgkmcnt(0)" ::: "memory");
; #pragma unroll
;       for (int s4 = 0; s4 < 4; ++s4) {
;         const bf16x8 pf = *reinterpret_cast<const bf16x8*>(&sm_p[(wid * 16 + (lane_c & 15)) * 136 + s4 * 32 + (lane_c >> 4) * 8]);
; #pragma unroll
;         for (int td = 0; td < 4; ++td) {
;           const bf16x8 vf = *reinterpret_cast<const bf16x8*>(&sm_vt[(td * 16 + (lane_c & 15)) * 136 + s4 * 32 + (lane_c >> 4) * 8]);
;           o[td] = __builtin_amdgcn_mfma_f32_16x16x32_bf16(pf, vf, o[td], 0, 0, 0);
	ds_read_b128 v[112:115], v144 offset:0
	ds_read_b128 v[116:119], v145 offset:0
	ds_read_b128 v[120:123], v144 offset:8192
	ds_read_b128 v[124:127], v145 offset:8192
	ds_read_b128 v[128:131], v144 offset:2048
	ds_read_b128 v[132:135], v145 offset:2048
	ds_read_b128 v[136:139], v144 offset:10240
	ds_read_b128 v[140:143], v145 offset:10240
	s_waitcnt lgkmcnt(7)
	v_mfma_f32_16x16x32_bf16 v[0:3], v[112:115], v[64:67], v[0:3]
	s_waitcnt lgkmcnt(6)
	v_mfma_f32_16x16x32_bf16 v[0:3], v[116:119], v[68:71], v[0:3]
	s_waitcnt lgkmcnt(5)
	v_mfma_f32_16x16x32_bf16 v[4:7], v[120:123], v[64:67], v[4:7]
	s_waitcnt lgkmcnt(4)
	v_mfma_f32_16x16x32_bf16 v[4:7], v[124:127], v[68:71], v[4:7]
	s_waitcnt lgkmcnt(3)
	v_mfma_f32_16x16x32_bf16 v[8:11], v[128:131], v[64:67], v[8:11]
	s_waitcnt lgkmcnt(2)
	v_mfma_f32_16x16x32_bf16 v[8:11], v[132:135], v[68:71], v[8:11]
	s_waitcnt lgkmcnt(1)
	v_mfma_f32_16x16x32_bf16 v[12:15], v[136:139], v[64:67], v[12:15]
	s_waitcnt lgkmcnt(0)
	v_mfma_f32_16x16x32_bf16 v[12:15], v[140:143], v[68:71], v[12:15]
	s_nop 7
	v_max3_f32 v203, v0, v1, v2
	v_max3_f32 v203, v203, v3, v4
	v_max3_f32 v203, v203, v5, v6
	v_max3_f32 v203, v203, v7, v8
	v_max3_f32 v203, v203, v9, v10
	v_max3_f32 v203, v203, v11, v12
	v_max3_f32 v203, v203, v13, v14
	v_max_f32_e32 v203, v203, v15
	v_mov_b32_e32 v205, v203
	s_nop 1
	v_permlane16_swap_b32_e32 v203, v205
	v_max_f32_e32 v203, v203, v205
	v_mov_b32_e32 v205, v203
	s_nop 1
	v_permlane32_swap_b32_e32 v203, v205
	v_max_f32_e32 v203, v203, v205
	v_max_f32_e32 v218, v200, v203
	v_sub_f32_e32 v220, v200, v218
	v_mov_b32_e32 v219, v218
	v_exp_f32_e32 v220, v220
	v_mov_b32_e32 v200, v218
	v_pk_add_f32 v[0:1], v[0:1], v[218:219] neg_lo:[0,1] neg_hi:[0,1]
	v_pk_add_f32 v[2:3], v[2:3], v[218:219] neg_lo:[0,1] neg_hi:[0,1]
	v_pk_add_f32 v[4:5], v[4:5], v[218:219] neg_lo:[0,1] neg_hi:[0,1]
	v_pk_add_f32 v[6:7], v[6:7], v[218:219] neg_lo:[0,1] neg_hi:[0,1]
	v_pk_add_f32 v[8:9], v[8:9], v[218:219] neg_lo:[0,1] neg_hi:[0,1]
	v_pk_add_f32 v[10:11], v[10:11], v[218:219] neg_lo:[0,1] neg_hi:[0,1]
	v_pk_add_f32 v[12:13], v[12:13], v[218:219] neg_lo:[0,1] neg_hi:[0,1]
	v_pk_add_f32 v[14:15], v[14:15], v[218:219] neg_lo:[0,1] neg_hi:[0,1]
	v_exp_f32_e32 v0, v0
	s_waitcnt vmcnt(0)
	v_exp_f32_e32 v1, v1
	ds_write_b128 v150, v[80:83] offset:32768
	v_exp_f32_e32 v2, v2
	ds_write_b128 v150, v[84:87] offset:36864
	v_exp_f32_e32 v3, v3
	ds_write_b128 v150, v[88:91] offset:40960
	v_exp_f32_e32 v4, v4
	ds_write_b128 v150, v[92:95] offset:45056
	v_exp_f32_e32 v5, v5
	ds_write_b64 v151, v[96:97] offset:32768
	v_exp_f32_e32 v6, v6
	ds_write_b64 v229, v[98:99] offset:32768
	v_exp_f32_e32 v7, v7
	ds_write_b64 v151, v[100:101] offset:36864
	v_exp_f32_e32 v8, v8
	ds_write_b64 v229, v[102:103] offset:36864
	v_exp_f32_e32 v9, v9
	ds_write_b64 v151, v[104:105] offset:40960
	v_exp_f32_e32 v10, v10
	ds_write_b64 v229, v[106:107] offset:40960
	v_exp_f32_e32 v11, v11
	ds_write_b64 v151, v[108:109] offset:45056
	v_exp_f32_e32 v12, v12
	ds_write_b64 v229, v[110:111] offset:45056
	v_exp_f32_e32 v13, v13
	s_add_u32 s100, s12, s20
	v_exp_f32_e32 v14, v14
	s_addc_u32 s101, s13, 0
	v_exp_f32_e32 v15, v15
	s_add_u32 s0, s14, s21
	s_addc_u32 s1, s15, 0
	global_load_dwordx4 v[80:83], v154, s[100:101] offset:2048
	global_load_dwordx4 v[96:99], v158, s[0:1]
	global_load_dwordx4 v[84:87], v155, s[100:101] offset:2048
	global_load_dwordx4 v[100:103], v159, s[0:1]
	global_load_dwordx4 v[88:91], v156, s[100:101] offset:2048
	global_load_dwordx4 v[104:107], v160, s[0:1]
	global_load_dwordx4 v[92:95], v157, s[100:101] offset:2048
	global_load_dwordx4 v[108:111], v161, s[0:1]
	ds_read_b128 v[112:115], v146 offset:0
	ds_read_b128 v[116:119], v146 offset:4096
	ds_read_b128 v[120:123], v146 offset:8192
	ds_read_b128 v[124:127], v146 offset:12288
	ds_read_b128 v[128:131], v147 offset:0
	ds_read_b128 v[132:135], v147 offset:4096
	ds_read_b128 v[136:139], v147 offset:8192
	ds_read_b128 v[140:143], v147 offset:12288
	v_mov_b32_e32 v221, v220
	v_pk_add_f32 v[222:223], v[0:1], v[2:3]
	v_pk_add_f32 v[222:223], v[222:223], v[4:5]
	v_pk_add_f32 v[222:223], v[222:223], v[6:7]
	v_pk_add_f32 v[222:223], v[222:223], v[8:9]
	v_pk_add_f32 v[222:223], v[222:223], v[10:11]
	v_pk_add_f32 v[222:223], v[222:223], v[12:13]
	v_pk_add_f32 v[222:223], v[222:223], v[14:15]
	v_pk_mul_f32 v[32:33], v[32:33], v[220:221]
	v_pk_mul_f32 v[34:35], v[34:35], v[220:221]
	v_pk_mul_f32 v[36:37], v[36:37], v[220:221]
	v_pk_mul_f32 v[38:39], v[38:39], v[220:221]
	v_pk_mul_f32 v[40:41], v[40:41], v[220:221]
	v_pk_mul_f32 v[42:43], v[42:43], v[220:221]
	v_pk_mul_f32 v[44:45], v[44:45], v[220:221]
	v_pk_mul_f32 v[46:47], v[46:47], v[220:221]
	v_add_f32_e32 v203, v222, v223
	v_fma_f32 v201, v201, v220, v203
	v_cvt_pk_bf16_f32 v48, v0, v1
	v_cvt_pk_bf16_f32 v49, v2, v3
	v_cvt_pk_bf16_f32 v50, v4, v5
	v_cvt_pk_bf16_f32 v51, v6, v7
	v_cvt_pk_bf16_f32 v52, v8, v9
	v_cvt_pk_bf16_f32 v53, v10, v11
	v_cvt_pk_bf16_f32 v54, v12, v13
	v_cvt_pk_bf16_f32 v55, v14, v15
	s_waitcnt lgkmcnt(7)
	v_mfma_f32_16x16x32_bf16 v[32:35], v[112:115], v[48:51], v[32:35]
	s_waitcnt lgkmcnt(6)
	v_mfma_f32_16x16x32_bf16 v[36:39], v[116:119], v[48:51], v[36:39]
	s_waitcnt lgkmcnt(5)
	v_mfma_f32_16x16x32_bf16 v[40:43], v[120:123], v[48:51], v[40:43]
	s_waitcnt lgkmcnt(4)
	v_mfma_f32_16x16x32_bf16 v[44:47], v[124:127], v[48:51], v[44:47]
	s_waitcnt lgkmcnt(3)
	v_mfma_f32_16x16x32_bf16 v[32:35], v[128:131], v[52:55], v[32:35]
	s_waitcnt lgkmcnt(2)
	v_mfma_f32_16x16x32_bf16 v[36:39], v[132:135], v[52:55], v[36:39]
	s_waitcnt lgkmcnt(1)
	v_mfma_f32_16x16x32_bf16 v[40:43], v[136:139], v[52:55], v[40:43]
	s_waitcnt lgkmcnt(0)
; __device__ __forceinline__ void attn_phase(const Params& P, char* smem_raw) {
;     ...
;       f32x4 sacc[8];
; #pragma unroll
;       for (int t8 = 0; t8 < 8; ++t8) sacc[t8] = f32x4{0.f, 0.f, 0.f, 0.f};
; #pragma unroll
;       for (int s = 0; s < 2; ++s)
; #pragma unroll
;         for (int t8 = 0; t8 < 8; ++t8) {
;           const bf16x8 kf = *reinterpret_cast<const bf16x8*>(&sm_k[(t8 * 16 + (lane_c & 15)) * LDSS + s * 32 + (lane_c >> 4) * 8]);
;           sacc[t8] = __builtin_amdgcn_mfma_f32_16x16x32_bf16(qf[s], kf, sacc[t8], 0, 0, 0);
;         }
;       if (ck < 5) {
;         ATT_ISSUE(t, ck + 1)
;       } else if (t + VGRID < 8192) {
;         ATT_ISSUE(t + VGRID, 0)
;         ATT_QLOAD(t + VGRID)
;       }
;       if (ck < 4) {
;         const float* rb0 = sm_rpb + (rs + ck * 2 - r + 7) * 31;
; #pragma unroll
;         for (int t8 = 0; t8 < 8; ++t8)
; #pragma unroll
;           for (int reg = 0; reg < 4; ++reg)
;             sacc[t8][reg] += rb0[(t8 >> 2) * 31 + dco[reg][t8 & 3]];
;       }
; #pragma unroll
;       for (int reg = 0; reg < 4; ++reg) {
;         float mx = sacc[0][reg];
; #pragma unroll
;         for (int t8 = 1; t8 < 8; ++t8) mx = fmaxf(mx, sacc[t8][reg]);
;         mx = row16_max(mx);
;         const float mnew = fmaxf(mrow[reg], mx);
;         const float alpha = __builtin_amdgcn_exp2f(mrow[reg] - mnew);
;         mrow[reg] = mnew;
;         float rsum = 0.f;
; #pragma unroll
;         for (int t8 = 0; t8 < 8; ++t8) {
;           const float p = __builtin_amdgcn_exp2f(sacc[t8][reg] - mnew);
;           rsum += p;
;           sm_p[(wid * 16 + (lane_c >> 4) * 4 + reg) * 136 + t8 * 16 + (lane_c & 15)] = f2bf(p);
;         }
;         rsum = row16_sum(rsum);
;         lrow[reg] = lrow[reg] * alpha + rsum;
; #pragma unroll
;         for (int td = 0; td < 4; ++td) o[td][reg] *= alpha;
;       }
;       asm volatile("s_waitcnt lgkmcnt(0)" ::: "memory");
; #pragma unroll
;       for (int s4 = 0; s4 < 4; ++s4) {
;         const bf16x8 pf = *reinterpret_cast<const bf16x8*>(&sm_p[(wid * 16 + (lane_c & 15)) * 136 + s4 * 32 + (lane_c >> 4) * 8]);
; #pragma unroll
;         for (int td = 0; td < 4; ++td) {
;           const bf16x8 vf = *reinterpret_cast<const bf16x8*>(&sm_vt[(td * 16 + (lane_c & 15)) * 136 + s4 * 32 + (lane_c >> 4) * 8]);
;           o[td] = __builtin_amdgcn_mfma_f32_16x16x32_bf16(pf, vf, o[td], 0, 0, 0);
;         }
;       }
	v_mfma_f32_16x16x32_bf16 v[44:47], v[140:143], v[52:55], v[44:47]
	ds_read_b32 v0, v184 offset:768
	ds_read_b32 v1, v185 offset:768
	ds_read_b32 v2, v186 offset:768
	ds_read_b32 v3, v187 offset:768
	ds_read_b32 v4, v184 offset:896
	ds_read_b32 v5, v185 offset:896
	ds_read_b32 v6, v186 offset:896
	ds_read_b32 v7, v187 offset:896
	ds_read_b32 v8, v188 offset:768
	ds_read_b32 v9, v189 offset:768
	ds_read_b32 v10, v190 offset:768
	ds_read_b32 v11, v191 offset:768
	ds_read_b32 v12, v188 offset:896
	ds_read_b32 v13, v189 offset:896
	ds_read_b32 v14, v190 offset:896
	ds_read_b32 v15, v191 offset:896
	ds_read_b128 v[112:115], v144 offset:0
	ds_read_b128 v[116:119], v145 offset:0
	ds_read_b128 v[120:123], v144 offset:8192
	ds_read_b128 v[124:127], v145 offset:8192
	ds_read_b128 v[128:131], v144 offset:2048
	ds_read_b128 v[132:135], v145 offset:2048
	ds_read_b128 v[136:139], v144 offset:10240
	ds_read_b128 v[140:143], v145 offset:10240
	s_waitcnt lgkmcnt(7)
	v_mfma_f32_16x16x32_bf16 v[0:3], v[112:115], v[230:233], v[0:3]
	s_waitcnt lgkmcnt(6)
	v_mfma_f32_16x16x32_bf16 v[0:3], v[116:119], v[234:237], v[0:3]
	s_waitcnt lgkmcnt(5)
	v_mfma_f32_16x16x32_bf16 v[4:7], v[120:123], v[230:233], v[4:7]
	s_waitcnt lgkmcnt(4)
	v_mfma_f32_16x16x32_bf16 v[4:7], v[124:127], v[234:237], v[4:7]
	s_waitcnt lgkmcnt(3)
	v_mfma_f32_16x16x32_bf16 v[8:11], v[128:131], v[230:233], v[8:11]
	s_waitcnt lgkmcnt(2)
	v_mfma_f32_16x16x32_bf16 v[8:11], v[132:135], v[234:237], v[8:11]
	s_waitcnt lgkmcnt(1)
	v_mfma_f32_16x16x32_bf16 v[12:15], v[136:139], v[230:233], v[12:15]
	s_waitcnt lgkmcnt(0)
	v_mfma_f32_16x16x32_bf16 v[12:15], v[140:143], v[234:237], v[12:15]
	s_nop 7
	v_max3_f32 v203, v0, v1, v2
	v_max3_f32 v203, v203, v3, v4
	v_max3_f32 v203, v203, v5, v6
	v_max3_f32 v203, v203, v7, v8
	v_max3_f32 v203, v203, v9, v10
	v_max3_f32 v203, v203, v11, v12
	v_max3_f32 v203, v203, v13, v14
	v_max_f32_e32 v203, v203, v15
	v_mov_b32_e32 v205, v203
	s_nop 1
	v_permlane16_swap_b32_e32 v203, v205
	v_max_f32_e32 v203, v203, v205
	v_mov_b32_e32 v205, v203
	s_nop 1
	v_permlane32_swap_b32_e32 v203, v205
	v_max_f32_e32 v203, v203, v205
	v_max_f32_e32 v218, v246, v203
	v_sub_f32_e32 v220, v246, v218
	v_mov_b32_e32 v219, v218
	v_exp_f32_e32 v220, v220
	v_mov_b32_e32 v246, v218
	v_pk_add_f32 v[0:1], v[0:1], v[218:219] neg_lo:[0,1] neg_hi:[0,1]
	v_pk_add_f32 v[2:3], v[2:3], v[218:219] neg_lo:[0,1] neg_hi:[0,1]
	v_pk_add_f32 v[4:5], v[4:5], v[218:219] neg_lo:[0,1] neg_hi:[0,1]
	v_pk_add_f32 v[6:7], v[6:7], v[218:219] neg_lo:[0,1] neg_hi:[0,1]
	v_pk_add_f32 v[8:9], v[8:9], v[218:219] neg_lo:[0,1] neg_hi:[0,1]
	v_pk_add_f32 v[10:11], v[10:11], v[218:219] neg_lo:[0,1] neg_hi:[0,1]
	v_pk_add_f32 v[12:13], v[12:13], v[218:219] neg_lo:[0,1] neg_hi:[0,1]
	v_pk_add_f32 v[14:15], v[14:15], v[218:219] neg_lo:[0,1] neg_hi:[0,1]
	v_exp_f32_e32 v0, v0
	v_exp_f32_e32 v1, v1
	v_exp_f32_e32 v2, v2
	v_exp_f32_e32 v3, v3
	v_exp_f32_e32 v4, v4
	v_exp_f32_e32 v5, v5
	v_exp_f32_e32 v6, v6
	v_exp_f32_e32 v7, v7
	v_exp_f32_e32 v8, v8
	v_exp_f32_e32 v9, v9
	v_exp_f32_e32 v10, v10
	v_exp_f32_e32 v11, v11
	v_exp_f32_e32 v12, v12
	v_exp_f32_e32 v13, v13
	v_exp_f32_e32 v14, v14
	v_exp_f32_e32 v15, v15
	ds_read_b128 v[112:115], v146 offset:0
	ds_read_b128 v[116:119], v146 offset:4096
	ds_read_b128 v[120:123], v146 offset:8192
	ds_read_b128 v[124:127], v146 offset:12288
	ds_read_b128 v[128:131], v147 offset:0
	ds_read_b128 v[132:135], v147 offset:4096
	ds_read_b128 v[136:139], v147 offset:8192
	ds_read_b128 v[140:143], v147 offset:12288
	v_mov_b32_e32 v221, v220
	v_pk_add_f32 v[222:223], v[0:1], v[2:3]
	v_pk_add_f32 v[222:223], v[222:223], v[4:5]
	v_pk_add_f32 v[222:223], v[222:223], v[6:7]
	v_pk_add_f32 v[222:223], v[222:223], v[8:9]
	v_pk_add_f32 v[222:223], v[222:223], v[10:11]
	v_pk_add_f32 v[222:223], v[222:223], v[12:13]
	v_pk_add_f32 v[222:223], v[222:223], v[14:15]
	v_pk_mul_f32 v[176:177], v[176:177], v[220:221]
	v_pk_mul_f32 v[178:179], v[178:179], v[220:221]
	v_pk_mul_f32 v[180:181], v[180:181], v[220:221]
	v_pk_mul_f32 v[182:183], v[182:183], v[220:221]
	v_pk_mul_f32 v[192:193], v[192:193], v[220:221]
	v_pk_mul_f32 v[194:195], v[194:195], v[220:221]
	v_pk_mul_f32 v[196:197], v[196:197], v[220:221]
	v_pk_mul_f32 v[198:199], v[198:199], v[220:221]
	v_add_f32_e32 v203, v222, v223
	v_fma_f32 v247, v247, v220, v203
	v_cvt_pk_bf16_f32 v48, v0, v1
	v_cvt_pk_bf16_f32 v49, v2, v3
	v_cvt_pk_bf16_f32 v50, v4, v5
	v_cvt_pk_bf16_f32 v51, v6, v7
	v_cvt_pk_bf16_f32 v52, v8, v9
	v_cvt_pk_bf16_f32 v53, v10, v11
	v_cvt_pk_bf16_f32 v54, v12, v13
	v_cvt_pk_bf16_f32 v55, v14, v15
	s_waitcnt lgkmcnt(7)
	v_mfma_f32_16x16x32_bf16 v[176:179], v[112:115], v[48:51], v[176:179]
	s_waitcnt lgkmcnt(6)
	v_mfma_f32_16x16x32_bf16 v[180:183], v[116:119], v[48:51], v[180:183]
	s_waitcnt lgkmcnt(5)
	v_mfma_f32_16x16x32_bf16 v[192:195], v[120:123], v[48:51], v[192:195]
	s_waitcnt lgkmcnt(4)
	v_mfma_f32_16x16x32_bf16 v[196:199], v[124:127], v[48:51], v[196:199]
	s_waitcnt lgkmcnt(3)
	v_mfma_f32_16x16x32_bf16 v[176:179], v[128:131], v[52:55], v[176:179]
	s_waitcnt lgkmcnt(2)
	v_mfma_f32_16x16x32_bf16 v[180:183], v[132:135], v[52:55], v[180:183]
	s_waitcnt lgkmcnt(1)
	v_mfma_f32_16x16x32_bf16 v[192:195], v[136:139], v[52:55], v[192:195]
	s_waitcnt lgkmcnt(0)
	v_mfma_f32_16x16x32_bf16 v[196:199], v[140:143], v[52:55], v[196:199]
	ds_read_b32 v0, v184 offset:1152
	ds_read_b32 v1, v185 offset:1152
	ds_read_b32 v2, v186 offset:1152
	ds_read_b32 v3, v187 offset:1152
	ds_read_b32 v4, v184 offset:1280
	ds_read_b32 v5, v185 offset:1280
	ds_read_b32 v6, v186 offset:1280
	ds_read_b32 v7, v187 offset:1280
	ds_read_b32 v8, v188 offset:1152
	ds_read_b32 v9, v189 offset:1152
	ds_read_b32 v10, v190 offset:1152
	ds_read_b32 v11, v191 offset:1152
	ds_read_b32 v12, v188 offset:1280
	ds_read_b32 v13, v189 offset:1280
	ds_read_b32 v14, v190 offset:1280
	ds_read_b32 v15, v191 offset:1280
	s_waitcnt lgkmcnt(0)
	s_barrier
; __device__ __forceinline__ void attn_phase(const Params& P, char* smem_raw) {
;     ...
;       __syncthreads();
;       f32x4 sacc[8];
; #pragma unroll
;       for (int t8 = 0; t8 < 8; ++t8) sacc[t8] = f32x4{0.f, 0.f, 0.f, 0.f};
; #pragma unroll
;       for (int s = 0; s < 2; ++s)
; #pragma unroll
;         for (int t8 = 0; t8 < 8; ++t8) {
;           const bf16x8 kf = *reinterpret_cast<const bf16x8*>(&sm_k[(t8 * 16 + (lane_c & 15)) * LDSS + s * 32 + (lane_c >> 4) * 8]);
;           sacc[t8] = __builtin_amdgcn_mfma_f32_16x16x32_bf16(qf[s], kf, sacc[t8], 0, 0, 0);
;         }
;       if (ck < 5) {
;         ATT_ISSUE(t, ck + 1)
;       } else if (t + VGRID < 8192) {
;         ATT_ISSUE(t + VGRID, 0)
;         ATT_QLOAD(t + VGRID)
;       }
;       if (ck < 4) {
;         const float* rb0 = sm_rpb + (rs + ck * 2 - r + 7) * 31;
; #pragma unroll
;         for (int t8 = 0; t8 < 8; ++t8)
; #pragma unroll
;           for (int reg = 0; reg < 4; ++reg)
;             sacc[t8][reg] += rb0[(t8 >> 2) * 31 + dco[reg][t8 & 3]];
;       }
; #pragma unroll
;       for (int reg = 0; reg < 4; ++reg) {
;         float mx = sacc[0][reg];
; #pragma unroll
;         for (int t8 = 1; t8 < 8; ++t8) mx = fmaxf(mx, sacc[t8][reg]);
;         mx = row16_max(mx);
;         const float mnew = fmaxf(mrow[reg], mx);
;         const float alpha = __builtin_amdgcn_exp2f(mrow[reg] - mnew);
;         mrow[reg] = mnew;
;         float rsum = 0.f;
; #pragma unroll
;         for (int t8 = 0; t8 < 8; ++t8) {
;           const float p = __builtin_amdgcn_exp2f(sacc[t8][reg] - mnew);
;           rsum += p;
;           sm_p[(wid * 16 + (lane_c >> 4) * 4 + reg) * 136 + t8 * 16 + (lane_c & 15)] = f2bf(p);
;         }
;         rsum = row16_sum(rsum);
;         lrow[reg] = lrow[reg] * alpha + rsum;
; #pragma unroll
;         for (int td = 0; td < 4; ++td) o[td][reg] *= alpha;
;       }
;       asm volatile("s_waitcnt lgkmcnt(0)" ::: "memory");
; #pragma unroll
;       for (int s4 = 0; s4 < 4; ++s4) {
;         const bf16x8 pf = *reinterpret_cast<const bf16x8*>(&sm_p[(wid * 16 + (lane_c & 15)) * 136 + s4 * 32 + (lane_c >> 4) * 8]);
; #pragma unroll
;         for (int td = 0; td < 4; ++td) {
;           const bf16x8 vf = *reinterpret_cast<const bf16x8*>(&sm_vt[(td * 16 + (lane_c & 15)) * 136 + s4 * 32 + (lane_c >> 4) * 8]);
;           o[td] = __builtin_amdgcn_mfma_f32_16x16x32_bf16(pf, vf, o[td], 0, 0, 0);
	ds_read_b128 v[112:115], v144 offset:32768
	ds_read_b128 v[116:119], v145 offset:32768
	ds_read_b128 v[120:123], v144 offset:40960
	ds_read_b128 v[124:127], v145 offset:40960
	ds_read_b128 v[128:131], v144 offset:34816
	ds_read_b128 v[132:135], v145 offset:34816
	ds_read_b128 v[136:139], v144 offset:43008
	ds_read_b128 v[140:143], v145 offset:43008
	s_waitcnt lgkmcnt(7)
	v_mfma_f32_16x16x32_bf16 v[0:3], v[112:115], v[64:67], v[0:3]
	s_waitcnt lgkmcnt(6)
	v_mfma_f32_16x16x32_bf16 v[0:3], v[116:119], v[68:71], v[0:3]
	s_waitcnt lgkmcnt(5)
	v_mfma_f32_16x16x32_bf16 v[4:7], v[120:123], v[64:67], v[4:7]
	s_waitcnt lgkmcnt(4)
	v_mfma_f32_16x16x32_bf16 v[4:7], v[124:127], v[68:71], v[4:7]
	s_waitcnt lgkmcnt(3)
	v_mfma_f32_16x16x32_bf16 v[8:11], v[128:131], v[64:67], v[8:11]
	s_waitcnt lgkmcnt(2)
	v_mfma_f32_16x16x32_bf16 v[8:11], v[132:135], v[68:71], v[8:11]
	s_waitcnt lgkmcnt(1)
	v_mfma_f32_16x16x32_bf16 v[12:15], v[136:139], v[64:67], v[12:15]
	s_waitcnt lgkmcnt(0)
	v_mfma_f32_16x16x32_bf16 v[12:15], v[140:143], v[68:71], v[12:15]
	s_nop 7
	v_max3_f32 v203, v0, v1, v2
	v_max3_f32 v203, v203, v3, v4
	v_max3_f32 v203, v203, v5, v6
	v_max3_f32 v203, v203, v7, v8
	v_max3_f32 v203, v203, v9, v10
	v_max3_f32 v203, v203, v11, v12
	v_max3_f32 v203, v203, v13, v14
	v_max_f32_e32 v203, v203, v15
	v_mov_b32_e32 v205, v203
	s_nop 1
	v_permlane16_swap_b32_e32 v203, v205
	v_max_f32_e32 v203, v203, v205
	v_mov_b32_e32 v205, v203
	s_nop 1
	v_permlane32_swap_b32_e32 v203, v205
	v_max_f32_e32 v203, v203, v205
	v_max_f32_e32 v218, v200, v203
	v_sub_f32_e32 v220, v200, v218
	v_mov_b32_e32 v219, v218
	v_exp_f32_e32 v220, v220
	v_mov_b32_e32 v200, v218
	v_pk_add_f32 v[0:1], v[0:1], v[218:219] neg_lo:[0,1] neg_hi:[0,1]
	v_pk_add_f32 v[2:3], v[2:3], v[218:219] neg_lo:[0,1] neg_hi:[0,1]
	v_pk_add_f32 v[4:5], v[4:5], v[218:219] neg_lo:[0,1] neg_hi:[0,1]
	v_pk_add_f32 v[6:7], v[6:7], v[218:219] neg_lo:[0,1] neg_hi:[0,1]
	v_pk_add_f32 v[8:9], v[8:9], v[218:219] neg_lo:[0,1] neg_hi:[0,1]
	v_pk_add_f32 v[10:11], v[10:11], v[218:219] neg_lo:[0,1] neg_hi:[0,1]
	v_pk_add_f32 v[12:13], v[12:13], v[218:219] neg_lo:[0,1] neg_hi:[0,1]
	v_pk_add_f32 v[14:15], v[14:15], v[218:219] neg_lo:[0,1] neg_hi:[0,1]
	v_exp_f32_e32 v0, v0
	s_waitcnt vmcnt(0)
	v_exp_f32_e32 v1, v1
	ds_write_b128 v150, v[80:83] offset:0
	v_exp_f32_e32 v2, v2
	ds_write_b128 v150, v[84:87] offset:4096
	v_exp_f32_e32 v3, v3
	ds_write_b128 v150, v[88:91] offset:8192
	v_exp_f32_e32 v4, v4
	ds_write_b128 v150, v[92:95] offset:12288
	v_exp_f32_e32 v5, v5
	ds_write_b64 v151, v[96:97] offset:0
	v_exp_f32_e32 v6, v6
	ds_write_b64 v229, v[98:99] offset:0
	v_exp_f32_e32 v7, v7
	ds_write_b64 v151, v[100:101] offset:4096
	v_exp_f32_e32 v8, v8
	ds_write_b64 v229, v[102:103] offset:4096
	v_exp_f32_e32 v9, v9
	ds_write_b64 v151, v[104:105] offset:8192
	v_exp_f32_e32 v10, v10
	ds_write_b64 v229, v[106:107] offset:8192
	v_exp_f32_e32 v11, v11
	ds_write_b64 v151, v[108:109] offset:12288
	v_exp_f32_e32 v12, v12
	ds_write_b64 v229, v[110:111] offset:12288
	v_exp_f32_e32 v13, v13
	s_add_u32 s100, s16, 0x0
	v_exp_f32_e32 v14, v14
	s_addc_u32 s101, s17, 0
	v_exp_f32_e32 v15, v15
	s_add_u32 s0, s36, 0x0
	s_addc_u32 s1, s37, 0
	global_load_dwordx4 v[80:83], v154, s[100:101] offset:2048
	global_load_dwordx4 v[96:99], v162, s[0:1]
	global_load_dwordx4 v[84:87], v155, s[100:101] offset:2048
	global_load_dwordx4 v[100:103], v163, s[0:1]
	global_load_dwordx4 v[88:91], v156, s[100:101] offset:2048
	global_load_dwordx4 v[104:107], v164, s[0:1]
	global_load_dwordx4 v[92:95], v157, s[100:101] offset:2048
	global_load_dwordx4 v[108:111], v165, s[0:1]
	ds_read_b128 v[112:115], v146 offset:32768
	ds_read_b128 v[116:119], v146 offset:36864
	ds_read_b128 v[120:123], v146 offset:40960
	ds_read_b128 v[124:127], v146 offset:45056
	ds_read_b128 v[128:131], v147 offset:32768
	ds_read_b128 v[132:135], v147 offset:36864
	ds_read_b128 v[136:139], v147 offset:40960
	ds_read_b128 v[140:143], v147 offset:45056
	v_mov_b32_e32 v221, v220
	v_pk_add_f32 v[222:223], v[0:1], v[2:3]
	v_pk_add_f32 v[222:223], v[222:223], v[4:5]
	v_pk_add_f32 v[222:223], v[222:223], v[6:7]
	v_pk_add_f32 v[222:223], v[222:223], v[8:9]
	v_pk_add_f32 v[222:223], v[222:223], v[10:11]
	v_pk_add_f32 v[222:223], v[222:223], v[12:13]
	v_pk_add_f32 v[222:223], v[222:223], v[14:15]
	v_pk_mul_f32 v[32:33], v[32:33], v[220:221]
	v_pk_mul_f32 v[34:35], v[34:35], v[220:221]
	v_pk_mul_f32 v[36:37], v[36:37], v[220:221]
	v_pk_mul_f32 v[38:39], v[38:39], v[220:221]
	v_pk_mul_f32 v[40:41], v[40:41], v[220:221]
	v_pk_mul_f32 v[42:43], v[42:43], v[220:221]
	v_pk_mul_f32 v[44:45], v[44:45], v[220:221]
	v_pk_mul_f32 v[46:47], v[46:47], v[220:221]
	v_add_f32_e32 v203, v222, v223
	v_fma_f32 v201, v201, v220, v203
	v_cvt_pk_bf16_f32 v48, v0, v1
	v_cvt_pk_bf16_f32 v49, v2, v3
	v_cvt_pk_bf16_f32 v50, v4, v5
	v_cvt_pk_bf16_f32 v51, v6, v7
	v_cvt_pk_bf16_f32 v52, v8, v9
	v_cvt_pk_bf16_f32 v53, v10, v11
	v_cvt_pk_bf16_f32 v54, v12, v13
	v_cvt_pk_bf16_f32 v55, v14, v15
	s_waitcnt lgkmcnt(7)
	v_mfma_f32_16x16x32_bf16 v[32:35], v[112:115], v[48:51], v[32:35]
	s_waitcnt lgkmcnt(6)
	v_mfma_f32_16x16x32_bf16 v[36:39], v[116:119], v[48:51], v[36:39]
	s_waitcnt lgkmcnt(5)
	v_mfma_f32_16x16x32_bf16 v[40:43], v[120:123], v[48:51], v[40:43]
	s_waitcnt lgkmcnt(4)
	v_mfma_f32_16x16x32_bf16 v[44:47], v[124:127], v[48:51], v[44:47]
	s_waitcnt lgkmcnt(3)
	v_mfma_f32_16x16x32_bf16 v[32:35], v[128:131], v[52:55], v[32:35]
	s_waitcnt lgkmcnt(2)
	v_mfma_f32_16x16x32_bf16 v[36:39], v[132:135], v[52:55], v[36:39]
	s_waitcnt lgkmcnt(1)
	v_mfma_f32_16x16x32_bf16 v[40:43], v[136:139], v[52:55], v[40:43]
	s_waitcnt lgkmcnt(0)
; __device__ __forceinline__ void attn_phase(const Params& P, char* smem_raw) {
;     ...
;       f32x4 sacc[8];
; #pragma unroll
;       for (int t8 = 0; t8 < 8; ++t8) sacc[t8] = f32x4{0.f, 0.f, 0.f, 0.f};
; #pragma unroll
;       for (int s = 0; s < 2; ++s)
; #pragma unroll
;         for (int t8 = 0; t8 < 8; ++t8) {
;           const bf16x8 kf = *reinterpret_cast<const bf16x8*>(&sm_k[(t8 * 16 + (lane_c & 15)) * LDSS + s * 32 + (lane_c >> 4) * 8]);
;           sacc[t8] = __builtin_amdgcn_mfma_f32_16x16x32_bf16(qf[s], kf, sacc[t8], 0, 0, 0);
;         }
;       if (ck < 5) {
;         ATT_ISSUE(t, ck + 1)
;       } else if (t + VGRID < 8192) {
;         ATT_ISSUE(t + VGRID, 0)
;         ATT_QLOAD(t + VGRID)
;       }
;       if (ck < 4) {
;         const float* rb0 = sm_rpb + (rs + ck * 2 - r + 7) * 31;
; #pragma unroll
;         for (int t8 = 0; t8 < 8; ++t8)
; #pragma unroll
;           for (int reg = 0; reg < 4; ++reg)
;             sacc[t8][reg] += rb0[(t8 >> 2) * 31 + dco[reg][t8 & 3]];
;       }
; #pragma unroll
;       for (int reg = 0; reg < 4; ++reg) {
;         float mx = sacc[0][reg];
; #pragma unroll
;         for (int t8 = 1; t8 < 8; ++t8) mx = fmaxf(mx, sacc[t8][reg]);
;         mx = row16_max(mx);
;         const float mnew = fmaxf(mrow[reg], mx);
;         const float alpha = __builtin_amdgcn_exp2f(mrow[reg] - mnew);
;         mrow[reg] = mnew;
;         float rsum = 0.f;
; #pragma unroll
;         for (int t8 = 0; t8 < 8; ++t8) {
;           const float p = __builtin_amdgcn_exp2f(sacc[t8][reg] - mnew);
;           rsum += p;
;           sm_p[(wid * 16 + (lane_c >> 4) * 4 + reg) * 136 + t8 * 16 + (lane_c & 15)] = f2bf(p);
;         }
;         rsum = row16_sum(rsum);
;         lrow[reg] = lrow[reg] * alpha + rsum;
; #pragma unroll
;         for (int td = 0; td < 4; ++td) o[td][reg] *= alpha;
;       }
;       asm volatile("s_waitcnt lgkmcnt(0)" ::: "memory");
; #pragma unroll
;       for (int s4 = 0; s4 < 4; ++s4) {
;         const bf16x8 pf = *reinterpret_cast<const bf16x8*>(&sm_p[(wid * 16 + (lane_c & 15)) * 136 + s4 * 32 + (lane_c >> 4) * 8]);
; #pragma unroll
;         for (int td = 0; td < 4; ++td) {
;           const bf16x8 vf = *reinterpret_cast<const bf16x8*>(&sm_vt[(td * 16 + (lane_c & 15)) * 136 + s4 * 32 + (lane_c >> 4) * 8]);
;           o[td] = __builtin_amdgcn_mfma_f32_16x16x32_bf16(pf, vf, o[td], 0, 0, 0);
;         }
;       }
	v_mfma_f32_16x16x32_bf16 v[44:47], v[140:143], v[52:55], v[44:47]
	ds_read_b32 v0, v184 offset:1024
	ds_read_b32 v1, v185 offset:1024
	ds_read_b32 v2, v186 offset:1024
	ds_read_b32 v3, v187 offset:1024
	ds_read_b32 v4, v184 offset:1152
	ds_read_b32 v5, v185 offset:1152
	ds_read_b32 v6, v186 offset:1152
	ds_read_b32 v7, v187 offset:1152
	ds_read_b32 v8, v188 offset:1024
	ds_read_b32 v9, v189 offset:1024
	ds_read_b32 v10, v190 offset:1024
	ds_read_b32 v11, v191 offset:1024
	ds_read_b32 v12, v188 offset:1152
	ds_read_b32 v13, v189 offset:1152
	ds_read_b32 v14, v190 offset:1152
	ds_read_b32 v15, v191 offset:1152
	ds_read_b128 v[112:115], v144 offset:32768
	ds_read_b128 v[116:119], v145 offset:32768
	ds_read_b128 v[120:123], v144 offset:40960
	ds_read_b128 v[124:127], v145 offset:40960
	ds_read_b128 v[128:131], v144 offset:34816
	ds_read_b128 v[132:135], v145 offset:34816
	ds_read_b128 v[136:139], v144 offset:43008
	ds_read_b128 v[140:143], v145 offset:43008
	s_waitcnt lgkmcnt(7)
	v_mfma_f32_16x16x32_bf16 v[0:3], v[112:115], v[230:233], v[0:3]
	s_waitcnt lgkmcnt(6)
	v_mfma_f32_16x16x32_bf16 v[0:3], v[116:119], v[234:237], v[0:3]
	s_waitcnt lgkmcnt(5)
	v_mfma_f32_16x16x32_bf16 v[4:7], v[120:123], v[230:233], v[4:7]
	s_waitcnt lgkmcnt(4)
	v_mfma_f32_16x16x32_bf16 v[4:7], v[124:127], v[234:237], v[4:7]
	s_waitcnt lgkmcnt(3)
	v_mfma_f32_16x16x32_bf16 v[8:11], v[128:131], v[230:233], v[8:11]
	s_waitcnt lgkmcnt(2)
	v_mfma_f32_16x16x32_bf16 v[8:11], v[132:135], v[234:237], v[8:11]
	s_waitcnt lgkmcnt(1)
	v_mfma_f32_16x16x32_bf16 v[12:15], v[136:139], v[230:233], v[12:15]
	s_waitcnt lgkmcnt(0)
	v_mfma_f32_16x16x32_bf16 v[12:15], v[140:143], v[234:237], v[12:15]
	s_nop 7
	v_max3_f32 v203, v0, v1, v2
	v_max3_f32 v203, v203, v3, v4
	v_max3_f32 v203, v203, v5, v6
	v_max3_f32 v203, v203, v7, v8
	v_max3_f32 v203, v203, v9, v10
	v_max3_f32 v203, v203, v11, v12
	v_max3_f32 v203, v203, v13, v14
	v_max_f32_e32 v203, v203, v15
	v_mov_b32_e32 v205, v203
	s_nop 1
	v_permlane16_swap_b32_e32 v203, v205
	v_max_f32_e32 v203, v203, v205
	v_mov_b32_e32 v205, v203
	s_nop 1
	v_permlane32_swap_b32_e32 v203, v205
	v_max_f32_e32 v203, v203, v205
	v_max_f32_e32 v218, v246, v203
	v_sub_f32_e32 v220, v246, v218
	v_mov_b32_e32 v219, v218
	v_exp_f32_e32 v220, v220
	v_mov_b32_e32 v246, v218
	v_pk_add_f32 v[0:1], v[0:1], v[218:219] neg_lo:[0,1] neg_hi:[0,1]
	v_pk_add_f32 v[2:3], v[2:3], v[218:219] neg_lo:[0,1] neg_hi:[0,1]
	v_pk_add_f32 v[4:5], v[4:5], v[218:219] neg_lo:[0,1] neg_hi:[0,1]
	v_pk_add_f32 v[6:7], v[6:7], v[218:219] neg_lo:[0,1] neg_hi:[0,1]
	v_pk_add_f32 v[8:9], v[8:9], v[218:219] neg_lo:[0,1] neg_hi:[0,1]
	v_pk_add_f32 v[10:11], v[10:11], v[218:219] neg_lo:[0,1] neg_hi:[0,1]
	v_pk_add_f32 v[12:13], v[12:13], v[218:219] neg_lo:[0,1] neg_hi:[0,1]
	v_pk_add_f32 v[14:15], v[14:15], v[218:219] neg_lo:[0,1] neg_hi:[0,1]
	v_exp_f32_e32 v0, v0
	v_exp_f32_e32 v1, v1
	v_exp_f32_e32 v2, v2
	v_exp_f32_e32 v3, v3
	v_exp_f32_e32 v4, v4
	v_exp_f32_e32 v5, v5
	v_exp_f32_e32 v6, v6
	v_exp_f32_e32 v7, v7
	v_exp_f32_e32 v8, v8
	v_exp_f32_e32 v9, v9
	v_exp_f32_e32 v10, v10
	v_exp_f32_e32 v11, v11
	v_exp_f32_e32 v12, v12
	v_exp_f32_e32 v13, v13
	v_exp_f32_e32 v14, v14
	v_exp_f32_e32 v15, v15
	ds_read_b128 v[112:115], v146 offset:32768
	ds_read_b128 v[116:119], v146 offset:36864
	ds_read_b128 v[120:123], v146 offset:40960
	ds_read_b128 v[124:127], v146 offset:45056
	ds_read_b128 v[128:131], v147 offset:32768
	ds_read_b128 v[132:135], v147 offset:36864
	ds_read_b128 v[136:139], v147 offset:40960
	ds_read_b128 v[140:143], v147 offset:45056
	v_mov_b32_e32 v221, v220
	v_pk_add_f32 v[222:223], v[0:1], v[2:3]
	v_pk_add_f32 v[222:223], v[222:223], v[4:5]
	v_pk_add_f32 v[222:223], v[222:223], v[6:7]
	v_pk_add_f32 v[222:223], v[222:223], v[8:9]
	v_pk_add_f32 v[222:223], v[222:223], v[10:11]
	v_pk_add_f32 v[222:223], v[222:223], v[12:13]
	v_pk_add_f32 v[222:223], v[222:223], v[14:15]
	v_pk_mul_f32 v[176:177], v[176:177], v[220:221]
	v_pk_mul_f32 v[178:179], v[178:179], v[220:221]
	v_pk_mul_f32 v[180:181], v[180:181], v[220:221]
	v_pk_mul_f32 v[182:183], v[182:183], v[220:221]
	v_pk_mul_f32 v[192:193], v[192:193], v[220:221]
	v_pk_mul_f32 v[194:195], v[194:195], v[220:221]
	v_pk_mul_f32 v[196:197], v[196:197], v[220:221]
	v_pk_mul_f32 v[198:199], v[198:199], v[220:221]
	v_add_f32_e32 v203, v222, v223
	v_fma_f32 v247, v247, v220, v203
	v_cvt_pk_bf16_f32 v48, v0, v1
	v_cvt_pk_bf16_f32 v49, v2, v3
	v_cvt_pk_bf16_f32 v50, v4, v5
	v_cvt_pk_bf16_f32 v51, v6, v7
	v_cvt_pk_bf16_f32 v52, v8, v9
	v_cvt_pk_bf16_f32 v53, v10, v11
	v_cvt_pk_bf16_f32 v54, v12, v13
	v_cvt_pk_bf16_f32 v55, v14, v15
	s_waitcnt lgkmcnt(7)
	v_mfma_f32_16x16x32_bf16 v[176:179], v[112:115], v[48:51], v[176:179]
	s_waitcnt lgkmcnt(6)
	v_mfma_f32_16x16x32_bf16 v[180:183], v[116:119], v[48:51], v[180:183]
	s_waitcnt lgkmcnt(5)
	v_mfma_f32_16x16x32_bf16 v[192:195], v[120:123], v[48:51], v[192:195]
	s_waitcnt lgkmcnt(4)
	v_mfma_f32_16x16x32_bf16 v[196:199], v[124:127], v[48:51], v[196:199]
	s_waitcnt lgkmcnt(3)
	v_mfma_f32_16x16x32_bf16 v[176:179], v[128:131], v[52:55], v[176:179]
	s_waitcnt lgkmcnt(2)
	v_mfma_f32_16x16x32_bf16 v[180:183], v[132:135], v[52:55], v[180:183]
	s_waitcnt lgkmcnt(1)
	v_mfma_f32_16x16x32_bf16 v[192:195], v[136:139], v[52:55], v[192:195]
	s_waitcnt lgkmcnt(0)
	v_mfma_f32_16x16x32_bf16 v[196:199], v[140:143], v[52:55], v[196:199]
	s_waitcnt lgkmcnt(0)
	s_barrier
	s_cmp_eq_u32 s19, 0
	s_cbranch_scc1 .Lmy_att_s4_1
; __device__ __forceinline__ void attn_phase(const Params& P, char* smem_raw) {
;     ...
; #pragma unroll
;       for (int reg = 0; reg < 4; ++reg) {
;         float mx = sacc[0][reg];
; #pragma unroll
;         for (int t8 = 1; t8 < 8; ++t8) mx = fmaxf(mx, sacc[t8][reg]);
;         mx = row16_max(mx);
;         const float mnew = fmaxf(mrow[reg], mx);
;         const float alpha = __builtin_amdgcn_exp2f(mrow[reg] - mnew);
;         mrow[reg] = mnew;
;         float rsum = 0.f;
; #pragma unroll
;         for (int t8 = 0; t8 < 8; ++t8) {
;           const float p = __builtin_amdgcn_exp2f(sacc[t8][reg] - mnew);
;           rsum += p;
;           sm_p[(wid * 16 + (lane_c >> 4) * 4 + reg) * 136 + t8 * 16 + (lane_c & 15)] = f2bf(p);
;         }
;         rsum = row16_sum(rsum);
;         lrow[reg] = lrow[reg] * alpha + rsum;
; #pragma unroll
;         for (int td = 0; td < 4; ++td) o[td][reg] *= alpha;
;       }
;       asm volatile("s_waitcnt lgkmcnt(0)" ::: "memory");
; #pragma unroll
;       for (int s4 = 0; s4 < 4; ++s4) {
;         const bf16x8 pf = *reinterpret_cast<const bf16x8*>(&sm_p[(wid * 16 + (lane_c & 15)) * 136 + s4 * 32 + (lane_c >> 4) * 8]);
; #pragma unroll
;         for (int td = 0; td < 4; ++td) {
;           const bf16x8 vf = *reinterpret_cast<const bf16x8*>(&sm_vt[(td * 16 + (lane_c & 15)) * 136 + s4 * 32 + (lane_c >> 4) * 8]);
;           o[td] = __builtin_amdgcn_mfma_f32_16x16x32_bf16(pf, vf, o[td], 0, 0, 0);
;         }
;       }
	ds_read_b32 v0, v184 offset:1280
	ds_read_b32 v1, v185 offset:1280
	ds_read_b32 v2, v186 offset:1280
	ds_read_b32 v3, v187 offset:1280
	ds_read_b32 v8, v188 offset:1280
	ds_read_b32 v9, v189 offset:1280
	ds_read_b32 v10, v190 offset:1280
	ds_read_b32 v11, v191 offset:1280
	v_mov_b32_e32 v4, 0xf149f2ca
	v_mov_b32_e32 v5, 0xf149f2ca
	v_mov_b32_e32 v6, 0xf149f2ca
	v_mov_b32_e32 v7, 0xf149f2ca
	v_mov_b32_e32 v12, 0xf149f2ca
	v_mov_b32_e32 v13, 0xf149f2ca
	v_mov_b32_e32 v14, 0xf149f2ca
	v_mov_b32_e32 v15, 0xf149f2ca
	ds_read_b128 v[112:115], v144 offset:0
	ds_read_b128 v[116:119], v145 offset:0
	ds_read_b128 v[120:123], v144 offset:8192
	ds_read_b128 v[124:127], v145 offset:8192
	ds_read_b128 v[128:131], v144 offset:2048
	ds_read_b128 v[132:135], v145 offset:2048
	ds_read_b128 v[136:139], v144 offset:10240
	ds_read_b128 v[140:143], v145 offset:10240
	s_waitcnt lgkmcnt(7)
	v_mfma_f32_16x16x32_bf16 v[0:3], v[112:115], v[230:233], v[0:3]
	s_waitcnt lgkmcnt(6)
	v_mfma_f32_16x16x32_bf16 v[0:3], v[116:119], v[234:237], v[0:3]
	s_waitcnt lgkmcnt(5)
	v_mfma_f32_16x16x32_bf16 v[4:7], v[120:123], v[230:233], v[4:7]
	s_waitcnt lgkmcnt(4)
	v_mfma_f32_16x16x32_bf16 v[4:7], v[124:127], v[234:237], v[4:7]
	s_waitcnt lgkmcnt(3)
	v_mfma_f32_16x16x32_bf16 v[8:11], v[128:131], v[230:233], v[8:11]
	s_waitcnt lgkmcnt(2)
	v_mfma_f32_16x16x32_bf16 v[8:11], v[132:135], v[234:237], v[8:11]
	s_waitcnt lgkmcnt(1)
	v_mfma_f32_16x16x32_bf16 v[12:15], v[136:139], v[230:233], v[12:15]
	s_waitcnt lgkmcnt(0)
	v_mfma_f32_16x16x32_bf16 v[12:15], v[140:143], v[234:237], v[12:15]
	s_nop 7
	v_max3_f32 v203, v0, v1, v2
	v_max3_f32 v203, v203, v3, v4
	v_max3_f32 v203, v203, v5, v6
	v_max3_f32 v203, v203, v7, v8
	v_max3_f32 v203, v203, v9, v10
	v_max3_f32 v203, v203, v11, v12
	v_max3_f32 v203, v203, v13, v14
	v_max_f32_e32 v203, v203, v15
	v_mov_b32_e32 v205, v203
	s_nop 1
	v_permlane16_swap_b32_e32 v203, v205
	v_max_f32_e32 v203, v203, v205
	v_mov_b32_e32 v205, v203
	s_nop 1
	v_permlane32_swap_b32_e32 v203, v205
	v_max_f32_e32 v203, v203, v205
	v_max_f32_e32 v218, v246, v203
	v_sub_f32_e32 v220, v246, v218
	v_mov_b32_e32 v219, v218
	v_exp_f32_e32 v220, v220
	v_mov_b32_e32 v246, v218
	v_pk_add_f32 v[0:1], v[0:1], v[218:219] neg_lo:[0,1] neg_hi:[0,1]
	v_pk_add_f32 v[2:3], v[2:3], v[218:219] neg_lo:[0,1] neg_hi:[0,1]
	v_pk_add_f32 v[4:5], v[4:5], v[218:219] neg_lo:[0,1] neg_hi:[0,1]
	v_pk_add_f32 v[6:7], v[6:7], v[218:219] neg_lo:[0,1] neg_hi:[0,1]
	v_pk_add_f32 v[8:9], v[8:9], v[218:219] neg_lo:[0,1] neg_hi:[0,1]
	v_pk_add_f32 v[10:11], v[10:11], v[218:219] neg_lo:[0,1] neg_hi:[0,1]
	v_pk_add_f32 v[12:13], v[12:13], v[218:219] neg_lo:[0,1] neg_hi:[0,1]
	v_pk_add_f32 v[14:15], v[14:15], v[218:219] neg_lo:[0,1] neg_hi:[0,1]
	v_exp_f32_e32 v0, v0
	s_waitcnt vmcnt(0)
	v_exp_f32_e32 v1, v1
	ds_write_b128 v150, v[80:83] offset:32768
	v_exp_f32_e32 v2, v2
	ds_write_b128 v150, v[84:87] offset:36864
	v_exp_f32_e32 v3, v3
	ds_write_b128 v150, v[88:91] offset:40960
	v_exp_f32_e32 v4, v4
	ds_write_b128 v150, v[92:95] offset:45056
	v_exp_f32_e32 v5, v5
	ds_write_b64 v151, v[96:97] offset:32768
	v_exp_f32_e32 v6, v6
	ds_write_b64 v229, v[98:99] offset:32768
	v_exp_f32_e32 v7, v7
	ds_write_b64 v151, v[100:101] offset:36864
	v_exp_f32_e32 v8, v8
	ds_write_b64 v229, v[102:103] offset:36864
	v_exp_f32_e32 v9, v9
	ds_write_b64 v151, v[104:105] offset:40960
	v_exp_f32_e32 v10, v10
	ds_write_b64 v229, v[106:107] offset:40960
	v_exp_f32_e32 v11, v11
	ds_write_b64 v151, v[108:109] offset:45056
	v_exp_f32_e32 v12, v12
	ds_write_b64 v229, v[110:111] offset:45056
	v_exp_f32_e32 v13, v13
	s_add_u32 s100, s16, 0xc0000
	v_exp_f32_e32 v14, v14
	s_addc_u32 s101, s17, 0
	v_exp_f32_e32 v15, v15
	s_add_u32 s0, s36, 0x100
	s_addc_u32 s1, s37, 0
	global_load_dwordx4 v[80:83], v154, s[100:101] offset:2048
	global_load_dwordx4 v[96:99], v162, s[0:1]
	global_load_dwordx4 v[84:87], v155, s[100:101] offset:2048
	global_load_dwordx4 v[100:103], v163, s[0:1]
	global_load_dwordx4 v[88:91], v156, s[100:101] offset:2048
	global_load_dwordx4 v[104:107], v164, s[0:1]
	global_load_dwordx4 v[92:95], v157, s[100:101] offset:2048
	global_load_dwordx4 v[108:111], v165, s[0:1]
	s_and_b32 s0, s3, 0xff
	s_add_u32 s0, s0, 1
	s_min_u32 s0, s0, 7
	s_lshr_b32 s1, s0, 1
	s_and_b32 s0, s0, 1
	s_lshl_b32 s0, s0, 5
	s_lshr_b32 vcc_lo, s3, 12
	s_add_u32 s0, s0, vcc_lo
	s_lshl_b32 s0, s0, 1
	s_sub_i32 vcc_lo, s0, 4
	s_max_i32 vcc_lo, vcc_lo, 0
	s_min_i32 vcc_lo, vcc_lo, 0x78
	s_lshl_b32 vcc_hi, s1, 13
	s_add_u32 s20, vcc_lo, 8
	s_min_u32 s20, s20, 0x7e
	s_sub_u32 s20, s20, vcc_lo
	s_lshl_b32 s21, s20, 7
	s_mul_i32 s20, s20, 0x60000
	s_lshl_b32 m0, vcc_lo, 6
	s_add_u32 m0, m0, vcc_hi
	s_mul_i32 m0, m0, 0x1800
	s_add_u32 s12, s4, m0
	s_addc_u32 s13, s5, 0
	s_lshl_b32 m0, s1, 24
	s_lshl_b32 s100, vcc_lo, 7
	s_add_u32 m0, m0, s100
	s_add_u32 s14, s6, m0
	s_addc_u32 s15, s7, 0
	s_lshl_b32 m0, s0, 6
	s_add_u32 m0, m0, vcc_hi
	s_mul_i32 m0, m0, 0x1800
	s_add_u32 s100, s4, m0
	s_addc_u32 s101, s5, 0
	global_load_dwordx4 v[72:75], v166, s[100:101]
	global_load_dwordx4 v[76:79], v166, s[100:101] offset:64
	s_add_u32 s100, s100, 0x60000
	s_addc_u32 s101, s101, 0
	global_load_dwordx4 v[238:241], v166, s[100:101]
	global_load_dwordx4 v[242:245], v166, s[100:101] offset:64
	ds_read_b128 v[112:115], v146 offset:0
	ds_read_b128 v[116:119], v146 offset:4096
	ds_read_b128 v[120:123], v146 offset:8192
	ds_read_b128 v[124:127], v146 offset:12288
	ds_read_b128 v[128:131], v147 offset:0
	ds_read_b128 v[132:135], v147 offset:4096
	ds_read_b128 v[136:139], v147 offset:8192
	ds_read_b128 v[140:143], v147 offset:12288
	v_mov_b32_e32 v221, v220
	v_pk_add_f32 v[222:223], v[0:1], v[2:3]
	v_pk_add_f32 v[222:223], v[222:223], v[4:5]
	v_pk_add_f32 v[222:223], v[222:223], v[6:7]
	v_pk_add_f32 v[222:223], v[222:223], v[8:9]
	v_pk_add_f32 v[222:223], v[222:223], v[10:11]
	v_pk_add_f32 v[222:223], v[222:223], v[12:13]
	v_pk_add_f32 v[222:223], v[222:223], v[14:15]
	v_pk_mul_f32 v[176:177], v[176:177], v[220:221]
	v_pk_mul_f32 v[178:179], v[178:179], v[220:221]
	v_pk_mul_f32 v[180:181], v[180:181], v[220:221]
	v_pk_mul_f32 v[182:183], v[182:183], v[220:221]
	v_pk_mul_f32 v[192:193], v[192:193], v[220:221]
	v_pk_mul_f32 v[194:195], v[194:195], v[220:221]
	v_pk_mul_f32 v[196:197], v[196:197], v[220:221]
	v_pk_mul_f32 v[198:199], v[198:199], v[220:221]
	v_add_f32_e32 v203, v222, v223
	v_fma_f32 v247, v247, v220, v203
	v_cvt_pk_bf16_f32 v48, v0, v1
	v_cvt_pk_bf16_f32 v49, v2, v3
	v_cvt_pk_bf16_f32 v50, v4, v5
	v_cvt_pk_bf16_f32 v51, v6, v7
	v_cvt_pk_bf16_f32 v52, v8, v9
	v_cvt_pk_bf16_f32 v53, v10, v11
	v_cvt_pk_bf16_f32 v54, v12, v13
	v_cvt_pk_bf16_f32 v55, v14, v15
	s_waitcnt lgkmcnt(7)
; __device__ __forceinline__ void attn_phase(const Params& P, char* smem_raw) {
;     ...
;     for (int ck = 0; ck < 6; ++ck) {
;       int lane_c = lane;
;       asm volatile("" : "+v"(lane_c));
;       __syncthreads();
; #pragma unroll
;       for (int i = 0; i < 4; ++i) {
;         const int idx = tid + 256 * i;
;         *reinterpret_cast<uint4*>(&sm_k[(idx >> 3) * LDSS + (idx & 7) * 8]) = kreg[i];
;         *reinterpret_cast<uint4*>(&sm_vt[(idx >> 4) * 136 + (idx & 15) * 8]) = vreg[i];
;       }
;       __syncthreads();
;       f32x4 sacc[8];
; #pragma unroll
;       for (int t8 = 0; t8 < 8; ++t8) sacc[t8] = f32x4{0.f, 0.f, 0.f, 0.f};
; #pragma unroll
;       for (int s = 0; s < 2; ++s)
; #pragma unroll
;         for (int t8 = 0; t8 < 8; ++t8) {
;           const bf16x8 kf = *reinterpret_cast<const bf16x8*>(&sm_k[(t8 * 16 + (lane_c & 15)) * LDSS + s * 32 + (lane_c >> 4) * 8]);
;           sacc[t8] = __builtin_amdgcn_mfma_f32_16x16x32_bf16(qf[s], kf, sacc[t8], 0, 0, 0);
;         }
;       if (ck < 5) {
;         ATT_ISSUE(t, ck + 1)
;       } else if (t + VGRID < 8192) {
;         ATT_ISSUE(t + VGRID, 0)
;         ATT_QLOAD(t + VGRID)
;       }
	v_mfma_f32_16x16x32_bf16 v[176:179], v[112:115], v[48:51], v[176:179]
	s_waitcnt lgkmcnt(6)
	v_mfma_f32_16x16x32_bf16 v[180:183], v[116:119], v[48:51], v[180:183]
	s_waitcnt lgkmcnt(5)
	v_mfma_f32_16x16x32_bf16 v[192:195], v[120:123], v[48:51], v[192:195]
	s_waitcnt lgkmcnt(4)
	v_mfma_f32_16x16x32_bf16 v[196:199], v[124:127], v[48:51], v[196:199]
	s_waitcnt lgkmcnt(3)
	v_mfma_f32_16x16x32_bf16 v[176:179], v[128:131], v[52:55], v[176:179]
	s_waitcnt lgkmcnt(2)
	v_mfma_f32_16x16x32_bf16 v[180:183], v[132:135], v[52:55], v[180:183]
	s_waitcnt lgkmcnt(1)
	v_mfma_f32_16x16x32_bf16 v[192:195], v[136:139], v[52:55], v[192:195]
	s_waitcnt lgkmcnt(0)
	v_mfma_f32_16x16x32_bf16 v[196:199], v[140:143], v[52:55], v[196:199]
	s_branch .Lmy_att_e4_1
.Lmy_att_s4_1:
	s_waitcnt vmcnt(0)
	ds_write_b128 v150, v[80:83] offset:32768
	ds_write_b128 v150, v[84:87] offset:36864
	ds_write_b128 v150, v[88:91] offset:40960
	ds_write_b128 v150, v[92:95] offset:45056
	ds_write_b64 v151, v[96:97] offset:32768
	ds_write_b64 v229, v[98:99] offset:32768
	ds_write_b64 v151, v[100:101] offset:36864
	ds_write_b64 v229, v[102:103] offset:36864
	ds_write_b64 v151, v[104:105] offset:40960
	ds_write_b64 v229, v[106:107] offset:40960
	ds_write_b64 v151, v[108:109] offset:45056
	ds_write_b64 v229, v[110:111] offset:45056
	s_add_u32 s100, s16, 0xc0000
	s_addc_u32 s101, s17, 0
	s_add_u32 s0, s36, 0x100
	s_addc_u32 s1, s37, 0
	global_load_dwordx4 v[80:83], v154, s[100:101] offset:2048
	global_load_dwordx4 v[96:99], v162, s[0:1]
	global_load_dwordx4 v[84:87], v155, s[100:101] offset:2048
	global_load_dwordx4 v[100:103], v163, s[0:1]
	global_load_dwordx4 v[88:91], v156, s[100:101] offset:2048
	global_load_dwordx4 v[104:107], v164, s[0:1]
	global_load_dwordx4 v[92:95], v157, s[100:101] offset:2048
	global_load_dwordx4 v[108:111], v165, s[0:1]
	s_and_b32 s0, s3, 0xff
	s_add_u32 s0, s0, 1
	s_min_u32 s0, s0, 7
	s_lshr_b32 s1, s0, 1
	s_and_b32 s0, s0, 1
	s_lshl_b32 s0, s0, 5
	s_lshr_b32 vcc_lo, s3, 12
	s_add_u32 s0, s0, vcc_lo
	s_lshl_b32 s0, s0, 1
	s_sub_i32 vcc_lo, s0, 4
	s_max_i32 vcc_lo, vcc_lo, 0
	s_min_i32 vcc_lo, vcc_lo, 0x78
	s_lshl_b32 vcc_hi, s1, 13
	s_add_u32 s20, vcc_lo, 8
	s_min_u32 s20, s20, 0x7e
	s_sub_u32 s20, s20, vcc_lo
	s_lshl_b32 s21, s20, 7
	s_mul_i32 s20, s20, 0x60000
	s_lshl_b32 m0, vcc_lo, 6
	s_add_u32 m0, m0, vcc_hi
	s_mul_i32 m0, m0, 0x1800
	s_add_u32 s12, s4, m0
	s_addc_u32 s13, s5, 0
	s_lshl_b32 m0, s1, 24
	s_lshl_b32 s100, vcc_lo, 7
	s_add_u32 m0, m0, s100
	s_add_u32 s14, s6, m0
	s_addc_u32 s15, s7, 0
	s_lshl_b32 m0, s0, 6
	s_add_u32 m0, m0, vcc_hi
	s_mul_i32 m0, m0, 0x1800
	s_add_u32 s100, s4, m0
	s_addc_u32 s101, s5, 0
	global_load_dwordx4 v[72:75], v166, s[100:101]
	global_load_dwordx4 v[76:79], v166, s[100:101] offset:64
	s_add_u32 s100, s100, 0x60000
	s_addc_u32 s101, s101, 0
	global_load_dwordx4 v[238:241], v166, s[100:101]
	global_load_dwordx4 v[242:245], v166, s[100:101] offset:64
.Lmy_att_e4_1:
	s_waitcnt lgkmcnt(0)
	s_barrier
	ds_read_b128 v[112:115], v149 offset:32768
	ds_read_b128 v[116:119], v224 offset:32768
	ds_read_b128 v[120:123], v149 offset:40960
	ds_read_b128 v[124:127], v224 offset:40960
	ds_read_b128 v[128:131], v149 offset:34816
	ds_read_b128 v[132:135], v224 offset:34816
	ds_read_b128 v[136:139], v149 offset:43008
	ds_read_b128 v[140:143], v224 offset:43008
	s_waitcnt lgkmcnt(7)
	v_mfma_f32_16x16x32_bf16 v[0:3], v[112:115], v[64:67], 0
	ds_read_b128 v[112:115], v149 offset:36864
	s_waitcnt lgkmcnt(7)
	v_mfma_f32_16x16x32_bf16 v[0:3], v[116:119], v[68:71], v[0:3]
	ds_read_b128 v[116:119], v224 offset:36864
	s_waitcnt lgkmcnt(7)
	v_mfma_f32_16x16x32_bf16 v[4:7], v[120:123], v[64:67], 0
	ds_read_b128 v[120:123], v149 offset:45056
	s_waitcnt lgkmcnt(7)
	v_mfma_f32_16x16x32_bf16 v[4:7], v[124:127], v[68:71], v[4:7]
	ds_read_b128 v[124:127], v224 offset:45056
	s_waitcnt lgkmcnt(7)
	v_mfma_f32_16x16x32_bf16 v[8:11], v[128:131], v[64:67], 0
	ds_read_b128 v[128:131], v149 offset:38912
	s_waitcnt lgkmcnt(7)
	v_mfma_f32_16x16x32_bf16 v[8:11], v[132:135], v[68:71], v[8:11]
	ds_read_b128 v[132:135], v224 offset:38912
	s_waitcnt lgkmcnt(7)
	v_mfma_f32_16x16x32_bf16 v[12:15], v[136:139], v[64:67], 0
	ds_read_b128 v[136:139], v149 offset:47104
	s_waitcnt lgkmcnt(7)
	v_mfma_f32_16x16x32_bf16 v[12:15], v[140:143], v[68:71], v[12:15]
	ds_read_b128 v[140:143], v224 offset:47104
	s_waitcnt lgkmcnt(7)
	v_mfma_f32_16x16x32_bf16 v[16:19], v[112:115], v[64:67], 0
	s_waitcnt lgkmcnt(6)
	v_mfma_f32_16x16x32_bf16 v[16:19], v[116:119], v[68:71], v[16:19]
	s_waitcnt lgkmcnt(5)
	v_mfma_f32_16x16x32_bf16 v[20:23], v[120:123], v[64:67], 0
	s_waitcnt lgkmcnt(4)
	v_mfma_f32_16x16x32_bf16 v[20:23], v[124:127], v[68:71], v[20:23]
	s_waitcnt lgkmcnt(3)
	v_mfma_f32_16x16x32_bf16 v[24:27], v[128:131], v[64:67], 0
	s_waitcnt lgkmcnt(2)
	v_mfma_f32_16x16x32_bf16 v[24:27], v[132:135], v[68:71], v[24:27]
	s_waitcnt lgkmcnt(1)
	v_mfma_f32_16x16x32_bf16 v[28:31], v[136:139], v[64:67], 0
	s_waitcnt lgkmcnt(0)
; __device__ __forceinline__ void attn_phase(const Params& P, char* smem_raw) {
;     ...
;       if (ck < 4) {
;         const float* rb0 = sm_rpb + (rs + ck * 2 - r + 7) * 31;
; #pragma unroll
;         for (int t8 = 0; t8 < 8; ++t8)
; #pragma unroll
;           for (int reg = 0; reg < 4; ++reg)
;             sacc[t8][reg] += rb0[(t8 >> 2) * 31 + dco[reg][t8 & 3]];
;       }
; #pragma unroll
;       for (int reg = 0; reg < 4; ++reg) {
;         float mx = sacc[0][reg];
; #pragma unroll
;         for (int t8 = 1; t8 < 8; ++t8) mx = fmaxf(mx, sacc[t8][reg]);
;         mx = row16_max(mx);
;         const float mnew = fmaxf(mrow[reg], mx);
;         const float alpha = __builtin_amdgcn_exp2f(mrow[reg] - mnew);
;         mrow[reg] = mnew;
;         float rsum = 0.f;
; #pragma unroll
;         for (int t8 = 0; t8 < 8; ++t8) {
;           const float p = __builtin_amdgcn_exp2f(sacc[t8][reg] - mnew);
;           rsum += p;
;           sm_p[(wid * 16 + (lane_c >> 4) * 4 + reg) * 136 + t8 * 16 + (lane_c & 15)] = f2bf(p);
;         }
;         rsum = row16_sum(rsum);
;         lrow[reg] = lrow[reg] * alpha + rsum;
; #pragma unroll
;         for (int td = 0; td < 4; ++td) o[td][reg] *= alpha;
;       }
;       asm volatile("s_waitcnt lgkmcnt(0)" ::: "memory");
; #pragma unroll
;       for (int s4 = 0; s4 < 4; ++s4) {
;         const bf16x8 pf = *reinterpret_cast<const bf16x8*>(&sm_p[(wid * 16 + (lane_c & 15)) * 136 + s4 * 32 + (lane_c >> 4) * 8]);
; #pragma unroll
;         for (int td = 0; td < 4; ++td) {
;           const bf16x8 vf = *reinterpret_cast<const bf16x8*>(&sm_vt[(td * 16 + (lane_c & 15)) * 136 + s4 * 32 + (lane_c >> 4) * 8]);
;           o[td] = __builtin_amdgcn_mfma_f32_16x16x32_bf16(pf, vf, o[td], 0, 0, 0);
;         }
;       }
	v_mfma_f32_16x16x32_bf16 v[28:31], v[140:143], v[68:71], v[28:31]
	s_nop 7
	v_max3_f32 v203, v0, v1, v2
	v_max3_f32 v203, v203, v3, v4
	v_max3_f32 v203, v203, v5, v6
	v_max3_f32 v203, v203, v7, v8
	v_max3_f32 v203, v203, v9, v10
	v_max3_f32 v203, v203, v11, v12
	v_max3_f32 v203, v203, v13, v14
	v_max3_f32 v203, v203, v15, v16
	v_max3_f32 v203, v203, v17, v18
	v_max3_f32 v203, v203, v19, v20
	v_max3_f32 v203, v203, v21, v22
	v_max3_f32 v203, v203, v23, v24
	v_max3_f32 v203, v203, v25, v26
	v_max3_f32 v203, v203, v27, v28
	v_max3_f32 v203, v203, v29, v30
	v_max_f32_e32 v203, v203, v31
	v_mov_b32_e32 v205, v203
	s_nop 1
	v_permlane16_swap_b32_e32 v203, v205
	v_max_f32_e32 v203, v203, v205
	v_mov_b32_e32 v205, v203
	s_nop 1
	v_permlane32_swap_b32_e32 v203, v205
	v_max_f32_e32 v203, v203, v205
	v_max_f32_e32 v218, v200, v203
	v_sub_f32_e32 v220, v200, v218
	v_mov_b32_e32 v219, v218
	v_exp_f32_e32 v220, v220
	v_mov_b32_e32 v200, v218
	v_pk_add_f32 v[0:1], v[0:1], v[218:219] neg_lo:[0,1] neg_hi:[0,1]
	v_pk_add_f32 v[2:3], v[2:3], v[218:219] neg_lo:[0,1] neg_hi:[0,1]
	v_pk_add_f32 v[4:5], v[4:5], v[218:219] neg_lo:[0,1] neg_hi:[0,1]
	v_pk_add_f32 v[6:7], v[6:7], v[218:219] neg_lo:[0,1] neg_hi:[0,1]
	v_pk_add_f32 v[8:9], v[8:9], v[218:219] neg_lo:[0,1] neg_hi:[0,1]
	v_pk_add_f32 v[10:11], v[10:11], v[218:219] neg_lo:[0,1] neg_hi:[0,1]
	v_pk_add_f32 v[12:13], v[12:13], v[218:219] neg_lo:[0,1] neg_hi:[0,1]
	v_pk_add_f32 v[14:15], v[14:15], v[218:219] neg_lo:[0,1] neg_hi:[0,1]
	v_pk_add_f32 v[16:17], v[16:17], v[218:219] neg_lo:[0,1] neg_hi:[0,1]
	v_pk_add_f32 v[18:19], v[18:19], v[218:219] neg_lo:[0,1] neg_hi:[0,1]
	v_pk_add_f32 v[20:21], v[20:21], v[218:219] neg_lo:[0,1] neg_hi:[0,1]
	v_pk_add_f32 v[22:23], v[22:23], v[218:219] neg_lo:[0,1] neg_hi:[0,1]
	v_pk_add_f32 v[24:25], v[24:25], v[218:219] neg_lo:[0,1] neg_hi:[0,1]
	v_pk_add_f32 v[26:27], v[26:27], v[218:219] neg_lo:[0,1] neg_hi:[0,1]
	v_pk_add_f32 v[28:29], v[28:29], v[218:219] neg_lo:[0,1] neg_hi:[0,1]
	v_pk_add_f32 v[30:31], v[30:31], v[218:219] neg_lo:[0,1] neg_hi:[0,1]
	v_exp_f32_e32 v0, v0
	s_waitcnt vmcnt(4)
	v_exp_f32_e32 v1, v1
	ds_write_b128 v150, v[80:83] offset:0
	v_exp_f32_e32 v2, v2
	ds_write_b128 v150, v[84:87] offset:4096
	v_exp_f32_e32 v3, v3
	ds_write_b128 v150, v[88:91] offset:8192
	v_exp_f32_e32 v4, v4
	ds_write_b128 v150, v[92:95] offset:12288
	v_exp_f32_e32 v5, v5
	ds_write_b64 v151, v[96:97] offset:0
	v_exp_f32_e32 v6, v6
	ds_write_b64 v229, v[98:99] offset:0
	v_exp_f32_e32 v7, v7
	ds_write_b64 v151, v[100:101] offset:4096
	v_exp_f32_e32 v8, v8
	ds_write_b64 v229, v[102:103] offset:4096
	v_exp_f32_e32 v9, v9
	ds_write_b64 v151, v[104:105] offset:8192
	v_exp_f32_e32 v10, v10
	ds_write_b64 v229, v[106:107] offset:8192
	v_exp_f32_e32 v11, v11
	ds_write_b64 v151, v[108:109] offset:12288
	v_exp_f32_e32 v12, v12
	ds_write_b64 v229, v[110:111] offset:12288
	v_exp_f32_e32 v13, v13
	s_add_u32 s100, s12, 0x0
	v_exp_f32_e32 v14, v14
	s_addc_u32 s101, s13, 0
	v_exp_f32_e32 v15, v15
	s_add_u32 s0, s14, 0x0
	v_exp_f32_e32 v16, v16
	s_addc_u32 s1, s15, 0
	v_exp_f32_e32 v17, v17
	global_load_dwordx4 v[80:83], v154, s[100:101] offset:2048
	v_exp_f32_e32 v18, v18
	global_load_dwordx4 v[96:99], v158, s[0:1]
	v_exp_f32_e32 v19, v19
	global_load_dwordx4 v[84:87], v155, s[100:101] offset:2048
	v_exp_f32_e32 v20, v20
	global_load_dwordx4 v[100:103], v159, s[0:1]
	v_exp_f32_e32 v21, v21
	global_load_dwordx4 v[88:91], v156, s[100:101] offset:2048
	v_exp_f32_e32 v22, v22
	global_load_dwordx4 v[104:107], v160, s[0:1]
	v_exp_f32_e32 v23, v23
	global_load_dwordx4 v[92:95], v157, s[100:101] offset:2048
	v_exp_f32_e32 v24, v24
	global_load_dwordx4 v[108:111], v161, s[0:1]
	v_exp_f32_e32 v25, v25
	v_exp_f32_e32 v26, v26
	v_exp_f32_e32 v27, v27
	v_exp_f32_e32 v28, v28
	v_exp_f32_e32 v29, v29
	v_exp_f32_e32 v30, v30
	v_exp_f32_e32 v31, v31
	s_and_b32 s0, s3, 0xff
	s_add_u32 s0, s0, 1
	s_min_u32 s0, s0, 7
	s_lshr_b32 s1, s0, 1
	s_and_b32 s0, s0, 1
	s_lshl_b32 s0, s0, 5
	s_lshr_b32 vcc_lo, s3, 12
	s_add_u32 s0, s0, vcc_lo
	s_lshl_b32 s0, s0, 1
	s_sub_i32 vcc_lo, s0, 4
	s_max_i32 vcc_lo, vcc_lo, 0
	s_min_i32 vcc_lo, vcc_lo, 0x78
	s_lshl_b32 vcc_hi, s1, 13
	s_sub_i32 vcc_lo, vcc_lo, s0
	s_add_i32 vcc_lo, vcc_lo, 4
	s_lshl_b32 vcc_lo, vcc_lo, 7
	s_bfe_u32 m0, s3, 0x10008
	s_mul_i32 m0, m0, 0x12000
	s_add_i32 vcc_lo, vcc_lo, m0
	s_add_i32 vcc_lo, vcc_lo, 0x10010
	v_add_u32_e32 v184, vcc_lo, v168
	v_add_u32_e32 v185, vcc_lo, v169
	v_add_u32_e32 v186, vcc_lo, v170
	v_add_u32_e32 v187, vcc_lo, v171
	v_add_u32_e32 v188, vcc_lo, v172
	v_add_u32_e32 v189, vcc_lo, v173
	v_add_u32_e32 v190, vcc_lo, v174
	v_add_u32_e32 v191, vcc_lo, v175
	ds_read_b128 v[112:115], v225 offset:32768
	ds_read_b128 v[116:119], v225 offset:36864
	ds_read_b128 v[120:123], v225 offset:40960
	ds_read_b128 v[124:127], v225 offset:45056
	ds_read_b128 v[128:131], v226 offset:32768
	ds_read_b128 v[132:135], v226 offset:36864
	ds_read_b128 v[136:139], v226 offset:40960
	ds_read_b128 v[140:143], v226 offset:45056
	v_mov_b32_e32 v221, v220
	v_pk_add_f32 v[222:223], v[0:1], v[2:3]
	v_pk_add_f32 v[222:223], v[222:223], v[4:5]
	v_pk_add_f32 v[222:223], v[222:223], v[6:7]
	v_pk_add_f32 v[222:223], v[222:223], v[8:9]
	v_pk_add_f32 v[222:223], v[222:223], v[10:11]
	v_pk_add_f32 v[222:223], v[222:223], v[12:13]
	v_pk_add_f32 v[222:223], v[222:223], v[14:15]
	v_pk_add_f32 v[222:223], v[222:223], v[16:17]
	v_pk_add_f32 v[222:223], v[222:223], v[18:19]
	v_pk_add_f32 v[222:223], v[222:223], v[20:21]
	v_pk_add_f32 v[222:223], v[222:223], v[22:23]
	v_pk_add_f32 v[222:223], v[222:223], v[24:25]
	v_pk_add_f32 v[222:223], v[222:223], v[26:27]
	v_pk_add_f32 v[222:223], v[222:223], v[28:29]
	v_pk_add_f32 v[222:223], v[222:223], v[30:31]
	v_pk_mul_f32 v[32:33], v[32:33], v[220:221]
	v_pk_mul_f32 v[34:35], v[34:35], v[220:221]
	v_pk_mul_f32 v[36:37], v[36:37], v[220:221]
	v_pk_mul_f32 v[38:39], v[38:39], v[220:221]
	v_pk_mul_f32 v[40:41], v[40:41], v[220:221]
	v_pk_mul_f32 v[42:43], v[42:43], v[220:221]
	v_pk_mul_f32 v[44:45], v[44:45], v[220:221]
	v_pk_mul_f32 v[46:47], v[46:47], v[220:221]
	v_add_f32_e32 v203, v222, v223
	v_fma_f32 v201, v201, v220, v203
	v_cvt_pk_bf16_f32 v48, v0, v1
	v_cvt_pk_bf16_f32 v49, v2, v3
	v_cvt_pk_bf16_f32 v50, v4, v5
	v_cvt_pk_bf16_f32 v51, v6, v7
	v_cvt_pk_bf16_f32 v52, v8, v9
	v_cvt_pk_bf16_f32 v53, v10, v11
	v_cvt_pk_bf16_f32 v54, v12, v13
	v_cvt_pk_bf16_f32 v55, v14, v15
	v_cvt_pk_bf16_f32 v56, v16, v17
	v_cvt_pk_bf16_f32 v57, v18, v19
	v_cvt_pk_bf16_f32 v58, v20, v21
	v_cvt_pk_bf16_f32 v59, v22, v23
	v_cvt_pk_bf16_f32 v60, v24, v25
	v_cvt_pk_bf16_f32 v61, v26, v27
	v_cvt_pk_bf16_f32 v62, v28, v29
	v_cvt_pk_bf16_f32 v63, v30, v31
	s_waitcnt lgkmcnt(7)
; __device__ __forceinline__ void attn_phase(const Params& P, char* smem_raw) {
;     ...
; #pragma unroll
;       for (int reg = 0; reg < 4; ++reg) {
;         float mx = sacc[0][reg];
; #pragma unroll
;         for (int t8 = 1; t8 < 8; ++t8) mx = fmaxf(mx, sacc[t8][reg]);
;         mx = row16_max(mx);
;         const float mnew = fmaxf(mrow[reg], mx);
;         const float alpha = __builtin_amdgcn_exp2f(mrow[reg] - mnew);
;         mrow[reg] = mnew;
;         float rsum = 0.f;
; #pragma unroll
;         for (int t8 = 0; t8 < 8; ++t8) {
;           const float p = __builtin_amdgcn_exp2f(sacc[t8][reg] - mnew);
;           rsum += p;
;           sm_p[(wid * 16 + (lane_c >> 4) * 4 + reg) * 136 + t8 * 16 + (lane_c & 15)] = f2bf(p);
;         }
;         rsum = row16_sum(rsum);
;         lrow[reg] = lrow[reg] * alpha + rsum;
; #pragma unroll
;         for (int td = 0; td < 4; ++td) o[td][reg] *= alpha;
;       }
;       asm volatile("s_waitcnt lgkmcnt(0)" ::: "memory");
; #pragma unroll
;       for (int s4 = 0; s4 < 4; ++s4) {
;         const bf16x8 pf = *reinterpret_cast<const bf16x8*>(&sm_p[(wid * 16 + (lane_c & 15)) * 136 + s4 * 32 + (lane_c >> 4) * 8]);
; #pragma unroll
;         for (int td = 0; td < 4; ++td) {
;           const bf16x8 vf = *reinterpret_cast<const bf16x8*>(&sm_vt[(td * 16 + (lane_c & 15)) * 136 + s4 * 32 + (lane_c >> 4) * 8]);
;           o[td] = __builtin_amdgcn_mfma_f32_16x16x32_bf16(pf, vf, o[td], 0, 0, 0);
;         }
;       }
	v_mfma_f32_16x16x32_bf16 v[32:35], v[112:115], v[48:51], v[32:35]
	ds_read_b128 v[112:115], v227 offset:32768
	s_waitcnt lgkmcnt(7)
	v_mfma_f32_16x16x32_bf16 v[36:39], v[116:119], v[48:51], v[36:39]
	ds_read_b128 v[116:119], v227 offset:36864
	s_waitcnt lgkmcnt(7)
	v_mfma_f32_16x16x32_bf16 v[40:43], v[120:123], v[48:51], v[40:43]
	ds_read_b128 v[120:123], v227 offset:40960
	s_waitcnt lgkmcnt(7)
	v_mfma_f32_16x16x32_bf16 v[44:47], v[124:127], v[48:51], v[44:47]
	ds_read_b128 v[124:127], v227 offset:45056
	s_waitcnt lgkmcnt(7)
	v_mfma_f32_16x16x32_bf16 v[32:35], v[128:131], v[52:55], v[32:35]
	ds_read_b128 v[128:131], v228 offset:32768
	s_waitcnt lgkmcnt(7)
	v_mfma_f32_16x16x32_bf16 v[36:39], v[132:135], v[52:55], v[36:39]
	ds_read_b128 v[132:135], v228 offset:36864
	s_waitcnt lgkmcnt(7)
	v_mfma_f32_16x16x32_bf16 v[40:43], v[136:139], v[52:55], v[40:43]
	ds_read_b128 v[136:139], v228 offset:40960
	s_waitcnt lgkmcnt(7)
	v_mfma_f32_16x16x32_bf16 v[44:47], v[140:143], v[52:55], v[44:47]
	ds_read_b128 v[140:143], v228 offset:45056
	s_waitcnt lgkmcnt(7)
	v_mfma_f32_16x16x32_bf16 v[32:35], v[112:115], v[56:59], v[32:35]
	s_waitcnt lgkmcnt(6)
	v_mfma_f32_16x16x32_bf16 v[36:39], v[116:119], v[56:59], v[36:39]
	s_waitcnt lgkmcnt(5)
	v_mfma_f32_16x16x32_bf16 v[40:43], v[120:123], v[56:59], v[40:43]
	s_waitcnt lgkmcnt(4)
	v_mfma_f32_16x16x32_bf16 v[44:47], v[124:127], v[56:59], v[44:47]
	s_waitcnt lgkmcnt(3)
	v_mfma_f32_16x16x32_bf16 v[32:35], v[128:131], v[60:63], v[32:35]
	s_waitcnt lgkmcnt(2)
	v_mfma_f32_16x16x32_bf16 v[36:39], v[132:135], v[60:63], v[36:39]
	s_waitcnt lgkmcnt(1)
	v_mfma_f32_16x16x32_bf16 v[40:43], v[136:139], v[60:63], v[40:43]
	s_waitcnt lgkmcnt(0)
	v_mfma_f32_16x16x32_bf16 v[44:47], v[140:143], v[60:63], v[44:47]
	ds_read_b128 v[112:115], v149 offset:32768
	ds_read_b128 v[116:119], v224 offset:32768
	ds_read_b128 v[120:123], v149 offset:40960
	ds_read_b128 v[124:127], v224 offset:40960
	ds_read_b128 v[128:131], v149 offset:34816
	ds_read_b128 v[132:135], v224 offset:34816
	ds_read_b128 v[136:139], v149 offset:43008
	ds_read_b128 v[140:143], v224 offset:43008
	s_waitcnt lgkmcnt(7)
	v_mfma_f32_16x16x32_bf16 v[0:3], v[112:115], v[230:233], 0
	ds_read_b128 v[112:115], v149 offset:36864
	s_waitcnt lgkmcnt(7)
	v_mfma_f32_16x16x32_bf16 v[0:3], v[116:119], v[234:237], v[0:3]
	ds_read_b128 v[116:119], v224 offset:36864
	s_waitcnt lgkmcnt(7)
	v_mfma_f32_16x16x32_bf16 v[4:7], v[120:123], v[230:233], 0
	ds_read_b128 v[120:123], v149 offset:45056
	s_waitcnt lgkmcnt(7)
	v_mfma_f32_16x16x32_bf16 v[4:7], v[124:127], v[234:237], v[4:7]
	ds_read_b128 v[124:127], v224 offset:45056
	s_waitcnt lgkmcnt(7)
	v_mfma_f32_16x16x32_bf16 v[8:11], v[128:131], v[230:233], 0
	ds_read_b128 v[128:131], v149 offset:38912
	s_waitcnt lgkmcnt(7)
	v_mfma_f32_16x16x32_bf16 v[8:11], v[132:135], v[234:237], v[8:11]
	ds_read_b128 v[132:135], v224 offset:38912
	s_waitcnt lgkmcnt(7)
	v_mfma_f32_16x16x32_bf16 v[12:15], v[136:139], v[230:233], 0
	ds_read_b128 v[136:139], v149 offset:47104
	s_waitcnt lgkmcnt(7)
	v_mfma_f32_16x16x32_bf16 v[12:15], v[140:143], v[234:237], v[12:15]
	ds_read_b128 v[140:143], v224 offset:47104
	s_waitcnt lgkmcnt(7)
	v_mfma_f32_16x16x32_bf16 v[16:19], v[112:115], v[230:233], 0
	s_waitcnt lgkmcnt(6)
	v_mfma_f32_16x16x32_bf16 v[16:19], v[116:119], v[234:237], v[16:19]
	s_waitcnt lgkmcnt(5)
	v_mfma_f32_16x16x32_bf16 v[20:23], v[120:123], v[230:233], 0
	s_waitcnt lgkmcnt(4)
	v_mfma_f32_16x16x32_bf16 v[20:23], v[124:127], v[234:237], v[20:23]
	s_waitcnt lgkmcnt(3)
	v_mfma_f32_16x16x32_bf16 v[24:27], v[128:131], v[230:233], 0
	s_waitcnt lgkmcnt(2)
	v_mfma_f32_16x16x32_bf16 v[24:27], v[132:135], v[234:237], v[24:27]
	s_waitcnt lgkmcnt(1)
	v_mfma_f32_16x16x32_bf16 v[28:31], v[136:139], v[230:233], 0
	s_waitcnt lgkmcnt(0)
	v_mfma_f32_16x16x32_bf16 v[28:31], v[140:143], v[234:237], v[28:31]
	s_nop 7
	v_max3_f32 v203, v0, v1, v2
	v_max3_f32 v203, v203, v3, v4
	v_max3_f32 v203, v203, v5, v6
	v_max3_f32 v203, v203, v7, v8
	v_max3_f32 v203, v203, v9, v10
	v_max3_f32 v203, v203, v11, v12
	v_max3_f32 v203, v203, v13, v14
	v_max3_f32 v203, v203, v15, v16
	v_max3_f32 v203, v203, v17, v18
	v_max3_f32 v203, v203, v19, v20
	v_max3_f32 v203, v203, v21, v22
	v_max3_f32 v203, v203, v23, v24
	v_max3_f32 v203, v203, v25, v26
	v_max3_f32 v203, v203, v27, v28
	v_max3_f32 v203, v203, v29, v30
	v_max_f32_e32 v203, v203, v31
	v_mov_b32_e32 v205, v203
	s_nop 1
	v_permlane16_swap_b32_e32 v203, v205
	v_max_f32_e32 v203, v203, v205
	v_mov_b32_e32 v205, v203
	s_nop 1
	v_permlane32_swap_b32_e32 v203, v205
	v_max_f32_e32 v203, v203, v205
	v_max_f32_e32 v218, v246, v203
	v_sub_f32_e32 v220, v246, v218
	v_mov_b32_e32 v219, v218
	v_exp_f32_e32 v220, v220
	v_mov_b32_e32 v246, v218
	v_pk_add_f32 v[0:1], v[0:1], v[218:219] neg_lo:[0,1] neg_hi:[0,1]
	v_pk_add_f32 v[2:3], v[2:3], v[218:219] neg_lo:[0,1] neg_hi:[0,1]
	v_pk_add_f32 v[4:5], v[4:5], v[218:219] neg_lo:[0,1] neg_hi:[0,1]
	v_pk_add_f32 v[6:7], v[6:7], v[218:219] neg_lo:[0,1] neg_hi:[0,1]
	v_pk_add_f32 v[8:9], v[8:9], v[218:219] neg_lo:[0,1] neg_hi:[0,1]
	v_pk_add_f32 v[10:11], v[10:11], v[218:219] neg_lo:[0,1] neg_hi:[0,1]
	v_pk_add_f32 v[12:13], v[12:13], v[218:219] neg_lo:[0,1] neg_hi:[0,1]
	v_pk_add_f32 v[14:15], v[14:15], v[218:219] neg_lo:[0,1] neg_hi:[0,1]
	v_pk_add_f32 v[16:17], v[16:17], v[218:219] neg_lo:[0,1] neg_hi:[0,1]
	v_pk_add_f32 v[18:19], v[18:19], v[218:219] neg_lo:[0,1] neg_hi:[0,1]
	v_pk_add_f32 v[20:21], v[20:21], v[218:219] neg_lo:[0,1] neg_hi:[0,1]
	v_pk_add_f32 v[22:23], v[22:23], v[218:219] neg_lo:[0,1] neg_hi:[0,1]
	v_pk_add_f32 v[24:25], v[24:25], v[218:219] neg_lo:[0,1] neg_hi:[0,1]
; __device__ __forceinline__ void attn_phase(const Params& P, char* smem_raw) {
;     ...
; #pragma unroll
;       for (int reg = 0; reg < 4; ++reg) {
;         float mx = sacc[0][reg];
; #pragma unroll
;         for (int t8 = 1; t8 < 8; ++t8) mx = fmaxf(mx, sacc[t8][reg]);
;         mx = row16_max(mx);
;         const float mnew = fmaxf(mrow[reg], mx);
;         const float alpha = __builtin_amdgcn_exp2f(mrow[reg] - mnew);
;         mrow[reg] = mnew;
;         float rsum = 0.f;
; #pragma unroll
;         for (int t8 = 0; t8 < 8; ++t8) {
;           const float p = __builtin_amdgcn_exp2f(sacc[t8][reg] - mnew);
;           rsum += p;
;           sm_p[(wid * 16 + (lane_c >> 4) * 4 + reg) * 136 + t8 * 16 + (lane_c & 15)] = f2bf(p);
;         }
;         rsum = row16_sum(rsum);
;         lrow[reg] = lrow[reg] * alpha + rsum;
; #pragma unroll
;         for (int td = 0; td < 4; ++td) o[td][reg] *= alpha;
;       }
;       asm volatile("s_waitcnt lgkmcnt(0)" ::: "memory");
; #pragma unroll
;       for (int s4 = 0; s4 < 4; ++s4) {
;         const bf16x8 pf = *reinterpret_cast<const bf16x8*>(&sm_p[(wid * 16 + (lane_c & 15)) * 136 + s4 * 32 + (lane_c >> 4) * 8]);
; #pragma unroll
;         for (int td = 0; td < 4; ++td) {
;           const bf16x8 vf = *reinterpret_cast<const bf16x8*>(&sm_vt[(td * 16 + (lane_c & 15)) * 136 + s4 * 32 + (lane_c >> 4) * 8]);
;           o[td] = __builtin_amdgcn_mfma_f32_16x16x32_bf16(pf, vf, o[td], 0, 0, 0);
;         }
;       }
	v_pk_add_f32 v[26:27], v[26:27], v[218:219] neg_lo:[0,1] neg_hi:[0,1]
	v_pk_add_f32 v[28:29], v[28:29], v[218:219] neg_lo:[0,1] neg_hi:[0,1]
	v_pk_add_f32 v[30:31], v[30:31], v[218:219] neg_lo:[0,1] neg_hi:[0,1]
	v_exp_f32_e32 v0, v0
	v_exp_f32_e32 v1, v1
	v_exp_f32_e32 v2, v2
	v_exp_f32_e32 v3, v3
	v_exp_f32_e32 v4, v4
	v_exp_f32_e32 v5, v5
	v_exp_f32_e32 v6, v6
	v_exp_f32_e32 v7, v7
	v_exp_f32_e32 v8, v8
	v_exp_f32_e32 v9, v9
	v_exp_f32_e32 v10, v10
	v_exp_f32_e32 v11, v11
	v_exp_f32_e32 v12, v12
	v_exp_f32_e32 v13, v13
	v_exp_f32_e32 v14, v14
	v_exp_f32_e32 v15, v15
	v_exp_f32_e32 v16, v16
	v_exp_f32_e32 v17, v17
	v_exp_f32_e32 v18, v18
	v_exp_f32_e32 v19, v19
	v_exp_f32_e32 v20, v20
	v_exp_f32_e32 v21, v21
	v_exp_f32_e32 v22, v22
	v_exp_f32_e32 v23, v23
	v_exp_f32_e32 v24, v24
	v_exp_f32_e32 v25, v25
	v_exp_f32_e32 v26, v26
	v_exp_f32_e32 v27, v27
	v_exp_f32_e32 v28, v28
	v_exp_f32_e32 v29, v29
	v_exp_f32_e32 v30, v30
	v_exp_f32_e32 v31, v31
	ds_read_b128 v[112:115], v225 offset:32768
	ds_read_b128 v[116:119], v225 offset:36864
	ds_read_b128 v[120:123], v225 offset:40960
	ds_read_b128 v[124:127], v225 offset:45056
	ds_read_b128 v[128:131], v226 offset:32768
	ds_read_b128 v[132:135], v226 offset:36864
	ds_read_b128 v[136:139], v226 offset:40960
	ds_read_b128 v[140:143], v226 offset:45056
	v_mov_b32_e32 v221, v220
	v_pk_add_f32 v[222:223], v[0:1], v[2:3]
	v_pk_add_f32 v[222:223], v[222:223], v[4:5]
	v_pk_add_f32 v[222:223], v[222:223], v[6:7]
	v_pk_add_f32 v[222:223], v[222:223], v[8:9]
	v_pk_add_f32 v[222:223], v[222:223], v[10:11]
	v_pk_add_f32 v[222:223], v[222:223], v[12:13]
	v_pk_add_f32 v[222:223], v[222:223], v[14:15]
	v_pk_add_f32 v[222:223], v[222:223], v[16:17]
	v_pk_add_f32 v[222:223], v[222:223], v[18:19]
	v_pk_add_f32 v[222:223], v[222:223], v[20:21]
	v_pk_add_f32 v[222:223], v[222:223], v[22:23]
	v_pk_add_f32 v[222:223], v[222:223], v[24:25]
	v_pk_add_f32 v[222:223], v[222:223], v[26:27]
	v_pk_add_f32 v[222:223], v[222:223], v[28:29]
	v_pk_add_f32 v[222:223], v[222:223], v[30:31]
	v_pk_mul_f32 v[176:177], v[176:177], v[220:221]
	v_pk_mul_f32 v[178:179], v[178:179], v[220:221]
	v_pk_mul_f32 v[180:181], v[180:181], v[220:221]
	v_pk_mul_f32 v[182:183], v[182:183], v[220:221]
	v_pk_mul_f32 v[192:193], v[192:193], v[220:221]
	v_pk_mul_f32 v[194:195], v[194:195], v[220:221]
	v_pk_mul_f32 v[196:197], v[196:197], v[220:221]
	v_pk_mul_f32 v[198:199], v[198:199], v[220:221]
	v_add_f32_e32 v203, v222, v223
	v_fma_f32 v247, v247, v220, v203
	v_cvt_pk_bf16_f32 v48, v0, v1
	v_cvt_pk_bf16_f32 v49, v2, v3
	v_cvt_pk_bf16_f32 v50, v4, v5
	v_cvt_pk_bf16_f32 v51, v6, v7
	v_cvt_pk_bf16_f32 v52, v8, v9
	v_cvt_pk_bf16_f32 v53, v10, v11
	v_cvt_pk_bf16_f32 v54, v12, v13
	v_cvt_pk_bf16_f32 v55, v14, v15
	v_cvt_pk_bf16_f32 v56, v16, v17
	v_cvt_pk_bf16_f32 v57, v18, v19
	v_cvt_pk_bf16_f32 v58, v20, v21
	v_cvt_pk_bf16_f32 v59, v22, v23
	v_cvt_pk_bf16_f32 v60, v24, v25
	v_cvt_pk_bf16_f32 v61, v26, v27
	v_cvt_pk_bf16_f32 v62, v28, v29
	v_cvt_pk_bf16_f32 v63, v30, v31
	s_waitcnt lgkmcnt(7)
	v_mfma_f32_16x16x32_bf16 v[176:179], v[112:115], v[48:51], v[176:179]
	ds_read_b128 v[112:115], v227 offset:32768
	s_waitcnt lgkmcnt(7)
	v_mfma_f32_16x16x32_bf16 v[180:183], v[116:119], v[48:51], v[180:183]
	ds_read_b128 v[116:119], v227 offset:36864
	s_waitcnt lgkmcnt(7)
	v_mfma_f32_16x16x32_bf16 v[192:195], v[120:123], v[48:51], v[192:195]
	ds_read_b128 v[120:123], v227 offset:40960
	s_waitcnt lgkmcnt(7)
	v_mfma_f32_16x16x32_bf16 v[196:199], v[124:127], v[48:51], v[196:199]
	ds_read_b128 v[124:127], v227 offset:45056
	s_waitcnt lgkmcnt(7)
	v_mfma_f32_16x16x32_bf16 v[176:179], v[128:131], v[52:55], v[176:179]
	ds_read_b128 v[128:131], v228 offset:32768
	s_waitcnt lgkmcnt(7)
	v_mfma_f32_16x16x32_bf16 v[180:183], v[132:135], v[52:55], v[180:183]
	ds_read_b128 v[132:135], v228 offset:36864
	s_waitcnt lgkmcnt(7)
	v_mfma_f32_16x16x32_bf16 v[192:195], v[136:139], v[52:55], v[192:195]
	ds_read_b128 v[136:139], v228 offset:40960
	s_waitcnt lgkmcnt(7)
	v_mfma_f32_16x16x32_bf16 v[196:199], v[140:143], v[52:55], v[196:199]
	ds_read_b128 v[140:143], v228 offset:45056
	s_waitcnt lgkmcnt(7)
	v_mfma_f32_16x16x32_bf16 v[176:179], v[112:115], v[56:59], v[176:179]
	s_waitcnt lgkmcnt(6)
	v_mfma_f32_16x16x32_bf16 v[180:183], v[116:119], v[56:59], v[180:183]
	s_waitcnt lgkmcnt(5)
	v_mfma_f32_16x16x32_bf16 v[192:195], v[120:123], v[56:59], v[192:195]
	s_waitcnt lgkmcnt(4)
	v_mfma_f32_16x16x32_bf16 v[196:199], v[124:127], v[56:59], v[196:199]
	s_waitcnt lgkmcnt(3)
	v_mfma_f32_16x16x32_bf16 v[176:179], v[128:131], v[60:63], v[176:179]
	s_waitcnt lgkmcnt(2)
	v_mfma_f32_16x16x32_bf16 v[180:183], v[132:135], v[60:63], v[180:183]
	s_waitcnt lgkmcnt(1)
	v_mfma_f32_16x16x32_bf16 v[192:195], v[136:139], v[60:63], v[192:195]
	s_waitcnt lgkmcnt(0)
	v_mfma_f32_16x16x32_bf16 v[196:199], v[140:143], v[60:63], v[196:199]
	s_waitcnt lgkmcnt(0)
	s_barrier
; __device__ __forceinline__ void attn_phase(const Params& P, char* smem_raw) {
;     ...
;     for (int ck = 0; ck < 6; ++ck) {
;       int lane_c = lane;
;       asm volatile("" : "+v"(lane_c));
;       __syncthreads();
; #pragma unroll
;       for (int i = 0; i < 4; ++i) {
;         const int idx = tid + 256 * i;
;         *reinterpret_cast<uint4*>(&sm_k[(idx >> 3) * LDSS + (idx & 7) * 8]) = kreg[i];
;         *reinterpret_cast<uint4*>(&sm_vt[(idx >> 4) * 136 + (idx & 15) * 8]) = vreg[i];
;       }
;       __syncthreads();
;       f32x4 sacc[8];
; #pragma unroll
;       for (int t8 = 0; t8 < 8; ++t8) sacc[t8] = f32x4{0.f, 0.f, 0.f, 0.f};
; #pragma unroll
;       for (int s = 0; s < 2; ++s)
; #pragma unroll
;         for (int t8 = 0; t8 < 8; ++t8) {
;           const bf16x8 kf = *reinterpret_cast<const bf16x8*>(&sm_k[(t8 * 16 + (lane_c & 15)) * LDSS + s * 32 + (lane_c >> 4) * 8]);
;           sacc[t8] = __builtin_amdgcn_mfma_f32_16x16x32_bf16(qf[s], kf, sacc[t8], 0, 0, 0);
;         }
;       if (ck < 5) {
;         ATT_ISSUE(t, ck + 1)
;       } else if (t + VGRID < 8192) {
;         ATT_ISSUE(t + VGRID, 0)
;         ATT_QLOAD(t + VGRID)
;       }
;       if (ck < 4) {
;         const float* rb0 = sm_rpb + (rs + ck * 2 - r + 7) * 31;
; #pragma unroll
;         for (int t8 = 0; t8 < 8; ++t8)
; #pragma unroll
;           for (int reg = 0; reg < 4; ++reg)
;             sacc[t8][reg] += rb0[(t8 >> 2) * 31 + dco[reg][t8 & 3]];
;       }
; #pragma unroll
;       for (int reg = 0; reg < 4; ++reg) {
;         float mx = sacc[0][reg];
; #pragma unroll
;         for (int t8 = 1; t8 < 8; ++t8) mx = fmaxf(mx, sacc[t8][reg]);
;         mx = row16_max(mx);
;         const float mnew = fmaxf(mrow[reg], mx);
;         const float alpha = __builtin_amdgcn_exp2f(mrow[reg] - mnew);
;         mrow[reg] = mnew;
;         float rsum = 0.f;
; #pragma unroll
;         for (int t8 = 0; t8 < 8; ++t8) {
;           const float p = __builtin_amdgcn_exp2f(sacc[t8][reg] - mnew);
;           rsum += p;
;           sm_p[(wid * 16 + (lane_c >> 4) * 4 + reg) * 136 + t8 * 16 + (lane_c & 15)] = f2bf(p);
;         }
;         rsum = row16_sum(rsum);
;         lrow[reg] = lrow[reg] * alpha + rsum;
; #pragma unroll
;         for (int td = 0; td < 4; ++td) o[td][reg] *= alpha;
;       }
;       asm volatile("s_waitcnt lgkmcnt(0)" ::: "memory");
; #pragma unroll
;       for (int s4 = 0; s4 < 4; ++s4) {
	ds_read_b128 v[112:115], v149 offset:0
	ds_read_b128 v[116:119], v224 offset:0
	ds_read_b128 v[120:123], v149 offset:8192
	ds_read_b128 v[124:127], v224 offset:8192
	ds_read_b128 v[128:131], v149 offset:2048
	ds_read_b128 v[132:135], v224 offset:2048
	ds_read_b128 v[136:139], v149 offset:10240
	ds_read_b128 v[140:143], v224 offset:10240
	s_waitcnt lgkmcnt(7)
	v_mfma_f32_16x16x32_bf16 v[0:3], v[112:115], v[64:67], 0
	ds_read_b128 v[112:115], v149 offset:4096
	s_waitcnt lgkmcnt(7)
	v_mfma_f32_16x16x32_bf16 v[0:3], v[116:119], v[68:71], v[0:3]
	ds_read_b128 v[116:119], v224 offset:4096
	s_waitcnt lgkmcnt(7)
	v_mfma_f32_16x16x32_bf16 v[4:7], v[120:123], v[64:67], 0
	ds_read_b128 v[120:123], v149 offset:12288
	s_waitcnt lgkmcnt(7)
	v_mfma_f32_16x16x32_bf16 v[4:7], v[124:127], v[68:71], v[4:7]
	ds_read_b128 v[124:127], v224 offset:12288
	s_waitcnt lgkmcnt(7)
	v_mfma_f32_16x16x32_bf16 v[8:11], v[128:131], v[64:67], 0
	ds_read_b128 v[128:131], v149 offset:6144
	s_waitcnt lgkmcnt(7)
	v_mfma_f32_16x16x32_bf16 v[8:11], v[132:135], v[68:71], v[8:11]
	ds_read_b128 v[132:135], v224 offset:6144
	s_waitcnt lgkmcnt(7)
	v_mfma_f32_16x16x32_bf16 v[12:15], v[136:139], v[64:67], 0
	ds_read_b128 v[136:139], v149 offset:14336
	s_waitcnt lgkmcnt(7)
	v_mfma_f32_16x16x32_bf16 v[12:15], v[140:143], v[68:71], v[12:15]
	ds_read_b128 v[140:143], v224 offset:14336
	s_waitcnt lgkmcnt(7)
	v_mfma_f32_16x16x32_bf16 v[16:19], v[112:115], v[64:67], 0
	s_waitcnt lgkmcnt(6)
	v_mfma_f32_16x16x32_bf16 v[16:19], v[116:119], v[68:71], v[16:19]
	s_waitcnt lgkmcnt(5)
	v_mfma_f32_16x16x32_bf16 v[20:23], v[120:123], v[64:67], 0
	s_waitcnt lgkmcnt(4)
	v_mfma_f32_16x16x32_bf16 v[20:23], v[124:127], v[68:71], v[20:23]
	s_waitcnt lgkmcnt(3)
	v_mfma_f32_16x16x32_bf16 v[24:27], v[128:131], v[64:67], 0
	s_waitcnt lgkmcnt(2)
	v_mfma_f32_16x16x32_bf16 v[24:27], v[132:135], v[68:71], v[24:27]
	s_waitcnt lgkmcnt(1)
	v_mfma_f32_16x16x32_bf16 v[28:31], v[136:139], v[64:67], 0
	s_waitcnt lgkmcnt(0)
	v_mfma_f32_16x16x32_bf16 v[28:31], v[140:143], v[68:71], v[28:31]
	s_nop 7
	v_max3_f32 v203, v0, v1, v2
	v_max3_f32 v203, v203, v3, v4
	v_max3_f32 v203, v203, v5, v6
	v_max3_f32 v203, v203, v7, v8
	v_max3_f32 v203, v203, v9, v10
	v_max3_f32 v203, v203, v11, v12
	v_max3_f32 v203, v203, v13, v14
	v_max3_f32 v203, v203, v15, v16
	v_max3_f32 v203, v203, v17, v18
	v_max3_f32 v203, v203, v19, v20
	v_max3_f32 v203, v203, v21, v22
	v_max3_f32 v203, v203, v23, v24
	v_max3_f32 v203, v203, v25, v26
	v_max3_f32 v203, v203, v27, v28
	v_max3_f32 v203, v203, v29, v30
	v_max_f32_e32 v203, v203, v31
	v_mov_b32_e32 v205, v203
	s_nop 1
	v_permlane16_swap_b32_e32 v203, v205
	v_max_f32_e32 v203, v203, v205
	v_mov_b32_e32 v205, v203
	s_nop 1
	v_permlane32_swap_b32_e32 v203, v205
	v_max_f32_e32 v203, v203, v205
	v_max_f32_e32 v218, v200, v203
	v_sub_f32_e32 v220, v200, v218
	v_mov_b32_e32 v219, v218
	v_exp_f32_e32 v220, v220
	v_mov_b32_e32 v200, v218
	v_pk_add_f32 v[0:1], v[0:1], v[218:219] neg_lo:[0,1] neg_hi:[0,1]
	v_pk_add_f32 v[2:3], v[2:3], v[218:219] neg_lo:[0,1] neg_hi:[0,1]
	v_pk_add_f32 v[4:5], v[4:5], v[218:219] neg_lo:[0,1] neg_hi:[0,1]
	v_pk_add_f32 v[6:7], v[6:7], v[218:219] neg_lo:[0,1] neg_hi:[0,1]
	v_pk_add_f32 v[8:9], v[8:9], v[218:219] neg_lo:[0,1] neg_hi:[0,1]
	v_pk_add_f32 v[10:11], v[10:11], v[218:219] neg_lo:[0,1] neg_hi:[0,1]
	v_pk_add_f32 v[12:13], v[12:13], v[218:219] neg_lo:[0,1] neg_hi:[0,1]
	v_pk_add_f32 v[14:15], v[14:15], v[218:219] neg_lo:[0,1] neg_hi:[0,1]
	v_pk_add_f32 v[16:17], v[16:17], v[218:219] neg_lo:[0,1] neg_hi:[0,1]
	v_pk_add_f32 v[18:19], v[18:19], v[218:219] neg_lo:[0,1] neg_hi:[0,1]
	v_pk_add_f32 v[20:21], v[20:21], v[218:219] neg_lo:[0,1] neg_hi:[0,1]
	v_pk_add_f32 v[22:23], v[22:23], v[218:219] neg_lo:[0,1] neg_hi:[0,1]
	v_pk_add_f32 v[24:25], v[24:25], v[218:219] neg_lo:[0,1] neg_hi:[0,1]
	v_pk_add_f32 v[26:27], v[26:27], v[218:219] neg_lo:[0,1] neg_hi:[0,1]
	v_pk_add_f32 v[28:29], v[28:29], v[218:219] neg_lo:[0,1] neg_hi:[0,1]
	v_pk_add_f32 v[30:31], v[30:31], v[218:219] neg_lo:[0,1] neg_hi:[0,1]
	v_exp_f32_e32 v0, v0
	s_waitcnt vmcnt(0)
	v_exp_f32_e32 v1, v1
	ds_write_b128 v150, v[80:83] offset:32768
	v_exp_f32_e32 v2, v2
	ds_write_b128 v150, v[84:87] offset:36864
	v_exp_f32_e32 v3, v3
	ds_write_b128 v150, v[88:91] offset:40960
	v_exp_f32_e32 v4, v4
	ds_write_b128 v150, v[92:95] offset:45056
	v_exp_f32_e32 v5, v5
	ds_write_b64 v151, v[96:97] offset:32768
	v_exp_f32_e32 v6, v6
	ds_write_b64 v229, v[98:99] offset:32768
	v_exp_f32_e32 v7, v7
	ds_write_b64 v151, v[100:101] offset:36864
	v_exp_f32_e32 v8, v8
	ds_write_b64 v229, v[102:103] offset:36864
	v_exp_f32_e32 v9, v9
	ds_write_b64 v151, v[104:105] offset:40960
	v_exp_f32_e32 v10, v10
	ds_write_b64 v229, v[106:107] offset:40960
	v_exp_f32_e32 v11, v11
	ds_write_b64 v151, v[108:109] offset:45056
	v_exp_f32_e32 v12, v12
	ds_write_b64 v229, v[110:111] offset:45056
	v_exp_f32_e32 v13, v13
	s_add_u32 s100, s12, 0xc0000
	v_exp_f32_e32 v14, v14
	s_addc_u32 s101, s13, 0
	v_exp_f32_e32 v15, v15
	s_add_u32 s0, s14, 0x100
	v_exp_f32_e32 v16, v16
	s_addc_u32 s1, s15, 0
	v_exp_f32_e32 v17, v17
	global_load_dwordx4 v[80:83], v154, s[100:101] offset:2048
	v_exp_f32_e32 v18, v18
	global_load_dwordx4 v[96:99], v158, s[0:1]
	v_exp_f32_e32 v19, v19
	global_load_dwordx4 v[84:87], v155, s[100:101] offset:2048
	v_exp_f32_e32 v20, v20
	global_load_dwordx4 v[100:103], v159, s[0:1]
	v_exp_f32_e32 v21, v21
	global_load_dwordx4 v[88:91], v156, s[100:101] offset:2048
	v_exp_f32_e32 v22, v22
	global_load_dwordx4 v[104:107], v160, s[0:1]
	v_exp_f32_e32 v23, v23
	global_load_dwordx4 v[92:95], v157, s[100:101] offset:2048
	v_exp_f32_e32 v24, v24
; __device__ __forceinline__ void attn_phase(const Params& P, char* smem_raw) {
;     ...
; #pragma unroll
;       for (int s = 0; s < 2; ++s)
; #pragma unroll
;         for (int t8 = 0; t8 < 8; ++t8) {
;           const bf16x8 kf = *reinterpret_cast<const bf16x8*>(&sm_k[(t8 * 16 + (lane_c & 15)) * LDSS + s * 32 + (lane_c >> 4) * 8]);
;           sacc[t8] = __builtin_amdgcn_mfma_f32_16x16x32_bf16(qf[s], kf, sacc[t8], 0, 0, 0);
;         }
;     ...
;         float rsum = 0.f;
; #pragma unroll
;         for (int t8 = 0; t8 < 8; ++t8) {
;           const float p = __builtin_amdgcn_exp2f(sacc[t8][reg] - mnew);
;           rsum += p;
;           sm_p[(wid * 16 + (lane_c >> 4) * 4 + reg) * 136 + t8 * 16 + (lane_c & 15)] = f2bf(p);
;         }
;         rsum = row16_sum(rsum);
;         lrow[reg] = lrow[reg] * alpha + rsum;
; #pragma unroll
;         for (int td = 0; td < 4; ++td) o[td][reg] *= alpha;
;       }
;       asm volatile("s_waitcnt lgkmcnt(0)" ::: "memory");
; #pragma unroll
;       for (int s4 = 0; s4 < 4; ++s4) {
;         const bf16x8 pf = *reinterpret_cast<const bf16x8*>(&sm_p[(wid * 16 + (lane_c & 15)) * 136 + s4 * 32 + (lane_c >> 4) * 8]);
; #pragma unroll
;         for (int td = 0; td < 4; ++td) {
;           const bf16x8 vf = *reinterpret_cast<const bf16x8*>(&sm_vt[(td * 16 + (lane_c & 15)) * 136 + s4 * 32 + (lane_c >> 4) * 8]);
;           o[td] = __builtin_amdgcn_mfma_f32_16x16x32_bf16(pf, vf, o[td], 0, 0, 0);
;         }
;       }
	global_load_dwordx4 v[108:111], v161, s[0:1]
	v_exp_f32_e32 v25, v25
	v_exp_f32_e32 v26, v26
	v_exp_f32_e32 v27, v27
	v_exp_f32_e32 v28, v28
	v_exp_f32_e32 v29, v29
	v_exp_f32_e32 v30, v30
	v_exp_f32_e32 v31, v31
	ds_read_b128 v[112:115], v225 offset:0
	ds_read_b128 v[116:119], v225 offset:4096
	ds_read_b128 v[120:123], v225 offset:8192
	ds_read_b128 v[124:127], v225 offset:12288
	ds_read_b128 v[128:131], v226 offset:0
	ds_read_b128 v[132:135], v226 offset:4096
	ds_read_b128 v[136:139], v226 offset:8192
	ds_read_b128 v[140:143], v226 offset:12288
	v_mov_b32_e32 v221, v220
	v_pk_add_f32 v[222:223], v[0:1], v[2:3]
	v_pk_add_f32 v[222:223], v[222:223], v[4:5]
	v_pk_add_f32 v[222:223], v[222:223], v[6:7]
	v_pk_add_f32 v[222:223], v[222:223], v[8:9]
	v_pk_add_f32 v[222:223], v[222:223], v[10:11]
	v_pk_add_f32 v[222:223], v[222:223], v[12:13]
	v_pk_add_f32 v[222:223], v[222:223], v[14:15]
	v_pk_add_f32 v[222:223], v[222:223], v[16:17]
	v_pk_add_f32 v[222:223], v[222:223], v[18:19]
	v_pk_add_f32 v[222:223], v[222:223], v[20:21]
	v_pk_add_f32 v[222:223], v[222:223], v[22:23]
	v_pk_add_f32 v[222:223], v[222:223], v[24:25]
	v_pk_add_f32 v[222:223], v[222:223], v[26:27]
	v_pk_add_f32 v[222:223], v[222:223], v[28:29]
	v_pk_add_f32 v[222:223], v[222:223], v[30:31]
	v_pk_mul_f32 v[32:33], v[32:33], v[220:221]
	v_pk_mul_f32 v[34:35], v[34:35], v[220:221]
	v_pk_mul_f32 v[36:37], v[36:37], v[220:221]
	v_pk_mul_f32 v[38:39], v[38:39], v[220:221]
	v_pk_mul_f32 v[40:41], v[40:41], v[220:221]
	v_pk_mul_f32 v[42:43], v[42:43], v[220:221]
	v_pk_mul_f32 v[44:45], v[44:45], v[220:221]
	v_pk_mul_f32 v[46:47], v[46:47], v[220:221]
	v_add_f32_e32 v203, v222, v223
	v_fma_f32 v201, v201, v220, v203
	v_cvt_pk_bf16_f32 v48, v0, v1
	v_cvt_pk_bf16_f32 v49, v2, v3
	v_cvt_pk_bf16_f32 v50, v4, v5
	v_cvt_pk_bf16_f32 v51, v6, v7
	v_cvt_pk_bf16_f32 v52, v8, v9
	v_cvt_pk_bf16_f32 v53, v10, v11
	v_cvt_pk_bf16_f32 v54, v12, v13
	v_cvt_pk_bf16_f32 v55, v14, v15
	v_cvt_pk_bf16_f32 v56, v16, v17
	v_cvt_pk_bf16_f32 v57, v18, v19
	v_cvt_pk_bf16_f32 v58, v20, v21
	v_cvt_pk_bf16_f32 v59, v22, v23
	v_cvt_pk_bf16_f32 v60, v24, v25
	v_cvt_pk_bf16_f32 v61, v26, v27
	v_cvt_pk_bf16_f32 v62, v28, v29
	v_cvt_pk_bf16_f32 v63, v30, v31
	s_waitcnt lgkmcnt(7)
	v_mfma_f32_16x16x32_bf16 v[32:35], v[112:115], v[48:51], v[32:35]
	ds_read_b128 v[112:115], v227 offset:0
	s_waitcnt lgkmcnt(7)
	v_mfma_f32_16x16x32_bf16 v[36:39], v[116:119], v[48:51], v[36:39]
	ds_read_b128 v[116:119], v227 offset:4096
	s_waitcnt lgkmcnt(7)
	v_mfma_f32_16x16x32_bf16 v[40:43], v[120:123], v[48:51], v[40:43]
	ds_read_b128 v[120:123], v227 offset:8192
	s_waitcnt lgkmcnt(7)
	v_mfma_f32_16x16x32_bf16 v[44:47], v[124:127], v[48:51], v[44:47]
	ds_read_b128 v[124:127], v227 offset:12288
	s_waitcnt lgkmcnt(7)
	v_mfma_f32_16x16x32_bf16 v[32:35], v[128:131], v[52:55], v[32:35]
	ds_read_b128 v[128:131], v228 offset:0
	s_waitcnt lgkmcnt(7)
	v_mfma_f32_16x16x32_bf16 v[36:39], v[132:135], v[52:55], v[36:39]
	ds_read_b128 v[132:135], v228 offset:4096
	s_waitcnt lgkmcnt(7)
	v_mfma_f32_16x16x32_bf16 v[40:43], v[136:139], v[52:55], v[40:43]
	ds_read_b128 v[136:139], v228 offset:8192
	s_waitcnt lgkmcnt(7)
	v_mfma_f32_16x16x32_bf16 v[44:47], v[140:143], v[52:55], v[44:47]
	ds_read_b128 v[140:143], v228 offset:12288
	s_waitcnt lgkmcnt(7)
	v_mfma_f32_16x16x32_bf16 v[32:35], v[112:115], v[56:59], v[32:35]
	s_waitcnt lgkmcnt(6)
	v_mfma_f32_16x16x32_bf16 v[36:39], v[116:119], v[56:59], v[36:39]
	s_waitcnt lgkmcnt(5)
	v_mfma_f32_16x16x32_bf16 v[40:43], v[120:123], v[56:59], v[40:43]
	s_waitcnt lgkmcnt(4)
	v_mfma_f32_16x16x32_bf16 v[44:47], v[124:127], v[56:59], v[44:47]
	s_waitcnt lgkmcnt(3)
	v_mfma_f32_16x16x32_bf16 v[32:35], v[128:131], v[60:63], v[32:35]
	s_waitcnt lgkmcnt(2)
	v_mfma_f32_16x16x32_bf16 v[36:39], v[132:135], v[60:63], v[36:39]
	s_waitcnt lgkmcnt(1)
	v_mfma_f32_16x16x32_bf16 v[40:43], v[136:139], v[60:63], v[40:43]
	s_waitcnt lgkmcnt(0)
	v_mfma_f32_16x16x32_bf16 v[44:47], v[140:143], v[60:63], v[44:47]
	ds_read_b128 v[112:115], v149 offset:0
	ds_read_b128 v[116:119], v224 offset:0
	ds_read_b128 v[120:123], v149 offset:8192
	ds_read_b128 v[124:127], v224 offset:8192
	ds_read_b128 v[128:131], v149 offset:2048
	ds_read_b128 v[132:135], v224 offset:2048
	ds_read_b128 v[136:139], v149 offset:10240
	ds_read_b128 v[140:143], v224 offset:10240
	s_waitcnt lgkmcnt(7)
	v_mfma_f32_16x16x32_bf16 v[0:3], v[112:115], v[230:233], 0
	ds_read_b128 v[112:115], v149 offset:4096
	s_waitcnt lgkmcnt(7)
	v_mfma_f32_16x16x32_bf16 v[0:3], v[116:119], v[234:237], v[0:3]
	ds_read_b128 v[116:119], v224 offset:4096
	s_waitcnt lgkmcnt(7)
	v_mfma_f32_16x16x32_bf16 v[4:7], v[120:123], v[230:233], 0
	ds_read_b128 v[120:123], v149 offset:12288
	s_waitcnt lgkmcnt(7)
	v_mfma_f32_16x16x32_bf16 v[4:7], v[124:127], v[234:237], v[4:7]
	ds_read_b128 v[124:127], v224 offset:12288
	s_waitcnt lgkmcnt(7)
	v_mfma_f32_16x16x32_bf16 v[8:11], v[128:131], v[230:233], 0
	ds_read_b128 v[128:131], v149 offset:6144
	s_waitcnt lgkmcnt(7)
	v_mfma_f32_16x16x32_bf16 v[8:11], v[132:135], v[234:237], v[8:11]
	ds_read_b128 v[132:135], v224 offset:6144
	s_waitcnt lgkmcnt(7)
	v_mfma_f32_16x16x32_bf16 v[12:15], v[136:139], v[230:233], 0
	ds_read_b128 v[136:139], v149 offset:14336
	s_waitcnt lgkmcnt(7)
	v_mfma_f32_16x16x32_bf16 v[12:15], v[140:143], v[234:237], v[12:15]
	ds_read_b128 v[140:143], v224 offset:14336
	s_waitcnt lgkmcnt(7)
	v_mfma_f32_16x16x32_bf16 v[16:19], v[112:115], v[230:233], 0
	s_waitcnt lgkmcnt(6)
	v_mfma_f32_16x16x32_bf16 v[16:19], v[116:119], v[234:237], v[16:19]
	s_waitcnt lgkmcnt(5)
	v_mfma_f32_16x16x32_bf16 v[20:23], v[120:123], v[230:233], 0
	s_waitcnt lgkmcnt(4)
; __device__ __forceinline__ void attn_phase(const Params& P, char* smem_raw) {
;     ...
; #pragma unroll
;       for (int reg = 0; reg < 4; ++reg) {
;         float mx = sacc[0][reg];
; #pragma unroll
;         for (int t8 = 1; t8 < 8; ++t8) mx = fmaxf(mx, sacc[t8][reg]);
;         mx = row16_max(mx);
;         const float mnew = fmaxf(mrow[reg], mx);
;         const float alpha = __builtin_amdgcn_exp2f(mrow[reg] - mnew);
;         mrow[reg] = mnew;
;         float rsum = 0.f;
; #pragma unroll
;         for (int t8 = 0; t8 < 8; ++t8) {
;           const float p = __builtin_amdgcn_exp2f(sacc[t8][reg] - mnew);
;           rsum += p;
;           sm_p[(wid * 16 + (lane_c >> 4) * 4 + reg) * 136 + t8 * 16 + (lane_c & 15)] = f2bf(p);
;         }
;         rsum = row16_sum(rsum);
;         lrow[reg] = lrow[reg] * alpha + rsum;
; #pragma unroll
;         for (int td = 0; td < 4; ++td) o[td][reg] *= alpha;
;       }
;       asm volatile("s_waitcnt lgkmcnt(0)" ::: "memory");
; #pragma unroll
;       for (int s4 = 0; s4 < 4; ++s4) {
;         const bf16x8 pf = *reinterpret_cast<const bf16x8*>(&sm_p[(wid * 16 + (lane_c & 15)) * 136 + s4 * 32 + (lane_c >> 4) * 8]);
; #pragma unroll
;         for (int td = 0; td < 4; ++td) {
;           const bf16x8 vf = *reinterpret_cast<const bf16x8*>(&sm_vt[(td * 16 + (lane_c & 15)) * 136 + s4 * 32 + (lane_c >> 4) * 8]);
;           o[td] = __builtin_amdgcn_mfma_f32_16x16x32_bf16(pf, vf, o[td], 0, 0, 0);
;         }
;       }
	v_mfma_f32_16x16x32_bf16 v[20:23], v[124:127], v[234:237], v[20:23]
	s_waitcnt lgkmcnt(3)
	v_mfma_f32_16x16x32_bf16 v[24:27], v[128:131], v[230:233], 0
	s_waitcnt lgkmcnt(2)
	v_mfma_f32_16x16x32_bf16 v[24:27], v[132:135], v[234:237], v[24:27]
	s_waitcnt lgkmcnt(1)
	v_mfma_f32_16x16x32_bf16 v[28:31], v[136:139], v[230:233], 0
	s_waitcnt lgkmcnt(0)
	v_mfma_f32_16x16x32_bf16 v[28:31], v[140:143], v[234:237], v[28:31]
	s_nop 7
	v_max3_f32 v203, v0, v1, v2
	v_max3_f32 v203, v203, v3, v4
	v_max3_f32 v203, v203, v5, v6
	v_max3_f32 v203, v203, v7, v8
	v_max3_f32 v203, v203, v9, v10
	v_max3_f32 v203, v203, v11, v12
	v_max3_f32 v203, v203, v13, v14
	v_max3_f32 v203, v203, v15, v16
	v_max3_f32 v203, v203, v17, v18
	v_max3_f32 v203, v203, v19, v20
	v_max3_f32 v203, v203, v21, v22
	v_max3_f32 v203, v203, v23, v24
	v_max3_f32 v203, v203, v25, v26
	v_max3_f32 v203, v203, v27, v28
	v_max3_f32 v203, v203, v29, v30
	v_max_f32_e32 v203, v203, v31
	v_mov_b32_e32 v205, v203
	s_nop 1
	v_permlane16_swap_b32_e32 v203, v205
	v_max_f32_e32 v203, v203, v205
	v_mov_b32_e32 v205, v203
	s_nop 1
	v_permlane32_swap_b32_e32 v203, v205
	v_max_f32_e32 v203, v203, v205
	v_max_f32_e32 v218, v246, v203
	v_sub_f32_e32 v220, v246, v218
	v_mov_b32_e32 v219, v218
	v_exp_f32_e32 v220, v220
	v_mov_b32_e32 v246, v218
	v_pk_add_f32 v[0:1], v[0:1], v[218:219] neg_lo:[0,1] neg_hi:[0,1]
	v_pk_add_f32 v[2:3], v[2:3], v[218:219] neg_lo:[0,1] neg_hi:[0,1]
	v_pk_add_f32 v[4:5], v[4:5], v[218:219] neg_lo:[0,1] neg_hi:[0,1]
	v_pk_add_f32 v[6:7], v[6:7], v[218:219] neg_lo:[0,1] neg_hi:[0,1]
	v_pk_add_f32 v[8:9], v[8:9], v[218:219] neg_lo:[0,1] neg_hi:[0,1]
	v_pk_add_f32 v[10:11], v[10:11], v[218:219] neg_lo:[0,1] neg_hi:[0,1]
	v_pk_add_f32 v[12:13], v[12:13], v[218:219] neg_lo:[0,1] neg_hi:[0,1]
	v_pk_add_f32 v[14:15], v[14:15], v[218:219] neg_lo:[0,1] neg_hi:[0,1]
	v_pk_add_f32 v[16:17], v[16:17], v[218:219] neg_lo:[0,1] neg_hi:[0,1]
	v_pk_add_f32 v[18:19], v[18:19], v[218:219] neg_lo:[0,1] neg_hi:[0,1]
	v_pk_add_f32 v[20:21], v[20:21], v[218:219] neg_lo:[0,1] neg_hi:[0,1]
	v_pk_add_f32 v[22:23], v[22:23], v[218:219] neg_lo:[0,1] neg_hi:[0,1]
	v_pk_add_f32 v[24:25], v[24:25], v[218:219] neg_lo:[0,1] neg_hi:[0,1]
	v_pk_add_f32 v[26:27], v[26:27], v[218:219] neg_lo:[0,1] neg_hi:[0,1]
	v_pk_add_f32 v[28:29], v[28:29], v[218:219] neg_lo:[0,1] neg_hi:[0,1]
	v_pk_add_f32 v[30:31], v[30:31], v[218:219] neg_lo:[0,1] neg_hi:[0,1]
	v_exp_f32_e32 v0, v0
	v_exp_f32_e32 v1, v1
	v_exp_f32_e32 v2, v2
	v_exp_f32_e32 v3, v3
	v_exp_f32_e32 v4, v4
	v_exp_f32_e32 v5, v5
	v_exp_f32_e32 v6, v6
	v_exp_f32_e32 v7, v7
	v_exp_f32_e32 v8, v8
	v_exp_f32_e32 v9, v9
	v_exp_f32_e32 v10, v10
	v_exp_f32_e32 v11, v11
	v_exp_f32_e32 v12, v12
	v_exp_f32_e32 v13, v13
	v_exp_f32_e32 v14, v14
	v_exp_f32_e32 v15, v15
	v_exp_f32_e32 v16, v16
	v_exp_f32_e32 v17, v17
	v_exp_f32_e32 v18, v18
	v_exp_f32_e32 v19, v19
	v_exp_f32_e32 v20, v20
	v_exp_f32_e32 v21, v21
	v_exp_f32_e32 v22, v22
	v_exp_f32_e32 v23, v23
	v_exp_f32_e32 v24, v24
	v_exp_f32_e32 v25, v25
	v_exp_f32_e32 v26, v26
	v_exp_f32_e32 v27, v27
	v_exp_f32_e32 v28, v28
	v_exp_f32_e32 v29, v29
	v_exp_f32_e32 v30, v30
	v_exp_f32_e32 v31, v31
	ds_read_b128 v[112:115], v225 offset:0
	ds_read_b128 v[116:119], v225 offset:4096
	ds_read_b128 v[120:123], v225 offset:8192
	ds_read_b128 v[124:127], v225 offset:12288
	ds_read_b128 v[128:131], v226 offset:0
	ds_read_b128 v[132:135], v226 offset:4096
	ds_read_b128 v[136:139], v226 offset:8192
	ds_read_b128 v[140:143], v226 offset:12288
	v_mov_b32_e32 v221, v220
	v_pk_add_f32 v[222:223], v[0:1], v[2:3]
	v_pk_add_f32 v[222:223], v[222:223], v[4:5]
	v_pk_add_f32 v[222:223], v[222:223], v[6:7]
	v_pk_add_f32 v[222:223], v[222:223], v[8:9]
	v_pk_add_f32 v[222:223], v[222:223], v[10:11]
	v_pk_add_f32 v[222:223], v[222:223], v[12:13]
	v_pk_add_f32 v[222:223], v[222:223], v[14:15]
	v_pk_add_f32 v[222:223], v[222:223], v[16:17]
	v_pk_add_f32 v[222:223], v[222:223], v[18:19]
	v_pk_add_f32 v[222:223], v[222:223], v[20:21]
	v_pk_add_f32 v[222:223], v[222:223], v[22:23]
	v_pk_add_f32 v[222:223], v[222:223], v[24:25]
	v_pk_add_f32 v[222:223], v[222:223], v[26:27]
	v_pk_add_f32 v[222:223], v[222:223], v[28:29]
	v_pk_add_f32 v[222:223], v[222:223], v[30:31]
	v_pk_mul_f32 v[176:177], v[176:177], v[220:221]
	v_pk_mul_f32 v[178:179], v[178:179], v[220:221]
	v_pk_mul_f32 v[180:181], v[180:181], v[220:221]
	v_pk_mul_f32 v[182:183], v[182:183], v[220:221]
	v_pk_mul_f32 v[192:193], v[192:193], v[220:221]
	v_pk_mul_f32 v[194:195], v[194:195], v[220:221]
	v_pk_mul_f32 v[196:197], v[196:197], v[220:221]
	v_pk_mul_f32 v[198:199], v[198:199], v[220:221]
	v_add_f32_e32 v203, v222, v223
	v_fma_f32 v247, v247, v220, v203
	v_cvt_pk_bf16_f32 v48, v0, v1
	v_cvt_pk_bf16_f32 v49, v2, v3
	v_cvt_pk_bf16_f32 v50, v4, v5
	v_cvt_pk_bf16_f32 v51, v6, v7
	v_cvt_pk_bf16_f32 v52, v8, v9
	v_cvt_pk_bf16_f32 v53, v10, v11
	v_cvt_pk_bf16_f32 v54, v12, v13
	v_cvt_pk_bf16_f32 v55, v14, v15
	v_cvt_pk_bf16_f32 v56, v16, v17
	v_cvt_pk_bf16_f32 v57, v18, v19
	v_cvt_pk_bf16_f32 v58, v20, v21
	v_cvt_pk_bf16_f32 v59, v22, v23
	v_cvt_pk_bf16_f32 v60, v24, v25
	v_cvt_pk_bf16_f32 v61, v26, v27
	v_cvt_pk_bf16_f32 v62, v28, v29
	v_cvt_pk_bf16_f32 v63, v30, v31
	s_waitcnt lgkmcnt(7)
	v_mfma_f32_16x16x32_bf16 v[176:179], v[112:115], v[48:51], v[176:179]
	ds_read_b128 v[112:115], v227 offset:0
	s_waitcnt lgkmcnt(7)
	v_mfma_f32_16x16x32_bf16 v[180:183], v[116:119], v[48:51], v[180:183]
	ds_read_b128 v[116:119], v227 offset:4096
	s_waitcnt lgkmcnt(7)
	v_mfma_f32_16x16x32_bf16 v[192:195], v[120:123], v[48:51], v[192:195]
	ds_read_b128 v[120:123], v227 offset:8192
	s_waitcnt lgkmcnt(7)
; __device__ __forceinline__ void attn_phase(const Params& P, char* smem_raw) {
;     ...
; #pragma unroll
;         for (int td = 0; td < 4; ++td) {
;           const bf16x8 vf = *reinterpret_cast<const bf16x8*>(&sm_vt[(td * 16 + (lane_c & 15)) * 136 + s4 * 32 + (lane_c >> 4) * 8]);
;           o[td] = __builtin_amdgcn_mfma_f32_16x16x32_bf16(pf, vf, o[td], 0, 0, 0);
;         }
;       }
;     }
;     u16* Ob = P.cat + ((long)b * 8192 + r * 64) * 1024 + h * 64;
; #pragma unroll
;     for (int td = 0; td < 4; ++td)
; #pragma unroll
;       for (int reg = 0; reg < 4; ++reg) {
;         const int rowl = wid * 16 + (lane >> 4) * 4 + reg;
;         Ob[(unsigned)(rowl * 1024 + td * 16 + (lane & 15))] = f2bf(o[td][reg] * __builtin_amdgcn_rcpf(lrow[reg]));
;       }
	v_mfma_f32_16x16x32_bf16 v[196:199], v[124:127], v[48:51], v[196:199]
	ds_read_b128 v[124:127], v227 offset:12288
	s_waitcnt lgkmcnt(7)
	v_mfma_f32_16x16x32_bf16 v[176:179], v[128:131], v[52:55], v[176:179]
	ds_read_b128 v[128:131], v228 offset:0
	s_waitcnt lgkmcnt(7)
	v_mfma_f32_16x16x32_bf16 v[180:183], v[132:135], v[52:55], v[180:183]
	ds_read_b128 v[132:135], v228 offset:4096
	s_waitcnt lgkmcnt(7)
	v_mfma_f32_16x16x32_bf16 v[192:195], v[136:139], v[52:55], v[192:195]
	ds_read_b128 v[136:139], v228 offset:8192
	s_waitcnt lgkmcnt(7)
	v_mfma_f32_16x16x32_bf16 v[196:199], v[140:143], v[52:55], v[196:199]
	ds_read_b128 v[140:143], v228 offset:12288
	s_waitcnt lgkmcnt(7)
	v_mfma_f32_16x16x32_bf16 v[176:179], v[112:115], v[56:59], v[176:179]
	s_waitcnt lgkmcnt(6)
	v_mfma_f32_16x16x32_bf16 v[180:183], v[116:119], v[56:59], v[180:183]
	s_waitcnt lgkmcnt(5)
	v_mfma_f32_16x16x32_bf16 v[192:195], v[120:123], v[56:59], v[192:195]
	s_waitcnt lgkmcnt(4)
	v_mfma_f32_16x16x32_bf16 v[196:199], v[124:127], v[56:59], v[196:199]
	s_waitcnt lgkmcnt(3)
	v_mfma_f32_16x16x32_bf16 v[176:179], v[128:131], v[60:63], v[176:179]
	s_waitcnt lgkmcnt(2)
	v_mfma_f32_16x16x32_bf16 v[180:183], v[132:135], v[60:63], v[180:183]
	s_waitcnt lgkmcnt(1)
	v_mfma_f32_16x16x32_bf16 v[192:195], v[136:139], v[60:63], v[192:195]
	s_waitcnt lgkmcnt(0)
	v_mfma_f32_16x16x32_bf16 v[196:199], v[140:143], v[60:63], v[196:199]
	ds_read_b32 v0, v184 offset:384
	ds_read_b32 v1, v185 offset:384
	ds_read_b32 v2, v186 offset:384
	ds_read_b32 v3, v187 offset:384
	ds_read_b32 v4, v184 offset:512
	ds_read_b32 v5, v185 offset:512
	ds_read_b32 v6, v186 offset:512
	ds_read_b32 v7, v187 offset:512
	ds_read_b32 v8, v188 offset:384
	ds_read_b32 v9, v189 offset:384
	ds_read_b32 v10, v190 offset:384
	ds_read_b32 v11, v191 offset:384
	ds_read_b32 v12, v188 offset:512
	ds_read_b32 v13, v189 offset:512
	ds_read_b32 v14, v190 offset:512
	ds_read_b32 v15, v191 offset:512
	s_waitcnt lgkmcnt(0)
	v_mov_b32_e32 v205, v201
	s_nop 1
	v_permlane16_swap_b32_e32 v201, v205
	v_add_f32_e32 v201, v201, v205
	v_mov_b32_e32 v205, v201
	s_nop 1
	v_permlane32_swap_b32_e32 v201, v205
	v_add_f32_e32 v201, v201, v205
	v_rcp_f32_e32 v203, v201
	s_nop 7
	v_mul_f32_e32 v32, v32, v203
	v_mul_f32_e32 v33, v33, v203
	v_mul_f32_e32 v34, v34, v203
	v_mul_f32_e32 v35, v35, v203
	v_mul_f32_e32 v36, v36, v203
	v_mul_f32_e32 v37, v37, v203
	v_mul_f32_e32 v38, v38, v203
	v_mul_f32_e32 v39, v39, v203
	v_mul_f32_e32 v40, v40, v203
	v_mul_f32_e32 v41, v41, v203
	v_mul_f32_e32 v42, v42, v203
	v_mul_f32_e32 v43, v43, v203
	v_mul_f32_e32 v44, v44, v203
	v_mul_f32_e32 v45, v45, v203
	v_mul_f32_e32 v46, v46, v203
	v_mul_f32_e32 v47, v47, v203
	v_cvt_pk_bf16_f32 v210, v32, v33
	v_cvt_pk_bf16_f32 v211, v34, v35
	v_cvt_pk_bf16_f32 v212, v36, v37
	v_cvt_pk_bf16_f32 v213, v38, v39
	v_cvt_pk_bf16_f32 v214, v40, v41
	v_cvt_pk_bf16_f32 v215, v42, v43
	v_cvt_pk_bf16_f32 v216, v44, v45
	v_cvt_pk_bf16_f32 v217, v46, v47
	global_store_dwordx2 v167, v[210:211], s[98:99] offset:0
	global_store_dwordx2 v167, v[212:213], s[98:99] offset:32
	global_store_dwordx2 v167, v[214:215], s[98:99] offset:64
	global_store_dwordx2 v167, v[216:217], s[98:99] offset:96
	v_mov_b32_e32 v200, 0xf149f2ca
	v_mov_b32_e32 v201, 0
	v_mov_b32_e32 v32, 0
	v_mov_b32_e32 v33, 0
	v_mov_b32_e32 v34, 0
	v_mov_b32_e32 v35, 0
	v_mov_b32_e32 v36, 0
	v_mov_b32_e32 v37, 0
	v_mov_b32_e32 v38, 0
	v_mov_b32_e32 v39, 0
	v_mov_b32_e32 v40, 0
	v_mov_b32_e32 v41, 0
	v_mov_b32_e32 v42, 0
	v_mov_b32_e32 v43, 0
	v_mov_b32_e32 v44, 0
	v_mov_b32_e32 v45, 0
	v_mov_b32_e32 v46, 0
	v_mov_b32_e32 v47, 0
	v_mov_b32_e32 v64, v72
	v_mov_b32_e32 v65, v73
	v_mov_b32_e32 v66, v74
	v_mov_b32_e32 v67, v75
	v_mov_b32_e32 v68, v76
	v_mov_b32_e32 v69, v77
	v_mov_b32_e32 v70, v78
	v_mov_b32_e32 v71, v79
	v_mov_b32_e32 v205, v247
	s_nop 1
	v_permlane16_swap_b32_e32 v247, v205
	v_add_f32_e32 v247, v247, v205
	v_mov_b32_e32 v205, v247
	s_nop 1
	v_permlane32_swap_b32_e32 v247, v205
	v_add_f32_e32 v247, v247, v205
	v_rcp_f32_e32 v203, v247
	s_nop 7
	v_mul_f32_e32 v176, v176, v203
	v_mul_f32_e32 v177, v177, v203
	v_mul_f32_e32 v178, v178, v203
	v_mul_f32_e32 v179, v179, v203
	v_mul_f32_e32 v180, v180, v203
	v_mul_f32_e32 v181, v181, v203
	v_mul_f32_e32 v182, v182, v203
	v_mul_f32_e32 v183, v183, v203
	v_mul_f32_e32 v192, v192, v203
	v_mul_f32_e32 v193, v193, v203
	v_mul_f32_e32 v194, v194, v203
	v_mul_f32_e32 v195, v195, v203
	v_mul_f32_e32 v196, v196, v203
	v_mul_f32_e32 v197, v197, v203
	v_mul_f32_e32 v198, v198, v203
	v_mul_f32_e32 v199, v199, v203
	v_cvt_pk_bf16_f32 v210, v176, v177
	v_cvt_pk_bf16_f32 v211, v178, v179
	v_cvt_pk_bf16_f32 v212, v180, v181
	v_cvt_pk_bf16_f32 v213, v182, v183
	v_cvt_pk_bf16_f32 v214, v192, v193
	v_cvt_pk_bf16_f32 v215, v194, v195
	v_cvt_pk_bf16_f32 v216, v196, v197
	v_cvt_pk_bf16_f32 v217, v198, v199
	s_add_u32 s0, s98, 0x20000
	s_addc_u32 s1, s99, 0
	global_store_dwordx2 v167, v[210:211], s[0:1] offset:0
	global_store_dwordx2 v167, v[212:213], s[0:1] offset:32
	global_store_dwordx2 v167, v[214:215], s[0:1] offset:64
	global_store_dwordx2 v167, v[216:217], s[0:1] offset:96
	v_mov_b32_e32 v246, 0xf149f2ca
	v_mov_b32_e32 v247, 0
	v_mov_b32_e32 v176, 0
	v_mov_b32_e32 v177, 0
	v_mov_b32_e32 v178, 0
	v_mov_b32_e32 v179, 0
	v_mov_b32_e32 v180, 0
	v_mov_b32_e32 v181, 0
	v_mov_b32_e32 v182, 0
	v_mov_b32_e32 v183, 0
	v_mov_b32_e32 v192, 0
	v_mov_b32_e32 v193, 0
	v_mov_b32_e32 v194, 0
	v_mov_b32_e32 v195, 0
	v_mov_b32_e32 v196, 0
	v_mov_b32_e32 v197, 0
	v_mov_b32_e32 v198, 0
	v_mov_b32_e32 v199, 0
	v_mov_b32_e32 v230, v238
	v_mov_b32_e32 v231, v239
	v_mov_b32_e32 v232, v240
	v_mov_b32_e32 v233, v241
	v_mov_b32_e32 v234, v242
	v_mov_b32_e32 v235, v243
	v_mov_b32_e32 v236, v244
	v_mov_b32_e32 v237, v245
	s_add_u32 s3, s3, 1
	s_barrier
; __device__ __forceinline__ void attn_phase(const Params& P, char* smem_raw) {
;     ...
;         *reinterpret_cast<uint4*>(&sm_k[(idx >> 3) * LDSS + (idx & 7) * 8]) = kreg[i];
;         *reinterpret_cast<uint4*>(&sm_vt[(idx >> 4) * 136 + (idx & 15) * 8]) = vreg[i];
;       }
;       __syncthreads();
;       f32x4 sacc[8];
; #pragma unroll
;       for (int t8 = 0; t8 < 8; ++t8) sacc[t8] = f32x4{0.f, 0.f, 0.f, 0.f};
; #pragma unroll
;       for (int s = 0; s < 2; ++s)
; #pragma unroll
;         for (int t8 = 0; t8 < 8; ++t8) {
;           const bf16x8 kf = *reinterpret_cast<const bf16x8*>(&sm_k[(t8 * 16 + (lane_c & 15)) * LDSS + s * 32 + (lane_c >> 4) * 8]);
;           sacc[t8] = __builtin_amdgcn_mfma_f32_16x16x32_bf16(qf[s], kf, sacc[t8], 0, 0, 0);
;         }
;       if (ck < 5) {
;         ATT_ISSUE(t, ck + 1)
;       } else if (t + VGRID < 8192) {
;         ATT_ISSUE(t + VGRID, 0)
;         ATT_QLOAD(t + VGRID)
;       }
;       if (ck < 4) {
;         const float* rb0 = sm_rpb + (rs + ck * 2 - r + 7) * 31;
; #pragma unroll
;         for (int t8 = 0; t8 < 8; ++t8)
; #pragma unroll
;           for (int reg = 0; reg < 4; ++reg)
;             sacc[t8][reg] += rb0[(t8 >> 2) * 31 + dco[reg][t8 & 3]];
;       }
; #pragma unroll
;       for (int reg = 0; reg < 4; ++reg) {
;         float mx = sacc[0][reg];
; #pragma unroll
;         for (int t8 = 1; t8 < 8; ++t8) mx = fmaxf(mx, sacc[t8][reg]);
;         mx = row16_max(mx);
;         const float mnew = fmaxf(mrow[reg], mx);
;         const float alpha = __builtin_amdgcn_exp2f(mrow[reg] - mnew);
;         mrow[reg] = mnew;
;         float rsum = 0.f;
; #pragma unroll
;         for (int t8 = 0; t8 < 8; ++t8) {
;           const float p = __builtin_amdgcn_exp2f(sacc[t8][reg] - mnew);
;           rsum += p;
;           sm_p[(wid * 16 + (lane_c >> 4) * 4 + reg) * 136 + t8 * 16 + (lane_c & 15)] = f2bf(p);
;         }
;         rsum = row16_sum(rsum);
;         lrow[reg] = lrow[reg] * alpha + rsum;
; #pragma unroll
;         for (int td = 0; td < 4; ++td) o[td][reg] *= alpha;
;       }
;       asm volatile("s_waitcnt lgkmcnt(0)" ::: "memory");
; #pragma unroll
;       for (int s4 = 0; s4 < 4; ++s4) {
;         const bf16x8 pf = *reinterpret_cast<const bf16x8*>(&sm_p[(wid * 16 + (lane_c & 15)) * 136 + s4 * 32 + (lane_c >> 4) * 8]);
; #pragma unroll
;         for (int td = 0; td < 4; ++td) {
	ds_read_b128 v[112:115], v144 offset:32768
	ds_read_b128 v[116:119], v145 offset:32768
	ds_read_b128 v[120:123], v144 offset:40960
	ds_read_b128 v[124:127], v145 offset:40960
	ds_read_b128 v[128:131], v144 offset:34816
	ds_read_b128 v[132:135], v145 offset:34816
	ds_read_b128 v[136:139], v144 offset:43008
	ds_read_b128 v[140:143], v145 offset:43008
	s_waitcnt lgkmcnt(7)
	v_mfma_f32_16x16x32_bf16 v[0:3], v[112:115], v[64:67], v[0:3]
	s_waitcnt lgkmcnt(6)
	v_mfma_f32_16x16x32_bf16 v[0:3], v[116:119], v[68:71], v[0:3]
	s_waitcnt lgkmcnt(5)
	v_mfma_f32_16x16x32_bf16 v[4:7], v[120:123], v[64:67], v[4:7]
	s_waitcnt lgkmcnt(4)
	v_mfma_f32_16x16x32_bf16 v[4:7], v[124:127], v[68:71], v[4:7]
	s_waitcnt lgkmcnt(3)
	v_mfma_f32_16x16x32_bf16 v[8:11], v[128:131], v[64:67], v[8:11]
	s_waitcnt lgkmcnt(2)
	v_mfma_f32_16x16x32_bf16 v[8:11], v[132:135], v[68:71], v[8:11]
	s_waitcnt lgkmcnt(1)
	v_mfma_f32_16x16x32_bf16 v[12:15], v[136:139], v[64:67], v[12:15]
	s_waitcnt lgkmcnt(0)
	v_mfma_f32_16x16x32_bf16 v[12:15], v[140:143], v[68:71], v[12:15]
	s_nop 7
	v_max3_f32 v203, v0, v1, v2
	v_max3_f32 v203, v203, v3, v4
	v_max3_f32 v203, v203, v5, v6
	v_max3_f32 v203, v203, v7, v8
	v_max3_f32 v203, v203, v9, v10
	v_max3_f32 v203, v203, v11, v12
	v_max3_f32 v203, v203, v13, v14
	v_max_f32_e32 v203, v203, v15
	v_mov_b32_e32 v205, v203
	s_nop 1
	v_permlane16_swap_b32_e32 v203, v205
	v_max_f32_e32 v203, v203, v205
	v_mov_b32_e32 v205, v203
	s_nop 1
	v_permlane32_swap_b32_e32 v203, v205
	v_max_f32_e32 v203, v203, v205
	v_max_f32_e32 v218, v200, v203
	v_sub_f32_e32 v220, v200, v218
	v_mov_b32_e32 v219, v218
	v_exp_f32_e32 v220, v220
	v_mov_b32_e32 v200, v218
	v_pk_add_f32 v[0:1], v[0:1], v[218:219] neg_lo:[0,1] neg_hi:[0,1]
	v_pk_add_f32 v[2:3], v[2:3], v[218:219] neg_lo:[0,1] neg_hi:[0,1]
	v_pk_add_f32 v[4:5], v[4:5], v[218:219] neg_lo:[0,1] neg_hi:[0,1]
	v_pk_add_f32 v[6:7], v[6:7], v[218:219] neg_lo:[0,1] neg_hi:[0,1]
	v_pk_add_f32 v[8:9], v[8:9], v[218:219] neg_lo:[0,1] neg_hi:[0,1]
	v_pk_add_f32 v[10:11], v[10:11], v[218:219] neg_lo:[0,1] neg_hi:[0,1]
	v_pk_add_f32 v[12:13], v[12:13], v[218:219] neg_lo:[0,1] neg_hi:[0,1]
	v_pk_add_f32 v[14:15], v[14:15], v[218:219] neg_lo:[0,1] neg_hi:[0,1]
	v_exp_f32_e32 v0, v0
	s_waitcnt vmcnt(8)
	v_exp_f32_e32 v1, v1
	ds_write_b128 v150, v[80:83] offset:0
	v_exp_f32_e32 v2, v2
	ds_write_b128 v150, v[84:87] offset:4096
	v_exp_f32_e32 v3, v3
	ds_write_b128 v150, v[88:91] offset:8192
	v_exp_f32_e32 v4, v4
	ds_write_b128 v150, v[92:95] offset:12288
	v_exp_f32_e32 v5, v5
	ds_write_b64 v151, v[96:97] offset:0
	v_exp_f32_e32 v6, v6
	ds_write_b64 v229, v[98:99] offset:0
	v_exp_f32_e32 v7, v7
	ds_write_b64 v151, v[100:101] offset:4096
	v_exp_f32_e32 v8, v8
	ds_write_b64 v229, v[102:103] offset:4096
	v_exp_f32_e32 v9, v9
	ds_write_b64 v151, v[104:105] offset:8192
	v_exp_f32_e32 v10, v10
	ds_write_b64 v229, v[106:107] offset:8192
	v_exp_f32_e32 v11, v11
	ds_write_b64 v151, v[108:109] offset:12288
	v_exp_f32_e32 v12, v12
	ds_write_b64 v229, v[110:111] offset:12288
	v_exp_f32_e32 v13, v13
	s_add_u32 s100, s12, 0x180000
	v_exp_f32_e32 v14, v14
	s_addc_u32 s101, s13, 0
	v_exp_f32_e32 v15, v15
	s_add_u32 s0, s14, 0x200
	s_addc_u32 s1, s15, 0
	global_load_dwordx4 v[80:83], v154, s[100:101] offset:2048
	global_load_dwordx4 v[96:99], v158, s[0:1]
	global_load_dwordx4 v[84:87], v155, s[100:101] offset:2048
	global_load_dwordx4 v[100:103], v159, s[0:1]
	global_load_dwordx4 v[88:91], v156, s[100:101] offset:2048
	global_load_dwordx4 v[104:107], v160, s[0:1]
	global_load_dwordx4 v[92:95], v157, s[100:101] offset:2048
	global_load_dwordx4 v[108:111], v161, s[0:1]
	s_and_b32 s0, s3, 0xff
	s_lshr_b32 s1, s0, 1
	s_and_b32 s0, s0, 1
	s_lshl_b32 s0, s0, 5
	s_lshr_b32 vcc_lo, s3, 12
	s_add_u32 s0, s0, vcc_lo
	s_lshl_b32 s0, s0, 1
	s_sub_i32 vcc_lo, s0, 4
	s_max_i32 vcc_lo, vcc_lo, 0
	s_min_i32 vcc_lo, vcc_lo, 0x78
	s_lshl_b32 vcc_hi, s1, 13
	s_sub_i32 s19, s0, 3
	s_max_i32 s19, s19, 0
	s_min_i32 s19, s19, 0x78
	s_sub_i32 s19, vcc_lo, s19
	s_lshl_b32 m0, s1, 8
	s_add_u32 m0, m0, 0x8000
	s_mul_i32 m0, m0, 0x1800
	s_add_u32 s16, s4, m0
	s_addc_u32 s17, s5, 0
	s_lshl_b32 m0, s1, 19
	s_add_u32 s36, s8, m0
	s_addc_u32 s37, s9, 0
	s_lshl_b32 m0, s0, 6
	s_add_u32 m0, m0, vcc_hi
	s_lshl_b32 m0, m0, 11
	s_add_u32 s98, s10, m0
	s_addc_u32 s99, s11, 0
	ds_read_b128 v[112:115], v146 offset:32768
	ds_read_b128 v[116:119], v146 offset:36864
	ds_read_b128 v[120:123], v146 offset:40960
	ds_read_b128 v[124:127], v146 offset:45056
	ds_read_b128 v[128:131], v147 offset:32768
	ds_read_b128 v[132:135], v147 offset:36864
	ds_read_b128 v[136:139], v147 offset:40960
	ds_read_b128 v[140:143], v147 offset:45056
	v_mov_b32_e32 v221, v220
	v_pk_add_f32 v[222:223], v[0:1], v[2:3]
	v_pk_add_f32 v[222:223], v[222:223], v[4:5]
	v_pk_add_f32 v[222:223], v[222:223], v[6:7]
	v_pk_add_f32 v[222:223], v[222:223], v[8:9]
	v_pk_add_f32 v[222:223], v[222:223], v[10:11]
	v_pk_add_f32 v[222:223], v[222:223], v[12:13]
	v_pk_add_f32 v[222:223], v[222:223], v[14:15]
	v_pk_mul_f32 v[32:33], v[32:33], v[220:221]
	v_pk_mul_f32 v[34:35], v[34:35], v[220:221]
	v_pk_mul_f32 v[36:37], v[36:37], v[220:221]
	v_pk_mul_f32 v[38:39], v[38:39], v[220:221]
	v_pk_mul_f32 v[40:41], v[40:41], v[220:221]
	v_pk_mul_f32 v[42:43], v[42:43], v[220:221]
	v_pk_mul_f32 v[44:45], v[44:45], v[220:221]
	v_pk_mul_f32 v[46:47], v[46:47], v[220:221]
	v_add_f32_e32 v203, v222, v223
	v_fma_f32 v201, v201, v220, v203
	v_cvt_pk_bf16_f32 v48, v0, v1
	v_cvt_pk_bf16_f32 v49, v2, v3
	v_cvt_pk_bf16_f32 v50, v4, v5
	v_cvt_pk_bf16_f32 v51, v6, v7
	v_cvt_pk_bf16_f32 v52, v8, v9
	v_cvt_pk_bf16_f32 v53, v10, v11
	v_cvt_pk_bf16_f32 v54, v12, v13
	v_cvt_pk_bf16_f32 v55, v14, v15
	s_waitcnt lgkmcnt(7)
	v_mfma_f32_16x16x32_bf16 v[32:35], v[112:115], v[48:51], v[32:35]
	s_waitcnt lgkmcnt(6)
	v_mfma_f32_16x16x32_bf16 v[36:39], v[116:119], v[48:51], v[36:39]
	s_waitcnt lgkmcnt(5)
	v_mfma_f32_16x16x32_bf16 v[40:43], v[120:123], v[48:51], v[40:43]
	s_waitcnt lgkmcnt(4)
	v_mfma_f32_16x16x32_bf16 v[44:47], v[124:127], v[48:51], v[44:47]
	s_waitcnt lgkmcnt(3)
	v_mfma_f32_16x16x32_bf16 v[32:35], v[128:131], v[52:55], v[32:35]
	s_waitcnt lgkmcnt(2)
	v_mfma_f32_16x16x32_bf16 v[36:39], v[132:135], v[52:55], v[36:39]
	s_waitcnt lgkmcnt(1)
	v_mfma_f32_16x16x32_bf16 v[40:43], v[136:139], v[52:55], v[40:43]
	s_waitcnt lgkmcnt(0)
	v_mfma_f32_16x16x32_bf16 v[44:47], v[140:143], v[52:55], v[44:47]
	s_cmp_eq_u32 s19, 0
	s_cbranch_scc1 .Lmy_att_b0_2
	v_mov_b32_e32 v0, 0xf149f2ca
	v_mov_b32_e32 v1, 0xf149f2ca
	v_mov_b32_e32 v2, 0xf149f2ca
	v_mov_b32_e32 v3, 0xf149f2ca
	v_mov_b32_e32 v8, 0xf149f2ca
	v_mov_b32_e32 v9, 0xf149f2ca
	v_mov_b32_e32 v10, 0xf149f2ca
	v_mov_b32_e32 v11, 0xf149f2ca
	s_branch .Lmy_att_b1_2

; __device__ __forceinline__ void attn_phase(const Params& P, char* smem_raw) {
;     ...
; #pragma unroll
;       for (int s = 0; s < 2; ++s)
; #pragma unroll
;         for (int t8 = 0; t8 < 8; ++t8) {
;           const bf16x8 kf = *reinterpret_cast<const bf16x8*>(&sm_k[(t8 * 16 + (lane_c & 15)) * LDSS + s * 32 + (lane_c >> 4) * 8]);
;           sacc[t8] = __builtin_amdgcn_mfma_f32_16x16x32_bf16(qf[s], kf, sacc[t8], 0, 0, 0);
;         }
;       if (ck < 5) {
;         ATT_ISSUE(t, ck + 1)
;       } else if (t + VGRID < 8192) {
;         ATT_ISSUE(t + VGRID, 0)
;         ATT_QLOAD(t + VGRID)
;       }
;       if (ck < 4) {
;         const float* rb0 = sm_rpb + (rs + ck * 2 - r + 7) * 31;
; #pragma unroll
;         for (int t8 = 0; t8 < 8; ++t8)
; #pragma unroll
;           for (int reg = 0; reg < 4; ++reg)
;             sacc[t8][reg] += rb0[(t8 >> 2) * 31 + dco[reg][t8 & 3]];
;       }
; #pragma unroll
;       for (int reg = 0; reg < 4; ++reg) {
;         float mx = sacc[0][reg];
; #pragma unroll
;         for (int t8 = 1; t8 < 8; ++t8) mx = fmaxf(mx, sacc[t8][reg]);
;         mx = row16_max(mx);
;         const float mnew = fmaxf(mrow[reg], mx);
;         const float alpha = __builtin_amdgcn_exp2f(mrow[reg] - mnew);
;         mrow[reg] = mnew;
;         float rsum = 0.f;
; #pragma unroll
;         for (int t8 = 0; t8 < 8; ++t8) {
;           const float p = __builtin_amdgcn_exp2f(sacc[t8][reg] - mnew);
;           rsum += p;
;           sm_p[(wid * 16 + (lane_c >> 4) * 4 + reg) * 136 + t8 * 16 + (lane_c & 15)] = f2bf(p);
;         }
;         rsum = row16_sum(rsum);
;         lrow[reg] = lrow[reg] * alpha + rsum;
; #pragma unroll
;         for (int td = 0; td < 4; ++td) o[td][reg] *= alpha;
;       }
;       asm volatile("s_waitcnt lgkmcnt(0)" ::: "memory");
; #pragma unroll
;       for (int s4 = 0; s4 < 4; ++s4) {
;         const bf16x8 pf = *reinterpret_cast<const bf16x8*>(&sm_p[(wid * 16 + (lane_c & 15)) * 136 + s4 * 32 + (lane_c >> 4) * 8]);
; #pragma unroll
;         for (int td = 0; td < 4; ++td) {
;           const bf16x8 vf = *reinterpret_cast<const bf16x8*>(&sm_vt[(td * 16 + (lane_c & 15)) * 136 + s4 * 32 + (lane_c >> 4) * 8]);
;           o[td] = __builtin_amdgcn_mfma_f32_16x16x32_bf16(pf, vf, o[td], 0, 0, 0);
;         }
;       }
.Lmy_att_b1_2:
	ds_read_b32 v4, v184 offset:384
	ds_read_b32 v5, v185 offset:384
	ds_read_b32 v6, v186 offset:384
	ds_read_b32 v7, v187 offset:384
	ds_read_b32 v12, v188 offset:384
	ds_read_b32 v13, v189 offset:384
	ds_read_b32 v14, v190 offset:384
	ds_read_b32 v15, v191 offset:384
	ds_read_b128 v[112:115], v144 offset:32768
	ds_read_b128 v[116:119], v145 offset:32768
	ds_read_b128 v[120:123], v144 offset:40960
	ds_read_b128 v[124:127], v145 offset:40960
	ds_read_b128 v[128:131], v144 offset:34816
	ds_read_b128 v[132:135], v145 offset:34816
	ds_read_b128 v[136:139], v144 offset:43008
	ds_read_b128 v[140:143], v145 offset:43008
	s_waitcnt lgkmcnt(7)
	v_mfma_f32_16x16x32_bf16 v[0:3], v[112:115], v[230:233], v[0:3]
	s_waitcnt lgkmcnt(6)
	v_mfma_f32_16x16x32_bf16 v[0:3], v[116:119], v[234:237], v[0:3]
	s_waitcnt lgkmcnt(5)
	v_mfma_f32_16x16x32_bf16 v[4:7], v[120:123], v[230:233], v[4:7]
	s_waitcnt lgkmcnt(4)
	v_mfma_f32_16x16x32_bf16 v[4:7], v[124:127], v[234:237], v[4:7]
	s_waitcnt lgkmcnt(3)
	v_mfma_f32_16x16x32_bf16 v[8:11], v[128:131], v[230:233], v[8:11]
	s_waitcnt lgkmcnt(2)
	v_mfma_f32_16x16x32_bf16 v[8:11], v[132:135], v[234:237], v[8:11]
	s_waitcnt lgkmcnt(1)
	v_mfma_f32_16x16x32_bf16 v[12:15], v[136:139], v[230:233], v[12:15]
	s_waitcnt lgkmcnt(0)
	v_mfma_f32_16x16x32_bf16 v[12:15], v[140:143], v[234:237], v[12:15]
	s_nop 7
	v_max3_f32 v203, v0, v1, v2
	v_max3_f32 v203, v203, v3, v4
	v_max3_f32 v203, v203, v5, v6
	v_max3_f32 v203, v203, v7, v8
	v_max3_f32 v203, v203, v9, v10
	v_max3_f32 v203, v203, v11, v12
	v_max3_f32 v203, v203, v13, v14
	v_max_f32_e32 v203, v203, v15
	v_mov_b32_e32 v205, v203
	s_nop 1
	v_permlane16_swap_b32_e32 v203, v205
	v_max_f32_e32 v203, v203, v205
	v_mov_b32_e32 v205, v203
	s_nop 1
	v_permlane32_swap_b32_e32 v203, v205
	v_max_f32_e32 v203, v203, v205
	v_max_f32_e32 v218, v246, v203
	v_sub_f32_e32 v220, v246, v218
	v_mov_b32_e32 v219, v218
	v_exp_f32_e32 v220, v220
	v_mov_b32_e32 v246, v218
	v_pk_add_f32 v[0:1], v[0:1], v[218:219] neg_lo:[0,1] neg_hi:[0,1]
	v_pk_add_f32 v[2:3], v[2:3], v[218:219] neg_lo:[0,1] neg_hi:[0,1]
	v_pk_add_f32 v[4:5], v[4:5], v[218:219] neg_lo:[0,1] neg_hi:[0,1]
	v_pk_add_f32 v[6:7], v[6:7], v[218:219] neg_lo:[0,1] neg_hi:[0,1]
	v_pk_add_f32 v[8:9], v[8:9], v[218:219] neg_lo:[0,1] neg_hi:[0,1]
	v_pk_add_f32 v[10:11], v[10:11], v[218:219] neg_lo:[0,1] neg_hi:[0,1]
	v_pk_add_f32 v[12:13], v[12:13], v[218:219] neg_lo:[0,1] neg_hi:[0,1]
	v_pk_add_f32 v[14:15], v[14:15], v[218:219] neg_lo:[0,1] neg_hi:[0,1]
	v_exp_f32_e32 v0, v0
	v_exp_f32_e32 v1, v1
	v_exp_f32_e32 v2, v2
	v_exp_f32_e32 v3, v3
	v_exp_f32_e32 v4, v4
	v_exp_f32_e32 v5, v5
	v_exp_f32_e32 v6, v6
	v_exp_f32_e32 v7, v7
	v_exp_f32_e32 v8, v8
	v_exp_f32_e32 v9, v9
	v_exp_f32_e32 v10, v10
	v_exp_f32_e32 v11, v11
	v_exp_f32_e32 v12, v12
	v_exp_f32_e32 v13, v13
	v_exp_f32_e32 v14, v14
	v_exp_f32_e32 v15, v15
	ds_read_b128 v[112:115], v146 offset:32768
	ds_read_b128 v[116:119], v146 offset:36864
	ds_read_b128 v[120:123], v146 offset:40960
	ds_read_b128 v[124:127], v146 offset:45056
	ds_read_b128 v[128:131], v147 offset:32768
	ds_read_b128 v[132:135], v147 offset:36864
	ds_read_b128 v[136:139], v147 offset:40960
	ds_read_b128 v[140:143], v147 offset:45056
	v_mov_b32_e32 v221, v220
	v_pk_add_f32 v[222:223], v[0:1], v[2:3]
	v_pk_add_f32 v[222:223], v[222:223], v[4:5]
	v_pk_add_f32 v[222:223], v[222:223], v[6:7]
	v_pk_add_f32 v[222:223], v[222:223], v[8:9]
	v_pk_add_f32 v[222:223], v[222:223], v[10:11]
	v_pk_add_f32 v[222:223], v[222:223], v[12:13]
	v_pk_add_f32 v[222:223], v[222:223], v[14:15]
	v_pk_mul_f32 v[176:177], v[176:177], v[220:221]
	v_pk_mul_f32 v[178:179], v[178:179], v[220:221]
	v_pk_mul_f32 v[180:181], v[180:181], v[220:221]
	v_pk_mul_f32 v[182:183], v[182:183], v[220:221]
	v_pk_mul_f32 v[192:193], v[192:193], v[220:221]
	v_pk_mul_f32 v[194:195], v[194:195], v[220:221]
	v_pk_mul_f32 v[196:197], v[196:197], v[220:221]
	v_pk_mul_f32 v[198:199], v[198:199], v[220:221]
	v_add_f32_e32 v203, v222, v223
	v_fma_f32 v247, v247, v220, v203
	v_cvt_pk_bf16_f32 v48, v0, v1
	v_cvt_pk_bf16_f32 v49, v2, v3
	v_cvt_pk_bf16_f32 v50, v4, v5
	v_cvt_pk_bf16_f32 v51, v6, v7
	v_cvt_pk_bf16_f32 v52, v8, v9
	v_cvt_pk_bf16_f32 v53, v10, v11
	v_cvt_pk_bf16_f32 v54, v12, v13
	v_cvt_pk_bf16_f32 v55, v14, v15
	s_waitcnt lgkmcnt(7)
	v_mfma_f32_16x16x32_bf16 v[176:179], v[112:115], v[48:51], v[176:179]
	s_waitcnt lgkmcnt(6)
	v_mfma_f32_16x16x32_bf16 v[180:183], v[116:119], v[48:51], v[180:183]
	s_waitcnt lgkmcnt(5)
	v_mfma_f32_16x16x32_bf16 v[192:195], v[120:123], v[48:51], v[192:195]
	s_waitcnt lgkmcnt(4)
	v_mfma_f32_16x16x32_bf16 v[196:199], v[124:127], v[48:51], v[196:199]
	s_waitcnt lgkmcnt(3)
	v_mfma_f32_16x16x32_bf16 v[176:179], v[128:131], v[52:55], v[176:179]
	s_waitcnt lgkmcnt(2)
	v_mfma_f32_16x16x32_bf16 v[180:183], v[132:135], v[52:55], v[180:183]
	s_waitcnt lgkmcnt(1)
	v_mfma_f32_16x16x32_bf16 v[192:195], v[136:139], v[52:55], v[192:195]
	s_waitcnt lgkmcnt(0)
	v_mfma_f32_16x16x32_bf16 v[196:199], v[140:143], v[52:55], v[196:199]
	ds_read_b32 v0, v184 offset:640
	ds_read_b32 v1, v185 offset:640
	ds_read_b32 v2, v186 offset:640
	ds_read_b32 v3, v187 offset:640
	ds_read_b32 v4, v184 offset:768
	ds_read_b32 v5, v185 offset:768
	ds_read_b32 v6, v186 offset:768
	ds_read_b32 v7, v187 offset:768
	ds_read_b32 v8, v188 offset:640
	ds_read_b32 v9, v189 offset:640
	ds_read_b32 v10, v190 offset:640
	ds_read_b32 v11, v191 offset:640
	ds_read_b32 v12, v188 offset:768
	ds_read_b32 v13, v189 offset:768
	ds_read_b32 v14, v190 offset:768
	ds_read_b32 v15, v191 offset:768
	s_waitcnt lgkmcnt(0)
	s_barrier
; __device__ __forceinline__ void attn_phase(const Params& P, char* smem_raw) {
;     ...
;         *reinterpret_cast<uint4*>(&sm_k[(idx >> 3) * LDSS + (idx & 7) * 8]) = kreg[i];
;         *reinterpret_cast<uint4*>(&sm_vt[(idx >> 4) * 136 + (idx & 15) * 8]) = vreg[i];
;       }
;       __syncthreads();
;       f32x4 sacc[8];
; #pragma unroll
;       for (int t8 = 0; t8 < 8; ++t8) sacc[t8] = f32x4{0.f, 0.f, 0.f, 0.f};
; #pragma unroll
;       for (int s = 0; s < 2; ++s)
; #pragma unroll
;         for (int t8 = 0; t8 < 8; ++t8) {
;           const bf16x8 kf = *reinterpret_cast<const bf16x8*>(&sm_k[(t8 * 16 + (lane_c & 15)) * LDSS + s * 32 + (lane_c >> 4) * 8]);
;           sacc[t8] = __builtin_amdgcn_mfma_f32_16x16x32_bf16(qf[s], kf, sacc[t8], 0, 0, 0);
;         }
;       if (ck < 5) {
;         ATT_ISSUE(t, ck + 1)
;       } else if (t + VGRID < 8192) {
;         ATT_ISSUE(t + VGRID, 0)
;         ATT_QLOAD(t + VGRID)
;       }
;       if (ck < 4) {
;         const float* rb0 = sm_rpb + (rs + ck * 2 - r + 7) * 31;
; #pragma unroll
;         for (int t8 = 0; t8 < 8; ++t8)
; #pragma unroll
;           for (int reg = 0; reg < 4; ++reg)
;             sacc[t8][reg] += rb0[(t8 >> 2) * 31 + dco[reg][t8 & 3]];
;       }
; #pragma unroll
;       for (int reg = 0; reg < 4; ++reg) {
;         float mx = sacc[0][reg];
; #pragma unroll
;         for (int t8 = 1; t8 < 8; ++t8) mx = fmaxf(mx, sacc[t8][reg]);
;         mx = row16_max(mx);
;         const float mnew = fmaxf(mrow[reg], mx);
;         const float alpha = __builtin_amdgcn_exp2f(mrow[reg] - mnew);
;         mrow[reg] = mnew;
;         float rsum = 0.f;
; #pragma unroll
;         for (int t8 = 0; t8 < 8; ++t8) {
;           const float p = __builtin_amdgcn_exp2f(sacc[t8][reg] - mnew);
;           rsum += p;
;           sm_p[(wid * 16 + (lane_c >> 4) * 4 + reg) * 136 + t8 * 16 + (lane_c & 15)] = f2bf(p);
;         }
;         rsum = row16_sum(rsum);
;         lrow[reg] = lrow[reg] * alpha + rsum;
; #pragma unroll
;         for (int td = 0; td < 4; ++td) o[td][reg] *= alpha;
;       }
;       asm volatile("s_waitcnt lgkmcnt(0)" ::: "memory");
; #pragma unroll
;       for (int s4 = 0; s4 < 4; ++s4) {
;         const bf16x8 pf = *reinterpret_cast<const bf16x8*>(&sm_p[(wid * 16 + (lane_c & 15)) * 136 + s4 * 32 + (lane_c >> 4) * 8]);
; #pragma unroll
;         for (int td = 0; td < 4; ++td) {
	ds_read_b128 v[112:115], v144 offset:0
	ds_read_b128 v[116:119], v145 offset:0
	ds_read_b128 v[120:123], v144 offset:8192
	ds_read_b128 v[124:127], v145 offset:8192
	ds_read_b128 v[128:131], v144 offset:2048
	ds_read_b128 v[132:135], v145 offset:2048
	ds_read_b128 v[136:139], v144 offset:10240
	ds_read_b128 v[140:143], v145 offset:10240
	s_waitcnt lgkmcnt(7)
	v_mfma_f32_16x16x32_bf16 v[0:3], v[112:115], v[64:67], v[0:3]
	s_waitcnt lgkmcnt(6)
	v_mfma_f32_16x16x32_bf16 v[0:3], v[116:119], v[68:71], v[0:3]
	s_waitcnt lgkmcnt(5)
	v_mfma_f32_16x16x32_bf16 v[4:7], v[120:123], v[64:67], v[4:7]
	s_waitcnt lgkmcnt(4)
	v_mfma_f32_16x16x32_bf16 v[4:7], v[124:127], v[68:71], v[4:7]
	s_waitcnt lgkmcnt(3)
	v_mfma_f32_16x16x32_bf16 v[8:11], v[128:131], v[64:67], v[8:11]
	s_waitcnt lgkmcnt(2)
	v_mfma_f32_16x16x32_bf16 v[8:11], v[132:135], v[68:71], v[8:11]
	s_waitcnt lgkmcnt(1)
	v_mfma_f32_16x16x32_bf16 v[12:15], v[136:139], v[64:67], v[12:15]
	s_waitcnt lgkmcnt(0)
	v_mfma_f32_16x16x32_bf16 v[12:15], v[140:143], v[68:71], v[12:15]
	s_nop 7
	v_max3_f32 v203, v0, v1, v2
	v_max3_f32 v203, v203, v3, v4
	v_max3_f32 v203, v203, v5, v6
	v_max3_f32 v203, v203, v7, v8
	v_max3_f32 v203, v203, v9, v10
	v_max3_f32 v203, v203, v11, v12
	v_max3_f32 v203, v203, v13, v14
	v_max_f32_e32 v203, v203, v15
	v_mov_b32_e32 v205, v203
	s_nop 1
	v_permlane16_swap_b32_e32 v203, v205
	v_max_f32_e32 v203, v203, v205
	v_mov_b32_e32 v205, v203
	s_nop 1
	v_permlane32_swap_b32_e32 v203, v205
	v_max_f32_e32 v203, v203, v205
	v_max_f32_e32 v218, v200, v203
	v_sub_f32_e32 v220, v200, v218
	v_mov_b32_e32 v219, v218
	v_exp_f32_e32 v220, v220
	v_mov_b32_e32 v200, v218
	v_pk_add_f32 v[0:1], v[0:1], v[218:219] neg_lo:[0,1] neg_hi:[0,1]
	v_pk_add_f32 v[2:3], v[2:3], v[218:219] neg_lo:[0,1] neg_hi:[0,1]
	v_pk_add_f32 v[4:5], v[4:5], v[218:219] neg_lo:[0,1] neg_hi:[0,1]
	v_pk_add_f32 v[6:7], v[6:7], v[218:219] neg_lo:[0,1] neg_hi:[0,1]
	v_pk_add_f32 v[8:9], v[8:9], v[218:219] neg_lo:[0,1] neg_hi:[0,1]
	v_pk_add_f32 v[10:11], v[10:11], v[218:219] neg_lo:[0,1] neg_hi:[0,1]
	v_pk_add_f32 v[12:13], v[12:13], v[218:219] neg_lo:[0,1] neg_hi:[0,1]
	v_pk_add_f32 v[14:15], v[14:15], v[218:219] neg_lo:[0,1] neg_hi:[0,1]
	v_exp_f32_e32 v0, v0
	s_waitcnt vmcnt(0)
	v_exp_f32_e32 v1, v1
	ds_write_b128 v150, v[80:83] offset:32768
	v_exp_f32_e32 v2, v2
	ds_write_b128 v150, v[84:87] offset:36864
	v_exp_f32_e32 v3, v3
	ds_write_b128 v150, v[88:91] offset:40960
	v_exp_f32_e32 v4, v4
	ds_write_b128 v150, v[92:95] offset:45056
	v_exp_f32_e32 v5, v5
	ds_write_b64 v151, v[96:97] offset:32768
	v_exp_f32_e32 v6, v6
	ds_write_b64 v229, v[98:99] offset:32768
	v_exp_f32_e32 v7, v7
	ds_write_b64 v151, v[100:101] offset:36864
	v_exp_f32_e32 v8, v8
	ds_write_b64 v229, v[102:103] offset:36864
	v_exp_f32_e32 v9, v9
	ds_write_b64 v151, v[104:105] offset:40960
	v_exp_f32_e32 v10, v10
	ds_write_b64 v229, v[106:107] offset:40960
	v_exp_f32_e32 v11, v11
	ds_write_b64 v151, v[108:109] offset:45056
	v_exp_f32_e32 v12, v12
	ds_write_b64 v229, v[110:111] offset:45056
	v_exp_f32_e32 v13, v13
	s_add_u32 s100, s12, 0x240000
	v_exp_f32_e32 v14, v14
	s_addc_u32 s101, s13, 0
	v_exp_f32_e32 v15, v15
	s_add_u32 s0, s14, 0x300
	s_addc_u32 s1, s15, 0
	global_load_dwordx4 v[80:83], v154, s[100:101] offset:2048
	global_load_dwordx4 v[96:99], v158, s[0:1]
	global_load_dwordx4 v[84:87], v155, s[100:101] offset:2048
	global_load_dwordx4 v[100:103], v159, s[0:1]
	global_load_dwordx4 v[88:91], v156, s[100:101] offset:2048
	global_load_dwordx4 v[104:107], v160, s[0:1]
	global_load_dwordx4 v[92:95], v157, s[100:101] offset:2048
	global_load_dwordx4 v[108:111], v161, s[0:1]
	ds_read_b128 v[112:115], v146 offset:0
	ds_read_b128 v[116:119], v146 offset:4096
	ds_read_b128 v[120:123], v146 offset:8192
	ds_read_b128 v[124:127], v146 offset:12288
	ds_read_b128 v[128:131], v147 offset:0
	ds_read_b128 v[132:135], v147 offset:4096
	ds_read_b128 v[136:139], v147 offset:8192
	ds_read_b128 v[140:143], v147 offset:12288
	v_mov_b32_e32 v221, v220
	v_pk_add_f32 v[222:223], v[0:1], v[2:3]
	v_pk_add_f32 v[222:223], v[222:223], v[4:5]
	v_pk_add_f32 v[222:223], v[222:223], v[6:7]
	v_pk_add_f32 v[222:223], v[222:223], v[8:9]
	v_pk_add_f32 v[222:223], v[222:223], v[10:11]
	v_pk_add_f32 v[222:223], v[222:223], v[12:13]
	v_pk_add_f32 v[222:223], v[222:223], v[14:15]
	v_pk_mul_f32 v[32:33], v[32:33], v[220:221]
	v_pk_mul_f32 v[34:35], v[34:35], v[220:221]
	v_pk_mul_f32 v[36:37], v[36:37], v[220:221]
	v_pk_mul_f32 v[38:39], v[38:39], v[220:221]
	v_pk_mul_f32 v[40:41], v[40:41], v[220:221]
	v_pk_mul_f32 v[42:43], v[42:43], v[220:221]
	v_pk_mul_f32 v[44:45], v[44:45], v[220:221]
	v_pk_mul_f32 v[46:47], v[46:47], v[220:221]
	v_add_f32_e32 v203, v222, v223
	v_fma_f32 v201, v201, v220, v203
	v_cvt_pk_bf16_f32 v48, v0, v1
	v_cvt_pk_bf16_f32 v49, v2, v3
	v_cvt_pk_bf16_f32 v50, v4, v5
	v_cvt_pk_bf16_f32 v51, v6, v7
	v_cvt_pk_bf16_f32 v52, v8, v9
	v_cvt_pk_bf16_f32 v53, v10, v11
	v_cvt_pk_bf16_f32 v54, v12, v13
	v_cvt_pk_bf16_f32 v55, v14, v15
	s_waitcnt lgkmcnt(7)
	v_mfma_f32_16x16x32_bf16 v[32:35], v[112:115], v[48:51], v[32:35]
	s_waitcnt lgkmcnt(6)
	v_mfma_f32_16x16x32_bf16 v[36:39], v[116:119], v[48:51], v[36:39]
	s_waitcnt lgkmcnt(5)
	v_mfma_f32_16x16x32_bf16 v[40:43], v[120:123], v[48:51], v[40:43]
	s_waitcnt lgkmcnt(4)
	v_mfma_f32_16x16x32_bf16 v[44:47], v[124:127], v[48:51], v[44:47]
	s_waitcnt lgkmcnt(3)
	v_mfma_f32_16x16x32_bf16 v[32:35], v[128:131], v[52:55], v[32:35]
	s_waitcnt lgkmcnt(2)
	v_mfma_f32_16x16x32_bf16 v[36:39], v[132:135], v[52:55], v[36:39]
	s_waitcnt lgkmcnt(1)
	v_mfma_f32_16x16x32_bf16 v[40:43], v[136:139], v[52:55], v[40:43]
	s_waitcnt lgkmcnt(0)
; __device__ __forceinline__ void attn_phase(const Params& P, char* smem_raw) {
;     ...
; #pragma unroll
;       for (int s = 0; s < 2; ++s)
; #pragma unroll
;         for (int t8 = 0; t8 < 8; ++t8) {
;           const bf16x8 kf = *reinterpret_cast<const bf16x8*>(&sm_k[(t8 * 16 + (lane_c & 15)) * LDSS + s * 32 + (lane_c >> 4) * 8]);
;           sacc[t8] = __builtin_amdgcn_mfma_f32_16x16x32_bf16(qf[s], kf, sacc[t8], 0, 0, 0);
;         }
;       if (ck < 5) {
;         ATT_ISSUE(t, ck + 1)
;       } else if (t + VGRID < 8192) {
;         ATT_ISSUE(t + VGRID, 0)
;         ATT_QLOAD(t + VGRID)
;       }
;       if (ck < 4) {
;         const float* rb0 = sm_rpb + (rs + ck * 2 - r + 7) * 31;
; #pragma unroll
;         for (int t8 = 0; t8 < 8; ++t8)
; #pragma unroll
;           for (int reg = 0; reg < 4; ++reg)
;             sacc[t8][reg] += rb0[(t8 >> 2) * 31 + dco[reg][t8 & 3]];
;       }
; #pragma unroll
;       for (int reg = 0; reg < 4; ++reg) {
;         float mx = sacc[0][reg];
; #pragma unroll
;         for (int t8 = 1; t8 < 8; ++t8) mx = fmaxf(mx, sacc[t8][reg]);
;         mx = row16_max(mx);
;         const float mnew = fmaxf(mrow[reg], mx);
;         const float alpha = __builtin_amdgcn_exp2f(mrow[reg] - mnew);
;         mrow[reg] = mnew;
;         float rsum = 0.f;
; #pragma unroll
;         for (int t8 = 0; t8 < 8; ++t8) {
;           const float p = __builtin_amdgcn_exp2f(sacc[t8][reg] - mnew);
;           rsum += p;
;           sm_p[(wid * 16 + (lane_c >> 4) * 4 + reg) * 136 + t8 * 16 + (lane_c & 15)] = f2bf(p);
;         }
;         rsum = row16_sum(rsum);
;         lrow[reg] = lrow[reg] * alpha + rsum;
; #pragma unroll
;         for (int td = 0; td < 4; ++td) o[td][reg] *= alpha;
;       }
;       asm volatile("s_waitcnt lgkmcnt(0)" ::: "memory");
; #pragma unroll
;       for (int s4 = 0; s4 < 4; ++s4) {
;         const bf16x8 pf = *reinterpret_cast<const bf16x8*>(&sm_p[(wid * 16 + (lane_c & 15)) * 136 + s4 * 32 + (lane_c >> 4) * 8]);
; #pragma unroll
;         for (int td = 0; td < 4; ++td) {
;           const bf16x8 vf = *reinterpret_cast<const bf16x8*>(&sm_vt[(td * 16 + (lane_c & 15)) * 136 + s4 * 32 + (lane_c >> 4) * 8]);
;           o[td] = __builtin_amdgcn_mfma_f32_16x16x32_bf16(pf, vf, o[td], 0, 0, 0);
;         }
;       }
	v_mfma_f32_16x16x32_bf16 v[44:47], v[140:143], v[52:55], v[44:47]
	ds_read_b32 v0, v184 offset:512
	ds_read_b32 v1, v185 offset:512
	ds_read_b32 v2, v186 offset:512
	ds_read_b32 v3, v187 offset:512
	ds_read_b32 v4, v184 offset:640
	ds_read_b32 v5, v185 offset:640
	ds_read_b32 v6, v186 offset:640
	ds_read_b32 v7, v187 offset:640
	ds_read_b32 v8, v188 offset:512
	ds_read_b32 v9, v189 offset:512
	ds_read_b32 v10, v190 offset:512
	ds_read_b32 v11, v191 offset:512
	ds_read_b32 v12, v188 offset:640
	ds_read_b32 v13, v189 offset:640
	ds_read_b32 v14, v190 offset:640
	ds_read_b32 v15, v191 offset:640
	ds_read_b128 v[112:115], v144 offset:0
	ds_read_b128 v[116:119], v145 offset:0
	ds_read_b128 v[120:123], v144 offset:8192
	ds_read_b128 v[124:127], v145 offset:8192
	ds_read_b128 v[128:131], v144 offset:2048
	ds_read_b128 v[132:135], v145 offset:2048
	ds_read_b128 v[136:139], v144 offset:10240
	ds_read_b128 v[140:143], v145 offset:10240
	s_waitcnt lgkmcnt(7)
	v_mfma_f32_16x16x32_bf16 v[0:3], v[112:115], v[230:233], v[0:3]
	s_waitcnt lgkmcnt(6)
	v_mfma_f32_16x16x32_bf16 v[0:3], v[116:119], v[234:237], v[0:3]
	s_waitcnt lgkmcnt(5)
	v_mfma_f32_16x16x32_bf16 v[4:7], v[120:123], v[230:233], v[4:7]
	s_waitcnt lgkmcnt(4)
	v_mfma_f32_16x16x32_bf16 v[4:7], v[124:127], v[234:237], v[4:7]
	s_waitcnt lgkmcnt(3)
	v_mfma_f32_16x16x32_bf16 v[8:11], v[128:131], v[230:233], v[8:11]
	s_waitcnt lgkmcnt(2)
	v_mfma_f32_16x16x32_bf16 v[8:11], v[132:135], v[234:237], v[8:11]
	s_waitcnt lgkmcnt(1)
	v_mfma_f32_16x16x32_bf16 v[12:15], v[136:139], v[230:233], v[12:15]
	s_waitcnt lgkmcnt(0)
	v_mfma_f32_16x16x32_bf16 v[12:15], v[140:143], v[234:237], v[12:15]
	s_nop 7
	v_max3_f32 v203, v0, v1, v2
	v_max3_f32 v203, v203, v3, v4
	v_max3_f32 v203, v203, v5, v6
	v_max3_f32 v203, v203, v7, v8
	v_max3_f32 v203, v203, v9, v10
	v_max3_f32 v203, v203, v11, v12
	v_max3_f32 v203, v203, v13, v14
	v_max_f32_e32 v203, v203, v15
	v_mov_b32_e32 v205, v203
	s_nop 1
	v_permlane16_swap_b32_e32 v203, v205
	v_max_f32_e32 v203, v203, v205
	v_mov_b32_e32 v205, v203
	s_nop 1
	v_permlane32_swap_b32_e32 v203, v205
	v_max_f32_e32 v203, v203, v205
	v_max_f32_e32 v218, v246, v203
	v_sub_f32_e32 v220, v246, v218
	v_mov_b32_e32 v219, v218
	v_exp_f32_e32 v220, v220
	v_mov_b32_e32 v246, v218
	v_pk_add_f32 v[0:1], v[0:1], v[218:219] neg_lo:[0,1] neg_hi:[0,1]
	v_pk_add_f32 v[2:3], v[2:3], v[218:219] neg_lo:[0,1] neg_hi:[0,1]
	v_pk_add_f32 v[4:5], v[4:5], v[218:219] neg_lo:[0,1] neg_hi:[0,1]
	v_pk_add_f32 v[6:7], v[6:7], v[218:219] neg_lo:[0,1] neg_hi:[0,1]
	v_pk_add_f32 v[8:9], v[8:9], v[218:219] neg_lo:[0,1] neg_hi:[0,1]
	v_pk_add_f32 v[10:11], v[10:11], v[218:219] neg_lo:[0,1] neg_hi:[0,1]
	v_pk_add_f32 v[12:13], v[12:13], v[218:219] neg_lo:[0,1] neg_hi:[0,1]
	v_pk_add_f32 v[14:15], v[14:15], v[218:219] neg_lo:[0,1] neg_hi:[0,1]
	v_exp_f32_e32 v0, v0
	v_exp_f32_e32 v1, v1
	v_exp_f32_e32 v2, v2
	v_exp_f32_e32 v3, v3
	v_exp_f32_e32 v4, v4
	v_exp_f32_e32 v5, v5
	v_exp_f32_e32 v6, v6
	v_exp_f32_e32 v7, v7
	v_exp_f32_e32 v8, v8
	v_exp_f32_e32 v9, v9
	v_exp_f32_e32 v10, v10
	v_exp_f32_e32 v11, v11
	v_exp_f32_e32 v12, v12
	v_exp_f32_e32 v13, v13
	v_exp_f32_e32 v14, v14
	v_exp_f32_e32 v15, v15
	ds_read_b128 v[112:115], v146 offset:0
	ds_read_b128 v[116:119], v146 offset:4096
	ds_read_b128 v[120:123], v146 offset:8192
	ds_read_b128 v[124:127], v146 offset:12288
	ds_read_b128 v[128:131], v147 offset:0
	ds_read_b128 v[132:135], v147 offset:4096
	ds_read_b128 v[136:139], v147 offset:8192
	ds_read_b128 v[140:143], v147 offset:12288
	v_mov_b32_e32 v221, v220
	v_pk_add_f32 v[222:223], v[0:1], v[2:3]
	v_pk_add_f32 v[222:223], v[222:223], v[4:5]
	v_pk_add_f32 v[222:223], v[222:223], v[6:7]
	v_pk_add_f32 v[222:223], v[222:223], v[8:9]
	v_pk_add_f32 v[222:223], v[222:223], v[10:11]
	v_pk_add_f32 v[222:223], v[222:223], v[12:13]
	v_pk_add_f32 v[222:223], v[222:223], v[14:15]
	v_pk_mul_f32 v[176:177], v[176:177], v[220:221]
	v_pk_mul_f32 v[178:179], v[178:179], v[220:221]
	v_pk_mul_f32 v[180:181], v[180:181], v[220:221]
	v_pk_mul_f32 v[182:183], v[182:183], v[220:221]
	v_pk_mul_f32 v[192:193], v[192:193], v[220:221]
	v_pk_mul_f32 v[194:195], v[194:195], v[220:221]
	v_pk_mul_f32 v[196:197], v[196:197], v[220:221]
	v_pk_mul_f32 v[198:199], v[198:199], v[220:221]
	v_add_f32_e32 v203, v222, v223
	v_fma_f32 v247, v247, v220, v203
	v_cvt_pk_bf16_f32 v48, v0, v1
	v_cvt_pk_bf16_f32 v49, v2, v3
	v_cvt_pk_bf16_f32 v50, v4, v5
	v_cvt_pk_bf16_f32 v51, v6, v7
	v_cvt_pk_bf16_f32 v52, v8, v9
	v_cvt_pk_bf16_f32 v53, v10, v11
	v_cvt_pk_bf16_f32 v54, v12, v13
	v_cvt_pk_bf16_f32 v55, v14, v15
	s_waitcnt lgkmcnt(7)
	v_mfma_f32_16x16x32_bf16 v[176:179], v[112:115], v[48:51], v[176:179]
	s_waitcnt lgkmcnt(6)
	v_mfma_f32_16x16x32_bf16 v[180:183], v[116:119], v[48:51], v[180:183]
	s_waitcnt lgkmcnt(5)
	v_mfma_f32_16x16x32_bf16 v[192:195], v[120:123], v[48:51], v[192:195]
	s_waitcnt lgkmcnt(4)
	v_mfma_f32_16x16x32_bf16 v[196:199], v[124:127], v[48:51], v[196:199]
	s_waitcnt lgkmcnt(3)
	v_mfma_f32_16x16x32_bf16 v[176:179], v[128:131], v[52:55], v[176:179]
	s_waitcnt lgkmcnt(2)
	v_mfma_f32_16x16x32_bf16 v[180:183], v[132:135], v[52:55], v[180:183]
	s_waitcnt lgkmcnt(1)
	v_mfma_f32_16x16x32_bf16 v[192:195], v[136:139], v[52:55], v[192:195]
	s_waitcnt lgkmcnt(0)
	v_mfma_f32_16x16x32_bf16 v[196:199], v[140:143], v[52:55], v[196:199]
	ds_read_b32 v0, v184 offset:896
	ds_read_b32 v1, v185 offset:896
	ds_read_b32 v2, v186 offset:896
	ds_read_b32 v3, v187 offset:896
	ds_read_b32 v4, v184 offset:1024
	ds_read_b32 v5, v185 offset:1024
	ds_read_b32 v6, v186 offset:1024
	ds_read_b32 v7, v187 offset:1024
	ds_read_b32 v8, v188 offset:896
	ds_read_b32 v9, v189 offset:896
	ds_read_b32 v10, v190 offset:896
	ds_read_b32 v11, v191 offset:896
	ds_read_b32 v12, v188 offset:1024
	ds_read_b32 v13, v189 offset:1024
	ds_read_b32 v14, v190 offset:1024
	ds_read_b32 v15, v191 offset:1024
	s_waitcnt lgkmcnt(0)
	s_barrier
; __device__ __forceinline__ void attn_phase(const Params& P, char* smem_raw) {
;     ...
;         *reinterpret_cast<uint4*>(&sm_k[(idx >> 3) * LDSS + (idx & 7) * 8]) = kreg[i];
;         *reinterpret_cast<uint4*>(&sm_vt[(idx >> 4) * 136 + (idx & 15) * 8]) = vreg[i];
;       }
;       __syncthreads();
;       f32x4 sacc[8];
; #pragma unroll
;       for (int t8 = 0; t8 < 8; ++t8) sacc[t8] = f32x4{0.f, 0.f, 0.f, 0.f};
; #pragma unroll
;       for (int s = 0; s < 2; ++s)
; #pragma unroll
;         for (int t8 = 0; t8 < 8; ++t8) {
;           const bf16x8 kf = *reinterpret_cast<const bf16x8*>(&sm_k[(t8 * 16 + (lane_c & 15)) * LDSS + s * 32 + (lane_c >> 4) * 8]);
;           sacc[t8] = __builtin_amdgcn_mfma_f32_16x16x32_bf16(qf[s], kf, sacc[t8], 0, 0, 0);
;         }
;       if (ck < 5) {
;         ATT_ISSUE(t, ck + 1)
;       } else if (t + VGRID < 8192) {
;         ATT_ISSUE(t + VGRID, 0)
;         ATT_QLOAD(t + VGRID)
;       }
;       if (ck < 4) {
;         const float* rb0 = sm_rpb + (rs + ck * 2 - r + 7) * 31;
; #pragma unroll
;         for (int t8 = 0; t8 < 8; ++t8)
; #pragma unroll
;           for (int reg = 0; reg < 4; ++reg)
;             sacc[t8][reg] += rb0[(t8 >> 2) * 31 + dco[reg][t8 & 3]];
;       }
; #pragma unroll
;       for (int reg = 0; reg < 4; ++reg) {
;         float mx = sacc[0][reg];
; #pragma unroll
;         for (int t8 = 1; t8 < 8; ++t8) mx = fmaxf(mx, sacc[t8][reg]);
;         mx = row16_max(mx);
;         const float mnew = fmaxf(mrow[reg], mx);
;         const float alpha = __builtin_amdgcn_exp2f(mrow[reg] - mnew);
;         mrow[reg] = mnew;
;         float rsum = 0.f;
; #pragma unroll
;         for (int t8 = 0; t8 < 8; ++t8) {
;           const float p = __builtin_amdgcn_exp2f(sacc[t8][reg] - mnew);
;           rsum += p;
;           sm_p[(wid * 16 + (lane_c >> 4) * 4 + reg) * 136 + t8 * 16 + (lane_c & 15)] = f2bf(p);
;         }
;         rsum = row16_sum(rsum);
;         lrow[reg] = lrow[reg] * alpha + rsum;
; #pragma unroll
;         for (int td = 0; td < 4; ++td) o[td][reg] *= alpha;
;       }
;       asm volatile("s_waitcnt lgkmcnt(0)" ::: "memory");
; #pragma unroll
;       for (int s4 = 0; s4 < 4; ++s4) {
;         const bf16x8 pf = *reinterpret_cast<const bf16x8*>(&sm_p[(wid * 16 + (lane_c & 15)) * 136 + s4 * 32 + (lane_c >> 4) * 8]);
; #pragma unroll
;         for (int td = 0; td < 4; ++td) {
	ds_read_b128 v[112:115], v144 offset:32768
	ds_read_b128 v[116:119], v145 offset:32768
	ds_read_b128 v[120:123], v144 offset:40960
	ds_read_b128 v[124:127], v145 offset:40960
	ds_read_b128 v[128:131], v144 offset:34816
	ds_read_b128 v[132:135], v145 offset:34816
	ds_read_b128 v[136:139], v144 offset:43008
	ds_read_b128 v[140:143], v145 offset:43008
	s_waitcnt lgkmcnt(7)
	v_mfma_f32_16x16x32_bf16 v[0:3], v[112:115], v[64:67], v[0:3]
	s_waitcnt lgkmcnt(6)
	v_mfma_f32_16x16x32_bf16 v[0:3], v[116:119], v[68:71], v[0:3]
	s_waitcnt lgkmcnt(5)
	v_mfma_f32_16x16x32_bf16 v[4:7], v[120:123], v[64:67], v[4:7]
	s_waitcnt lgkmcnt(4)
	v_mfma_f32_16x16x32_bf16 v[4:7], v[124:127], v[68:71], v[4:7]
	s_waitcnt lgkmcnt(3)
	v_mfma_f32_16x16x32_bf16 v[8:11], v[128:131], v[64:67], v[8:11]
	s_waitcnt lgkmcnt(2)
	v_mfma_f32_16x16x32_bf16 v[8:11], v[132:135], v[68:71], v[8:11]
	s_waitcnt lgkmcnt(1)
	v_mfma_f32_16x16x32_bf16 v[12:15], v[136:139], v[64:67], v[12:15]
	s_waitcnt lgkmcnt(0)
	v_mfma_f32_16x16x32_bf16 v[12:15], v[140:143], v[68:71], v[12:15]
	s_nop 7
	v_max3_f32 v203, v0, v1, v2
	v_max3_f32 v203, v203, v3, v4
	v_max3_f32 v203, v203, v5, v6
	v_max3_f32 v203, v203, v7, v8
	v_max3_f32 v203, v203, v9, v10
	v_max3_f32 v203, v203, v11, v12
	v_max3_f32 v203, v203, v13, v14
	v_max_f32_e32 v203, v203, v15
	v_mov_b32_e32 v205, v203
	s_nop 1
	v_permlane16_swap_b32_e32 v203, v205
	v_max_f32_e32 v203, v203, v205
	v_mov_b32_e32 v205, v203
	s_nop 1
	v_permlane32_swap_b32_e32 v203, v205
	v_max_f32_e32 v203, v203, v205
	v_max_f32_e32 v218, v200, v203
	v_sub_f32_e32 v220, v200, v218
	v_mov_b32_e32 v219, v218
	v_exp_f32_e32 v220, v220
	v_mov_b32_e32 v200, v218
	v_pk_add_f32 v[0:1], v[0:1], v[218:219] neg_lo:[0,1] neg_hi:[0,1]
	v_pk_add_f32 v[2:3], v[2:3], v[218:219] neg_lo:[0,1] neg_hi:[0,1]
	v_pk_add_f32 v[4:5], v[4:5], v[218:219] neg_lo:[0,1] neg_hi:[0,1]
	v_pk_add_f32 v[6:7], v[6:7], v[218:219] neg_lo:[0,1] neg_hi:[0,1]
	v_pk_add_f32 v[8:9], v[8:9], v[218:219] neg_lo:[0,1] neg_hi:[0,1]
	v_pk_add_f32 v[10:11], v[10:11], v[218:219] neg_lo:[0,1] neg_hi:[0,1]
	v_pk_add_f32 v[12:13], v[12:13], v[218:219] neg_lo:[0,1] neg_hi:[0,1]
	v_pk_add_f32 v[14:15], v[14:15], v[218:219] neg_lo:[0,1] neg_hi:[0,1]
	v_exp_f32_e32 v0, v0
	s_waitcnt vmcnt(0)
	v_exp_f32_e32 v1, v1
	ds_write_b128 v150, v[80:83] offset:0
	v_exp_f32_e32 v2, v2
	ds_write_b128 v150, v[84:87] offset:4096
	v_exp_f32_e32 v3, v3
	ds_write_b128 v150, v[88:91] offset:8192
	v_exp_f32_e32 v4, v4
	ds_write_b128 v150, v[92:95] offset:12288
	v_exp_f32_e32 v5, v5
	ds_write_b64 v151, v[96:97] offset:0
	v_exp_f32_e32 v6, v6
	ds_write_b64 v229, v[98:99] offset:0
	v_exp_f32_e32 v7, v7
	ds_write_b64 v151, v[100:101] offset:4096
	v_exp_f32_e32 v8, v8
	ds_write_b64 v229, v[102:103] offset:4096
	v_exp_f32_e32 v9, v9
	ds_write_b64 v151, v[104:105] offset:8192
	v_exp_f32_e32 v10, v10
	ds_write_b64 v229, v[106:107] offset:8192
	v_exp_f32_e32 v11, v11
	ds_write_b64 v151, v[108:109] offset:12288
	v_exp_f32_e32 v12, v12
	ds_write_b64 v229, v[110:111] offset:12288
	v_exp_f32_e32 v13, v13
	s_add_u32 s100, s12, s20
	v_exp_f32_e32 v14, v14
	s_addc_u32 s101, s13, 0
	v_exp_f32_e32 v15, v15
	s_add_u32 s0, s14, s21
	s_addc_u32 s1, s15, 0
	global_load_dwordx4 v[80:83], v154, s[100:101] offset:2048
	global_load_dwordx4 v[96:99], v158, s[0:1]
	global_load_dwordx4 v[84:87], v155, s[100:101] offset:2048
	global_load_dwordx4 v[100:103], v159, s[0:1]
	global_load_dwordx4 v[88:91], v156, s[100:101] offset:2048
	global_load_dwordx4 v[104:107], v160, s[0:1]
	global_load_dwordx4 v[92:95], v157, s[100:101] offset:2048
	global_load_dwordx4 v[108:111], v161, s[0:1]
	ds_read_b128 v[112:115], v146 offset:32768
	ds_read_b128 v[116:119], v146 offset:36864
	ds_read_b128 v[120:123], v146 offset:40960
	ds_read_b128 v[124:127], v146 offset:45056
	ds_read_b128 v[128:131], v147 offset:32768
	ds_read_b128 v[132:135], v147 offset:36864
	ds_read_b128 v[136:139], v147 offset:40960
	ds_read_b128 v[140:143], v147 offset:45056
	v_mov_b32_e32 v221, v220
	v_pk_add_f32 v[222:223], v[0:1], v[2:3]
	v_pk_add_f32 v[222:223], v[222:223], v[4:5]
	v_pk_add_f32 v[222:223], v[222:223], v[6:7]
	v_pk_add_f32 v[222:223], v[222:223], v[8:9]
	v_pk_add_f32 v[222:223], v[222:223], v[10:11]
	v_pk_add_f32 v[222:223], v[222:223], v[12:13]
	v_pk_add_f32 v[222:223], v[222:223], v[14:15]
	v_pk_mul_f32 v[32:33], v[32:33], v[220:221]
	v_pk_mul_f32 v[34:35], v[34:35], v[220:221]
	v_pk_mul_f32 v[36:37], v[36:37], v[220:221]
	v_pk_mul_f32 v[38:39], v[38:39], v[220:221]
	v_pk_mul_f32 v[40:41], v[40:41], v[220:221]
	v_pk_mul_f32 v[42:43], v[42:43], v[220:221]
	v_pk_mul_f32 v[44:45], v[44:45], v[220:221]
	v_pk_mul_f32 v[46:47], v[46:47], v[220:221]
	v_add_f32_e32 v203, v222, v223
	v_fma_f32 v201, v201, v220, v203
	v_cvt_pk_bf16_f32 v48, v0, v1
	v_cvt_pk_bf16_f32 v49, v2, v3
	v_cvt_pk_bf16_f32 v50, v4, v5
	v_cvt_pk_bf16_f32 v51, v6, v7
	v_cvt_pk_bf16_f32 v52, v8, v9
	v_cvt_pk_bf16_f32 v53, v10, v11
	v_cvt_pk_bf16_f32 v54, v12, v13
	v_cvt_pk_bf16_f32 v55, v14, v15
	s_waitcnt lgkmcnt(7)
	v_mfma_f32_16x16x32_bf16 v[32:35], v[112:115], v[48:51], v[32:35]
	s_waitcnt lgkmcnt(6)
	v_mfma_f32_16x16x32_bf16 v[36:39], v[116:119], v[48:51], v[36:39]
	s_waitcnt lgkmcnt(5)
	v_mfma_f32_16x16x32_bf16 v[40:43], v[120:123], v[48:51], v[40:43]
	s_waitcnt lgkmcnt(4)
	v_mfma_f32_16x16x32_bf16 v[44:47], v[124:127], v[48:51], v[44:47]
	s_waitcnt lgkmcnt(3)
	v_mfma_f32_16x16x32_bf16 v[32:35], v[128:131], v[52:55], v[32:35]
	s_waitcnt lgkmcnt(2)
	v_mfma_f32_16x16x32_bf16 v[36:39], v[132:135], v[52:55], v[36:39]
	s_waitcnt lgkmcnt(1)
	v_mfma_f32_16x16x32_bf16 v[40:43], v[136:139], v[52:55], v[40:43]
	s_waitcnt lgkmcnt(0)
; __device__ __forceinline__ void attn_phase(const Params& P, char* smem_raw) {
;     ...
; #pragma unroll
;       for (int s = 0; s < 2; ++s)
; #pragma unroll
;         for (int t8 = 0; t8 < 8; ++t8) {
;           const bf16x8 kf = *reinterpret_cast<const bf16x8*>(&sm_k[(t8 * 16 + (lane_c & 15)) * LDSS + s * 32 + (lane_c >> 4) * 8]);
;           sacc[t8] = __builtin_amdgcn_mfma_f32_16x16x32_bf16(qf[s], kf, sacc[t8], 0, 0, 0);
;         }
;       if (ck < 5) {
;         ATT_ISSUE(t, ck + 1)
;       } else if (t + VGRID < 8192) {
;         ATT_ISSUE(t + VGRID, 0)
;         ATT_QLOAD(t + VGRID)
;       }
;       if (ck < 4) {
;         const float* rb0 = sm_rpb + (rs + ck * 2 - r + 7) * 31;
; #pragma unroll
;         for (int t8 = 0; t8 < 8; ++t8)
; #pragma unroll
;           for (int reg = 0; reg < 4; ++reg)
;             sacc[t8][reg] += rb0[(t8 >> 2) * 31 + dco[reg][t8 & 3]];
;       }
; #pragma unroll
;       for (int reg = 0; reg < 4; ++reg) {
;         float mx = sacc[0][reg];
; #pragma unroll
;         for (int t8 = 1; t8 < 8; ++t8) mx = fmaxf(mx, sacc[t8][reg]);
;         mx = row16_max(mx);
;         const float mnew = fmaxf(mrow[reg], mx);
;         const float alpha = __builtin_amdgcn_exp2f(mrow[reg] - mnew);
;         mrow[reg] = mnew;
;         float rsum = 0.f;
; #pragma unroll
;         for (int t8 = 0; t8 < 8; ++t8) {
;           const float p = __builtin_amdgcn_exp2f(sacc[t8][reg] - mnew);
;           rsum += p;
;           sm_p[(wid * 16 + (lane_c >> 4) * 4 + reg) * 136 + t8 * 16 + (lane_c & 15)] = f2bf(p);
;         }
;         rsum = row16_sum(rsum);
;         lrow[reg] = lrow[reg] * alpha + rsum;
; #pragma unroll
;         for (int td = 0; td < 4; ++td) o[td][reg] *= alpha;
;       }
;       asm volatile("s_waitcnt lgkmcnt(0)" ::: "memory");
; #pragma unroll
;       for (int s4 = 0; s4 < 4; ++s4) {
;         const bf16x8 pf = *reinterpret_cast<const bf16x8*>(&sm_p[(wid * 16 + (lane_c & 15)) * 136 + s4 * 32 + (lane_c >> 4) * 8]);
; #pragma unroll
;         for (int td = 0; td < 4; ++td) {
;           const bf16x8 vf = *reinterpret_cast<const bf16x8*>(&sm_vt[(td * 16 + (lane_c & 15)) * 136 + s4 * 32 + (lane_c >> 4) * 8]);
;           o[td] = __builtin_amdgcn_mfma_f32_16x16x32_bf16(pf, vf, o[td], 0, 0, 0);
;         }
;       }
	v_mfma_f32_16x16x32_bf16 v[44:47], v[140:143], v[52:55], v[44:47]
	ds_read_b32 v0, v184 offset:768
	ds_read_b32 v1, v185 offset:768
	ds_read_b32 v2, v186 offset:768
	ds_read_b32 v3, v187 offset:768
	ds_read_b32 v4, v184 offset:896
	ds_read_b32 v5, v185 offset:896
	ds_read_b32 v6, v186 offset:896
	ds_read_b32 v7, v187 offset:896
	ds_read_b32 v8, v188 offset:768
	ds_read_b32 v9, v189 offset:768
	ds_read_b32 v10, v190 offset:768
	ds_read_b32 v11, v191 offset:768
	ds_read_b32 v12, v188 offset:896
	ds_read_b32 v13, v189 offset:896
	ds_read_b32 v14, v190 offset:896
	ds_read_b32 v15, v191 offset:896
	ds_read_b128 v[112:115], v144 offset:32768
	ds_read_b128 v[116:119], v145 offset:32768
	ds_read_b128 v[120:123], v144 offset:40960
	ds_read_b128 v[124:127], v145 offset:40960
	ds_read_b128 v[128:131], v144 offset:34816
	ds_read_b128 v[132:135], v145 offset:34816
	ds_read_b128 v[136:139], v144 offset:43008
	ds_read_b128 v[140:143], v145 offset:43008
	s_waitcnt lgkmcnt(7)
	v_mfma_f32_16x16x32_bf16 v[0:3], v[112:115], v[230:233], v[0:3]
	s_waitcnt lgkmcnt(6)
	v_mfma_f32_16x16x32_bf16 v[0:3], v[116:119], v[234:237], v[0:3]
	s_waitcnt lgkmcnt(5)
	v_mfma_f32_16x16x32_bf16 v[4:7], v[120:123], v[230:233], v[4:7]
	s_waitcnt lgkmcnt(4)
	v_mfma_f32_16x16x32_bf16 v[4:7], v[124:127], v[234:237], v[4:7]
	s_waitcnt lgkmcnt(3)
	v_mfma_f32_16x16x32_bf16 v[8:11], v[128:131], v[230:233], v[8:11]
	s_waitcnt lgkmcnt(2)
	v_mfma_f32_16x16x32_bf16 v[8:11], v[132:135], v[234:237], v[8:11]
	s_waitcnt lgkmcnt(1)
	v_mfma_f32_16x16x32_bf16 v[12:15], v[136:139], v[230:233], v[12:15]
	s_waitcnt lgkmcnt(0)
	v_mfma_f32_16x16x32_bf16 v[12:15], v[140:143], v[234:237], v[12:15]
	s_nop 7
	v_max3_f32 v203, v0, v1, v2
	v_max3_f32 v203, v203, v3, v4
	v_max3_f32 v203, v203, v5, v6
	v_max3_f32 v203, v203, v7, v8
	v_max3_f32 v203, v203, v9, v10
	v_max3_f32 v203, v203, v11, v12
	v_max3_f32 v203, v203, v13, v14
	v_max_f32_e32 v203, v203, v15
	v_mov_b32_e32 v205, v203
	s_nop 1
	v_permlane16_swap_b32_e32 v203, v205
	v_max_f32_e32 v203, v203, v205
	v_mov_b32_e32 v205, v203
	s_nop 1
	v_permlane32_swap_b32_e32 v203, v205
	v_max_f32_e32 v203, v203, v205
	v_max_f32_e32 v218, v246, v203
	v_sub_f32_e32 v220, v246, v218
	v_mov_b32_e32 v219, v218
	v_exp_f32_e32 v220, v220
	v_mov_b32_e32 v246, v218
	v_pk_add_f32 v[0:1], v[0:1], v[218:219] neg_lo:[0,1] neg_hi:[0,1]
	v_pk_add_f32 v[2:3], v[2:3], v[218:219] neg_lo:[0,1] neg_hi:[0,1]
	v_pk_add_f32 v[4:5], v[4:5], v[218:219] neg_lo:[0,1] neg_hi:[0,1]
	v_pk_add_f32 v[6:7], v[6:7], v[218:219] neg_lo:[0,1] neg_hi:[0,1]
	v_pk_add_f32 v[8:9], v[8:9], v[218:219] neg_lo:[0,1] neg_hi:[0,1]
	v_pk_add_f32 v[10:11], v[10:11], v[218:219] neg_lo:[0,1] neg_hi:[0,1]
	v_pk_add_f32 v[12:13], v[12:13], v[218:219] neg_lo:[0,1] neg_hi:[0,1]
	v_pk_add_f32 v[14:15], v[14:15], v[218:219] neg_lo:[0,1] neg_hi:[0,1]
	v_exp_f32_e32 v0, v0
	v_exp_f32_e32 v1, v1
	v_exp_f32_e32 v2, v2
	v_exp_f32_e32 v3, v3
	v_exp_f32_e32 v4, v4
	v_exp_f32_e32 v5, v5
	v_exp_f32_e32 v6, v6
	v_exp_f32_e32 v7, v7
	v_exp_f32_e32 v8, v8
	v_exp_f32_e32 v9, v9
	v_exp_f32_e32 v10, v10
	v_exp_f32_e32 v11, v11
	v_exp_f32_e32 v12, v12
	v_exp_f32_e32 v13, v13
	v_exp_f32_e32 v14, v14
	v_exp_f32_e32 v15, v15
	ds_read_b128 v[112:115], v146 offset:32768
	ds_read_b128 v[116:119], v146 offset:36864
	ds_read_b128 v[120:123], v146 offset:40960
	ds_read_b128 v[124:127], v146 offset:45056
	ds_read_b128 v[128:131], v147 offset:32768
	ds_read_b128 v[132:135], v147 offset:36864
	ds_read_b128 v[136:139], v147 offset:40960
	ds_read_b128 v[140:143], v147 offset:45056
	v_mov_b32_e32 v221, v220
	v_pk_add_f32 v[222:223], v[0:1], v[2:3]
	v_pk_add_f32 v[222:223], v[222:223], v[4:5]
	v_pk_add_f32 v[222:223], v[222:223], v[6:7]
	v_pk_add_f32 v[222:223], v[222:223], v[8:9]
	v_pk_add_f32 v[222:223], v[222:223], v[10:11]
	v_pk_add_f32 v[222:223], v[222:223], v[12:13]
	v_pk_add_f32 v[222:223], v[222:223], v[14:15]
	v_pk_mul_f32 v[176:177], v[176:177], v[220:221]
	v_pk_mul_f32 v[178:179], v[178:179], v[220:221]
	v_pk_mul_f32 v[180:181], v[180:181], v[220:221]
	v_pk_mul_f32 v[182:183], v[182:183], v[220:221]
	v_pk_mul_f32 v[192:193], v[192:193], v[220:221]
	v_pk_mul_f32 v[194:195], v[194:195], v[220:221]
	v_pk_mul_f32 v[196:197], v[196:197], v[220:221]
	v_pk_mul_f32 v[198:199], v[198:199], v[220:221]
	v_add_f32_e32 v203, v222, v223
	v_fma_f32 v247, v247, v220, v203
	v_cvt_pk_bf16_f32 v48, v0, v1
	v_cvt_pk_bf16_f32 v49, v2, v3
	v_cvt_pk_bf16_f32 v50, v4, v5
	v_cvt_pk_bf16_f32 v51, v6, v7
	v_cvt_pk_bf16_f32 v52, v8, v9
	v_cvt_pk_bf16_f32 v53, v10, v11
	v_cvt_pk_bf16_f32 v54, v12, v13
	v_cvt_pk_bf16_f32 v55, v14, v15
	s_waitcnt lgkmcnt(7)
	v_mfma_f32_16x16x32_bf16 v[176:179], v[112:115], v[48:51], v[176:179]
	s_waitcnt lgkmcnt(6)
	v_mfma_f32_16x16x32_bf16 v[180:183], v[116:119], v[48:51], v[180:183]
	s_waitcnt lgkmcnt(5)
	v_mfma_f32_16x16x32_bf16 v[192:195], v[120:123], v[48:51], v[192:195]
	s_waitcnt lgkmcnt(4)
	v_mfma_f32_16x16x32_bf16 v[196:199], v[124:127], v[48:51], v[196:199]
	s_waitcnt lgkmcnt(3)
	v_mfma_f32_16x16x32_bf16 v[176:179], v[128:131], v[52:55], v[176:179]
	s_waitcnt lgkmcnt(2)
	v_mfma_f32_16x16x32_bf16 v[180:183], v[132:135], v[52:55], v[180:183]
	s_waitcnt lgkmcnt(1)
	v_mfma_f32_16x16x32_bf16 v[192:195], v[136:139], v[52:55], v[192:195]
	s_waitcnt lgkmcnt(0)
	v_mfma_f32_16x16x32_bf16 v[196:199], v[140:143], v[52:55], v[196:199]
	ds_read_b32 v0, v184 offset:1152
	ds_read_b32 v1, v185 offset:1152
	ds_read_b32 v2, v186 offset:1152
	ds_read_b32 v3, v187 offset:1152
	ds_read_b32 v4, v184 offset:1280
	ds_read_b32 v5, v185 offset:1280
	ds_read_b32 v6, v186 offset:1280
	ds_read_b32 v7, v187 offset:1280
	ds_read_b32 v8, v188 offset:1152
	ds_read_b32 v9, v189 offset:1152
	ds_read_b32 v10, v190 offset:1152
	ds_read_b32 v11, v191 offset:1152
	ds_read_b32 v12, v188 offset:1280
	ds_read_b32 v13, v189 offset:1280
	ds_read_b32 v14, v190 offset:1280
	ds_read_b32 v15, v191 offset:1280
	s_waitcnt lgkmcnt(0)
	s_barrier
; __device__ __forceinline__ void attn_phase(const Params& P, char* smem_raw) {
;     ...
;         *reinterpret_cast<uint4*>(&sm_k[(idx >> 3) * LDSS + (idx & 7) * 8]) = kreg[i];
;         *reinterpret_cast<uint4*>(&sm_vt[(idx >> 4) * 136 + (idx & 15) * 8]) = vreg[i];
;       }
;       __syncthreads();
;       f32x4 sacc[8];
; #pragma unroll
;       for (int t8 = 0; t8 < 8; ++t8) sacc[t8] = f32x4{0.f, 0.f, 0.f, 0.f};
; #pragma unroll
;       for (int s = 0; s < 2; ++s)
; #pragma unroll
;         for (int t8 = 0; t8 < 8; ++t8) {
;           const bf16x8 kf = *reinterpret_cast<const bf16x8*>(&sm_k[(t8 * 16 + (lane_c & 15)) * LDSS + s * 32 + (lane_c >> 4) * 8]);
;           sacc[t8] = __builtin_amdgcn_mfma_f32_16x16x32_bf16(qf[s], kf, sacc[t8], 0, 0, 0);
;         }
;       if (ck < 5) {
;         ATT_ISSUE(t, ck + 1)
;       } else if (t + VGRID < 8192) {
;         ATT_ISSUE(t + VGRID, 0)
;         ATT_QLOAD(t + VGRID)
;       }
;       if (ck < 4) {
;         const float* rb0 = sm_rpb + (rs + ck * 2 - r + 7) * 31;
; #pragma unroll
;         for (int t8 = 0; t8 < 8; ++t8)
; #pragma unroll
;           for (int reg = 0; reg < 4; ++reg)
;             sacc[t8][reg] += rb0[(t8 >> 2) * 31 + dco[reg][t8 & 3]];
;       }
; #pragma unroll
;       for (int reg = 0; reg < 4; ++reg) {
;         float mx = sacc[0][reg];
; #pragma unroll
;         for (int t8 = 1; t8 < 8; ++t8) mx = fmaxf(mx, sacc[t8][reg]);
;         mx = row16_max(mx);
;         const float mnew = fmaxf(mrow[reg], mx);
;         const float alpha = __builtin_amdgcn_exp2f(mrow[reg] - mnew);
;         mrow[reg] = mnew;
;         float rsum = 0.f;
; #pragma unroll
;         for (int t8 = 0; t8 < 8; ++t8) {
;           const float p = __builtin_amdgcn_exp2f(sacc[t8][reg] - mnew);
;           rsum += p;
;           sm_p[(wid * 16 + (lane_c >> 4) * 4 + reg) * 136 + t8 * 16 + (lane_c & 15)] = f2bf(p);
;         }
;         rsum = row16_sum(rsum);
;         lrow[reg] = lrow[reg] * alpha + rsum;
; #pragma unroll
;         for (int td = 0; td < 4; ++td) o[td][reg] *= alpha;
;       }
;       asm volatile("s_waitcnt lgkmcnt(0)" ::: "memory");
; #pragma unroll
;       for (int s4 = 0; s4 < 4; ++s4) {
;         const bf16x8 pf = *reinterpret_cast<const bf16x8*>(&sm_p[(wid * 16 + (lane_c & 15)) * 136 + s4 * 32 + (lane_c >> 4) * 8]);
; #pragma unroll
;         for (int td = 0; td < 4; ++td) {
	ds_read_b128 v[112:115], v144 offset:0
	ds_read_b128 v[116:119], v145 offset:0
	ds_read_b128 v[120:123], v144 offset:8192
	ds_read_b128 v[124:127], v145 offset:8192
	ds_read_b128 v[128:131], v144 offset:2048
	ds_read_b128 v[132:135], v145 offset:2048
	ds_read_b128 v[136:139], v144 offset:10240
	ds_read_b128 v[140:143], v145 offset:10240
	s_waitcnt lgkmcnt(7)
	v_mfma_f32_16x16x32_bf16 v[0:3], v[112:115], v[64:67], v[0:3]
	s_waitcnt lgkmcnt(6)
	v_mfma_f32_16x16x32_bf16 v[0:3], v[116:119], v[68:71], v[0:3]
	s_waitcnt lgkmcnt(5)
	v_mfma_f32_16x16x32_bf16 v[4:7], v[120:123], v[64:67], v[4:7]
	s_waitcnt lgkmcnt(4)
	v_mfma_f32_16x16x32_bf16 v[4:7], v[124:127], v[68:71], v[4:7]
	s_waitcnt lgkmcnt(3)
	v_mfma_f32_16x16x32_bf16 v[8:11], v[128:131], v[64:67], v[8:11]
	s_waitcnt lgkmcnt(2)
	v_mfma_f32_16x16x32_bf16 v[8:11], v[132:135], v[68:71], v[8:11]
	s_waitcnt lgkmcnt(1)
	v_mfma_f32_16x16x32_bf16 v[12:15], v[136:139], v[64:67], v[12:15]
	s_waitcnt lgkmcnt(0)
	v_mfma_f32_16x16x32_bf16 v[12:15], v[140:143], v[68:71], v[12:15]
	s_nop 7
	v_max3_f32 v203, v0, v1, v2
	v_max3_f32 v203, v203, v3, v4
	v_max3_f32 v203, v203, v5, v6
	v_max3_f32 v203, v203, v7, v8
	v_max3_f32 v203, v203, v9, v10
	v_max3_f32 v203, v203, v11, v12
	v_max3_f32 v203, v203, v13, v14
	v_max_f32_e32 v203, v203, v15
	v_mov_b32_e32 v205, v203
	s_nop 1
	v_permlane16_swap_b32_e32 v203, v205
	v_max_f32_e32 v203, v203, v205
	v_mov_b32_e32 v205, v203
	s_nop 1
	v_permlane32_swap_b32_e32 v203, v205
	v_max_f32_e32 v203, v203, v205
	v_max_f32_e32 v218, v200, v203
	v_sub_f32_e32 v220, v200, v218
	v_mov_b32_e32 v219, v218
	v_exp_f32_e32 v220, v220
	v_mov_b32_e32 v200, v218
	v_pk_add_f32 v[0:1], v[0:1], v[218:219] neg_lo:[0,1] neg_hi:[0,1]
	v_pk_add_f32 v[2:3], v[2:3], v[218:219] neg_lo:[0,1] neg_hi:[0,1]
	v_pk_add_f32 v[4:5], v[4:5], v[218:219] neg_lo:[0,1] neg_hi:[0,1]
	v_pk_add_f32 v[6:7], v[6:7], v[218:219] neg_lo:[0,1] neg_hi:[0,1]
	v_pk_add_f32 v[8:9], v[8:9], v[218:219] neg_lo:[0,1] neg_hi:[0,1]
	v_pk_add_f32 v[10:11], v[10:11], v[218:219] neg_lo:[0,1] neg_hi:[0,1]
	v_pk_add_f32 v[12:13], v[12:13], v[218:219] neg_lo:[0,1] neg_hi:[0,1]
	v_pk_add_f32 v[14:15], v[14:15], v[218:219] neg_lo:[0,1] neg_hi:[0,1]
	v_exp_f32_e32 v0, v0
	s_waitcnt vmcnt(0)
	v_exp_f32_e32 v1, v1
	ds_write_b128 v150, v[80:83] offset:32768
	v_exp_f32_e32 v2, v2
	ds_write_b128 v150, v[84:87] offset:36864
	v_exp_f32_e32 v3, v3
	ds_write_b128 v150, v[88:91] offset:40960
	v_exp_f32_e32 v4, v4
	ds_write_b128 v150, v[92:95] offset:45056
	v_exp_f32_e32 v5, v5
	ds_write_b64 v151, v[96:97] offset:32768
	v_exp_f32_e32 v6, v6
	ds_write_b64 v229, v[98:99] offset:32768
	v_exp_f32_e32 v7, v7
	ds_write_b64 v151, v[100:101] offset:36864
	v_exp_f32_e32 v8, v8
	ds_write_b64 v229, v[102:103] offset:36864
	v_exp_f32_e32 v9, v9
	ds_write_b64 v151, v[104:105] offset:40960
	v_exp_f32_e32 v10, v10
	ds_write_b64 v229, v[106:107] offset:40960
	v_exp_f32_e32 v11, v11
	ds_write_b64 v151, v[108:109] offset:45056
	v_exp_f32_e32 v12, v12
	ds_write_b64 v229, v[110:111] offset:45056
	v_exp_f32_e32 v13, v13
	s_add_u32 s100, s16, 0x0
	v_exp_f32_e32 v14, v14
	s_addc_u32 s101, s17, 0
	v_exp_f32_e32 v15, v15
	s_add_u32 s0, s36, 0x0
	s_addc_u32 s1, s37, 0
	global_load_dwordx4 v[80:83], v154, s[100:101] offset:2048
	global_load_dwordx4 v[96:99], v162, s[0:1]
	global_load_dwordx4 v[84:87], v155, s[100:101] offset:2048
	global_load_dwordx4 v[100:103], v163, s[0:1]
	global_load_dwordx4 v[88:91], v156, s[100:101] offset:2048
	global_load_dwordx4 v[104:107], v164, s[0:1]
	global_load_dwordx4 v[92:95], v157, s[100:101] offset:2048
	global_load_dwordx4 v[108:111], v165, s[0:1]
	ds_read_b128 v[112:115], v146 offset:0
	ds_read_b128 v[116:119], v146 offset:4096
	ds_read_b128 v[120:123], v146 offset:8192
	ds_read_b128 v[124:127], v146 offset:12288
	ds_read_b128 v[128:131], v147 offset:0
	ds_read_b128 v[132:135], v147 offset:4096
	ds_read_b128 v[136:139], v147 offset:8192
	ds_read_b128 v[140:143], v147 offset:12288
	v_mov_b32_e32 v221, v220
	v_pk_add_f32 v[222:223], v[0:1], v[2:3]
	v_pk_add_f32 v[222:223], v[222:223], v[4:5]
	v_pk_add_f32 v[222:223], v[222:223], v[6:7]
	v_pk_add_f32 v[222:223], v[222:223], v[8:9]
	v_pk_add_f32 v[222:223], v[222:223], v[10:11]
	v_pk_add_f32 v[222:223], v[222:223], v[12:13]
	v_pk_add_f32 v[222:223], v[222:223], v[14:15]
	v_pk_mul_f32 v[32:33], v[32:33], v[220:221]
	v_pk_mul_f32 v[34:35], v[34:35], v[220:221]
	v_pk_mul_f32 v[36:37], v[36:37], v[220:221]
	v_pk_mul_f32 v[38:39], v[38:39], v[220:221]
	v_pk_mul_f32 v[40:41], v[40:41], v[220:221]
	v_pk_mul_f32 v[42:43], v[42:43], v[220:221]
	v_pk_mul_f32 v[44:45], v[44:45], v[220:221]
	v_pk_mul_f32 v[46:47], v[46:47], v[220:221]
	v_add_f32_e32 v203, v222, v223
	v_fma_f32 v201, v201, v220, v203
	v_cvt_pk_bf16_f32 v48, v0, v1
	v_cvt_pk_bf16_f32 v49, v2, v3
	v_cvt_pk_bf16_f32 v50, v4, v5
	v_cvt_pk_bf16_f32 v51, v6, v7
	v_cvt_pk_bf16_f32 v52, v8, v9
	v_cvt_pk_bf16_f32 v53, v10, v11
	v_cvt_pk_bf16_f32 v54, v12, v13
	v_cvt_pk_bf16_f32 v55, v14, v15
	s_waitcnt lgkmcnt(7)
	v_mfma_f32_16x16x32_bf16 v[32:35], v[112:115], v[48:51], v[32:35]
	s_waitcnt lgkmcnt(6)
	v_mfma_f32_16x16x32_bf16 v[36:39], v[116:119], v[48:51], v[36:39]
	s_waitcnt lgkmcnt(5)
	v_mfma_f32_16x16x32_bf16 v[40:43], v[120:123], v[48:51], v[40:43]
	s_waitcnt lgkmcnt(4)
	v_mfma_f32_16x16x32_bf16 v[44:47], v[124:127], v[48:51], v[44:47]
	s_waitcnt lgkmcnt(3)
	v_mfma_f32_16x16x32_bf16 v[32:35], v[128:131], v[52:55], v[32:35]
	s_waitcnt lgkmcnt(2)
	v_mfma_f32_16x16x32_bf16 v[36:39], v[132:135], v[52:55], v[36:39]
	s_waitcnt lgkmcnt(1)
	v_mfma_f32_16x16x32_bf16 v[40:43], v[136:139], v[52:55], v[40:43]
	s_waitcnt lgkmcnt(0)
; __device__ __forceinline__ void attn_phase(const Params& P, char* smem_raw) {
;     ...
; #pragma unroll
;       for (int s = 0; s < 2; ++s)
; #pragma unroll
;         for (int t8 = 0; t8 < 8; ++t8) {
;           const bf16x8 kf = *reinterpret_cast<const bf16x8*>(&sm_k[(t8 * 16 + (lane_c & 15)) * LDSS + s * 32 + (lane_c >> 4) * 8]);
;           sacc[t8] = __builtin_amdgcn_mfma_f32_16x16x32_bf16(qf[s], kf, sacc[t8], 0, 0, 0);
;         }
;       if (ck < 5) {
;         ATT_ISSUE(t, ck + 1)
;       } else if (t + VGRID < 8192) {
;         ATT_ISSUE(t + VGRID, 0)
;         ATT_QLOAD(t + VGRID)
;       }
;       if (ck < 4) {
;         const float* rb0 = sm_rpb + (rs + ck * 2 - r + 7) * 31;
; #pragma unroll
;         for (int t8 = 0; t8 < 8; ++t8)
; #pragma unroll
;           for (int reg = 0; reg < 4; ++reg)
;             sacc[t8][reg] += rb0[(t8 >> 2) * 31 + dco[reg][t8 & 3]];
;       }
; #pragma unroll
;       for (int reg = 0; reg < 4; ++reg) {
;         float mx = sacc[0][reg];
; #pragma unroll
;         for (int t8 = 1; t8 < 8; ++t8) mx = fmaxf(mx, sacc[t8][reg]);
;         mx = row16_max(mx);
;         const float mnew = fmaxf(mrow[reg], mx);
;         const float alpha = __builtin_amdgcn_exp2f(mrow[reg] - mnew);
;         mrow[reg] = mnew;
;         float rsum = 0.f;
; #pragma unroll
;         for (int t8 = 0; t8 < 8; ++t8) {
;           const float p = __builtin_amdgcn_exp2f(sacc[t8][reg] - mnew);
;           rsum += p;
;           sm_p[(wid * 16 + (lane_c >> 4) * 4 + reg) * 136 + t8 * 16 + (lane_c & 15)] = f2bf(p);
;         }
;         rsum = row16_sum(rsum);
;         lrow[reg] = lrow[reg] * alpha + rsum;
; #pragma unroll
;         for (int td = 0; td < 4; ++td) o[td][reg] *= alpha;
;       }
;       asm volatile("s_waitcnt lgkmcnt(0)" ::: "memory");
; #pragma unroll
;       for (int s4 = 0; s4 < 4; ++s4) {
;         const bf16x8 pf = *reinterpret_cast<const bf16x8*>(&sm_p[(wid * 16 + (lane_c & 15)) * 136 + s4 * 32 + (lane_c >> 4) * 8]);
; #pragma unroll
;         for (int td = 0; td < 4; ++td) {
;           const bf16x8 vf = *reinterpret_cast<const bf16x8*>(&sm_vt[(td * 16 + (lane_c & 15)) * 136 + s4 * 32 + (lane_c >> 4) * 8]);
;           o[td] = __builtin_amdgcn_mfma_f32_16x16x32_bf16(pf, vf, o[td], 0, 0, 0);
;         }
;       }
	v_mfma_f32_16x16x32_bf16 v[44:47], v[140:143], v[52:55], v[44:47]
	ds_read_b32 v0, v184 offset:1024
	ds_read_b32 v1, v185 offset:1024
	ds_read_b32 v2, v186 offset:1024
	ds_read_b32 v3, v187 offset:1024
	ds_read_b32 v4, v184 offset:1152
	ds_read_b32 v5, v185 offset:1152
	ds_read_b32 v6, v186 offset:1152
	ds_read_b32 v7, v187 offset:1152
	ds_read_b32 v8, v188 offset:1024
	ds_read_b32 v9, v189 offset:1024
	ds_read_b32 v10, v190 offset:1024
	ds_read_b32 v11, v191 offset:1024
	ds_read_b32 v12, v188 offset:1152
	ds_read_b32 v13, v189 offset:1152
	ds_read_b32 v14, v190 offset:1152
	ds_read_b32 v15, v191 offset:1152
	ds_read_b128 v[112:115], v144 offset:0
	ds_read_b128 v[116:119], v145 offset:0
	ds_read_b128 v[120:123], v144 offset:8192
	ds_read_b128 v[124:127], v145 offset:8192
	ds_read_b128 v[128:131], v144 offset:2048
	ds_read_b128 v[132:135], v145 offset:2048
	ds_read_b128 v[136:139], v144 offset:10240
	ds_read_b128 v[140:143], v145 offset:10240
	s_waitcnt lgkmcnt(7)
	v_mfma_f32_16x16x32_bf16 v[0:3], v[112:115], v[230:233], v[0:3]
	s_waitcnt lgkmcnt(6)
	v_mfma_f32_16x16x32_bf16 v[0:3], v[116:119], v[234:237], v[0:3]
	s_waitcnt lgkmcnt(5)
	v_mfma_f32_16x16x32_bf16 v[4:7], v[120:123], v[230:233], v[4:7]
	s_waitcnt lgkmcnt(4)
	v_mfma_f32_16x16x32_bf16 v[4:7], v[124:127], v[234:237], v[4:7]
	s_waitcnt lgkmcnt(3)
	v_mfma_f32_16x16x32_bf16 v[8:11], v[128:131], v[230:233], v[8:11]
	s_waitcnt lgkmcnt(2)
	v_mfma_f32_16x16x32_bf16 v[8:11], v[132:135], v[234:237], v[8:11]
	s_waitcnt lgkmcnt(1)
	v_mfma_f32_16x16x32_bf16 v[12:15], v[136:139], v[230:233], v[12:15]
	s_waitcnt lgkmcnt(0)
	v_mfma_f32_16x16x32_bf16 v[12:15], v[140:143], v[234:237], v[12:15]
	s_nop 7
	v_max3_f32 v203, v0, v1, v2
	v_max3_f32 v203, v203, v3, v4
	v_max3_f32 v203, v203, v5, v6
	v_max3_f32 v203, v203, v7, v8
	v_max3_f32 v203, v203, v9, v10
	v_max3_f32 v203, v203, v11, v12
	v_max3_f32 v203, v203, v13, v14
	v_max_f32_e32 v203, v203, v15
	v_mov_b32_e32 v205, v203
	s_nop 1
	v_permlane16_swap_b32_e32 v203, v205
	v_max_f32_e32 v203, v203, v205
	v_mov_b32_e32 v205, v203
	s_nop 1
	v_permlane32_swap_b32_e32 v203, v205
	v_max_f32_e32 v203, v203, v205
	v_max_f32_e32 v218, v246, v203
	v_sub_f32_e32 v220, v246, v218
	v_mov_b32_e32 v219, v218
	v_exp_f32_e32 v220, v220
	v_mov_b32_e32 v246, v218
	v_pk_add_f32 v[0:1], v[0:1], v[218:219] neg_lo:[0,1] neg_hi:[0,1]
	v_pk_add_f32 v[2:3], v[2:3], v[218:219] neg_lo:[0,1] neg_hi:[0,1]
	v_pk_add_f32 v[4:5], v[4:5], v[218:219] neg_lo:[0,1] neg_hi:[0,1]
	v_pk_add_f32 v[6:7], v[6:7], v[218:219] neg_lo:[0,1] neg_hi:[0,1]
	v_pk_add_f32 v[8:9], v[8:9], v[218:219] neg_lo:[0,1] neg_hi:[0,1]
	v_pk_add_f32 v[10:11], v[10:11], v[218:219] neg_lo:[0,1] neg_hi:[0,1]
	v_pk_add_f32 v[12:13], v[12:13], v[218:219] neg_lo:[0,1] neg_hi:[0,1]
	v_pk_add_f32 v[14:15], v[14:15], v[218:219] neg_lo:[0,1] neg_hi:[0,1]
	v_exp_f32_e32 v0, v0
	v_exp_f32_e32 v1, v1
	v_exp_f32_e32 v2, v2
	v_exp_f32_e32 v3, v3
	v_exp_f32_e32 v4, v4
	v_exp_f32_e32 v5, v5
	v_exp_f32_e32 v6, v6
	v_exp_f32_e32 v7, v7
	v_exp_f32_e32 v8, v8
	v_exp_f32_e32 v9, v9
	v_exp_f32_e32 v10, v10
	v_exp_f32_e32 v11, v11
	v_exp_f32_e32 v12, v12
	v_exp_f32_e32 v13, v13
	v_exp_f32_e32 v14, v14
	v_exp_f32_e32 v15, v15
	ds_read_b128 v[112:115], v146 offset:0
	ds_read_b128 v[116:119], v146 offset:4096
	ds_read_b128 v[120:123], v146 offset:8192
	ds_read_b128 v[124:127], v146 offset:12288
	ds_read_b128 v[128:131], v147 offset:0
	ds_read_b128 v[132:135], v147 offset:4096
	ds_read_b128 v[136:139], v147 offset:8192
	ds_read_b128 v[140:143], v147 offset:12288
	v_mov_b32_e32 v221, v220
	v_pk_add_f32 v[222:223], v[0:1], v[2:3]
	v_pk_add_f32 v[222:223], v[222:223], v[4:5]
	v_pk_add_f32 v[222:223], v[222:223], v[6:7]
	v_pk_add_f32 v[222:223], v[222:223], v[8:9]
	v_pk_add_f32 v[222:223], v[222:223], v[10:11]
	v_pk_add_f32 v[222:223], v[222:223], v[12:13]
	v_pk_add_f32 v[222:223], v[222:223], v[14:15]
	v_pk_mul_f32 v[176:177], v[176:177], v[220:221]
	v_pk_mul_f32 v[178:179], v[178:179], v[220:221]
	v_pk_mul_f32 v[180:181], v[180:181], v[220:221]
	v_pk_mul_f32 v[182:183], v[182:183], v[220:221]
	v_pk_mul_f32 v[192:193], v[192:193], v[220:221]
	v_pk_mul_f32 v[194:195], v[194:195], v[220:221]
	v_pk_mul_f32 v[196:197], v[196:197], v[220:221]
	v_pk_mul_f32 v[198:199], v[198:199], v[220:221]
	v_add_f32_e32 v203, v222, v223
	v_fma_f32 v247, v247, v220, v203
	v_cvt_pk_bf16_f32 v48, v0, v1
	v_cvt_pk_bf16_f32 v49, v2, v3
	v_cvt_pk_bf16_f32 v50, v4, v5
	v_cvt_pk_bf16_f32 v51, v6, v7
	v_cvt_pk_bf16_f32 v52, v8, v9
	v_cvt_pk_bf16_f32 v53, v10, v11
	v_cvt_pk_bf16_f32 v54, v12, v13
	v_cvt_pk_bf16_f32 v55, v14, v15
	s_waitcnt lgkmcnt(7)
	v_mfma_f32_16x16x32_bf16 v[176:179], v[112:115], v[48:51], v[176:179]
	s_waitcnt lgkmcnt(6)
	v_mfma_f32_16x16x32_bf16 v[180:183], v[116:119], v[48:51], v[180:183]
	s_waitcnt lgkmcnt(5)
	v_mfma_f32_16x16x32_bf16 v[192:195], v[120:123], v[48:51], v[192:195]
	s_waitcnt lgkmcnt(4)
	v_mfma_f32_16x16x32_bf16 v[196:199], v[124:127], v[48:51], v[196:199]
	s_waitcnt lgkmcnt(3)
	v_mfma_f32_16x16x32_bf16 v[176:179], v[128:131], v[52:55], v[176:179]
	s_waitcnt lgkmcnt(2)
	v_mfma_f32_16x16x32_bf16 v[180:183], v[132:135], v[52:55], v[180:183]
	s_waitcnt lgkmcnt(1)
	v_mfma_f32_16x16x32_bf16 v[192:195], v[136:139], v[52:55], v[192:195]
	s_waitcnt lgkmcnt(0)
	v_mfma_f32_16x16x32_bf16 v[196:199], v[140:143], v[52:55], v[196:199]
	s_waitcnt lgkmcnt(0)
	s_barrier
	s_cmp_eq_u32 s19, 0
	s_cbranch_scc1 .Lmy_att_s4_3
; __device__ __forceinline__ void attn_phase(const Params& P, char* smem_raw) {
;     ...
; #pragma unroll
;       for (int s = 0; s < 2; ++s)
; #pragma unroll
;         for (int t8 = 0; t8 < 8; ++t8) {
;           const bf16x8 kf = *reinterpret_cast<const bf16x8*>(&sm_k[(t8 * 16 + (lane_c & 15)) * LDSS + s * 32 + (lane_c >> 4) * 8]);
;           sacc[t8] = __builtin_amdgcn_mfma_f32_16x16x32_bf16(qf[s], kf, sacc[t8], 0, 0, 0);
;         }
;       if (ck < 5) {
;         ATT_ISSUE(t, ck + 1)
;       } else if (t + VGRID < 8192) {
;         ATT_ISSUE(t + VGRID, 0)
;         ATT_QLOAD(t + VGRID)
;       }
;       if (ck < 4) {
;         const float* rb0 = sm_rpb + (rs + ck * 2 - r + 7) * 31;
; #pragma unroll
;         for (int t8 = 0; t8 < 8; ++t8)
; #pragma unroll
;           for (int reg = 0; reg < 4; ++reg)
;             sacc[t8][reg] += rb0[(t8 >> 2) * 31 + dco[reg][t8 & 3]];
;       }
; #pragma unroll
;       for (int reg = 0; reg < 4; ++reg) {
;         float mx = sacc[0][reg];
; #pragma unroll
;         for (int t8 = 1; t8 < 8; ++t8) mx = fmaxf(mx, sacc[t8][reg]);
;         mx = row16_max(mx);
;         const float mnew = fmaxf(mrow[reg], mx);
;         const float alpha = __builtin_amdgcn_exp2f(mrow[reg] - mnew);
;         mrow[reg] = mnew;
;         float rsum = 0.f;
; #pragma unroll
;         for (int t8 = 0; t8 < 8; ++t8) {
;           const float p = __builtin_amdgcn_exp2f(sacc[t8][reg] - mnew);
;           rsum += p;
;           sm_p[(wid * 16 + (lane_c >> 4) * 4 + reg) * 136 + t8 * 16 + (lane_c & 15)] = f2bf(p);
;         }
;         rsum = row16_sum(rsum);
;         lrow[reg] = lrow[reg] * alpha + rsum;
; #pragma unroll
;         for (int td = 0; td < 4; ++td) o[td][reg] *= alpha;
;       }
	ds_read_b32 v0, v184 offset:1280
	ds_read_b32 v1, v185 offset:1280
	ds_read_b32 v2, v186 offset:1280
	ds_read_b32 v3, v187 offset:1280
	ds_read_b32 v8, v188 offset:1280
	ds_read_b32 v9, v189 offset:1280
	ds_read_b32 v10, v190 offset:1280
	ds_read_b32 v11, v191 offset:1280
	v_mov_b32_e32 v4, 0xf149f2ca
	v_mov_b32_e32 v5, 0xf149f2ca
	v_mov_b32_e32 v6, 0xf149f2ca
	v_mov_b32_e32 v7, 0xf149f2ca
	v_mov_b32_e32 v12, 0xf149f2ca
	v_mov_b32_e32 v13, 0xf149f2ca
	v_mov_b32_e32 v14, 0xf149f2ca
	v_mov_b32_e32 v15, 0xf149f2ca
	ds_read_b128 v[112:115], v144 offset:32768
	ds_read_b128 v[116:119], v145 offset:32768
	ds_read_b128 v[120:123], v144 offset:40960
	ds_read_b128 v[124:127], v145 offset:40960
	ds_read_b128 v[128:131], v144 offset:34816
	ds_read_b128 v[132:135], v145 offset:34816
	ds_read_b128 v[136:139], v144 offset:43008
	ds_read_b128 v[140:143], v145 offset:43008
	s_waitcnt lgkmcnt(7)
	v_mfma_f32_16x16x32_bf16 v[0:3], v[112:115], v[230:233], v[0:3]
	s_waitcnt lgkmcnt(6)
	v_mfma_f32_16x16x32_bf16 v[0:3], v[116:119], v[234:237], v[0:3]
	s_waitcnt lgkmcnt(5)
	v_mfma_f32_16x16x32_bf16 v[4:7], v[120:123], v[230:233], v[4:7]
	s_waitcnt lgkmcnt(4)
	v_mfma_f32_16x16x32_bf16 v[4:7], v[124:127], v[234:237], v[4:7]
	s_waitcnt lgkmcnt(3)
	v_mfma_f32_16x16x32_bf16 v[8:11], v[128:131], v[230:233], v[8:11]
	s_waitcnt lgkmcnt(2)
	v_mfma_f32_16x16x32_bf16 v[8:11], v[132:135], v[234:237], v[8:11]
	s_waitcnt lgkmcnt(1)
	v_mfma_f32_16x16x32_bf16 v[12:15], v[136:139], v[230:233], v[12:15]
	s_waitcnt lgkmcnt(0)
	v_mfma_f32_16x16x32_bf16 v[12:15], v[140:143], v[234:237], v[12:15]
	s_nop 7
	v_max3_f32 v203, v0, v1, v2
	v_max3_f32 v203, v203, v3, v4
	v_max3_f32 v203, v203, v5, v6
	v_max3_f32 v203, v203, v7, v8
	v_max3_f32 v203, v203, v9, v10
	v_max3_f32 v203, v203, v11, v12
	v_max3_f32 v203, v203, v13, v14
	v_max_f32_e32 v203, v203, v15
	v_mov_b32_e32 v205, v203
	s_nop 1
	v_permlane16_swap_b32_e32 v203, v205
	v_max_f32_e32 v203, v203, v205
	v_mov_b32_e32 v205, v203
	s_nop 1
	v_permlane32_swap_b32_e32 v203, v205
	v_max_f32_e32 v203, v203, v205
	v_max_f32_e32 v218, v246, v203
	v_sub_f32_e32 v220, v246, v218
	v_mov_b32_e32 v219, v218
	v_exp_f32_e32 v220, v220
	v_mov_b32_e32 v246, v218
	v_pk_add_f32 v[0:1], v[0:1], v[218:219] neg_lo:[0,1] neg_hi:[0,1]
	v_pk_add_f32 v[2:3], v[2:3], v[218:219] neg_lo:[0,1] neg_hi:[0,1]
	v_pk_add_f32 v[4:5], v[4:5], v[218:219] neg_lo:[0,1] neg_hi:[0,1]
	v_pk_add_f32 v[6:7], v[6:7], v[218:219] neg_lo:[0,1] neg_hi:[0,1]
	v_pk_add_f32 v[8:9], v[8:9], v[218:219] neg_lo:[0,1] neg_hi:[0,1]
	v_pk_add_f32 v[10:11], v[10:11], v[218:219] neg_lo:[0,1] neg_hi:[0,1]
	v_pk_add_f32 v[12:13], v[12:13], v[218:219] neg_lo:[0,1] neg_hi:[0,1]
	v_pk_add_f32 v[14:15], v[14:15], v[218:219] neg_lo:[0,1] neg_hi:[0,1]
	v_exp_f32_e32 v0, v0
	s_waitcnt vmcnt(0)
	v_exp_f32_e32 v1, v1
	ds_write_b128 v150, v[80:83] offset:0
	v_exp_f32_e32 v2, v2
	ds_write_b128 v150, v[84:87] offset:4096
	v_exp_f32_e32 v3, v3
	ds_write_b128 v150, v[88:91] offset:8192
	v_exp_f32_e32 v4, v4
	ds_write_b128 v150, v[92:95] offset:12288
	v_exp_f32_e32 v5, v5
	ds_write_b64 v151, v[96:97] offset:0
	v_exp_f32_e32 v6, v6
	ds_write_b64 v229, v[98:99] offset:0
	v_exp_f32_e32 v7, v7
	ds_write_b64 v151, v[100:101] offset:4096
	v_exp_f32_e32 v8, v8
	ds_write_b64 v229, v[102:103] offset:4096
	v_exp_f32_e32 v9, v9
	ds_write_b64 v151, v[104:105] offset:8192
	v_exp_f32_e32 v10, v10
	ds_write_b64 v229, v[106:107] offset:8192
	v_exp_f32_e32 v11, v11
	ds_write_b64 v151, v[108:109] offset:12288
	v_exp_f32_e32 v12, v12
	ds_write_b64 v229, v[110:111] offset:12288
	v_exp_f32_e32 v13, v13
	s_add_u32 s100, s16, 0xc0000
	v_exp_f32_e32 v14, v14
	s_addc_u32 s101, s17, 0
	v_exp_f32_e32 v15, v15
	s_add_u32 s0, s36, 0x100
	s_addc_u32 s1, s37, 0
	global_load_dwordx4 v[80:83], v154, s[100:101] offset:2048
	global_load_dwordx4 v[96:99], v162, s[0:1]
	global_load_dwordx4 v[84:87], v155, s[100:101] offset:2048
	global_load_dwordx4 v[100:103], v163, s[0:1]
	global_load_dwordx4 v[88:91], v156, s[100:101] offset:2048
	global_load_dwordx4 v[104:107], v164, s[0:1]
	global_load_dwordx4 v[92:95], v157, s[100:101] offset:2048
	global_load_dwordx4 v[108:111], v165, s[0:1]
	s_and_b32 s0, s3, 0xff
	s_add_u32 s0, s0, 1
	s_min_u32 s0, s0, 7
	s_lshr_b32 s1, s0, 1
	s_and_b32 s0, s0, 1
	s_lshl_b32 s0, s0, 5
	s_lshr_b32 vcc_lo, s3, 12
	s_add_u32 s0, s0, vcc_lo
	s_lshl_b32 s0, s0, 1
	s_sub_i32 vcc_lo, s0, 4
	s_max_i32 vcc_lo, vcc_lo, 0
	s_min_i32 vcc_lo, vcc_lo, 0x78
	s_lshl_b32 vcc_hi, s1, 13
	s_add_u32 s20, vcc_lo, 8
	s_min_u32 s20, s20, 0x7e
	s_sub_u32 s20, s20, vcc_lo
	s_lshl_b32 s21, s20, 7
	s_mul_i32 s20, s20, 0x60000
	s_lshl_b32 m0, vcc_lo, 6
	s_add_u32 m0, m0, vcc_hi
	s_mul_i32 m0, m0, 0x1800
	s_add_u32 s12, s4, m0
	s_addc_u32 s13, s5, 0
	s_lshl_b32 m0, s1, 24
	s_lshl_b32 s100, vcc_lo, 7
	s_add_u32 m0, m0, s100
	s_add_u32 s14, s6, m0
	s_addc_u32 s15, s7, 0
	s_lshl_b32 m0, s0, 6
	s_add_u32 m0, m0, vcc_hi
	s_mul_i32 m0, m0, 0x1800
	s_add_u32 s100, s4, m0
	s_addc_u32 s101, s5, 0
	global_load_dwordx4 v[72:75], v166, s[100:101]
	global_load_dwordx4 v[76:79], v166, s[100:101] offset:64
	s_add_u32 s100, s100, 0x60000
	s_addc_u32 s101, s101, 0
	global_load_dwordx4 v[238:241], v166, s[100:101]
	global_load_dwordx4 v[242:245], v166, s[100:101] offset:64
	ds_read_b128 v[112:115], v146 offset:32768
	ds_read_b128 v[116:119], v146 offset:36864
	ds_read_b128 v[120:123], v146 offset:40960
	ds_read_b128 v[124:127], v146 offset:45056
	ds_read_b128 v[128:131], v147 offset:32768
	ds_read_b128 v[132:135], v147 offset:36864
	ds_read_b128 v[136:139], v147 offset:40960
	ds_read_b128 v[140:143], v147 offset:45056
	v_mov_b32_e32 v221, v220
	v_pk_add_f32 v[222:223], v[0:1], v[2:3]
	v_pk_add_f32 v[222:223], v[222:223], v[4:5]
	v_pk_add_f32 v[222:223], v[222:223], v[6:7]
	v_pk_add_f32 v[222:223], v[222:223], v[8:9]
	v_pk_add_f32 v[222:223], v[222:223], v[10:11]
	v_pk_add_f32 v[222:223], v[222:223], v[12:13]
	v_pk_add_f32 v[222:223], v[222:223], v[14:15]
	v_pk_mul_f32 v[176:177], v[176:177], v[220:221]
	v_pk_mul_f32 v[178:179], v[178:179], v[220:221]
	v_pk_mul_f32 v[180:181], v[180:181], v[220:221]
	v_pk_mul_f32 v[182:183], v[182:183], v[220:221]
	v_pk_mul_f32 v[192:193], v[192:193], v[220:221]
	v_pk_mul_f32 v[194:195], v[194:195], v[220:221]
	v_pk_mul_f32 v[196:197], v[196:197], v[220:221]
	v_pk_mul_f32 v[198:199], v[198:199], v[220:221]
	v_add_f32_e32 v203, v222, v223
	v_fma_f32 v247, v247, v220, v203
	v_cvt_pk_bf16_f32 v48, v0, v1
	v_cvt_pk_bf16_f32 v49, v2, v3
	v_cvt_pk_bf16_f32 v50, v4, v5
	v_cvt_pk_bf16_f32 v51, v6, v7
	v_cvt_pk_bf16_f32 v52, v8, v9
	v_cvt_pk_bf16_f32 v53, v10, v11
	v_cvt_pk_bf16_f32 v54, v12, v13
	v_cvt_pk_bf16_f32 v55, v14, v15
	s_waitcnt lgkmcnt(7)
; __device__ __forceinline__ void attn_phase(const Params& P, char* smem_raw) {
;     ...
; #pragma unroll
;       for (int s = 0; s < 2; ++s)
; #pragma unroll
;         for (int t8 = 0; t8 < 8; ++t8) {
;           const bf16x8 kf = *reinterpret_cast<const bf16x8*>(&sm_k[(t8 * 16 + (lane_c & 15)) * LDSS + s * 32 + (lane_c >> 4) * 8]);
;           sacc[t8] = __builtin_amdgcn_mfma_f32_16x16x32_bf16(qf[s], kf, sacc[t8], 0, 0, 0);
;         }
	v_mfma_f32_16x16x32_bf16 v[176:179], v[112:115], v[48:51], v[176:179]
	s_waitcnt lgkmcnt(6)
	v_mfma_f32_16x16x32_bf16 v[180:183], v[116:119], v[48:51], v[180:183]
	s_waitcnt lgkmcnt(5)
	v_mfma_f32_16x16x32_bf16 v[192:195], v[120:123], v[48:51], v[192:195]
	s_waitcnt lgkmcnt(4)
	v_mfma_f32_16x16x32_bf16 v[196:199], v[124:127], v[48:51], v[196:199]
	s_waitcnt lgkmcnt(3)
	v_mfma_f32_16x16x32_bf16 v[176:179], v[128:131], v[52:55], v[176:179]
	s_waitcnt lgkmcnt(2)
	v_mfma_f32_16x16x32_bf16 v[180:183], v[132:135], v[52:55], v[180:183]
	s_waitcnt lgkmcnt(1)
	v_mfma_f32_16x16x32_bf16 v[192:195], v[136:139], v[52:55], v[192:195]
	s_waitcnt lgkmcnt(0)
	v_mfma_f32_16x16x32_bf16 v[196:199], v[140:143], v[52:55], v[196:199]
	s_branch .Lmy_att_e4_3
.Lmy_att_s4_3:
	s_waitcnt vmcnt(0)
	ds_write_b128 v150, v[80:83] offset:0
	ds_write_b128 v150, v[84:87] offset:4096
	ds_write_b128 v150, v[88:91] offset:8192
	ds_write_b128 v150, v[92:95] offset:12288
	ds_write_b64 v151, v[96:97] offset:0
	ds_write_b64 v229, v[98:99] offset:0
	ds_write_b64 v151, v[100:101] offset:4096
	ds_write_b64 v229, v[102:103] offset:4096
	ds_write_b64 v151, v[104:105] offset:8192
	ds_write_b64 v229, v[106:107] offset:8192
	ds_write_b64 v151, v[108:109] offset:12288
	ds_write_b64 v229, v[110:111] offset:12288
	s_add_u32 s100, s16, 0xc0000
	s_addc_u32 s101, s17, 0
	s_add_u32 s0, s36, 0x100
	s_addc_u32 s1, s37, 0
	global_load_dwordx4 v[80:83], v154, s[100:101] offset:2048
	global_load_dwordx4 v[96:99], v162, s[0:1]
	global_load_dwordx4 v[84:87], v155, s[100:101] offset:2048
	global_load_dwordx4 v[100:103], v163, s[0:1]
	global_load_dwordx4 v[88:91], v156, s[100:101] offset:2048
	global_load_dwordx4 v[104:107], v164, s[0:1]
	global_load_dwordx4 v[92:95], v157, s[100:101] offset:2048
	global_load_dwordx4 v[108:111], v165, s[0:1]
	s_and_b32 s0, s3, 0xff
	s_add_u32 s0, s0, 1
	s_min_u32 s0, s0, 7
	s_lshr_b32 s1, s0, 1
	s_and_b32 s0, s0, 1
	s_lshl_b32 s0, s0, 5
	s_lshr_b32 vcc_lo, s3, 12
	s_add_u32 s0, s0, vcc_lo
	s_lshl_b32 s0, s0, 1
	s_sub_i32 vcc_lo, s0, 4
	s_max_i32 vcc_lo, vcc_lo, 0
	s_min_i32 vcc_lo, vcc_lo, 0x78
	s_lshl_b32 vcc_hi, s1, 13
	s_add_u32 s20, vcc_lo, 8
	s_min_u32 s20, s20, 0x7e
	s_sub_u32 s20, s20, vcc_lo
	s_lshl_b32 s21, s20, 7
	s_mul_i32 s20, s20, 0x60000
	s_lshl_b32 m0, vcc_lo, 6
	s_add_u32 m0, m0, vcc_hi
	s_mul_i32 m0, m0, 0x1800
	s_add_u32 s12, s4, m0
	s_addc_u32 s13, s5, 0
	s_lshl_b32 m0, s1, 24
	s_lshl_b32 s100, vcc_lo, 7
	s_add_u32 m0, m0, s100
	s_add_u32 s14, s6, m0
	s_addc_u32 s15, s7, 0
	s_lshl_b32 m0, s0, 6
	s_add_u32 m0, m0, vcc_hi
	s_mul_i32 m0, m0, 0x1800
	s_add_u32 s100, s4, m0
	s_addc_u32 s101, s5, 0
	global_load_dwordx4 v[72:75], v166, s[100:101]
	global_load_dwordx4 v[76:79], v166, s[100:101] offset:64
	s_add_u32 s100, s100, 0x60000
	s_addc_u32 s101, s101, 0
	global_load_dwordx4 v[238:241], v166, s[100:101]
	global_load_dwordx4 v[242:245], v166, s[100:101] offset:64
.Lmy_att_e4_3:
	s_waitcnt lgkmcnt(0)
	s_barrier
	ds_read_b128 v[112:115], v149 offset:0
	ds_read_b128 v[116:119], v224 offset:0
	ds_read_b128 v[120:123], v149 offset:8192
	ds_read_b128 v[124:127], v224 offset:8192
	ds_read_b128 v[128:131], v149 offset:2048
	ds_read_b128 v[132:135], v224 offset:2048
	ds_read_b128 v[136:139], v149 offset:10240
	ds_read_b128 v[140:143], v224 offset:10240
	s_waitcnt lgkmcnt(7)
	v_mfma_f32_16x16x32_bf16 v[0:3], v[112:115], v[64:67], 0
	ds_read_b128 v[112:115], v149 offset:4096
	s_waitcnt lgkmcnt(7)
	v_mfma_f32_16x16x32_bf16 v[0:3], v[116:119], v[68:71], v[0:3]
	ds_read_b128 v[116:119], v224 offset:4096
	s_waitcnt lgkmcnt(7)
	v_mfma_f32_16x16x32_bf16 v[4:7], v[120:123], v[64:67], 0
	ds_read_b128 v[120:123], v149 offset:12288
	s_waitcnt lgkmcnt(7)
	v_mfma_f32_16x16x32_bf16 v[4:7], v[124:127], v[68:71], v[4:7]
	ds_read_b128 v[124:127], v224 offset:12288
	s_waitcnt lgkmcnt(7)
	v_mfma_f32_16x16x32_bf16 v[8:11], v[128:131], v[64:67], 0
	ds_read_b128 v[128:131], v149 offset:6144
	s_waitcnt lgkmcnt(7)
	v_mfma_f32_16x16x32_bf16 v[8:11], v[132:135], v[68:71], v[8:11]
	ds_read_b128 v[132:135], v224 offset:6144
	s_waitcnt lgkmcnt(7)
	v_mfma_f32_16x16x32_bf16 v[12:15], v[136:139], v[64:67], 0
	ds_read_b128 v[136:139], v149 offset:14336
	s_waitcnt lgkmcnt(7)
	v_mfma_f32_16x16x32_bf16 v[12:15], v[140:143], v[68:71], v[12:15]
	ds_read_b128 v[140:143], v224 offset:14336
	s_waitcnt lgkmcnt(7)
	v_mfma_f32_16x16x32_bf16 v[16:19], v[112:115], v[64:67], 0
	s_waitcnt lgkmcnt(6)
	v_mfma_f32_16x16x32_bf16 v[16:19], v[116:119], v[68:71], v[16:19]
	s_waitcnt lgkmcnt(5)
	v_mfma_f32_16x16x32_bf16 v[20:23], v[120:123], v[64:67], 0
	s_waitcnt lgkmcnt(4)
	v_mfma_f32_16x16x32_bf16 v[20:23], v[124:127], v[68:71], v[20:23]
	s_waitcnt lgkmcnt(3)
	v_mfma_f32_16x16x32_bf16 v[24:27], v[128:131], v[64:67], 0
	s_waitcnt lgkmcnt(2)
	v_mfma_f32_16x16x32_bf16 v[24:27], v[132:135], v[68:71], v[24:27]
	s_waitcnt lgkmcnt(1)
	v_mfma_f32_16x16x32_bf16 v[28:31], v[136:139], v[64:67], 0
	s_waitcnt lgkmcnt(0)
; __device__ __forceinline__ void attn_phase(const Params& P, char* smem_raw) {
;     ...
;       if (ck < 5) {
;         ATT_ISSUE(t, ck + 1)
;       } else if (t + VGRID < 8192) {
;         ATT_ISSUE(t + VGRID, 0)
;         ATT_QLOAD(t + VGRID)
;       }
;       if (ck < 4) {
;         const float* rb0 = sm_rpb + (rs + ck * 2 - r + 7) * 31;
; #pragma unroll
;         for (int t8 = 0; t8 < 8; ++t8)
; #pragma unroll
;           for (int reg = 0; reg < 4; ++reg)
;             sacc[t8][reg] += rb0[(t8 >> 2) * 31 + dco[reg][t8 & 3]];
;       }
; #pragma unroll
;       for (int reg = 0; reg < 4; ++reg) {
;         float mx = sacc[0][reg];
; #pragma unroll
;         for (int t8 = 1; t8 < 8; ++t8) mx = fmaxf(mx, sacc[t8][reg]);
;         mx = row16_max(mx);
;         const float mnew = fmaxf(mrow[reg], mx);
;         const float alpha = __builtin_amdgcn_exp2f(mrow[reg] - mnew);
;         mrow[reg] = mnew;
;         float rsum = 0.f;
; #pragma unroll
;         for (int t8 = 0; t8 < 8; ++t8) {
;           const float p = __builtin_amdgcn_exp2f(sacc[t8][reg] - mnew);
;           rsum += p;
;           sm_p[(wid * 16 + (lane_c >> 4) * 4 + reg) * 136 + t8 * 16 + (lane_c & 15)] = f2bf(p);
;         }
;         rsum = row16_sum(rsum);
;         lrow[reg] = lrow[reg] * alpha + rsum;
; #pragma unroll
;         for (int td = 0; td < 4; ++td) o[td][reg] *= alpha;
;       }
;       asm volatile("s_waitcnt lgkmcnt(0)" ::: "memory");
; #pragma unroll
;       for (int s4 = 0; s4 < 4; ++s4) {
;         const bf16x8 pf = *reinterpret_cast<const bf16x8*>(&sm_p[(wid * 16 + (lane_c & 15)) * 136 + s4 * 32 + (lane_c >> 4) * 8]);
; #pragma unroll
;         for (int td = 0; td < 4; ++td) {
;           const bf16x8 vf = *reinterpret_cast<const bf16x8*>(&sm_vt[(td * 16 + (lane_c & 15)) * 136 + s4 * 32 + (lane_c >> 4) * 8]);
;           o[td] = __builtin_amdgcn_mfma_f32_16x16x32_bf16(pf, vf, o[td], 0, 0, 0);
;         }
;       }
	v_mfma_f32_16x16x32_bf16 v[28:31], v[140:143], v[68:71], v[28:31]
	s_nop 7
	v_max3_f32 v203, v0, v1, v2
	v_max3_f32 v203, v203, v3, v4
	v_max3_f32 v203, v203, v5, v6
	v_max3_f32 v203, v203, v7, v8
	v_max3_f32 v203, v203, v9, v10
	v_max3_f32 v203, v203, v11, v12
	v_max3_f32 v203, v203, v13, v14
	v_max3_f32 v203, v203, v15, v16
	v_max3_f32 v203, v203, v17, v18
	v_max3_f32 v203, v203, v19, v20
	v_max3_f32 v203, v203, v21, v22
	v_max3_f32 v203, v203, v23, v24
	v_max3_f32 v203, v203, v25, v26
	v_max3_f32 v203, v203, v27, v28
	v_max3_f32 v203, v203, v29, v30
	v_max_f32_e32 v203, v203, v31
	v_mov_b32_e32 v205, v203
	s_nop 1
	v_permlane16_swap_b32_e32 v203, v205
	v_max_f32_e32 v203, v203, v205
	v_mov_b32_e32 v205, v203
	s_nop 1
	v_permlane32_swap_b32_e32 v203, v205
	v_max_f32_e32 v203, v203, v205
	v_max_f32_e32 v218, v200, v203
	v_sub_f32_e32 v220, v200, v218
	v_mov_b32_e32 v219, v218
	v_exp_f32_e32 v220, v220
	v_mov_b32_e32 v200, v218
	v_pk_add_f32 v[0:1], v[0:1], v[218:219] neg_lo:[0,1] neg_hi:[0,1]
	v_pk_add_f32 v[2:3], v[2:3], v[218:219] neg_lo:[0,1] neg_hi:[0,1]
	v_pk_add_f32 v[4:5], v[4:5], v[218:219] neg_lo:[0,1] neg_hi:[0,1]
	v_pk_add_f32 v[6:7], v[6:7], v[218:219] neg_lo:[0,1] neg_hi:[0,1]
	v_pk_add_f32 v[8:9], v[8:9], v[218:219] neg_lo:[0,1] neg_hi:[0,1]
	v_pk_add_f32 v[10:11], v[10:11], v[218:219] neg_lo:[0,1] neg_hi:[0,1]
	v_pk_add_f32 v[12:13], v[12:13], v[218:219] neg_lo:[0,1] neg_hi:[0,1]
	v_pk_add_f32 v[14:15], v[14:15], v[218:219] neg_lo:[0,1] neg_hi:[0,1]
	v_pk_add_f32 v[16:17], v[16:17], v[218:219] neg_lo:[0,1] neg_hi:[0,1]
	v_pk_add_f32 v[18:19], v[18:19], v[218:219] neg_lo:[0,1] neg_hi:[0,1]
	v_pk_add_f32 v[20:21], v[20:21], v[218:219] neg_lo:[0,1] neg_hi:[0,1]
	v_pk_add_f32 v[22:23], v[22:23], v[218:219] neg_lo:[0,1] neg_hi:[0,1]
	v_pk_add_f32 v[24:25], v[24:25], v[218:219] neg_lo:[0,1] neg_hi:[0,1]
	v_pk_add_f32 v[26:27], v[26:27], v[218:219] neg_lo:[0,1] neg_hi:[0,1]
	v_pk_add_f32 v[28:29], v[28:29], v[218:219] neg_lo:[0,1] neg_hi:[0,1]
	v_pk_add_f32 v[30:31], v[30:31], v[218:219] neg_lo:[0,1] neg_hi:[0,1]
	v_exp_f32_e32 v0, v0
	s_waitcnt vmcnt(4)
	v_exp_f32_e32 v1, v1
	ds_write_b128 v150, v[80:83] offset:32768
	v_exp_f32_e32 v2, v2
	ds_write_b128 v150, v[84:87] offset:36864
	v_exp_f32_e32 v3, v3
	ds_write_b128 v150, v[88:91] offset:40960
	v_exp_f32_e32 v4, v4
	ds_write_b128 v150, v[92:95] offset:45056
	v_exp_f32_e32 v5, v5
	ds_write_b64 v151, v[96:97] offset:32768
	v_exp_f32_e32 v6, v6
	ds_write_b64 v229, v[98:99] offset:32768
	v_exp_f32_e32 v7, v7
	ds_write_b64 v151, v[100:101] offset:36864
	v_exp_f32_e32 v8, v8
	ds_write_b64 v229, v[102:103] offset:36864
	v_exp_f32_e32 v9, v9
	ds_write_b64 v151, v[104:105] offset:40960
	v_exp_f32_e32 v10, v10
	ds_write_b64 v229, v[106:107] offset:40960
	v_exp_f32_e32 v11, v11
	ds_write_b64 v151, v[108:109] offset:45056
	v_exp_f32_e32 v12, v12
	ds_write_b64 v229, v[110:111] offset:45056
	v_exp_f32_e32 v13, v13
	s_add_u32 s100, s12, 0x0
	v_exp_f32_e32 v14, v14
	s_addc_u32 s101, s13, 0
	v_exp_f32_e32 v15, v15
	s_add_u32 s0, s14, 0x0
	v_exp_f32_e32 v16, v16
	s_addc_u32 s1, s15, 0
	v_exp_f32_e32 v17, v17
	global_load_dwordx4 v[80:83], v154, s[100:101] offset:2048
	v_exp_f32_e32 v18, v18
	global_load_dwordx4 v[96:99], v158, s[0:1]
	v_exp_f32_e32 v19, v19
	global_load_dwordx4 v[84:87], v155, s[100:101] offset:2048
	v_exp_f32_e32 v20, v20
	global_load_dwordx4 v[100:103], v159, s[0:1]
	v_exp_f32_e32 v21, v21
	global_load_dwordx4 v[88:91], v156, s[100:101] offset:2048
	v_exp_f32_e32 v22, v22
	global_load_dwordx4 v[104:107], v160, s[0:1]
	v_exp_f32_e32 v23, v23
	global_load_dwordx4 v[92:95], v157, s[100:101] offset:2048
	v_exp_f32_e32 v24, v24
	global_load_dwordx4 v[108:111], v161, s[0:1]
	v_exp_f32_e32 v25, v25
	v_exp_f32_e32 v26, v26
	v_exp_f32_e32 v27, v27
	v_exp_f32_e32 v28, v28
	v_exp_f32_e32 v29, v29
	v_exp_f32_e32 v30, v30
	v_exp_f32_e32 v31, v31
	s_and_b32 s0, s3, 0xff
	s_add_u32 s0, s0, 1
	s_min_u32 s0, s0, 7
	s_lshr_b32 s1, s0, 1
	s_and_b32 s0, s0, 1
	s_lshl_b32 s0, s0, 5
	s_lshr_b32 vcc_lo, s3, 12
	s_add_u32 s0, s0, vcc_lo
	s_lshl_b32 s0, s0, 1
	s_sub_i32 vcc_lo, s0, 4
	s_max_i32 vcc_lo, vcc_lo, 0
	s_min_i32 vcc_lo, vcc_lo, 0x78
	s_lshl_b32 vcc_hi, s1, 13
	s_sub_i32 vcc_lo, vcc_lo, s0
	s_add_i32 vcc_lo, vcc_lo, 4
	s_lshl_b32 vcc_lo, vcc_lo, 7
	s_bfe_u32 m0, s3, 0x10008
	s_mul_i32 m0, m0, 0x12000
	s_add_i32 vcc_lo, vcc_lo, m0
	s_add_i32 vcc_lo, vcc_lo, 0x10010
	v_add_u32_e32 v184, vcc_lo, v168
	v_add_u32_e32 v185, vcc_lo, v169
	v_add_u32_e32 v186, vcc_lo, v170
	v_add_u32_e32 v187, vcc_lo, v171
	v_add_u32_e32 v188, vcc_lo, v172
	v_add_u32_e32 v189, vcc_lo, v173
	v_add_u32_e32 v190, vcc_lo, v174
	v_add_u32_e32 v191, vcc_lo, v175
	ds_read_b128 v[112:115], v225 offset:0
	ds_read_b128 v[116:119], v225 offset:4096
	ds_read_b128 v[120:123], v225 offset:8192
	ds_read_b128 v[124:127], v225 offset:12288
	ds_read_b128 v[128:131], v226 offset:0
	ds_read_b128 v[132:135], v226 offset:4096
	ds_read_b128 v[136:139], v226 offset:8192
	ds_read_b128 v[140:143], v226 offset:12288
	v_mov_b32_e32 v221, v220
	v_pk_add_f32 v[222:223], v[0:1], v[2:3]
	v_pk_add_f32 v[222:223], v[222:223], v[4:5]
	v_pk_add_f32 v[222:223], v[222:223], v[6:7]
	v_pk_add_f32 v[222:223], v[222:223], v[8:9]
	v_pk_add_f32 v[222:223], v[222:223], v[10:11]
	v_pk_add_f32 v[222:223], v[222:223], v[12:13]
	v_pk_add_f32 v[222:223], v[222:223], v[14:15]
	v_pk_add_f32 v[222:223], v[222:223], v[16:17]
	v_pk_add_f32 v[222:223], v[222:223], v[18:19]
	v_pk_add_f32 v[222:223], v[222:223], v[20:21]
	v_pk_add_f32 v[222:223], v[222:223], v[22:23]
	v_pk_add_f32 v[222:223], v[222:223], v[24:25]
	v_pk_add_f32 v[222:223], v[222:223], v[26:27]
	v_pk_add_f32 v[222:223], v[222:223], v[28:29]
	v_pk_add_f32 v[222:223], v[222:223], v[30:31]
	v_pk_mul_f32 v[32:33], v[32:33], v[220:221]
	v_pk_mul_f32 v[34:35], v[34:35], v[220:221]
	v_pk_mul_f32 v[36:37], v[36:37], v[220:221]
	v_pk_mul_f32 v[38:39], v[38:39], v[220:221]
	v_pk_mul_f32 v[40:41], v[40:41], v[220:221]
	v_pk_mul_f32 v[42:43], v[42:43], v[220:221]
	v_pk_mul_f32 v[44:45], v[44:45], v[220:221]
	v_pk_mul_f32 v[46:47], v[46:47], v[220:221]
	v_add_f32_e32 v203, v222, v223
	v_fma_f32 v201, v201, v220, v203
	v_cvt_pk_bf16_f32 v48, v0, v1
	v_cvt_pk_bf16_f32 v49, v2, v3
	v_cvt_pk_bf16_f32 v50, v4, v5
	v_cvt_pk_bf16_f32 v51, v6, v7
	v_cvt_pk_bf16_f32 v52, v8, v9
	v_cvt_pk_bf16_f32 v53, v10, v11
	v_cvt_pk_bf16_f32 v54, v12, v13
	v_cvt_pk_bf16_f32 v55, v14, v15
	v_cvt_pk_bf16_f32 v56, v16, v17
	v_cvt_pk_bf16_f32 v57, v18, v19
	v_cvt_pk_bf16_f32 v58, v20, v21
	v_cvt_pk_bf16_f32 v59, v22, v23
	v_cvt_pk_bf16_f32 v60, v24, v25
	v_cvt_pk_bf16_f32 v61, v26, v27
	v_cvt_pk_bf16_f32 v62, v28, v29
	v_cvt_pk_bf16_f32 v63, v30, v31
	s_waitcnt lgkmcnt(7)
; __device__ __forceinline__ void attn_phase(const Params& P, char* smem_raw) {
;     ...
; #pragma unroll
;       for (int s = 0; s < 2; ++s)
; #pragma unroll
;         for (int t8 = 0; t8 < 8; ++t8) {
;           const bf16x8 kf = *reinterpret_cast<const bf16x8*>(&sm_k[(t8 * 16 + (lane_c & 15)) * LDSS + s * 32 + (lane_c >> 4) * 8]);
;           sacc[t8] = __builtin_amdgcn_mfma_f32_16x16x32_bf16(qf[s], kf, sacc[t8], 0, 0, 0);
;         }
;       if (ck < 5) {
;         ATT_ISSUE(t, ck + 1)
;       } else if (t + VGRID < 8192) {
;         ATT_ISSUE(t + VGRID, 0)
;         ATT_QLOAD(t + VGRID)
;       }
;       if (ck < 4) {
;         const float* rb0 = sm_rpb + (rs + ck * 2 - r + 7) * 31;
; #pragma unroll
;         for (int t8 = 0; t8 < 8; ++t8)
; #pragma unroll
;           for (int reg = 0; reg < 4; ++reg)
;             sacc[t8][reg] += rb0[(t8 >> 2) * 31 + dco[reg][t8 & 3]];
;       }
; #pragma unroll
;       for (int reg = 0; reg < 4; ++reg) {
;         float mx = sacc[0][reg];
; #pragma unroll
;         for (int t8 = 1; t8 < 8; ++t8) mx = fmaxf(mx, sacc[t8][reg]);
;         mx = row16_max(mx);
;         const float mnew = fmaxf(mrow[reg], mx);
;         const float alpha = __builtin_amdgcn_exp2f(mrow[reg] - mnew);
;         mrow[reg] = mnew;
;         float rsum = 0.f;
; #pragma unroll
;         for (int t8 = 0; t8 < 8; ++t8) {
;           const float p = __builtin_amdgcn_exp2f(sacc[t8][reg] - mnew);
;           rsum += p;
;           sm_p[(wid * 16 + (lane_c >> 4) * 4 + reg) * 136 + t8 * 16 + (lane_c & 15)] = f2bf(p);
;         }
;         rsum = row16_sum(rsum);
;         lrow[reg] = lrow[reg] * alpha + rsum;
; #pragma unroll
;         for (int td = 0; td < 4; ++td) o[td][reg] *= alpha;
;       }
;       asm volatile("s_waitcnt lgkmcnt(0)" ::: "memory");
; #pragma unroll
;       for (int s4 = 0; s4 < 4; ++s4) {
;         const bf16x8 pf = *reinterpret_cast<const bf16x8*>(&sm_p[(wid * 16 + (lane_c & 15)) * 136 + s4 * 32 + (lane_c >> 4) * 8]);
; #pragma unroll
;         for (int td = 0; td < 4; ++td) {
;           const bf16x8 vf = *reinterpret_cast<const bf16x8*>(&sm_vt[(td * 16 + (lane_c & 15)) * 136 + s4 * 32 + (lane_c >> 4) * 8]);
;           o[td] = __builtin_amdgcn_mfma_f32_16x16x32_bf16(pf, vf, o[td], 0, 0, 0);
;         }
;       }
	v_mfma_f32_16x16x32_bf16 v[32:35], v[112:115], v[48:51], v[32:35]
	ds_read_b128 v[112:115], v227 offset:0
	s_waitcnt lgkmcnt(7)
	v_mfma_f32_16x16x32_bf16 v[36:39], v[116:119], v[48:51], v[36:39]
	ds_read_b128 v[116:119], v227 offset:4096
	s_waitcnt lgkmcnt(7)
	v_mfma_f32_16x16x32_bf16 v[40:43], v[120:123], v[48:51], v[40:43]
	ds_read_b128 v[120:123], v227 offset:8192
	s_waitcnt lgkmcnt(7)
	v_mfma_f32_16x16x32_bf16 v[44:47], v[124:127], v[48:51], v[44:47]
	ds_read_b128 v[124:127], v227 offset:12288
	s_waitcnt lgkmcnt(7)
	v_mfma_f32_16x16x32_bf16 v[32:35], v[128:131], v[52:55], v[32:35]
	ds_read_b128 v[128:131], v228 offset:0
	s_waitcnt lgkmcnt(7)
	v_mfma_f32_16x16x32_bf16 v[36:39], v[132:135], v[52:55], v[36:39]
	ds_read_b128 v[132:135], v228 offset:4096
	s_waitcnt lgkmcnt(7)
	v_mfma_f32_16x16x32_bf16 v[40:43], v[136:139], v[52:55], v[40:43]
	ds_read_b128 v[136:139], v228 offset:8192
	s_waitcnt lgkmcnt(7)
	v_mfma_f32_16x16x32_bf16 v[44:47], v[140:143], v[52:55], v[44:47]
	ds_read_b128 v[140:143], v228 offset:12288
	s_waitcnt lgkmcnt(7)
	v_mfma_f32_16x16x32_bf16 v[32:35], v[112:115], v[56:59], v[32:35]
	s_waitcnt lgkmcnt(6)
	v_mfma_f32_16x16x32_bf16 v[36:39], v[116:119], v[56:59], v[36:39]
	s_waitcnt lgkmcnt(5)
	v_mfma_f32_16x16x32_bf16 v[40:43], v[120:123], v[56:59], v[40:43]
	s_waitcnt lgkmcnt(4)
	v_mfma_f32_16x16x32_bf16 v[44:47], v[124:127], v[56:59], v[44:47]
	s_waitcnt lgkmcnt(3)
	v_mfma_f32_16x16x32_bf16 v[32:35], v[128:131], v[60:63], v[32:35]
	s_waitcnt lgkmcnt(2)
	v_mfma_f32_16x16x32_bf16 v[36:39], v[132:135], v[60:63], v[36:39]
	s_waitcnt lgkmcnt(1)
	v_mfma_f32_16x16x32_bf16 v[40:43], v[136:139], v[60:63], v[40:43]
	s_waitcnt lgkmcnt(0)
	v_mfma_f32_16x16x32_bf16 v[44:47], v[140:143], v[60:63], v[44:47]
	ds_read_b128 v[112:115], v149 offset:0
	ds_read_b128 v[116:119], v224 offset:0
	ds_read_b128 v[120:123], v149 offset:8192
	ds_read_b128 v[124:127], v224 offset:8192
	ds_read_b128 v[128:131], v149 offset:2048
	ds_read_b128 v[132:135], v224 offset:2048
	ds_read_b128 v[136:139], v149 offset:10240
	ds_read_b128 v[140:143], v224 offset:10240
	s_waitcnt lgkmcnt(7)
	v_mfma_f32_16x16x32_bf16 v[0:3], v[112:115], v[230:233], 0
	ds_read_b128 v[112:115], v149 offset:4096
	s_waitcnt lgkmcnt(7)
	v_mfma_f32_16x16x32_bf16 v[0:3], v[116:119], v[234:237], v[0:3]
	ds_read_b128 v[116:119], v224 offset:4096
	s_waitcnt lgkmcnt(7)
	v_mfma_f32_16x16x32_bf16 v[4:7], v[120:123], v[230:233], 0
	ds_read_b128 v[120:123], v149 offset:12288
	s_waitcnt lgkmcnt(7)
	v_mfma_f32_16x16x32_bf16 v[4:7], v[124:127], v[234:237], v[4:7]
	ds_read_b128 v[124:127], v224 offset:12288
	s_waitcnt lgkmcnt(7)
	v_mfma_f32_16x16x32_bf16 v[8:11], v[128:131], v[230:233], 0
	ds_read_b128 v[128:131], v149 offset:6144
	s_waitcnt lgkmcnt(7)
	v_mfma_f32_16x16x32_bf16 v[8:11], v[132:135], v[234:237], v[8:11]
	ds_read_b128 v[132:135], v224 offset:6144
	s_waitcnt lgkmcnt(7)
	v_mfma_f32_16x16x32_bf16 v[12:15], v[136:139], v[230:233], 0
	ds_read_b128 v[136:139], v149 offset:14336
	s_waitcnt lgkmcnt(7)
	v_mfma_f32_16x16x32_bf16 v[12:15], v[140:143], v[234:237], v[12:15]
	ds_read_b128 v[140:143], v224 offset:14336
	s_waitcnt lgkmcnt(7)
	v_mfma_f32_16x16x32_bf16 v[16:19], v[112:115], v[230:233], 0
	s_waitcnt lgkmcnt(6)
	v_mfma_f32_16x16x32_bf16 v[16:19], v[116:119], v[234:237], v[16:19]
	s_waitcnt lgkmcnt(5)
	v_mfma_f32_16x16x32_bf16 v[20:23], v[120:123], v[230:233], 0
	s_waitcnt lgkmcnt(4)
	v_mfma_f32_16x16x32_bf16 v[20:23], v[124:127], v[234:237], v[20:23]
	s_waitcnt lgkmcnt(3)
	v_mfma_f32_16x16x32_bf16 v[24:27], v[128:131], v[230:233], 0
	s_waitcnt lgkmcnt(2)
	v_mfma_f32_16x16x32_bf16 v[24:27], v[132:135], v[234:237], v[24:27]
	s_waitcnt lgkmcnt(1)
	v_mfma_f32_16x16x32_bf16 v[28:31], v[136:139], v[230:233], 0
	s_waitcnt lgkmcnt(0)
	v_mfma_f32_16x16x32_bf16 v[28:31], v[140:143], v[234:237], v[28:31]
	s_nop 7
	v_max3_f32 v203, v0, v1, v2
	v_max3_f32 v203, v203, v3, v4
	v_max3_f32 v203, v203, v5, v6
	v_max3_f32 v203, v203, v7, v8
	v_max3_f32 v203, v203, v9, v10
	v_max3_f32 v203, v203, v11, v12
	v_max3_f32 v203, v203, v13, v14
	v_max3_f32 v203, v203, v15, v16
	v_max3_f32 v203, v203, v17, v18
	v_max3_f32 v203, v203, v19, v20
	v_max3_f32 v203, v203, v21, v22
	v_max3_f32 v203, v203, v23, v24
	v_max3_f32 v203, v203, v25, v26
	v_max3_f32 v203, v203, v27, v28
	v_max3_f32 v203, v203, v29, v30
	v_max_f32_e32 v203, v203, v31
	v_mov_b32_e32 v205, v203
	s_nop 1
	v_permlane16_swap_b32_e32 v203, v205
	v_max_f32_e32 v203, v203, v205
	v_mov_b32_e32 v205, v203
	s_nop 1
	v_permlane32_swap_b32_e32 v203, v205
	v_max_f32_e32 v203, v203, v205
	v_max_f32_e32 v218, v246, v203
	v_sub_f32_e32 v220, v246, v218
	v_mov_b32_e32 v219, v218
	v_exp_f32_e32 v220, v220
	v_mov_b32_e32 v246, v218
	v_pk_add_f32 v[0:1], v[0:1], v[218:219] neg_lo:[0,1] neg_hi:[0,1]
	v_pk_add_f32 v[2:3], v[2:3], v[218:219] neg_lo:[0,1] neg_hi:[0,1]
	v_pk_add_f32 v[4:5], v[4:5], v[218:219] neg_lo:[0,1] neg_hi:[0,1]
	v_pk_add_f32 v[6:7], v[6:7], v[218:219] neg_lo:[0,1] neg_hi:[0,1]
	v_pk_add_f32 v[8:9], v[8:9], v[218:219] neg_lo:[0,1] neg_hi:[0,1]
	v_pk_add_f32 v[10:11], v[10:11], v[218:219] neg_lo:[0,1] neg_hi:[0,1]
	v_pk_add_f32 v[12:13], v[12:13], v[218:219] neg_lo:[0,1] neg_hi:[0,1]
	v_pk_add_f32 v[14:15], v[14:15], v[218:219] neg_lo:[0,1] neg_hi:[0,1]
	v_pk_add_f32 v[16:17], v[16:17], v[218:219] neg_lo:[0,1] neg_hi:[0,1]
	v_pk_add_f32 v[18:19], v[18:19], v[218:219] neg_lo:[0,1] neg_hi:[0,1]
	v_pk_add_f32 v[20:21], v[20:21], v[218:219] neg_lo:[0,1] neg_hi:[0,1]
	v_pk_add_f32 v[22:23], v[22:23], v[218:219] neg_lo:[0,1] neg_hi:[0,1]
	v_pk_add_f32 v[24:25], v[24:25], v[218:219] neg_lo:[0,1] neg_hi:[0,1]
	v_pk_add_f32 v[26:27], v[26:27], v[218:219] neg_lo:[0,1] neg_hi:[0,1]
; __device__ __forceinline__ void attn_phase(const Params& P, char* smem_raw) {
;     ...
; #pragma unroll
;       for (int reg = 0; reg < 4; ++reg) {
;         float mx = sacc[0][reg];
; #pragma unroll
;         for (int t8 = 1; t8 < 8; ++t8) mx = fmaxf(mx, sacc[t8][reg]);
;         mx = row16_max(mx);
;         const float mnew = fmaxf(mrow[reg], mx);
;         const float alpha = __builtin_amdgcn_exp2f(mrow[reg] - mnew);
;         mrow[reg] = mnew;
;         float rsum = 0.f;
; #pragma unroll
;         for (int t8 = 0; t8 < 8; ++t8) {
;           const float p = __builtin_amdgcn_exp2f(sacc[t8][reg] - mnew);
;           rsum += p;
;           sm_p[(wid * 16 + (lane_c >> 4) * 4 + reg) * 136 + t8 * 16 + (lane_c & 15)] = f2bf(p);
;         }
;         rsum = row16_sum(rsum);
;         lrow[reg] = lrow[reg] * alpha + rsum;
; #pragma unroll
;         for (int td = 0; td < 4; ++td) o[td][reg] *= alpha;
;       }
;       asm volatile("s_waitcnt lgkmcnt(0)" ::: "memory");
; #pragma unroll
;       for (int s4 = 0; s4 < 4; ++s4) {
;         const bf16x8 pf = *reinterpret_cast<const bf16x8*>(&sm_p[(wid * 16 + (lane_c & 15)) * 136 + s4 * 32 + (lane_c >> 4) * 8]);
; #pragma unroll
;         for (int td = 0; td < 4; ++td) {
;           const bf16x8 vf = *reinterpret_cast<const bf16x8*>(&sm_vt[(td * 16 + (lane_c & 15)) * 136 + s4 * 32 + (lane_c >> 4) * 8]);
;           o[td] = __builtin_amdgcn_mfma_f32_16x16x32_bf16(pf, vf, o[td], 0, 0, 0);
;         }
;       }
	v_pk_add_f32 v[28:29], v[28:29], v[218:219] neg_lo:[0,1] neg_hi:[0,1]
	v_pk_add_f32 v[30:31], v[30:31], v[218:219] neg_lo:[0,1] neg_hi:[0,1]
	v_exp_f32_e32 v0, v0
	v_exp_f32_e32 v1, v1
	v_exp_f32_e32 v2, v2
	v_exp_f32_e32 v3, v3
	v_exp_f32_e32 v4, v4
	v_exp_f32_e32 v5, v5
	v_exp_f32_e32 v6, v6
	v_exp_f32_e32 v7, v7
	v_exp_f32_e32 v8, v8
	v_exp_f32_e32 v9, v9
	v_exp_f32_e32 v10, v10
	v_exp_f32_e32 v11, v11
	v_exp_f32_e32 v12, v12
	v_exp_f32_e32 v13, v13
	v_exp_f32_e32 v14, v14
	v_exp_f32_e32 v15, v15
	v_exp_f32_e32 v16, v16
	v_exp_f32_e32 v17, v17
	v_exp_f32_e32 v18, v18
	v_exp_f32_e32 v19, v19
	v_exp_f32_e32 v20, v20
	v_exp_f32_e32 v21, v21
	v_exp_f32_e32 v22, v22
	v_exp_f32_e32 v23, v23
	v_exp_f32_e32 v24, v24
	v_exp_f32_e32 v25, v25
	v_exp_f32_e32 v26, v26
	v_exp_f32_e32 v27, v27
	v_exp_f32_e32 v28, v28
	v_exp_f32_e32 v29, v29
	v_exp_f32_e32 v30, v30
	v_exp_f32_e32 v31, v31
	ds_read_b128 v[112:115], v225 offset:0
	ds_read_b128 v[116:119], v225 offset:4096
	ds_read_b128 v[120:123], v225 offset:8192
	ds_read_b128 v[124:127], v225 offset:12288
	ds_read_b128 v[128:131], v226 offset:0
	ds_read_b128 v[132:135], v226 offset:4096
	ds_read_b128 v[136:139], v226 offset:8192
	ds_read_b128 v[140:143], v226 offset:12288
	v_mov_b32_e32 v221, v220
	v_pk_add_f32 v[222:223], v[0:1], v[2:3]
	v_pk_add_f32 v[222:223], v[222:223], v[4:5]
	v_pk_add_f32 v[222:223], v[222:223], v[6:7]
	v_pk_add_f32 v[222:223], v[222:223], v[8:9]
	v_pk_add_f32 v[222:223], v[222:223], v[10:11]
	v_pk_add_f32 v[222:223], v[222:223], v[12:13]
	v_pk_add_f32 v[222:223], v[222:223], v[14:15]
	v_pk_add_f32 v[222:223], v[222:223], v[16:17]
	v_pk_add_f32 v[222:223], v[222:223], v[18:19]
	v_pk_add_f32 v[222:223], v[222:223], v[20:21]
	v_pk_add_f32 v[222:223], v[222:223], v[22:23]
	v_pk_add_f32 v[222:223], v[222:223], v[24:25]
	v_pk_add_f32 v[222:223], v[222:223], v[26:27]
	v_pk_add_f32 v[222:223], v[222:223], v[28:29]
	v_pk_add_f32 v[222:223], v[222:223], v[30:31]
	v_pk_mul_f32 v[176:177], v[176:177], v[220:221]
	v_pk_mul_f32 v[178:179], v[178:179], v[220:221]
	v_pk_mul_f32 v[180:181], v[180:181], v[220:221]
	v_pk_mul_f32 v[182:183], v[182:183], v[220:221]
	v_pk_mul_f32 v[192:193], v[192:193], v[220:221]
	v_pk_mul_f32 v[194:195], v[194:195], v[220:221]
	v_pk_mul_f32 v[196:197], v[196:197], v[220:221]
	v_pk_mul_f32 v[198:199], v[198:199], v[220:221]
	v_add_f32_e32 v203, v222, v223
	v_fma_f32 v247, v247, v220, v203
	v_cvt_pk_bf16_f32 v48, v0, v1
	v_cvt_pk_bf16_f32 v49, v2, v3
	v_cvt_pk_bf16_f32 v50, v4, v5
	v_cvt_pk_bf16_f32 v51, v6, v7
	v_cvt_pk_bf16_f32 v52, v8, v9
	v_cvt_pk_bf16_f32 v53, v10, v11
	v_cvt_pk_bf16_f32 v54, v12, v13
	v_cvt_pk_bf16_f32 v55, v14, v15
	v_cvt_pk_bf16_f32 v56, v16, v17
	v_cvt_pk_bf16_f32 v57, v18, v19
	v_cvt_pk_bf16_f32 v58, v20, v21
	v_cvt_pk_bf16_f32 v59, v22, v23
	v_cvt_pk_bf16_f32 v60, v24, v25
	v_cvt_pk_bf16_f32 v61, v26, v27
	v_cvt_pk_bf16_f32 v62, v28, v29
	v_cvt_pk_bf16_f32 v63, v30, v31
	s_waitcnt lgkmcnt(7)
	v_mfma_f32_16x16x32_bf16 v[176:179], v[112:115], v[48:51], v[176:179]
	ds_read_b128 v[112:115], v227 offset:0
	s_waitcnt lgkmcnt(7)
	v_mfma_f32_16x16x32_bf16 v[180:183], v[116:119], v[48:51], v[180:183]
	ds_read_b128 v[116:119], v227 offset:4096
	s_waitcnt lgkmcnt(7)
	v_mfma_f32_16x16x32_bf16 v[192:195], v[120:123], v[48:51], v[192:195]
	ds_read_b128 v[120:123], v227 offset:8192
	s_waitcnt lgkmcnt(7)
	v_mfma_f32_16x16x32_bf16 v[196:199], v[124:127], v[48:51], v[196:199]
	ds_read_b128 v[124:127], v227 offset:12288
	s_waitcnt lgkmcnt(7)
	v_mfma_f32_16x16x32_bf16 v[176:179], v[128:131], v[52:55], v[176:179]
	ds_read_b128 v[128:131], v228 offset:0
	s_waitcnt lgkmcnt(7)
	v_mfma_f32_16x16x32_bf16 v[180:183], v[132:135], v[52:55], v[180:183]
	ds_read_b128 v[132:135], v228 offset:4096
	s_waitcnt lgkmcnt(7)
	v_mfma_f32_16x16x32_bf16 v[192:195], v[136:139], v[52:55], v[192:195]
	ds_read_b128 v[136:139], v228 offset:8192
	s_waitcnt lgkmcnt(7)
	v_mfma_f32_16x16x32_bf16 v[196:199], v[140:143], v[52:55], v[196:199]
	ds_read_b128 v[140:143], v228 offset:12288
	s_waitcnt lgkmcnt(7)
	v_mfma_f32_16x16x32_bf16 v[176:179], v[112:115], v[56:59], v[176:179]
	s_waitcnt lgkmcnt(6)
	v_mfma_f32_16x16x32_bf16 v[180:183], v[116:119], v[56:59], v[180:183]
	s_waitcnt lgkmcnt(5)
	v_mfma_f32_16x16x32_bf16 v[192:195], v[120:123], v[56:59], v[192:195]
	s_waitcnt lgkmcnt(4)
	v_mfma_f32_16x16x32_bf16 v[196:199], v[124:127], v[56:59], v[196:199]
	s_waitcnt lgkmcnt(3)
	v_mfma_f32_16x16x32_bf16 v[176:179], v[128:131], v[60:63], v[176:179]
	s_waitcnt lgkmcnt(2)
	v_mfma_f32_16x16x32_bf16 v[180:183], v[132:135], v[60:63], v[180:183]
	s_waitcnt lgkmcnt(1)
	v_mfma_f32_16x16x32_bf16 v[192:195], v[136:139], v[60:63], v[192:195]
	s_waitcnt lgkmcnt(0)
	v_mfma_f32_16x16x32_bf16 v[196:199], v[140:143], v[60:63], v[196:199]
	s_waitcnt lgkmcnt(0)
	s_barrier
; __device__ __forceinline__ void attn_phase(const Params& P, char* smem_raw) {
;     ...
;       __syncthreads();
; #pragma unroll
;       for (int i = 0; i < 4; ++i) {
;         const int idx = tid + 256 * i;
;         *reinterpret_cast<uint4*>(&sm_k[(idx >> 3) * LDSS + (idx & 7) * 8]) = kreg[i];
;         *reinterpret_cast<uint4*>(&sm_vt[(idx >> 4) * 136 + (idx & 15) * 8]) = vreg[i];
;       }
;       __syncthreads();
;       f32x4 sacc[8];
; #pragma unroll
;       for (int t8 = 0; t8 < 8; ++t8) sacc[t8] = f32x4{0.f, 0.f, 0.f, 0.f};
; #pragma unroll
;       for (int s = 0; s < 2; ++s)
; #pragma unroll
;         for (int t8 = 0; t8 < 8; ++t8) {
;           const bf16x8 kf = *reinterpret_cast<const bf16x8*>(&sm_k[(t8 * 16 + (lane_c & 15)) * LDSS + s * 32 + (lane_c >> 4) * 8]);
;           sacc[t8] = __builtin_amdgcn_mfma_f32_16x16x32_bf16(qf[s], kf, sacc[t8], 0, 0, 0);
;         }
;       if (ck < 5) {
;         ATT_ISSUE(t, ck + 1)
;       } else if (t + VGRID < 8192) {
;         ATT_ISSUE(t + VGRID, 0)
;         ATT_QLOAD(t + VGRID)
;       }
;       if (ck < 4) {
;         const float* rb0 = sm_rpb + (rs + ck * 2 - r + 7) * 31;
; #pragma unroll
;         for (int t8 = 0; t8 < 8; ++t8)
; #pragma unroll
;           for (int reg = 0; reg < 4; ++reg)
;             sacc[t8][reg] += rb0[(t8 >> 2) * 31 + dco[reg][t8 & 3]];
;       }
; #pragma unroll
;       for (int reg = 0; reg < 4; ++reg) {
;         float mx = sacc[0][reg];
; #pragma unroll
;         for (int t8 = 1; t8 < 8; ++t8) mx = fmaxf(mx, sacc[t8][reg]);
;         mx = row16_max(mx);
;         const float mnew = fmaxf(mrow[reg], mx);
;         const float alpha = __builtin_amdgcn_exp2f(mrow[reg] - mnew);
;         mrow[reg] = mnew;
;         float rsum = 0.f;
; #pragma unroll
;         for (int t8 = 0; t8 < 8; ++t8) {
;           const float p = __builtin_amdgcn_exp2f(sacc[t8][reg] - mnew);
;           rsum += p;
;           sm_p[(wid * 16 + (lane_c >> 4) * 4 + reg) * 136 + t8 * 16 + (lane_c & 15)] = f2bf(p);
;         }
;         rsum = row16_sum(rsum);
;         lrow[reg] = lrow[reg] * alpha + rsum;
; #pragma unroll
;         for (int td = 0; td < 4; ++td) o[td][reg] *= alpha;
;       }
	ds_read_b128 v[112:115], v149 offset:32768
	ds_read_b128 v[116:119], v224 offset:32768
	ds_read_b128 v[120:123], v149 offset:40960
	ds_read_b128 v[124:127], v224 offset:40960
	ds_read_b128 v[128:131], v149 offset:34816
	ds_read_b128 v[132:135], v224 offset:34816
	ds_read_b128 v[136:139], v149 offset:43008
	ds_read_b128 v[140:143], v224 offset:43008
	s_waitcnt lgkmcnt(7)
	v_mfma_f32_16x16x32_bf16 v[0:3], v[112:115], v[64:67], 0
	ds_read_b128 v[112:115], v149 offset:36864
	s_waitcnt lgkmcnt(7)
	v_mfma_f32_16x16x32_bf16 v[0:3], v[116:119], v[68:71], v[0:3]
	ds_read_b128 v[116:119], v224 offset:36864
	s_waitcnt lgkmcnt(7)
	v_mfma_f32_16x16x32_bf16 v[4:7], v[120:123], v[64:67], 0
	ds_read_b128 v[120:123], v149 offset:45056
	s_waitcnt lgkmcnt(7)
	v_mfma_f32_16x16x32_bf16 v[4:7], v[124:127], v[68:71], v[4:7]
	ds_read_b128 v[124:127], v224 offset:45056
	s_waitcnt lgkmcnt(7)
	v_mfma_f32_16x16x32_bf16 v[8:11], v[128:131], v[64:67], 0
	ds_read_b128 v[128:131], v149 offset:38912
	s_waitcnt lgkmcnt(7)
	v_mfma_f32_16x16x32_bf16 v[8:11], v[132:135], v[68:71], v[8:11]
	ds_read_b128 v[132:135], v224 offset:38912
	s_waitcnt lgkmcnt(7)
	v_mfma_f32_16x16x32_bf16 v[12:15], v[136:139], v[64:67], 0
	ds_read_b128 v[136:139], v149 offset:47104
	s_waitcnt lgkmcnt(7)
	v_mfma_f32_16x16x32_bf16 v[12:15], v[140:143], v[68:71], v[12:15]
	ds_read_b128 v[140:143], v224 offset:47104
	s_waitcnt lgkmcnt(7)
	v_mfma_f32_16x16x32_bf16 v[16:19], v[112:115], v[64:67], 0
	s_waitcnt lgkmcnt(6)
	v_mfma_f32_16x16x32_bf16 v[16:19], v[116:119], v[68:71], v[16:19]
	s_waitcnt lgkmcnt(5)
	v_mfma_f32_16x16x32_bf16 v[20:23], v[120:123], v[64:67], 0
	s_waitcnt lgkmcnt(4)
	v_mfma_f32_16x16x32_bf16 v[20:23], v[124:127], v[68:71], v[20:23]
	s_waitcnt lgkmcnt(3)
	v_mfma_f32_16x16x32_bf16 v[24:27], v[128:131], v[64:67], 0
	s_waitcnt lgkmcnt(2)
	v_mfma_f32_16x16x32_bf16 v[24:27], v[132:135], v[68:71], v[24:27]
	s_waitcnt lgkmcnt(1)
	v_mfma_f32_16x16x32_bf16 v[28:31], v[136:139], v[64:67], 0
	s_waitcnt lgkmcnt(0)
	v_mfma_f32_16x16x32_bf16 v[28:31], v[140:143], v[68:71], v[28:31]
	s_nop 7
	v_max3_f32 v203, v0, v1, v2
	v_max3_f32 v203, v203, v3, v4
	v_max3_f32 v203, v203, v5, v6
	v_max3_f32 v203, v203, v7, v8
	v_max3_f32 v203, v203, v9, v10
	v_max3_f32 v203, v203, v11, v12
	v_max3_f32 v203, v203, v13, v14
	v_max3_f32 v203, v203, v15, v16
	v_max3_f32 v203, v203, v17, v18
	v_max3_f32 v203, v203, v19, v20
	v_max3_f32 v203, v203, v21, v22
	v_max3_f32 v203, v203, v23, v24
	v_max3_f32 v203, v203, v25, v26
	v_max3_f32 v203, v203, v27, v28
	v_max3_f32 v203, v203, v29, v30
	v_max_f32_e32 v203, v203, v31
	v_mov_b32_e32 v205, v203
	s_nop 1
	v_permlane16_swap_b32_e32 v203, v205
	v_max_f32_e32 v203, v203, v205
	v_mov_b32_e32 v205, v203
	s_nop 1
	v_permlane32_swap_b32_e32 v203, v205
	v_max_f32_e32 v203, v203, v205
	v_max_f32_e32 v218, v200, v203
	v_sub_f32_e32 v220, v200, v218
	v_mov_b32_e32 v219, v218
	v_exp_f32_e32 v220, v220
	v_mov_b32_e32 v200, v218
	v_pk_add_f32 v[0:1], v[0:1], v[218:219] neg_lo:[0,1] neg_hi:[0,1]
	v_pk_add_f32 v[2:3], v[2:3], v[218:219] neg_lo:[0,1] neg_hi:[0,1]
	v_pk_add_f32 v[4:5], v[4:5], v[218:219] neg_lo:[0,1] neg_hi:[0,1]
	v_pk_add_f32 v[6:7], v[6:7], v[218:219] neg_lo:[0,1] neg_hi:[0,1]
	v_pk_add_f32 v[8:9], v[8:9], v[218:219] neg_lo:[0,1] neg_hi:[0,1]
	v_pk_add_f32 v[10:11], v[10:11], v[218:219] neg_lo:[0,1] neg_hi:[0,1]
	v_pk_add_f32 v[12:13], v[12:13], v[218:219] neg_lo:[0,1] neg_hi:[0,1]
	v_pk_add_f32 v[14:15], v[14:15], v[218:219] neg_lo:[0,1] neg_hi:[0,1]
	v_pk_add_f32 v[16:17], v[16:17], v[218:219] neg_lo:[0,1] neg_hi:[0,1]
	v_pk_add_f32 v[18:19], v[18:19], v[218:219] neg_lo:[0,1] neg_hi:[0,1]
	v_pk_add_f32 v[20:21], v[20:21], v[218:219] neg_lo:[0,1] neg_hi:[0,1]
	v_pk_add_f32 v[22:23], v[22:23], v[218:219] neg_lo:[0,1] neg_hi:[0,1]
	v_pk_add_f32 v[24:25], v[24:25], v[218:219] neg_lo:[0,1] neg_hi:[0,1]
	v_pk_add_f32 v[26:27], v[26:27], v[218:219] neg_lo:[0,1] neg_hi:[0,1]
	v_pk_add_f32 v[28:29], v[28:29], v[218:219] neg_lo:[0,1] neg_hi:[0,1]
	v_pk_add_f32 v[30:31], v[30:31], v[218:219] neg_lo:[0,1] neg_hi:[0,1]
	v_exp_f32_e32 v0, v0
	s_waitcnt vmcnt(0)
	v_exp_f32_e32 v1, v1
	ds_write_b128 v150, v[80:83] offset:0
	v_exp_f32_e32 v2, v2
	ds_write_b128 v150, v[84:87] offset:4096
	v_exp_f32_e32 v3, v3
	ds_write_b128 v150, v[88:91] offset:8192
	v_exp_f32_e32 v4, v4
	ds_write_b128 v150, v[92:95] offset:12288
	v_exp_f32_e32 v5, v5
	ds_write_b64 v151, v[96:97] offset:0
	v_exp_f32_e32 v6, v6
	ds_write_b64 v229, v[98:99] offset:0
	v_exp_f32_e32 v7, v7
	ds_write_b64 v151, v[100:101] offset:4096
	v_exp_f32_e32 v8, v8
	ds_write_b64 v229, v[102:103] offset:4096
	v_exp_f32_e32 v9, v9
	ds_write_b64 v151, v[104:105] offset:8192
	v_exp_f32_e32 v10, v10
	ds_write_b64 v229, v[106:107] offset:8192
	v_exp_f32_e32 v11, v11
	ds_write_b64 v151, v[108:109] offset:12288
	v_exp_f32_e32 v12, v12
	ds_write_b64 v229, v[110:111] offset:12288
	v_exp_f32_e32 v13, v13
	s_add_u32 s100, s12, 0xc0000
	v_exp_f32_e32 v14, v14
	s_addc_u32 s101, s13, 0
	v_exp_f32_e32 v15, v15
	s_add_u32 s0, s14, 0x100
	v_exp_f32_e32 v16, v16
	s_addc_u32 s1, s15, 0
	v_exp_f32_e32 v17, v17
	global_load_dwordx4 v[80:83], v154, s[100:101] offset:2048
	v_exp_f32_e32 v18, v18
	global_load_dwordx4 v[96:99], v158, s[0:1]
	v_exp_f32_e32 v19, v19
	global_load_dwordx4 v[84:87], v155, s[100:101] offset:2048
	v_exp_f32_e32 v20, v20
	global_load_dwordx4 v[100:103], v159, s[0:1]
	v_exp_f32_e32 v21, v21
	global_load_dwordx4 v[88:91], v156, s[100:101] offset:2048
	v_exp_f32_e32 v22, v22
	global_load_dwordx4 v[104:107], v160, s[0:1]
	v_exp_f32_e32 v23, v23
	global_load_dwordx4 v[92:95], v157, s[100:101] offset:2048
	v_exp_f32_e32 v24, v24
; __device__ __forceinline__ void attn_phase(const Params& P, char* smem_raw) {
;     ...
; #pragma unroll
;       for (int s = 0; s < 2; ++s)
; #pragma unroll
;         for (int t8 = 0; t8 < 8; ++t8) {
;           const bf16x8 kf = *reinterpret_cast<const bf16x8*>(&sm_k[(t8 * 16 + (lane_c & 15)) * LDSS + s * 32 + (lane_c >> 4) * 8]);
;           sacc[t8] = __builtin_amdgcn_mfma_f32_16x16x32_bf16(qf[s], kf, sacc[t8], 0, 0, 0);
;         }
;     ...
;         float rsum = 0.f;
; #pragma unroll
;         for (int t8 = 0; t8 < 8; ++t8) {
;           const float p = __builtin_amdgcn_exp2f(sacc[t8][reg] - mnew);
;           rsum += p;
;           sm_p[(wid * 16 + (lane_c >> 4) * 4 + reg) * 136 + t8 * 16 + (lane_c & 15)] = f2bf(p);
;         }
;         rsum = row16_sum(rsum);
;         lrow[reg] = lrow[reg] * alpha + rsum;
; #pragma unroll
;         for (int td = 0; td < 4; ++td) o[td][reg] *= alpha;
;       }
;       asm volatile("s_waitcnt lgkmcnt(0)" ::: "memory");
; #pragma unroll
;       for (int s4 = 0; s4 < 4; ++s4) {
;         const bf16x8 pf = *reinterpret_cast<const bf16x8*>(&sm_p[(wid * 16 + (lane_c & 15)) * 136 + s4 * 32 + (lane_c >> 4) * 8]);
; #pragma unroll
;         for (int td = 0; td < 4; ++td) {
;           const bf16x8 vf = *reinterpret_cast<const bf16x8*>(&sm_vt[(td * 16 + (lane_c & 15)) * 136 + s4 * 32 + (lane_c >> 4) * 8]);
;           o[td] = __builtin_amdgcn_mfma_f32_16x16x32_bf16(pf, vf, o[td], 0, 0, 0);
;         }
;       }
	global_load_dwordx4 v[108:111], v161, s[0:1]
	v_exp_f32_e32 v25, v25
	v_exp_f32_e32 v26, v26
	v_exp_f32_e32 v27, v27
	v_exp_f32_e32 v28, v28
	v_exp_f32_e32 v29, v29
	v_exp_f32_e32 v30, v30
	v_exp_f32_e32 v31, v31
	ds_read_b128 v[112:115], v225 offset:32768
	ds_read_b128 v[116:119], v225 offset:36864
	ds_read_b128 v[120:123], v225 offset:40960
	ds_read_b128 v[124:127], v225 offset:45056
	ds_read_b128 v[128:131], v226 offset:32768
	ds_read_b128 v[132:135], v226 offset:36864
	ds_read_b128 v[136:139], v226 offset:40960
	ds_read_b128 v[140:143], v226 offset:45056
	v_mov_b32_e32 v221, v220
	v_pk_add_f32 v[222:223], v[0:1], v[2:3]
	v_pk_add_f32 v[222:223], v[222:223], v[4:5]
	v_pk_add_f32 v[222:223], v[222:223], v[6:7]
	v_pk_add_f32 v[222:223], v[222:223], v[8:9]
	v_pk_add_f32 v[222:223], v[222:223], v[10:11]
	v_pk_add_f32 v[222:223], v[222:223], v[12:13]
	v_pk_add_f32 v[222:223], v[222:223], v[14:15]
	v_pk_add_f32 v[222:223], v[222:223], v[16:17]
	v_pk_add_f32 v[222:223], v[222:223], v[18:19]
	v_pk_add_f32 v[222:223], v[222:223], v[20:21]
	v_pk_add_f32 v[222:223], v[222:223], v[22:23]
	v_pk_add_f32 v[222:223], v[222:223], v[24:25]
	v_pk_add_f32 v[222:223], v[222:223], v[26:27]
	v_pk_add_f32 v[222:223], v[222:223], v[28:29]
	v_pk_add_f32 v[222:223], v[222:223], v[30:31]
	v_pk_mul_f32 v[32:33], v[32:33], v[220:221]
	v_pk_mul_f32 v[34:35], v[34:35], v[220:221]
	v_pk_mul_f32 v[36:37], v[36:37], v[220:221]
	v_pk_mul_f32 v[38:39], v[38:39], v[220:221]
	v_pk_mul_f32 v[40:41], v[40:41], v[220:221]
	v_pk_mul_f32 v[42:43], v[42:43], v[220:221]
	v_pk_mul_f32 v[44:45], v[44:45], v[220:221]
	v_pk_mul_f32 v[46:47], v[46:47], v[220:221]
	v_add_f32_e32 v203, v222, v223
	v_fma_f32 v201, v201, v220, v203
	v_cvt_pk_bf16_f32 v48, v0, v1
	v_cvt_pk_bf16_f32 v49, v2, v3
	v_cvt_pk_bf16_f32 v50, v4, v5
	v_cvt_pk_bf16_f32 v51, v6, v7
	v_cvt_pk_bf16_f32 v52, v8, v9
	v_cvt_pk_bf16_f32 v53, v10, v11
	v_cvt_pk_bf16_f32 v54, v12, v13
	v_cvt_pk_bf16_f32 v55, v14, v15
	v_cvt_pk_bf16_f32 v56, v16, v17
	v_cvt_pk_bf16_f32 v57, v18, v19
	v_cvt_pk_bf16_f32 v58, v20, v21
	v_cvt_pk_bf16_f32 v59, v22, v23
	v_cvt_pk_bf16_f32 v60, v24, v25
	v_cvt_pk_bf16_f32 v61, v26, v27
	v_cvt_pk_bf16_f32 v62, v28, v29
	v_cvt_pk_bf16_f32 v63, v30, v31
	s_waitcnt lgkmcnt(7)
	v_mfma_f32_16x16x32_bf16 v[32:35], v[112:115], v[48:51], v[32:35]
	ds_read_b128 v[112:115], v227 offset:32768
	s_waitcnt lgkmcnt(7)
	v_mfma_f32_16x16x32_bf16 v[36:39], v[116:119], v[48:51], v[36:39]
	ds_read_b128 v[116:119], v227 offset:36864
	s_waitcnt lgkmcnt(7)
	v_mfma_f32_16x16x32_bf16 v[40:43], v[120:123], v[48:51], v[40:43]
	ds_read_b128 v[120:123], v227 offset:40960
	s_waitcnt lgkmcnt(7)
	v_mfma_f32_16x16x32_bf16 v[44:47], v[124:127], v[48:51], v[44:47]
	ds_read_b128 v[124:127], v227 offset:45056
	s_waitcnt lgkmcnt(7)
	v_mfma_f32_16x16x32_bf16 v[32:35], v[128:131], v[52:55], v[32:35]
	ds_read_b128 v[128:131], v228 offset:32768
	s_waitcnt lgkmcnt(7)
	v_mfma_f32_16x16x32_bf16 v[36:39], v[132:135], v[52:55], v[36:39]
	ds_read_b128 v[132:135], v228 offset:36864
	s_waitcnt lgkmcnt(7)
	v_mfma_f32_16x16x32_bf16 v[40:43], v[136:139], v[52:55], v[40:43]
	ds_read_b128 v[136:139], v228 offset:40960
	s_waitcnt lgkmcnt(7)
	v_mfma_f32_16x16x32_bf16 v[44:47], v[140:143], v[52:55], v[44:47]
	ds_read_b128 v[140:143], v228 offset:45056
	s_waitcnt lgkmcnt(7)
	v_mfma_f32_16x16x32_bf16 v[32:35], v[112:115], v[56:59], v[32:35]
	s_waitcnt lgkmcnt(6)
	v_mfma_f32_16x16x32_bf16 v[36:39], v[116:119], v[56:59], v[36:39]
	s_waitcnt lgkmcnt(5)
	v_mfma_f32_16x16x32_bf16 v[40:43], v[120:123], v[56:59], v[40:43]
	s_waitcnt lgkmcnt(4)
	v_mfma_f32_16x16x32_bf16 v[44:47], v[124:127], v[56:59], v[44:47]
	s_waitcnt lgkmcnt(3)
	v_mfma_f32_16x16x32_bf16 v[32:35], v[128:131], v[60:63], v[32:35]
	s_waitcnt lgkmcnt(2)
	v_mfma_f32_16x16x32_bf16 v[36:39], v[132:135], v[60:63], v[36:39]
	s_waitcnt lgkmcnt(1)
	v_mfma_f32_16x16x32_bf16 v[40:43], v[136:139], v[60:63], v[40:43]
	s_waitcnt lgkmcnt(0)
	v_mfma_f32_16x16x32_bf16 v[44:47], v[140:143], v[60:63], v[44:47]
	ds_read_b128 v[112:115], v149 offset:32768
	ds_read_b128 v[116:119], v224 offset:32768
	ds_read_b128 v[120:123], v149 offset:40960
	ds_read_b128 v[124:127], v224 offset:40960
	ds_read_b128 v[128:131], v149 offset:34816
	ds_read_b128 v[132:135], v224 offset:34816
	ds_read_b128 v[136:139], v149 offset:43008
	ds_read_b128 v[140:143], v224 offset:43008
	s_waitcnt lgkmcnt(7)
	v_mfma_f32_16x16x32_bf16 v[0:3], v[112:115], v[230:233], 0
	ds_read_b128 v[112:115], v149 offset:36864
	s_waitcnt lgkmcnt(7)
	v_mfma_f32_16x16x32_bf16 v[0:3], v[116:119], v[234:237], v[0:3]
	ds_read_b128 v[116:119], v224 offset:36864
	s_waitcnt lgkmcnt(7)
	v_mfma_f32_16x16x32_bf16 v[4:7], v[120:123], v[230:233], 0
	ds_read_b128 v[120:123], v149 offset:45056
	s_waitcnt lgkmcnt(7)
	v_mfma_f32_16x16x32_bf16 v[4:7], v[124:127], v[234:237], v[4:7]
	ds_read_b128 v[124:127], v224 offset:45056
	s_waitcnt lgkmcnt(7)
	v_mfma_f32_16x16x32_bf16 v[8:11], v[128:131], v[230:233], 0
	ds_read_b128 v[128:131], v149 offset:38912
	s_waitcnt lgkmcnt(7)
	v_mfma_f32_16x16x32_bf16 v[8:11], v[132:135], v[234:237], v[8:11]
	ds_read_b128 v[132:135], v224 offset:38912
	s_waitcnt lgkmcnt(7)
	v_mfma_f32_16x16x32_bf16 v[12:15], v[136:139], v[230:233], 0
	ds_read_b128 v[136:139], v149 offset:47104
	s_waitcnt lgkmcnt(7)
	v_mfma_f32_16x16x32_bf16 v[12:15], v[140:143], v[234:237], v[12:15]
	ds_read_b128 v[140:143], v224 offset:47104
	s_waitcnt lgkmcnt(7)
	v_mfma_f32_16x16x32_bf16 v[16:19], v[112:115], v[230:233], 0
	s_waitcnt lgkmcnt(6)
	v_mfma_f32_16x16x32_bf16 v[16:19], v[116:119], v[234:237], v[16:19]
	s_waitcnt lgkmcnt(5)
	v_mfma_f32_16x16x32_bf16 v[20:23], v[120:123], v[230:233], 0
	s_waitcnt lgkmcnt(4)
; __device__ __forceinline__ void attn_phase(const Params& P, char* smem_raw) {
;     ...
; #pragma unroll
;       for (int reg = 0; reg < 4; ++reg) {
;         float mx = sacc[0][reg];
; #pragma unroll
;         for (int t8 = 1; t8 < 8; ++t8) mx = fmaxf(mx, sacc[t8][reg]);
;         mx = row16_max(mx);
;         const float mnew = fmaxf(mrow[reg], mx);
;         const float alpha = __builtin_amdgcn_exp2f(mrow[reg] - mnew);
;         mrow[reg] = mnew;
;         float rsum = 0.f;
; #pragma unroll
;         for (int t8 = 0; t8 < 8; ++t8) {
;           const float p = __builtin_amdgcn_exp2f(sacc[t8][reg] - mnew);
;           rsum += p;
;           sm_p[(wid * 16 + (lane_c >> 4) * 4 + reg) * 136 + t8 * 16 + (lane_c & 15)] = f2bf(p);
;         }
;         rsum = row16_sum(rsum);
;         lrow[reg] = lrow[reg] * alpha + rsum;
; #pragma unroll
;         for (int td = 0; td < 4; ++td) o[td][reg] *= alpha;
;       }
;       asm volatile("s_waitcnt lgkmcnt(0)" ::: "memory");
; #pragma unroll
;       for (int s4 = 0; s4 < 4; ++s4) {
;         const bf16x8 pf = *reinterpret_cast<const bf16x8*>(&sm_p[(wid * 16 + (lane_c & 15)) * 136 + s4 * 32 + (lane_c >> 4) * 8]);
; #pragma unroll
;         for (int td = 0; td < 4; ++td) {
;           const bf16x8 vf = *reinterpret_cast<const bf16x8*>(&sm_vt[(td * 16 + (lane_c & 15)) * 136 + s4 * 32 + (lane_c >> 4) * 8]);
;           o[td] = __builtin_amdgcn_mfma_f32_16x16x32_bf16(pf, vf, o[td], 0, 0, 0);
;         }
;       }
	v_mfma_f32_16x16x32_bf16 v[20:23], v[124:127], v[234:237], v[20:23]
	s_waitcnt lgkmcnt(3)
	v_mfma_f32_16x16x32_bf16 v[24:27], v[128:131], v[230:233], 0
	s_waitcnt lgkmcnt(2)
	v_mfma_f32_16x16x32_bf16 v[24:27], v[132:135], v[234:237], v[24:27]
	s_waitcnt lgkmcnt(1)
	v_mfma_f32_16x16x32_bf16 v[28:31], v[136:139], v[230:233], 0
	s_waitcnt lgkmcnt(0)
	v_mfma_f32_16x16x32_bf16 v[28:31], v[140:143], v[234:237], v[28:31]
	s_nop 7
	v_max3_f32 v203, v0, v1, v2
	v_max3_f32 v203, v203, v3, v4
	v_max3_f32 v203, v203, v5, v6
	v_max3_f32 v203, v203, v7, v8
	v_max3_f32 v203, v203, v9, v10
	v_max3_f32 v203, v203, v11, v12
	v_max3_f32 v203, v203, v13, v14
	v_max3_f32 v203, v203, v15, v16
	v_max3_f32 v203, v203, v17, v18
	v_max3_f32 v203, v203, v19, v20
	v_max3_f32 v203, v203, v21, v22
	v_max3_f32 v203, v203, v23, v24
	v_max3_f32 v203, v203, v25, v26
	v_max3_f32 v203, v203, v27, v28
	v_max3_f32 v203, v203, v29, v30
	v_max_f32_e32 v203, v203, v31
	v_mov_b32_e32 v205, v203
	s_nop 1
	v_permlane16_swap_b32_e32 v203, v205
	v_max_f32_e32 v203, v203, v205
	v_mov_b32_e32 v205, v203
	s_nop 1
	v_permlane32_swap_b32_e32 v203, v205
	v_max_f32_e32 v203, v203, v205
	v_max_f32_e32 v218, v246, v203
	v_sub_f32_e32 v220, v246, v218
	v_mov_b32_e32 v219, v218
	v_exp_f32_e32 v220, v220
	v_mov_b32_e32 v246, v218
	v_pk_add_f32 v[0:1], v[0:1], v[218:219] neg_lo:[0,1] neg_hi:[0,1]
	v_pk_add_f32 v[2:3], v[2:3], v[218:219] neg_lo:[0,1] neg_hi:[0,1]
	v_pk_add_f32 v[4:5], v[4:5], v[218:219] neg_lo:[0,1] neg_hi:[0,1]
	v_pk_add_f32 v[6:7], v[6:7], v[218:219] neg_lo:[0,1] neg_hi:[0,1]
	v_pk_add_f32 v[8:9], v[8:9], v[218:219] neg_lo:[0,1] neg_hi:[0,1]
	v_pk_add_f32 v[10:11], v[10:11], v[218:219] neg_lo:[0,1] neg_hi:[0,1]
	v_pk_add_f32 v[12:13], v[12:13], v[218:219] neg_lo:[0,1] neg_hi:[0,1]
	v_pk_add_f32 v[14:15], v[14:15], v[218:219] neg_lo:[0,1] neg_hi:[0,1]
	v_pk_add_f32 v[16:17], v[16:17], v[218:219] neg_lo:[0,1] neg_hi:[0,1]
	v_pk_add_f32 v[18:19], v[18:19], v[218:219] neg_lo:[0,1] neg_hi:[0,1]
	v_pk_add_f32 v[20:21], v[20:21], v[218:219] neg_lo:[0,1] neg_hi:[0,1]
	v_pk_add_f32 v[22:23], v[22:23], v[218:219] neg_lo:[0,1] neg_hi:[0,1]
	v_pk_add_f32 v[24:25], v[24:25], v[218:219] neg_lo:[0,1] neg_hi:[0,1]
	v_pk_add_f32 v[26:27], v[26:27], v[218:219] neg_lo:[0,1] neg_hi:[0,1]
	v_pk_add_f32 v[28:29], v[28:29], v[218:219] neg_lo:[0,1] neg_hi:[0,1]
	v_pk_add_f32 v[30:31], v[30:31], v[218:219] neg_lo:[0,1] neg_hi:[0,1]
	v_exp_f32_e32 v0, v0
	v_exp_f32_e32 v1, v1
	v_exp_f32_e32 v2, v2
	v_exp_f32_e32 v3, v3
	v_exp_f32_e32 v4, v4
	v_exp_f32_e32 v5, v5
	v_exp_f32_e32 v6, v6
	v_exp_f32_e32 v7, v7
	v_exp_f32_e32 v8, v8
	v_exp_f32_e32 v9, v9
	v_exp_f32_e32 v10, v10
	v_exp_f32_e32 v11, v11
	v_exp_f32_e32 v12, v12
	v_exp_f32_e32 v13, v13
	v_exp_f32_e32 v14, v14
	v_exp_f32_e32 v15, v15
	v_exp_f32_e32 v16, v16
	v_exp_f32_e32 v17, v17
	v_exp_f32_e32 v18, v18
	v_exp_f32_e32 v19, v19
	v_exp_f32_e32 v20, v20
	v_exp_f32_e32 v21, v21
	v_exp_f32_e32 v22, v22
	v_exp_f32_e32 v23, v23
	v_exp_f32_e32 v24, v24
	v_exp_f32_e32 v25, v25
	v_exp_f32_e32 v26, v26
	v_exp_f32_e32 v27, v27
	v_exp_f32_e32 v28, v28
	v_exp_f32_e32 v29, v29
	v_exp_f32_e32 v30, v30
	v_exp_f32_e32 v31, v31
	ds_read_b128 v[112:115], v225 offset:32768
	ds_read_b128 v[116:119], v225 offset:36864
	ds_read_b128 v[120:123], v225 offset:40960
	ds_read_b128 v[124:127], v225 offset:45056
	ds_read_b128 v[128:131], v226 offset:32768
	ds_read_b128 v[132:135], v226 offset:36864
	ds_read_b128 v[136:139], v226 offset:40960
	ds_read_b128 v[140:143], v226 offset:45056
	v_mov_b32_e32 v221, v220
	v_pk_add_f32 v[222:223], v[0:1], v[2:3]
	v_pk_add_f32 v[222:223], v[222:223], v[4:5]
	v_pk_add_f32 v[222:223], v[222:223], v[6:7]
	v_pk_add_f32 v[222:223], v[222:223], v[8:9]
	v_pk_add_f32 v[222:223], v[222:223], v[10:11]
	v_pk_add_f32 v[222:223], v[222:223], v[12:13]
	v_pk_add_f32 v[222:223], v[222:223], v[14:15]
	v_pk_add_f32 v[222:223], v[222:223], v[16:17]
	v_pk_add_f32 v[222:223], v[222:223], v[18:19]
	v_pk_add_f32 v[222:223], v[222:223], v[20:21]
	v_pk_add_f32 v[222:223], v[222:223], v[22:23]
	v_pk_add_f32 v[222:223], v[222:223], v[24:25]
	v_pk_add_f32 v[222:223], v[222:223], v[26:27]
	v_pk_add_f32 v[222:223], v[222:223], v[28:29]
	v_pk_add_f32 v[222:223], v[222:223], v[30:31]
	v_pk_mul_f32 v[176:177], v[176:177], v[220:221]
	v_pk_mul_f32 v[178:179], v[178:179], v[220:221]
	v_pk_mul_f32 v[180:181], v[180:181], v[220:221]
	v_pk_mul_f32 v[182:183], v[182:183], v[220:221]
	v_pk_mul_f32 v[192:193], v[192:193], v[220:221]
	v_pk_mul_f32 v[194:195], v[194:195], v[220:221]
	v_pk_mul_f32 v[196:197], v[196:197], v[220:221]
	v_pk_mul_f32 v[198:199], v[198:199], v[220:221]
	v_add_f32_e32 v203, v222, v223
	v_fma_f32 v247, v247, v220, v203
	v_cvt_pk_bf16_f32 v48, v0, v1
	v_cvt_pk_bf16_f32 v49, v2, v3
	v_cvt_pk_bf16_f32 v50, v4, v5
	v_cvt_pk_bf16_f32 v51, v6, v7
	v_cvt_pk_bf16_f32 v52, v8, v9
	v_cvt_pk_bf16_f32 v53, v10, v11
	v_cvt_pk_bf16_f32 v54, v12, v13
	v_cvt_pk_bf16_f32 v55, v14, v15
	v_cvt_pk_bf16_f32 v56, v16, v17
	v_cvt_pk_bf16_f32 v57, v18, v19
	v_cvt_pk_bf16_f32 v58, v20, v21
	v_cvt_pk_bf16_f32 v59, v22, v23
	v_cvt_pk_bf16_f32 v60, v24, v25
	v_cvt_pk_bf16_f32 v61, v26, v27
	v_cvt_pk_bf16_f32 v62, v28, v29
	v_cvt_pk_bf16_f32 v63, v30, v31
	s_waitcnt lgkmcnt(7)
	v_mfma_f32_16x16x32_bf16 v[176:179], v[112:115], v[48:51], v[176:179]
	ds_read_b128 v[112:115], v227 offset:32768
	s_waitcnt lgkmcnt(7)
	v_mfma_f32_16x16x32_bf16 v[180:183], v[116:119], v[48:51], v[180:183]
	ds_read_b128 v[116:119], v227 offset:36864
	s_waitcnt lgkmcnt(7)
	v_mfma_f32_16x16x32_bf16 v[192:195], v[120:123], v[48:51], v[192:195]
	ds_read_b128 v[120:123], v227 offset:40960
	s_waitcnt lgkmcnt(7)
; __device__ __forceinline__ void attn_phase(const Params& P, char* smem_raw) {
;     ...
; #pragma unroll
;         for (int td = 0; td < 4; ++td) {
;           const bf16x8 vf = *reinterpret_cast<const bf16x8*>(&sm_vt[(td * 16 + (lane_c & 15)) * 136 + s4 * 32 + (lane_c >> 4) * 8]);
;           o[td] = __builtin_amdgcn_mfma_f32_16x16x32_bf16(pf, vf, o[td], 0, 0, 0);
;         }
;       }
;     }
;     u16* Ob = P.cat + ((long)b * 8192 + r * 64) * 1024 + h * 64;
; #pragma unroll
;     for (int td = 0; td < 4; ++td)
; #pragma unroll
;       for (int reg = 0; reg < 4; ++reg) {
;         const int rowl = wid * 16 + (lane >> 4) * 4 + reg;
;         Ob[(unsigned)(rowl * 1024 + td * 16 + (lane & 15))] = f2bf(o[td][reg] * __builtin_amdgcn_rcpf(lrow[reg]));
;       }
;   }
	v_mfma_f32_16x16x32_bf16 v[196:199], v[124:127], v[48:51], v[196:199]
	ds_read_b128 v[124:127], v227 offset:45056
	s_waitcnt lgkmcnt(7)
	v_mfma_f32_16x16x32_bf16 v[176:179], v[128:131], v[52:55], v[176:179]
	ds_read_b128 v[128:131], v228 offset:32768
	s_waitcnt lgkmcnt(7)
	v_mfma_f32_16x16x32_bf16 v[180:183], v[132:135], v[52:55], v[180:183]
	ds_read_b128 v[132:135], v228 offset:36864
	s_waitcnt lgkmcnt(7)
	v_mfma_f32_16x16x32_bf16 v[192:195], v[136:139], v[52:55], v[192:195]
	ds_read_b128 v[136:139], v228 offset:40960
	s_waitcnt lgkmcnt(7)
	v_mfma_f32_16x16x32_bf16 v[196:199], v[140:143], v[52:55], v[196:199]
	ds_read_b128 v[140:143], v228 offset:45056
	s_waitcnt lgkmcnt(7)
	v_mfma_f32_16x16x32_bf16 v[176:179], v[112:115], v[56:59], v[176:179]
	s_waitcnt lgkmcnt(6)
	v_mfma_f32_16x16x32_bf16 v[180:183], v[116:119], v[56:59], v[180:183]
	s_waitcnt lgkmcnt(5)
	v_mfma_f32_16x16x32_bf16 v[192:195], v[120:123], v[56:59], v[192:195]
	s_waitcnt lgkmcnt(4)
	v_mfma_f32_16x16x32_bf16 v[196:199], v[124:127], v[56:59], v[196:199]
	s_waitcnt lgkmcnt(3)
	v_mfma_f32_16x16x32_bf16 v[176:179], v[128:131], v[60:63], v[176:179]
	s_waitcnt lgkmcnt(2)
	v_mfma_f32_16x16x32_bf16 v[180:183], v[132:135], v[60:63], v[180:183]
	s_waitcnt lgkmcnt(1)
	v_mfma_f32_16x16x32_bf16 v[192:195], v[136:139], v[60:63], v[192:195]
	s_waitcnt lgkmcnt(0)
	v_mfma_f32_16x16x32_bf16 v[196:199], v[140:143], v[60:63], v[196:199]
	ds_read_b32 v0, v184 offset:384
	ds_read_b32 v1, v185 offset:384
	ds_read_b32 v2, v186 offset:384
	ds_read_b32 v3, v187 offset:384
	ds_read_b32 v4, v184 offset:512
	ds_read_b32 v5, v185 offset:512
	ds_read_b32 v6, v186 offset:512
	ds_read_b32 v7, v187 offset:512
	ds_read_b32 v8, v188 offset:384
	ds_read_b32 v9, v189 offset:384
	ds_read_b32 v10, v190 offset:384
	ds_read_b32 v11, v191 offset:384
	ds_read_b32 v12, v188 offset:512
	ds_read_b32 v13, v189 offset:512
	ds_read_b32 v14, v190 offset:512
	ds_read_b32 v15, v191 offset:512
	s_waitcnt lgkmcnt(0)
	v_mov_b32_e32 v205, v201
	s_nop 1
	v_permlane16_swap_b32_e32 v201, v205
	v_add_f32_e32 v201, v201, v205
	v_mov_b32_e32 v205, v201
	s_nop 1
	v_permlane32_swap_b32_e32 v201, v205
	v_add_f32_e32 v201, v201, v205
	v_rcp_f32_e32 v203, v201
	s_nop 7
	v_mul_f32_e32 v32, v32, v203
	v_mul_f32_e32 v33, v33, v203
	v_mul_f32_e32 v34, v34, v203
	v_mul_f32_e32 v35, v35, v203
	v_mul_f32_e32 v36, v36, v203
	v_mul_f32_e32 v37, v37, v203
	v_mul_f32_e32 v38, v38, v203
	v_mul_f32_e32 v39, v39, v203
	v_mul_f32_e32 v40, v40, v203
	v_mul_f32_e32 v41, v41, v203
	v_mul_f32_e32 v42, v42, v203
	v_mul_f32_e32 v43, v43, v203
	v_mul_f32_e32 v44, v44, v203
	v_mul_f32_e32 v45, v45, v203
	v_mul_f32_e32 v46, v46, v203
	v_mul_f32_e32 v47, v47, v203
	v_cvt_pk_bf16_f32 v210, v32, v33
	v_cvt_pk_bf16_f32 v211, v34, v35
	v_cvt_pk_bf16_f32 v212, v36, v37
	v_cvt_pk_bf16_f32 v213, v38, v39
	v_cvt_pk_bf16_f32 v214, v40, v41
	v_cvt_pk_bf16_f32 v215, v42, v43
	v_cvt_pk_bf16_f32 v216, v44, v45
	v_cvt_pk_bf16_f32 v217, v46, v47
	global_store_dwordx2 v167, v[210:211], s[98:99] offset:0
	global_store_dwordx2 v167, v[212:213], s[98:99] offset:32
	global_store_dwordx2 v167, v[214:215], s[98:99] offset:64
	global_store_dwordx2 v167, v[216:217], s[98:99] offset:96
	v_mov_b32_e32 v200, 0xf149f2ca
	v_mov_b32_e32 v201, 0
	v_mov_b32_e32 v32, 0
	v_mov_b32_e32 v33, 0
	v_mov_b32_e32 v34, 0
	v_mov_b32_e32 v35, 0
	v_mov_b32_e32 v36, 0
	v_mov_b32_e32 v37, 0
	v_mov_b32_e32 v38, 0
	v_mov_b32_e32 v39, 0
	v_mov_b32_e32 v40, 0
	v_mov_b32_e32 v41, 0
	v_mov_b32_e32 v42, 0
	v_mov_b32_e32 v43, 0
	v_mov_b32_e32 v44, 0
	v_mov_b32_e32 v45, 0
	v_mov_b32_e32 v46, 0
	v_mov_b32_e32 v47, 0
	v_mov_b32_e32 v64, v72
	v_mov_b32_e32 v65, v73
	v_mov_b32_e32 v66, v74
	v_mov_b32_e32 v67, v75
	v_mov_b32_e32 v68, v76
	v_mov_b32_e32 v69, v77
	v_mov_b32_e32 v70, v78
	v_mov_b32_e32 v71, v79
	v_mov_b32_e32 v205, v247
	s_nop 1
	v_permlane16_swap_b32_e32 v247, v205
	v_add_f32_e32 v247, v247, v205
	v_mov_b32_e32 v205, v247
	s_nop 1
	v_permlane32_swap_b32_e32 v247, v205
	v_add_f32_e32 v247, v247, v205
	v_rcp_f32_e32 v203, v247
	s_nop 7
	v_mul_f32_e32 v176, v176, v203
	v_mul_f32_e32 v177, v177, v203
	v_mul_f32_e32 v178, v178, v203
	v_mul_f32_e32 v179, v179, v203
	v_mul_f32_e32 v180, v180, v203
	v_mul_f32_e32 v181, v181, v203
	v_mul_f32_e32 v182, v182, v203
	v_mul_f32_e32 v183, v183, v203
	v_mul_f32_e32 v192, v192, v203
	v_mul_f32_e32 v193, v193, v203
	v_mul_f32_e32 v194, v194, v203
	v_mul_f32_e32 v195, v195, v203
	v_mul_f32_e32 v196, v196, v203
	v_mul_f32_e32 v197, v197, v203
	v_mul_f32_e32 v198, v198, v203
	v_mul_f32_e32 v199, v199, v203
	v_cvt_pk_bf16_f32 v210, v176, v177
	v_cvt_pk_bf16_f32 v211, v178, v179
	v_cvt_pk_bf16_f32 v212, v180, v181
	v_cvt_pk_bf16_f32 v213, v182, v183
	v_cvt_pk_bf16_f32 v214, v192, v193
	v_cvt_pk_bf16_f32 v215, v194, v195
	v_cvt_pk_bf16_f32 v216, v196, v197
	v_cvt_pk_bf16_f32 v217, v198, v199
	s_add_u32 s0, s98, 0x20000
	s_addc_u32 s1, s99, 0
	global_store_dwordx2 v167, v[210:211], s[0:1] offset:0
	global_store_dwordx2 v167, v[212:213], s[0:1] offset:32
	global_store_dwordx2 v167, v[214:215], s[0:1] offset:64
	global_store_dwordx2 v167, v[216:217], s[0:1] offset:96
	v_mov_b32_e32 v246, 0xf149f2ca
	v_mov_b32_e32 v247, 0
	v_mov_b32_e32 v176, 0
	v_mov_b32_e32 v177, 0
	v_mov_b32_e32 v178, 0
	v_mov_b32_e32 v179, 0
	v_mov_b32_e32 v180, 0
	v_mov_b32_e32 v181, 0
	v_mov_b32_e32 v182, 0
	v_mov_b32_e32 v183, 0
	v_mov_b32_e32 v192, 0
	v_mov_b32_e32 v193, 0
	v_mov_b32_e32 v194, 0
	v_mov_b32_e32 v195, 0
	v_mov_b32_e32 v196, 0
	v_mov_b32_e32 v197, 0
	v_mov_b32_e32 v198, 0
	v_mov_b32_e32 v199, 0
	v_mov_b32_e32 v230, v238
	v_mov_b32_e32 v231, v239
	v_mov_b32_e32 v232, v240
	v_mov_b32_e32 v233, v241
	v_mov_b32_e32 v234, v242
	v_mov_b32_e32 v235, v243
	v_mov_b32_e32 v236, v244
	v_mov_b32_e32 v237, v245
	s_add_u32 s3, s3, 1
	s_and_b32 s0, s3, 0xff
	s_cmp_lt_u32 s0, 8
	s_cbranch_scc1 .Lmy_att_tile
	s_waitcnt vmcnt(0)
	s_branch .LBB0_1501
